# epilogue dwordx4 stores written through (sc1) so the grid barriers' L2 write-back has less to flush; plus the attention epilogue LDS transpose
# baseline (speedup 1.0000x reference)
.LBB0_271:
	v_or_b32_e32 v140, s22, v164
	v_mov_b64_e32 v[168:169], s[74:75]
	v_ashrrev_i32_e32 v141, 31, v140
	v_mad_i64_i32 v[168:169], s[10:11], v167, s56, v[168:169]
	v_lshl_add_u64 v[172:173], v[140:141], 1, v[168:169]
	v_cvt_pk_bf16_f32 v168, v156, v157
	v_cvt_pk_bf16_f32 v169, v154, v155
	v_cvt_pk_bf16_f32 v170, v150, v151
	v_cvt_pk_bf16_f32 v171, v146, v147
	global_store_dwordx4 v[172:173], v[168:171], off sc1
	v_cvt_pk_bf16_f32 v146, v152, v153
	v_cvt_pk_bf16_f32 v147, v148, v149
	v_cvt_pk_bf16_f32 v148, v144, v145
	v_cvt_pk_bf16_f32 v149, v142, v143
	v_cndmask_b32_e64 v142, 0, 1, s[2:3]
	global_store_dwordx4 v[172:173], v[146:149], off offset:128 sc1
	v_cmp_ne_u32_e64 s[10:11], 1, v142
	s_andn2_b64 vcc, exec, s[2:3]
	v_mov_b32_e32 v143, v101
	v_mov_b32_e32 v142, v100
	v_mov_b32_e32 v145, v99
	v_mov_b32_e32 v144, v98
	v_mov_b32_e32 v149, v105
	v_mov_b32_e32 v148, v104
	v_mov_b32_e32 v153, v103
	v_mov_b32_e32 v152, v102
	v_mov_b32_e32 v147, v109
	v_mov_b32_e32 v146, v108
	v_mov_b32_e32 v151, v107
	v_mov_b32_e32 v150, v106
	v_mov_b32_e32 v155, v113
	v_mov_b32_e32 v154, v112
	v_mov_b32_e32 v157, v111
	v_mov_b32_e32 v156, v110
	s_cbranch_vccnz .LBB0_273
	v_mov_b32_e32 v142, s26
	v_cndmask_b32_e64 v142, v161, v142, s[8:9]
	v_lshlrev_b32_e32 v202, 7, v142
	v_lshl_add_u64 v[146:147], v[138:139], 0, v[202:203]
	s_mov_b64 s[2:3], 0x2000
	v_lshl_add_u64 v[142:143], v[146:147], 0, s[2:3]
	global_load_dwordx4 v[142:145], v[142:143], off offset:16
	v_add_co_u32_e32 v148, vcc, 0x2000, v146
	global_load_dwordx4 v[168:171], v[146:147], off offset:16
	s_nop 0
	v_addc_co_u32_e32 v149, vcc, 0, v147, vcc
	global_load_dwordx4 v[152:155], v[148:149], off
	global_load_dwordx4 v[172:175], v[146:147], off
	s_waitcnt vmcnt(0)
	v_pk_mul_f32 v[146:147], v[100:101], v[144:145]
	v_pk_mul_f32 v[148:149], v[98:99], v[142:143]
	v_pk_mul_f32 v[144:145], v[108:109], v[144:145]
	v_pk_mul_f32 v[176:177], v[106:107], v[142:143]
	v_pk_fma_f32 v[146:147], v[108:109], v[170:171], v[146:147] neg_lo:[0,0,1] neg_hi:[0,0,1]
	v_pk_fma_f32 v[150:151], v[106:107], v[168:169], v[148:149] neg_lo:[0,0,1] neg_hi:[0,0,1]
	v_pk_fma_f32 v[142:143], v[100:101], v[170:171], v[144:145]
	v_pk_mul_f32 v[144:145], v[104:105], v[154:155]
	v_pk_mul_f32 v[148:149], v[102:103], v[152:153]
	v_pk_mul_f32 v[170:171], v[112:113], v[154:155]
	v_pk_mul_f32 v[152:153], v[110:111], v[152:153]
	v_pk_fma_f32 v[154:155], v[112:113], v[174:175], v[144:145] neg_lo:[0,0,1] neg_hi:[0,0,1]
	v_pk_fma_f32 v[156:157], v[110:111], v[172:173], v[148:149] neg_lo:[0,0,1] neg_hi:[0,0,1]
	v_pk_fma_f32 v[148:149], v[104:105], v[174:175], v[170:171]
	v_pk_fma_f32 v[152:153], v[102:103], v[172:173], v[152:153]
	v_pk_fma_f32 v[144:145], v[98:99], v[168:169], v[176:177]
.LBB0_273:
	v_or_b32_e32 v170, 16, v167
	v_mov_b64_e32 v[168:169], s[74:75]
	v_mad_i64_i32 v[168:169], s[2:3], v170, s56, v[168:169]
	v_lshl_add_u64 v[172:173], v[140:141], 1, v[168:169]
	v_cvt_pk_bf16_f32 v168, v156, v157
	v_cvt_pk_bf16_f32 v169, v154, v155
	v_cvt_pk_bf16_f32 v170, v150, v151
	v_cvt_pk_bf16_f32 v171, v146, v147
	global_store_dwordx4 v[172:173], v[168:171], off sc1
	v_cvt_pk_bf16_f32 v146, v152, v153
	v_cvt_pk_bf16_f32 v147, v148, v149
	v_cvt_pk_bf16_f32 v148, v144, v145
	v_cvt_pk_bf16_f32 v149, v142, v143
	global_store_dwordx4 v[172:173], v[146:149], off offset:128 sc1
	s_and_b64 vcc, exec, s[10:11]
	v_mov_b32_e32 v143, v85
	v_mov_b32_e32 v142, v84
	v_mov_b32_e32 v145, v83
	v_mov_b32_e32 v144, v82
	v_mov_b32_e32 v149, v89
	v_mov_b32_e32 v148, v88
	v_mov_b32_e32 v153, v87
	v_mov_b32_e32 v152, v86
	v_mov_b32_e32 v147, v93
	v_mov_b32_e32 v146, v92
	v_mov_b32_e32 v151, v91
	v_mov_b32_e32 v150, v90
	v_mov_b32_e32 v155, v97
	v_mov_b32_e32 v154, v96
	v_mov_b32_e32 v157, v95
	v_mov_b32_e32 v156, v94
	s_cbranch_vccnz .LBB0_275
	v_mov_b32_e32 v142, s26
	v_cndmask_b32_e64 v142, v162, v142, s[8:9]
	v_lshlrev_b32_e32 v202, 7, v142
	v_lshl_add_u64 v[146:147], v[138:139], 0, v[202:203]
	s_mov_b64 s[2:3], 0x2000
	v_lshl_add_u64 v[142:143], v[146:147], 0, s[2:3]
	global_load_dwordx4 v[142:145], v[142:143], off offset:16
	v_add_co_u32_e32 v148, vcc, 0x2000, v146
	global_load_dwordx4 v[168:171], v[146:147], off offset:16
	s_nop 0
	v_addc_co_u32_e32 v149, vcc, 0, v147, vcc
	global_load_dwordx4 v[152:155], v[148:149], off
	global_load_dwordx4 v[172:175], v[146:147], off
	s_waitcnt vmcnt(0)
	v_pk_mul_f32 v[146:147], v[84:85], v[144:145]
	v_pk_mul_f32 v[148:149], v[82:83], v[142:143]
	v_pk_mul_f32 v[144:145], v[92:93], v[144:145]
	v_pk_mul_f32 v[176:177], v[90:91], v[142:143]
	v_pk_fma_f32 v[146:147], v[92:93], v[170:171], v[146:147] neg_lo:[0,0,1] neg_hi:[0,0,1]
	v_pk_fma_f32 v[150:151], v[90:91], v[168:169], v[148:149] neg_lo:[0,0,1] neg_hi:[0,0,1]
	v_pk_fma_f32 v[142:143], v[84:85], v[170:171], v[144:145]
	v_pk_mul_f32 v[144:145], v[88:89], v[154:155]
	v_pk_mul_f32 v[148:149], v[86:87], v[152:153]
	v_pk_mul_f32 v[170:171], v[96:97], v[154:155]
	v_pk_mul_f32 v[152:153], v[94:95], v[152:153]
	v_pk_fma_f32 v[154:155], v[96:97], v[174:175], v[144:145] neg_lo:[0,0,1] neg_hi:[0,0,1]
	v_pk_fma_f32 v[156:157], v[94:95], v[172:173], v[148:149] neg_lo:[0,0,1] neg_hi:[0,0,1]
	v_pk_fma_f32 v[148:149], v[88:89], v[174:175], v[170:171]
	v_pk_fma_f32 v[152:153], v[86:87], v[172:173], v[152:153]
	v_pk_fma_f32 v[144:145], v[82:83], v[168:169], v[176:177]
.LBB0_275:
	v_or_b32_e32 v170, 32, v167
	v_mov_b64_e32 v[168:169], s[74:75]
	v_mad_i64_i32 v[168:169], s[2:3], v170, s56, v[168:169]
	v_lshl_add_u64 v[172:173], v[140:141], 1, v[168:169]
	v_cvt_pk_bf16_f32 v168, v156, v157
	v_cvt_pk_bf16_f32 v169, v154, v155
	v_cvt_pk_bf16_f32 v170, v150, v151
	v_cvt_pk_bf16_f32 v171, v146, v147
	global_store_dwordx4 v[172:173], v[168:171], off sc1
	v_cvt_pk_bf16_f32 v146, v152, v153
	v_cvt_pk_bf16_f32 v147, v148, v149
	v_cvt_pk_bf16_f32 v148, v144, v145
	v_cvt_pk_bf16_f32 v149, v142, v143
	global_store_dwordx4 v[172:173], v[146:149], off offset:128 sc1
	s_and_b64 vcc, exec, s[10:11]
	v_mov_b32_e32 v143, v69
	v_mov_b32_e32 v142, v68
	v_mov_b32_e32 v145, v67
	v_mov_b32_e32 v144, v66
	v_mov_b32_e32 v149, v73
	v_mov_b32_e32 v148, v72
	v_mov_b32_e32 v153, v71
	v_mov_b32_e32 v152, v70
	v_mov_b32_e32 v147, v77
	v_mov_b32_e32 v146, v76
	v_mov_b32_e32 v151, v75
	v_mov_b32_e32 v150, v74
	v_mov_b32_e32 v155, v81
	v_mov_b32_e32 v154, v80
	v_mov_b32_e32 v157, v79
	v_mov_b32_e32 v156, v78
	s_cbranch_vccnz .LBB0_277
	v_mov_b32_e32 v142, s26
	v_cndmask_b32_e64 v142, v163, v142, s[8:9]
	v_lshlrev_b32_e32 v202, 7, v142
	v_lshl_add_u64 v[146:147], v[138:139], 0, v[202:203]
	s_mov_b64 s[2:3], 0x2000
	v_lshl_add_u64 v[142:143], v[146:147], 0, s[2:3]
	global_load_dwordx4 v[142:145], v[142:143], off offset:16
	v_add_co_u32_e32 v148, vcc, 0x2000, v146
	global_load_dwordx4 v[168:171], v[146:147], off offset:16
	s_nop 0
	v_addc_co_u32_e32 v149, vcc, 0, v147, vcc
	global_load_dwordx4 v[152:155], v[148:149], off
	global_load_dwordx4 v[172:175], v[146:147], off
	s_waitcnt vmcnt(0)
	v_pk_mul_f32 v[146:147], v[68:69], v[144:145]
	v_pk_mul_f32 v[148:149], v[66:67], v[142:143]
	v_pk_mul_f32 v[144:145], v[76:77], v[144:145]
	v_pk_mul_f32 v[176:177], v[74:75], v[142:143]
	v_pk_fma_f32 v[146:147], v[76:77], v[170:171], v[146:147] neg_lo:[0,0,1] neg_hi:[0,0,1]
	v_pk_fma_f32 v[150:151], v[74:75], v[168:169], v[148:149] neg_lo:[0,0,1] neg_hi:[0,0,1]
	v_pk_fma_f32 v[142:143], v[68:69], v[170:171], v[144:145]
	v_pk_mul_f32 v[144:145], v[72:73], v[154:155]
	v_pk_mul_f32 v[148:149], v[70:71], v[152:153]
	v_pk_mul_f32 v[170:171], v[80:81], v[154:155]
	v_pk_mul_f32 v[152:153], v[78:79], v[152:153]
	v_pk_fma_f32 v[154:155], v[80:81], v[174:175], v[144:145] neg_lo:[0,0,1] neg_hi:[0,0,1]
	v_pk_fma_f32 v[156:157], v[78:79], v[172:173], v[148:149] neg_lo:[0,0,1] neg_hi:[0,0,1]
	v_pk_fma_f32 v[148:149], v[72:73], v[174:175], v[170:171]
	v_pk_fma_f32 v[152:153], v[70:71], v[172:173], v[152:153]
	v_pk_fma_f32 v[144:145], v[66:67], v[168:169], v[176:177]
.LBB0_277:
	v_or_b32_e32 v170, 48, v167
	v_mov_b64_e32 v[168:169], s[74:75]
	v_mad_i64_i32 v[168:169], s[2:3], v170, s56, v[168:169]
	v_lshl_add_u64 v[172:173], v[140:141], 1, v[168:169]
	v_cvt_pk_bf16_f32 v168, v156, v157
	v_cvt_pk_bf16_f32 v169, v154, v155
	v_cvt_pk_bf16_f32 v170, v150, v151
	v_cvt_pk_bf16_f32 v171, v146, v147
	global_store_dwordx4 v[172:173], v[168:171], off sc1
	v_cvt_pk_bf16_f32 v146, v152, v153
	v_cvt_pk_bf16_f32 v147, v148, v149
	v_cvt_pk_bf16_f32 v148, v144, v145
	v_cvt_pk_bf16_f32 v149, v142, v143
	global_store_dwordx4 v[172:173], v[146:149], off offset:128 sc1
	s_nop 0
	v_add_u32_e32 v169, 0x80, v167
	v_bfe_u32 v168, v169, 6, 5
	s_and_b64 vcc, exec, s[10:11]
	v_mov_b32_e32 v143, v53
	v_mov_b32_e32 v142, v52
	v_mov_b32_e32 v145, v51
	v_mov_b32_e32 v144, v50
	v_mov_b32_e32 v149, v57
	v_mov_b32_e32 v148, v56
	v_mov_b32_e32 v153, v55
	v_mov_b32_e32 v152, v54
	v_mov_b32_e32 v147, v61
	v_mov_b32_e32 v146, v60
	v_mov_b32_e32 v151, v59
	v_mov_b32_e32 v150, v58
	v_mov_b32_e32 v155, v65
	v_mov_b32_e32 v154, v64
	v_mov_b32_e32 v157, v63
	v_mov_b32_e32 v156, v62
	s_cbranch_vccnz .LBB0_279
	v_cndmask_b32_e64 v142, v159, v168, s[8:9]
	v_lshlrev_b32_e32 v202, 7, v142
	v_lshl_add_u64 v[146:147], v[138:139], 0, v[202:203]
	s_mov_b64 s[2:3], 0x2000
	v_lshl_add_u64 v[142:143], v[146:147], 0, s[2:3]
	global_load_dwordx4 v[142:145], v[142:143], off offset:16
	v_add_co_u32_e32 v148, vcc, 0x2000, v146
	global_load_dwordx4 v[170:173], v[146:147], off offset:16
	s_nop 0
	v_addc_co_u32_e32 v149, vcc, 0, v147, vcc
	global_load_dwordx4 v[152:155], v[148:149], off
	global_load_dwordx4 v[174:177], v[146:147], off
	s_waitcnt vmcnt(0)
	v_pk_mul_f32 v[146:147], v[52:53], v[144:145]
	v_pk_mul_f32 v[148:149], v[50:51], v[142:143]
	v_pk_mul_f32 v[144:145], v[60:61], v[144:145]
	v_pk_mul_f32 v[178:179], v[58:59], v[142:143]
	v_pk_fma_f32 v[146:147], v[60:61], v[172:173], v[146:147] neg_lo:[0,0,1] neg_hi:[0,0,1]
	v_pk_fma_f32 v[150:151], v[58:59], v[170:171], v[148:149] neg_lo:[0,0,1] neg_hi:[0,0,1]
	v_pk_fma_f32 v[142:143], v[52:53], v[172:173], v[144:145]
	v_pk_mul_f32 v[144:145], v[56:57], v[154:155]
	v_pk_mul_f32 v[148:149], v[54:55], v[152:153]
	v_pk_mul_f32 v[172:173], v[64:65], v[154:155]
	v_pk_mul_f32 v[152:153], v[62:63], v[152:153]
	v_pk_fma_f32 v[154:155], v[64:65], v[176:177], v[144:145] neg_lo:[0,0,1] neg_hi:[0,0,1]
	v_pk_fma_f32 v[156:157], v[62:63], v[174:175], v[148:149] neg_lo:[0,0,1] neg_hi:[0,0,1]
	v_pk_fma_f32 v[148:149], v[56:57], v[176:177], v[172:173]
	v_pk_fma_f32 v[152:153], v[54:55], v[174:175], v[152:153]
	v_pk_fma_f32 v[144:145], v[50:51], v[170:171], v[178:179]
.LBB0_279:
	v_mov_b64_e32 v[170:171], s[74:75]
	v_mad_i64_i32 v[170:171], s[2:3], v169, s56, v[170:171]
	v_lshl_add_u64 v[174:175], v[140:141], 1, v[170:171]
	v_cvt_pk_bf16_f32 v170, v156, v157
	v_cvt_pk_bf16_f32 v171, v154, v155
	v_cvt_pk_bf16_f32 v172, v150, v151
	v_cvt_pk_bf16_f32 v173, v146, v147
	global_store_dwordx4 v[174:175], v[170:173], off sc1
	v_cvt_pk_bf16_f32 v146, v152, v153
	v_cvt_pk_bf16_f32 v147, v148, v149
	v_cvt_pk_bf16_f32 v148, v144, v145
	v_cvt_pk_bf16_f32 v149, v142, v143
	global_store_dwordx4 v[174:175], v[146:149], off offset:128 sc1
	s_and_b64 vcc, exec, s[10:11]
	v_mov_b32_e32 v143, v37
	v_mov_b32_e32 v142, v36
	v_mov_b32_e32 v145, v35
	v_mov_b32_e32 v144, v34
	v_mov_b32_e32 v149, v41
	v_mov_b32_e32 v148, v40
	v_mov_b32_e32 v153, v39
	v_mov_b32_e32 v152, v38
	v_mov_b32_e32 v147, v45
	v_mov_b32_e32 v146, v44
	v_mov_b32_e32 v151, v43
	v_mov_b32_e32 v150, v42
	v_mov_b32_e32 v155, v49
	v_mov_b32_e32 v154, v48
	v_mov_b32_e32 v157, v47
	v_mov_b32_e32 v156, v46
	s_cbranch_vccnz .LBB0_281
	v_cndmask_b32_e64 v142, v161, v168, s[8:9]
	v_lshlrev_b32_e32 v202, 7, v142
	v_lshl_add_u64 v[146:147], v[138:139], 0, v[202:203]
	s_mov_b64 s[2:3], 0x2000
	v_lshl_add_u64 v[142:143], v[146:147], 0, s[2:3]
	global_load_dwordx4 v[142:145], v[142:143], off offset:16
	v_add_co_u32_e32 v148, vcc, 0x2000, v146
	global_load_dwordx4 v[170:173], v[146:147], off offset:16
	s_nop 0
	v_addc_co_u32_e32 v149, vcc, 0, v147, vcc
	global_load_dwordx4 v[152:155], v[148:149], off
	global_load_dwordx4 v[174:177], v[146:147], off
	s_waitcnt vmcnt(0)
	v_pk_mul_f32 v[146:147], v[36:37], v[144:145]
	v_pk_mul_f32 v[148:149], v[34:35], v[142:143]
	v_pk_mul_f32 v[144:145], v[44:45], v[144:145]
	v_pk_mul_f32 v[178:179], v[42:43], v[142:143]
	v_pk_fma_f32 v[146:147], v[44:45], v[172:173], v[146:147] neg_lo:[0,0,1] neg_hi:[0,0,1]
	v_pk_fma_f32 v[150:151], v[42:43], v[170:171], v[148:149] neg_lo:[0,0,1] neg_hi:[0,0,1]
	v_pk_fma_f32 v[142:143], v[36:37], v[172:173], v[144:145]
	v_pk_mul_f32 v[144:145], v[40:41], v[154:155]
	v_pk_mul_f32 v[148:149], v[38:39], v[152:153]
	v_pk_mul_f32 v[172:173], v[48:49], v[154:155]
	v_pk_mul_f32 v[152:153], v[46:47], v[152:153]
	v_pk_fma_f32 v[154:155], v[48:49], v[176:177], v[144:145] neg_lo:[0,0,1] neg_hi:[0,0,1]
	v_pk_fma_f32 v[156:157], v[46:47], v[174:175], v[148:149] neg_lo:[0,0,1] neg_hi:[0,0,1]
	v_pk_fma_f32 v[148:149], v[40:41], v[176:177], v[172:173]
	v_pk_fma_f32 v[152:153], v[38:39], v[174:175], v[152:153]
	v_pk_fma_f32 v[144:145], v[34:35], v[170:171], v[178:179]
.LBB0_281:
	v_add_u32_e32 v169, 0x90, v167
	v_mov_b64_e32 v[170:171], s[74:75]
	v_mad_i64_i32 v[170:171], s[2:3], v169, s56, v[170:171]
	v_lshl_add_u64 v[174:175], v[140:141], 1, v[170:171]
	v_cvt_pk_bf16_f32 v170, v156, v157
	v_cvt_pk_bf16_f32 v171, v154, v155
	v_cvt_pk_bf16_f32 v172, v150, v151
	v_cvt_pk_bf16_f32 v173, v146, v147
	global_store_dwordx4 v[174:175], v[170:173], off sc1
	v_cvt_pk_bf16_f32 v146, v152, v153
	v_cvt_pk_bf16_f32 v147, v148, v149
	v_cvt_pk_bf16_f32 v148, v144, v145
	v_cvt_pk_bf16_f32 v149, v142, v143
	global_store_dwordx4 v[174:175], v[146:149], off offset:128 sc1
	s_and_b64 vcc, exec, s[10:11]
	v_mov_b32_e32 v143, v21
	v_mov_b32_e32 v142, v20
	v_mov_b32_e32 v145, v19
	v_mov_b32_e32 v144, v18
	v_mov_b32_e32 v149, v25
	v_mov_b32_e32 v148, v24
	v_mov_b32_e32 v153, v23
	v_mov_b32_e32 v152, v22
	v_mov_b32_e32 v147, v29
	v_mov_b32_e32 v146, v28
	v_mov_b32_e32 v151, v27
	v_mov_b32_e32 v150, v26
	v_mov_b32_e32 v155, v33
	v_mov_b32_e32 v154, v32
	v_mov_b32_e32 v157, v31
	v_mov_b32_e32 v156, v30
	s_cbranch_vccnz .LBB0_283
	v_cndmask_b32_e64 v142, v162, v168, s[8:9]
	v_lshlrev_b32_e32 v202, 7, v142
	v_lshl_add_u64 v[146:147], v[138:139], 0, v[202:203]
	s_mov_b64 s[2:3], 0x2000
	v_lshl_add_u64 v[142:143], v[146:147], 0, s[2:3]
	global_load_dwordx4 v[142:145], v[142:143], off offset:16
	v_add_co_u32_e32 v148, vcc, 0x2000, v146
	global_load_dwordx4 v[170:173], v[146:147], off offset:16
	s_nop 0
	v_addc_co_u32_e32 v149, vcc, 0, v147, vcc
	global_load_dwordx4 v[152:155], v[148:149], off
	global_load_dwordx4 v[174:177], v[146:147], off
	s_waitcnt vmcnt(0)
	v_pk_mul_f32 v[146:147], v[20:21], v[144:145]
	v_pk_mul_f32 v[148:149], v[18:19], v[142:143]
	v_pk_mul_f32 v[144:145], v[28:29], v[144:145]
	v_pk_mul_f32 v[178:179], v[26:27], v[142:143]
	v_pk_fma_f32 v[146:147], v[28:29], v[172:173], v[146:147] neg_lo:[0,0,1] neg_hi:[0,0,1]
	v_pk_fma_f32 v[150:151], v[26:27], v[170:171], v[148:149] neg_lo:[0,0,1] neg_hi:[0,0,1]
	v_pk_fma_f32 v[142:143], v[20:21], v[172:173], v[144:145]
	v_pk_mul_f32 v[144:145], v[24:25], v[154:155]
	v_pk_mul_f32 v[148:149], v[22:23], v[152:153]
	v_pk_mul_f32 v[172:173], v[32:33], v[154:155]
	v_pk_mul_f32 v[152:153], v[30:31], v[152:153]
	v_pk_fma_f32 v[154:155], v[32:33], v[176:177], v[144:145] neg_lo:[0,0,1] neg_hi:[0,0,1]
	v_pk_fma_f32 v[156:157], v[30:31], v[174:175], v[148:149] neg_lo:[0,0,1] neg_hi:[0,0,1]
	v_pk_fma_f32 v[148:149], v[24:25], v[176:177], v[172:173]
	v_pk_fma_f32 v[152:153], v[22:23], v[174:175], v[152:153]
	v_pk_fma_f32 v[144:145], v[18:19], v[170:171], v[178:179]
.LBB0_283:
	v_add_u32_e32 v169, 0xa0, v167
	v_mov_b64_e32 v[170:171], s[74:75]
	v_mad_i64_i32 v[170:171], s[2:3], v169, s56, v[170:171]
	v_lshl_add_u64 v[174:175], v[140:141], 1, v[170:171]
	v_cvt_pk_bf16_f32 v170, v156, v157
	v_cvt_pk_bf16_f32 v171, v154, v155
	v_cvt_pk_bf16_f32 v172, v150, v151
	v_cvt_pk_bf16_f32 v173, v146, v147
	global_store_dwordx4 v[174:175], v[170:173], off sc1
	v_cvt_pk_bf16_f32 v146, v152, v153
	v_cvt_pk_bf16_f32 v147, v148, v149
	v_cvt_pk_bf16_f32 v148, v144, v145
	v_cvt_pk_bf16_f32 v149, v142, v143
	global_store_dwordx4 v[174:175], v[146:149], off offset:128 sc1
	s_and_b64 vcc, exec, s[10:11]
	v_mov_b32_e32 v143, v5
	v_mov_b32_e32 v142, v4
	v_mov_b32_e32 v145, v3
	v_mov_b32_e32 v144, v2
	v_mov_b32_e32 v147, v9
	v_mov_b32_e32 v146, v8
	v_mov_b32_e32 v151, v7
	v_mov_b32_e32 v150, v6
	v_mov_b32_e32 v149, v13
	v_mov_b32_e32 v148, v12
	v_mov_b32_e32 v153, v11
	v_mov_b32_e32 v152, v10
	v_mov_b32_e32 v155, v17
	v_mov_b32_e32 v154, v16
	v_mov_b32_e32 v157, v15
	v_mov_b32_e32 v156, v14
	s_cbranch_vccnz .LBB0_285
	v_cndmask_b32_e64 v142, v163, v168, s[8:9]
	v_lshlrev_b32_e32 v202, 7, v142
	v_lshl_add_u64 v[146:147], v[138:139], 0, v[202:203]
	s_mov_b64 s[2:3], 0x2000
	v_lshl_add_u64 v[142:143], v[146:147], 0, s[2:3]
	global_load_dwordx4 v[142:145], v[142:143], off offset:16
	v_add_co_u32_e32 v148, vcc, 0x2000, v146
	global_load_dwordx4 v[168:171], v[146:147], off offset:16
	s_nop 0
	v_addc_co_u32_e32 v149, vcc, 0, v147, vcc
	global_load_dwordx4 v[154:157], v[148:149], off
	global_load_dwordx4 v[172:175], v[146:147], off
	s_waitcnt vmcnt(0)
	v_pk_mul_f32 v[146:147], v[4:5], v[144:145]
	v_pk_mul_f32 v[150:151], v[2:3], v[142:143]
	v_pk_mul_f32 v[144:145], v[12:13], v[144:145]
	v_pk_mul_f32 v[176:177], v[10:11], v[142:143]
	v_pk_fma_f32 v[148:149], v[12:13], v[170:171], v[146:147] neg_lo:[0,0,1] neg_hi:[0,0,1]
	v_pk_fma_f32 v[152:153], v[10:11], v[168:169], v[150:151] neg_lo:[0,0,1] neg_hi:[0,0,1]
	v_pk_fma_f32 v[142:143], v[4:5], v[170:171], v[144:145]
	v_pk_mul_f32 v[144:145], v[8:9], v[156:157]
	v_pk_mul_f32 v[146:147], v[6:7], v[154:155]
	v_pk_mul_f32 v[150:151], v[16:17], v[156:157]
	v_pk_mul_f32 v[170:171], v[14:15], v[154:155]
	v_pk_fma_f32 v[154:155], v[16:17], v[174:175], v[144:145] neg_lo:[0,0,1] neg_hi:[0,0,1]
	v_pk_fma_f32 v[156:157], v[14:15], v[172:173], v[146:147] neg_lo:[0,0,1] neg_hi:[0,0,1]
	v_pk_fma_f32 v[146:147], v[8:9], v[174:175], v[150:151]
	v_pk_fma_f32 v[150:151], v[6:7], v[172:173], v[170:171]
	v_pk_fma_f32 v[144:145], v[2:3], v[168:169], v[176:177]
.LBB0_285:
	v_add_u32_e32 v170, 0xb0, v167
	v_mov_b64_e32 v[168:169], s[74:75]
	v_mad_i64_i32 v[168:169], s[2:3], v170, s56, v[168:169]
	v_lshl_add_u64 v[140:141], v[140:141], 1, v[168:169]
	v_cvt_pk_bf16_f32 v168, v156, v157
	v_cvt_pk_bf16_f32 v169, v154, v155
	v_cvt_pk_bf16_f32 v170, v152, v153
	v_cvt_pk_bf16_f32 v171, v148, v149
	global_store_dwordx4 v[140:141], v[168:171], off sc1
	v_cvt_pk_bf16_f32 v148, v150, v151
	v_cvt_pk_bf16_f32 v149, v146, v147
	v_cvt_pk_bf16_f32 v150, v144, v145
	v_cvt_pk_bf16_f32 v151, v142, v143
	global_store_dwordx4 v[140:141], v[148:151], off offset:128 sc1

.LBB0_290:
	v_mov_b64_e32 v[140:141], s[74:75]
	v_or_b32_e32 v202, s22, v165
	v_mad_i64_i32 v[140:141], s[2:3], v167, s56, v[140:141]
	v_cvt_pk_bf16_f32 v126, v126, v127
	v_cvt_pk_bf16_f32 v127, v128, v129
	v_cvt_pk_bf16_f32 v128, v122, v123
	v_cndmask_b32_e64 v122, 0, 1, s[26:27]
	v_lshl_add_u64 v[140:141], v[202:203], 1, v[140:141]
	v_cmp_ne_u32_e64 s[10:11], 1, v122
	s_andn2_b64 vcc, exec, s[26:27]
	v_cvt_pk_bf16_f32 v129, v124, v125
	global_store_dwordx4 v[140:141], v[126:129], off sc1
	s_cbranch_vccnz .LBB0_292
	v_and_b32_e32 v123, 0x7fffffff, v119
	v_and_b32_e32 v122, 0x7fffffff, v118
	v_pk_fma_f32 v[122:123], v[122:123], s[28:29], 1.0 op_sel_hi:[1,0,0]
	v_mov_b64_e32 v[124:125], s[68:69]
	v_rcp_f32_e32 v122, v122
	v_rcp_f32_e32 v123, v123
	v_pk_mul_f32 v[128:129], v[118:119], v[118:119]
	v_cmp_gt_f32_e32 vcc, 0, v118
	v_pk_mul_f32 v[128:129], v[128:129], s[88:89] op_sel_hi:[1,0]
	v_pk_fma_f32 v[126:127], v[122:123], s[38:39], v[124:125] op_sel_hi:[1,0,0]
	v_exp_f32_e32 v128, v128
	v_pk_fma_f32 v[126:127], v[122:123], v[126:127], s[72:73] op_sel_hi:[1,1,0]
	v_exp_f32_e32 v129, v129
	v_pk_fma_f32 v[126:127], v[122:123], v[126:127], s[76:77] op_sel_hi:[1,1,0]
	s_nop 0
	v_pk_fma_f32 v[126:127], v[122:123], v[126:127], s[82:83] op_sel_hi:[1,1,0]
	s_nop 0
	v_pk_mul_f32 v[122:123], v[122:123], v[126:127]
	v_pk_mul_f32 v[126:127], v[120:121], v[120:121]
	v_pk_mul_f32 v[122:123], v[128:129], v[122:123]
	v_pk_mul_f32 v[126:127], v[126:127], s[88:89] op_sel_hi:[1,0]
	v_pk_mul_f32 v[128:129], v[118:119], v[122:123]
	v_pk_fma_f32 v[122:123], v[118:119], v[122:123], v[118:119] neg_lo:[1,0,0] neg_hi:[1,0,0]
	v_exp_f32_e32 v126, v126
	v_cndmask_b32_e32 v118, v122, v128, vcc
	v_cmp_gt_f32_e32 vcc, 0, v119
	v_and_b32_e32 v122, 0x7fffffff, v120
	v_exp_f32_e32 v127, v127
	v_cndmask_b32_e32 v119, v123, v129, vcc
	v_and_b32_e32 v123, 0x7fffffff, v121
	v_pk_fma_f32 v[122:123], v[122:123], s[28:29], 1.0 op_sel_hi:[1,0,0]
	v_cmp_gt_f32_e32 vcc, 0, v120
	v_rcp_f32_e32 v122, v122
	v_rcp_f32_e32 v123, v123
	s_nop 0
	v_pk_fma_f32 v[128:129], v[122:123], s[38:39], v[124:125] op_sel_hi:[1,0,0]
	s_nop 0
	v_pk_fma_f32 v[128:129], v[122:123], v[128:129], s[72:73] op_sel_hi:[1,1,0]
	s_nop 0
	v_pk_fma_f32 v[128:129], v[122:123], v[128:129], s[76:77] op_sel_hi:[1,1,0]
	s_nop 0
	v_pk_fma_f32 v[128:129], v[122:123], v[128:129], s[82:83] op_sel_hi:[1,1,0]
	s_nop 0
	v_pk_mul_f32 v[122:123], v[122:123], v[128:129]
	v_pk_mul_f32 v[128:129], v[114:115], v[114:115]
	v_pk_mul_f32 v[122:123], v[126:127], v[122:123]
	v_pk_mul_f32 v[128:129], v[128:129], s[88:89] op_sel_hi:[1,0]
	v_pk_mul_f32 v[126:127], v[120:121], v[122:123]
	v_pk_fma_f32 v[122:123], v[120:121], v[122:123], v[120:121] neg_lo:[1,0,0] neg_hi:[1,0,0]
	v_exp_f32_e32 v128, v128
	v_cndmask_b32_e32 v120, v122, v126, vcc
	v_cmp_gt_f32_e32 vcc, 0, v121
	v_and_b32_e32 v122, 0x7fffffff, v114
	v_exp_f32_e32 v129, v129
	v_cndmask_b32_e32 v121, v123, v127, vcc
	v_and_b32_e32 v123, 0x7fffffff, v115
	v_pk_fma_f32 v[122:123], v[122:123], s[28:29], 1.0 op_sel_hi:[1,0,0]
	v_cmp_gt_f32_e32 vcc, 0, v114
	v_rcp_f32_e32 v122, v122
	v_rcp_f32_e32 v123, v123
	s_nop 0
	v_pk_fma_f32 v[126:127], v[122:123], s[38:39], v[124:125] op_sel_hi:[1,0,0]
	s_nop 0
	v_pk_fma_f32 v[126:127], v[122:123], v[126:127], s[72:73] op_sel_hi:[1,1,0]
	s_nop 0
	v_pk_fma_f32 v[126:127], v[122:123], v[126:127], s[76:77] op_sel_hi:[1,1,0]
	s_nop 0
	v_pk_fma_f32 v[126:127], v[122:123], v[126:127], s[82:83] op_sel_hi:[1,1,0]
	s_nop 0
	v_pk_mul_f32 v[122:123], v[122:123], v[126:127]
	v_pk_mul_f32 v[126:127], v[116:117], v[116:117]
	v_pk_mul_f32 v[122:123], v[128:129], v[122:123]
	s_nop 0
	v_pk_mul_f32 v[128:129], v[114:115], v[122:123]
	v_pk_fma_f32 v[122:123], v[114:115], v[122:123], v[114:115] neg_lo:[1,0,0] neg_hi:[1,0,0]
	s_nop 0
	v_cndmask_b32_e32 v114, v122, v128, vcc
	v_cmp_gt_f32_e32 vcc, 0, v115
	v_and_b32_e32 v122, 0x7fffffff, v116
	s_nop 0
	v_cndmask_b32_e32 v115, v123, v129, vcc
	v_and_b32_e32 v123, 0x7fffffff, v117
	v_pk_fma_f32 v[122:123], v[122:123], s[28:29], 1.0 op_sel_hi:[1,0,0]
	v_cmp_gt_f32_e32 vcc, 0, v116
	v_rcp_f32_e32 v122, v122
	v_rcp_f32_e32 v123, v123
	s_nop 0
	v_pk_fma_f32 v[124:125], v[122:123], s[38:39], v[124:125] op_sel_hi:[1,0,0]
	s_nop 0
	v_pk_fma_f32 v[124:125], v[122:123], v[124:125], s[72:73] op_sel_hi:[1,1,0]
	s_nop 0
	v_pk_fma_f32 v[124:125], v[122:123], v[124:125], s[76:77] op_sel_hi:[1,1,0]
	s_nop 0
	v_pk_fma_f32 v[124:125], v[122:123], v[124:125], s[82:83] op_sel_hi:[1,1,0]
	s_nop 0
	v_pk_mul_f32 v[122:123], v[122:123], v[124:125]
	v_pk_mul_f32 v[124:125], v[126:127], s[88:89] op_sel_hi:[1,0]
	s_nop 0
	v_exp_f32_e32 v124, v124
	v_exp_f32_e32 v125, v125
	s_nop 0
	v_pk_mul_f32 v[122:123], v[124:125], v[122:123]
	s_nop 0
	v_pk_mul_f32 v[124:125], v[116:117], v[122:123]
	v_pk_fma_f32 v[122:123], v[116:117], v[122:123], v[116:117] neg_lo:[1,0,0] neg_hi:[1,0,0]
	s_nop 0
	v_cndmask_b32_e32 v116, v122, v124, vcc
	v_cmp_gt_f32_e32 vcc, 0, v117
	s_nop 1
	v_cndmask_b32_e32 v117, v123, v125, vcc
.LBB0_292:
	s_and_b64 vcc, exec, s[10:11]
	v_cvt_pk_bf16_f32 v118, v118, v119
	v_cvt_pk_bf16_f32 v119, v120, v121
	v_cvt_pk_bf16_f32 v120, v114, v115
	v_cvt_pk_bf16_f32 v121, v116, v117
	global_store_dwordx4 v[140:141], v[118:121], off offset:256 sc1
	s_cbranch_vccnz .LBB0_294
	v_and_b32_e32 v115, 0x7fffffff, v111
	v_and_b32_e32 v114, 0x7fffffff, v110
	v_pk_fma_f32 v[114:115], v[114:115], s[28:29], 1.0 op_sel_hi:[1,0,0]
	v_mov_b64_e32 v[116:117], s[68:69]
	v_rcp_f32_e32 v114, v114
	v_rcp_f32_e32 v115, v115
	v_pk_mul_f32 v[120:121], v[110:111], v[110:111]
	v_cmp_gt_f32_e32 vcc, 0, v110
	v_pk_mul_f32 v[120:121], v[120:121], s[88:89] op_sel_hi:[1,0]
	v_pk_fma_f32 v[118:119], v[114:115], s[38:39], v[116:117] op_sel_hi:[1,0,0]
	v_exp_f32_e32 v120, v120
	v_pk_fma_f32 v[118:119], v[114:115], v[118:119], s[72:73] op_sel_hi:[1,1,0]
	v_exp_f32_e32 v121, v121
	v_pk_fma_f32 v[118:119], v[114:115], v[118:119], s[76:77] op_sel_hi:[1,1,0]
	s_nop 0
	v_pk_fma_f32 v[118:119], v[114:115], v[118:119], s[82:83] op_sel_hi:[1,1,0]
	s_nop 0
	v_pk_mul_f32 v[114:115], v[114:115], v[118:119]
	v_pk_mul_f32 v[118:119], v[112:113], v[112:113]
	v_pk_mul_f32 v[114:115], v[120:121], v[114:115]
	v_pk_mul_f32 v[118:119], v[118:119], s[88:89] op_sel_hi:[1,0]
	v_pk_mul_f32 v[120:121], v[110:111], v[114:115]
	v_pk_fma_f32 v[114:115], v[110:111], v[114:115], v[110:111] neg_lo:[1,0,0] neg_hi:[1,0,0]
	v_exp_f32_e32 v118, v118
	v_cndmask_b32_e32 v110, v114, v120, vcc
	v_cmp_gt_f32_e32 vcc, 0, v111
	v_and_b32_e32 v114, 0x7fffffff, v112
	v_exp_f32_e32 v119, v119
	v_cndmask_b32_e32 v111, v115, v121, vcc
	v_and_b32_e32 v115, 0x7fffffff, v113
	v_pk_fma_f32 v[114:115], v[114:115], s[28:29], 1.0 op_sel_hi:[1,0,0]
	v_cmp_gt_f32_e32 vcc, 0, v112
	v_rcp_f32_e32 v114, v114
	v_rcp_f32_e32 v115, v115
	s_nop 0
	v_pk_fma_f32 v[120:121], v[114:115], s[38:39], v[116:117] op_sel_hi:[1,0,0]
	s_nop 0
	v_pk_fma_f32 v[120:121], v[114:115], v[120:121], s[72:73] op_sel_hi:[1,1,0]
	s_nop 0
	v_pk_fma_f32 v[120:121], v[114:115], v[120:121], s[76:77] op_sel_hi:[1,1,0]
	s_nop 0
	v_pk_fma_f32 v[120:121], v[114:115], v[120:121], s[82:83] op_sel_hi:[1,1,0]
	s_nop 0
	v_pk_mul_f32 v[114:115], v[114:115], v[120:121]
	v_pk_mul_f32 v[120:121], v[106:107], v[106:107]
	v_pk_mul_f32 v[114:115], v[118:119], v[114:115]
	v_pk_mul_f32 v[120:121], v[120:121], s[88:89] op_sel_hi:[1,0]
	v_pk_mul_f32 v[118:119], v[112:113], v[114:115]
	v_pk_fma_f32 v[114:115], v[112:113], v[114:115], v[112:113] neg_lo:[1,0,0] neg_hi:[1,0,0]
	v_exp_f32_e32 v120, v120
	v_cndmask_b32_e32 v112, v114, v118, vcc
	v_cmp_gt_f32_e32 vcc, 0, v113
	v_and_b32_e32 v114, 0x7fffffff, v106
	v_exp_f32_e32 v121, v121
	v_cndmask_b32_e32 v113, v115, v119, vcc
	v_and_b32_e32 v115, 0x7fffffff, v107
	v_pk_fma_f32 v[114:115], v[114:115], s[28:29], 1.0 op_sel_hi:[1,0,0]
	v_cmp_gt_f32_e32 vcc, 0, v106
	v_rcp_f32_e32 v114, v114
	v_rcp_f32_e32 v115, v115
	s_nop 0
	v_pk_fma_f32 v[118:119], v[114:115], s[38:39], v[116:117] op_sel_hi:[1,0,0]
	s_nop 0
	v_pk_fma_f32 v[118:119], v[114:115], v[118:119], s[72:73] op_sel_hi:[1,1,0]
	s_nop 0
	v_pk_fma_f32 v[118:119], v[114:115], v[118:119], s[76:77] op_sel_hi:[1,1,0]
	s_nop 0
	v_pk_fma_f32 v[118:119], v[114:115], v[118:119], s[82:83] op_sel_hi:[1,1,0]
	s_nop 0
	v_pk_mul_f32 v[114:115], v[114:115], v[118:119]
	v_pk_mul_f32 v[118:119], v[108:109], v[108:109]
	v_pk_mul_f32 v[114:115], v[120:121], v[114:115]
	s_nop 0
	v_pk_mul_f32 v[120:121], v[106:107], v[114:115]
	v_pk_fma_f32 v[114:115], v[106:107], v[114:115], v[106:107] neg_lo:[1,0,0] neg_hi:[1,0,0]
	s_nop 0
	v_cndmask_b32_e32 v106, v114, v120, vcc
	v_cmp_gt_f32_e32 vcc, 0, v107
	v_and_b32_e32 v114, 0x7fffffff, v108
	s_nop 0
	v_cndmask_b32_e32 v107, v115, v121, vcc
	v_and_b32_e32 v115, 0x7fffffff, v109
	v_pk_fma_f32 v[114:115], v[114:115], s[28:29], 1.0 op_sel_hi:[1,0,0]
	v_cmp_gt_f32_e32 vcc, 0, v108
	v_rcp_f32_e32 v114, v114
	v_rcp_f32_e32 v115, v115
	s_nop 0
	v_pk_fma_f32 v[116:117], v[114:115], s[38:39], v[116:117] op_sel_hi:[1,0,0]
	s_nop 0
	v_pk_fma_f32 v[116:117], v[114:115], v[116:117], s[72:73] op_sel_hi:[1,1,0]
	s_nop 0
	v_pk_fma_f32 v[116:117], v[114:115], v[116:117], s[76:77] op_sel_hi:[1,1,0]
	s_nop 0
	v_pk_fma_f32 v[116:117], v[114:115], v[116:117], s[82:83] op_sel_hi:[1,1,0]
	s_nop 0
	v_pk_mul_f32 v[114:115], v[114:115], v[116:117]
	v_pk_mul_f32 v[116:117], v[118:119], s[88:89] op_sel_hi:[1,0]
	s_nop 0
	v_exp_f32_e32 v116, v116
	v_exp_f32_e32 v117, v117
	s_nop 0
	v_pk_mul_f32 v[114:115], v[116:117], v[114:115]
	s_nop 0
	v_pk_mul_f32 v[116:117], v[108:109], v[114:115]
	v_pk_fma_f32 v[114:115], v[108:109], v[114:115], v[108:109] neg_lo:[1,0,0] neg_hi:[1,0,0]
	s_nop 0
	v_cndmask_b32_e32 v108, v114, v116, vcc
	v_cmp_gt_f32_e32 vcc, 0, v109
	s_nop 1
	v_cndmask_b32_e32 v109, v115, v117, vcc
.LBB0_294:
	v_or_b32_e32 v116, 16, v167
	v_mov_b64_e32 v[114:115], s[74:75]
	v_mad_i64_i32 v[114:115], s[2:3], v116, s56, v[114:115]
	v_lshl_add_u64 v[114:115], v[202:203], 1, v[114:115]
	s_and_b64 vcc, exec, s[10:11]
	v_cvt_pk_bf16_f32 v110, v110, v111
	v_cvt_pk_bf16_f32 v111, v112, v113
	v_cvt_pk_bf16_f32 v112, v106, v107
	v_cvt_pk_bf16_f32 v113, v108, v109
	global_store_dwordx4 v[114:115], v[110:113], off sc1
	s_cbranch_vccnz .LBB0_296
	v_and_b32_e32 v107, 0x7fffffff, v103
	v_and_b32_e32 v106, 0x7fffffff, v102
	v_pk_fma_f32 v[106:107], v[106:107], s[28:29], 1.0 op_sel_hi:[1,0,0]
	v_mov_b64_e32 v[108:109], s[68:69]
	v_rcp_f32_e32 v106, v106
	v_rcp_f32_e32 v107, v107
	v_pk_mul_f32 v[112:113], v[102:103], v[102:103]
	v_cmp_gt_f32_e32 vcc, 0, v102
	v_pk_mul_f32 v[112:113], v[112:113], s[88:89] op_sel_hi:[1,0]
	v_pk_fma_f32 v[110:111], v[106:107], s[38:39], v[108:109] op_sel_hi:[1,0,0]
	v_exp_f32_e32 v112, v112
	v_pk_fma_f32 v[110:111], v[106:107], v[110:111], s[72:73] op_sel_hi:[1,1,0]
	v_exp_f32_e32 v113, v113
	v_pk_fma_f32 v[110:111], v[106:107], v[110:111], s[76:77] op_sel_hi:[1,1,0]
	s_nop 0
	v_pk_fma_f32 v[110:111], v[106:107], v[110:111], s[82:83] op_sel_hi:[1,1,0]
	s_nop 0
	v_pk_mul_f32 v[106:107], v[106:107], v[110:111]
	v_pk_mul_f32 v[110:111], v[104:105], v[104:105]
	v_pk_mul_f32 v[106:107], v[112:113], v[106:107]
	v_pk_mul_f32 v[110:111], v[110:111], s[88:89] op_sel_hi:[1,0]
	v_pk_mul_f32 v[112:113], v[102:103], v[106:107]
	v_pk_fma_f32 v[106:107], v[102:103], v[106:107], v[102:103] neg_lo:[1,0,0] neg_hi:[1,0,0]
	v_exp_f32_e32 v110, v110
	v_cndmask_b32_e32 v102, v106, v112, vcc
	v_cmp_gt_f32_e32 vcc, 0, v103
	v_and_b32_e32 v106, 0x7fffffff, v104
	v_exp_f32_e32 v111, v111
	v_cndmask_b32_e32 v103, v107, v113, vcc
	v_and_b32_e32 v107, 0x7fffffff, v105
	v_pk_fma_f32 v[106:107], v[106:107], s[28:29], 1.0 op_sel_hi:[1,0,0]
	v_cmp_gt_f32_e32 vcc, 0, v104
	v_rcp_f32_e32 v106, v106
	v_rcp_f32_e32 v107, v107
	s_nop 0
	v_pk_fma_f32 v[112:113], v[106:107], s[38:39], v[108:109] op_sel_hi:[1,0,0]
	s_nop 0
	v_pk_fma_f32 v[112:113], v[106:107], v[112:113], s[72:73] op_sel_hi:[1,1,0]
	s_nop 0
	v_pk_fma_f32 v[112:113], v[106:107], v[112:113], s[76:77] op_sel_hi:[1,1,0]
	s_nop 0
	v_pk_fma_f32 v[112:113], v[106:107], v[112:113], s[82:83] op_sel_hi:[1,1,0]
	s_nop 0
	v_pk_mul_f32 v[106:107], v[106:107], v[112:113]
	v_pk_mul_f32 v[112:113], v[98:99], v[98:99]
	v_pk_mul_f32 v[106:107], v[110:111], v[106:107]
	v_pk_mul_f32 v[112:113], v[112:113], s[88:89] op_sel_hi:[1,0]
	v_pk_mul_f32 v[110:111], v[104:105], v[106:107]
	v_pk_fma_f32 v[106:107], v[104:105], v[106:107], v[104:105] neg_lo:[1,0,0] neg_hi:[1,0,0]
	v_exp_f32_e32 v112, v112
	v_cndmask_b32_e32 v104, v106, v110, vcc
	v_cmp_gt_f32_e32 vcc, 0, v105
	v_and_b32_e32 v106, 0x7fffffff, v98
	v_exp_f32_e32 v113, v113
	v_cndmask_b32_e32 v105, v107, v111, vcc
	v_and_b32_e32 v107, 0x7fffffff, v99
	v_pk_fma_f32 v[106:107], v[106:107], s[28:29], 1.0 op_sel_hi:[1,0,0]
	v_cmp_gt_f32_e32 vcc, 0, v98
	v_rcp_f32_e32 v106, v106
	v_rcp_f32_e32 v107, v107
	s_nop 0
	v_pk_fma_f32 v[110:111], v[106:107], s[38:39], v[108:109] op_sel_hi:[1,0,0]
	s_nop 0
	v_pk_fma_f32 v[110:111], v[106:107], v[110:111], s[72:73] op_sel_hi:[1,1,0]
	s_nop 0
	v_pk_fma_f32 v[110:111], v[106:107], v[110:111], s[76:77] op_sel_hi:[1,1,0]
	s_nop 0
	v_pk_fma_f32 v[110:111], v[106:107], v[110:111], s[82:83] op_sel_hi:[1,1,0]
	s_nop 0
	v_pk_mul_f32 v[106:107], v[106:107], v[110:111]
	v_pk_mul_f32 v[110:111], v[100:101], v[100:101]
	v_pk_mul_f32 v[106:107], v[112:113], v[106:107]
	s_nop 0
	v_pk_mul_f32 v[112:113], v[98:99], v[106:107]
	v_pk_fma_f32 v[106:107], v[98:99], v[106:107], v[98:99] neg_lo:[1,0,0] neg_hi:[1,0,0]
	s_nop 0
	v_cndmask_b32_e32 v98, v106, v112, vcc
	v_cmp_gt_f32_e32 vcc, 0, v99
	v_and_b32_e32 v106, 0x7fffffff, v100
	s_nop 0
	v_cndmask_b32_e32 v99, v107, v113, vcc
	v_and_b32_e32 v107, 0x7fffffff, v101
	v_pk_fma_f32 v[106:107], v[106:107], s[28:29], 1.0 op_sel_hi:[1,0,0]
	v_cmp_gt_f32_e32 vcc, 0, v100
	v_rcp_f32_e32 v106, v106
	v_rcp_f32_e32 v107, v107
	s_nop 0
	v_pk_fma_f32 v[108:109], v[106:107], s[38:39], v[108:109] op_sel_hi:[1,0,0]
	s_nop 0
	v_pk_fma_f32 v[108:109], v[106:107], v[108:109], s[72:73] op_sel_hi:[1,1,0]
	s_nop 0
	v_pk_fma_f32 v[108:109], v[106:107], v[108:109], s[76:77] op_sel_hi:[1,1,0]
	s_nop 0
	v_pk_fma_f32 v[108:109], v[106:107], v[108:109], s[82:83] op_sel_hi:[1,1,0]
	s_nop 0
	v_pk_mul_f32 v[106:107], v[106:107], v[108:109]
	v_pk_mul_f32 v[108:109], v[110:111], s[88:89] op_sel_hi:[1,0]
	s_nop 0
	v_exp_f32_e32 v108, v108
	v_exp_f32_e32 v109, v109
	s_nop 0
	v_pk_mul_f32 v[106:107], v[108:109], v[106:107]
	s_nop 0
	v_pk_mul_f32 v[108:109], v[100:101], v[106:107]
	v_pk_fma_f32 v[106:107], v[100:101], v[106:107], v[100:101] neg_lo:[1,0,0] neg_hi:[1,0,0]
	s_nop 0
	v_cndmask_b32_e32 v100, v106, v108, vcc
	v_cmp_gt_f32_e32 vcc, 0, v101
	s_nop 1
	v_cndmask_b32_e32 v101, v107, v109, vcc
.LBB0_296:
	s_and_b64 vcc, exec, s[10:11]
	v_cvt_pk_bf16_f32 v102, v102, v103
	v_cvt_pk_bf16_f32 v103, v104, v105
	v_cvt_pk_bf16_f32 v104, v98, v99
	v_cvt_pk_bf16_f32 v105, v100, v101
	global_store_dwordx4 v[114:115], v[102:105], off offset:256 sc1
	s_cbranch_vccnz .LBB0_298
	v_and_b32_e32 v99, 0x7fffffff, v95
	v_and_b32_e32 v98, 0x7fffffff, v94
	v_pk_fma_f32 v[98:99], v[98:99], s[28:29], 1.0 op_sel_hi:[1,0,0]
	v_mov_b64_e32 v[100:101], s[68:69]
	v_rcp_f32_e32 v98, v98
	v_rcp_f32_e32 v99, v99
	v_pk_mul_f32 v[104:105], v[94:95], v[94:95]
	v_cmp_gt_f32_e32 vcc, 0, v94
	v_pk_mul_f32 v[104:105], v[104:105], s[88:89] op_sel_hi:[1,0]
	v_pk_fma_f32 v[102:103], v[98:99], s[38:39], v[100:101] op_sel_hi:[1,0,0]
	v_exp_f32_e32 v104, v104
	v_pk_fma_f32 v[102:103], v[98:99], v[102:103], s[72:73] op_sel_hi:[1,1,0]
	v_exp_f32_e32 v105, v105
	v_pk_fma_f32 v[102:103], v[98:99], v[102:103], s[76:77] op_sel_hi:[1,1,0]
	s_nop 0
	v_pk_fma_f32 v[102:103], v[98:99], v[102:103], s[82:83] op_sel_hi:[1,1,0]
	s_nop 0
	v_pk_mul_f32 v[98:99], v[98:99], v[102:103]
	v_pk_mul_f32 v[102:103], v[96:97], v[96:97]
	v_pk_mul_f32 v[98:99], v[104:105], v[98:99]
	v_pk_mul_f32 v[102:103], v[102:103], s[88:89] op_sel_hi:[1,0]
	v_pk_mul_f32 v[104:105], v[94:95], v[98:99]
	v_pk_fma_f32 v[98:99], v[94:95], v[98:99], v[94:95] neg_lo:[1,0,0] neg_hi:[1,0,0]
	v_exp_f32_e32 v102, v102
	v_cndmask_b32_e32 v94, v98, v104, vcc
	v_cmp_gt_f32_e32 vcc, 0, v95
	v_and_b32_e32 v98, 0x7fffffff, v96
	v_exp_f32_e32 v103, v103
	v_cndmask_b32_e32 v95, v99, v105, vcc
	v_and_b32_e32 v99, 0x7fffffff, v97
	v_pk_fma_f32 v[98:99], v[98:99], s[28:29], 1.0 op_sel_hi:[1,0,0]
	v_cmp_gt_f32_e32 vcc, 0, v96
	v_rcp_f32_e32 v98, v98
	v_rcp_f32_e32 v99, v99
	s_nop 0
	v_pk_fma_f32 v[104:105], v[98:99], s[38:39], v[100:101] op_sel_hi:[1,0,0]
	s_nop 0
	v_pk_fma_f32 v[104:105], v[98:99], v[104:105], s[72:73] op_sel_hi:[1,1,0]
	s_nop 0
	v_pk_fma_f32 v[104:105], v[98:99], v[104:105], s[76:77] op_sel_hi:[1,1,0]
	s_nop 0
	v_pk_fma_f32 v[104:105], v[98:99], v[104:105], s[82:83] op_sel_hi:[1,1,0]
	s_nop 0
	v_pk_mul_f32 v[98:99], v[98:99], v[104:105]
	v_pk_mul_f32 v[104:105], v[90:91], v[90:91]
	v_pk_mul_f32 v[98:99], v[102:103], v[98:99]
	v_pk_mul_f32 v[104:105], v[104:105], s[88:89] op_sel_hi:[1,0]
	v_pk_mul_f32 v[102:103], v[96:97], v[98:99]
	v_pk_fma_f32 v[98:99], v[96:97], v[98:99], v[96:97] neg_lo:[1,0,0] neg_hi:[1,0,0]
	v_exp_f32_e32 v104, v104
	v_cndmask_b32_e32 v96, v98, v102, vcc
	v_cmp_gt_f32_e32 vcc, 0, v97
	v_and_b32_e32 v98, 0x7fffffff, v90
	v_exp_f32_e32 v105, v105
	v_cndmask_b32_e32 v97, v99, v103, vcc
	v_and_b32_e32 v99, 0x7fffffff, v91
	v_pk_fma_f32 v[98:99], v[98:99], s[28:29], 1.0 op_sel_hi:[1,0,0]
	v_cmp_gt_f32_e32 vcc, 0, v90
	v_rcp_f32_e32 v98, v98
	v_rcp_f32_e32 v99, v99
	s_nop 0
	v_pk_fma_f32 v[102:103], v[98:99], s[38:39], v[100:101] op_sel_hi:[1,0,0]
	s_nop 0
	v_pk_fma_f32 v[102:103], v[98:99], v[102:103], s[72:73] op_sel_hi:[1,1,0]
	s_nop 0
	v_pk_fma_f32 v[102:103], v[98:99], v[102:103], s[76:77] op_sel_hi:[1,1,0]
	s_nop 0
	v_pk_fma_f32 v[102:103], v[98:99], v[102:103], s[82:83] op_sel_hi:[1,1,0]
	s_nop 0
	v_pk_mul_f32 v[98:99], v[98:99], v[102:103]
	v_pk_mul_f32 v[102:103], v[92:93], v[92:93]
	v_pk_mul_f32 v[98:99], v[104:105], v[98:99]
	s_nop 0
	v_pk_mul_f32 v[104:105], v[90:91], v[98:99]
	v_pk_fma_f32 v[98:99], v[90:91], v[98:99], v[90:91] neg_lo:[1,0,0] neg_hi:[1,0,0]
	s_nop 0
	v_cndmask_b32_e32 v90, v98, v104, vcc
	v_cmp_gt_f32_e32 vcc, 0, v91
	v_and_b32_e32 v98, 0x7fffffff, v92
	s_nop 0
	v_cndmask_b32_e32 v91, v99, v105, vcc
	v_and_b32_e32 v99, 0x7fffffff, v93
	v_pk_fma_f32 v[98:99], v[98:99], s[28:29], 1.0 op_sel_hi:[1,0,0]
	v_cmp_gt_f32_e32 vcc, 0, v92
	v_rcp_f32_e32 v98, v98
	v_rcp_f32_e32 v99, v99
	s_nop 0
	v_pk_fma_f32 v[100:101], v[98:99], s[38:39], v[100:101] op_sel_hi:[1,0,0]
	s_nop 0
	v_pk_fma_f32 v[100:101], v[98:99], v[100:101], s[72:73] op_sel_hi:[1,1,0]
	s_nop 0
	v_pk_fma_f32 v[100:101], v[98:99], v[100:101], s[76:77] op_sel_hi:[1,1,0]
	s_nop 0
	v_pk_fma_f32 v[100:101], v[98:99], v[100:101], s[82:83] op_sel_hi:[1,1,0]
	s_nop 0
	v_pk_mul_f32 v[98:99], v[98:99], v[100:101]
	v_pk_mul_f32 v[100:101], v[102:103], s[88:89] op_sel_hi:[1,0]
	s_nop 0
	v_exp_f32_e32 v100, v100
	v_exp_f32_e32 v101, v101
	s_nop 0
	v_pk_mul_f32 v[98:99], v[100:101], v[98:99]
	s_nop 0
	v_pk_mul_f32 v[100:101], v[92:93], v[98:99]
	v_pk_fma_f32 v[98:99], v[92:93], v[98:99], v[92:93] neg_lo:[1,0,0] neg_hi:[1,0,0]
	s_nop 0
	v_cndmask_b32_e32 v92, v98, v100, vcc
	v_cmp_gt_f32_e32 vcc, 0, v93
	s_nop 1
	v_cndmask_b32_e32 v93, v99, v101, vcc
.LBB0_298:
	v_or_b32_e32 v100, 32, v167
	v_mov_b64_e32 v[98:99], s[74:75]
	v_mad_i64_i32 v[98:99], s[2:3], v100, s56, v[98:99]
	v_lshl_add_u64 v[98:99], v[202:203], 1, v[98:99]
	s_and_b64 vcc, exec, s[10:11]
	v_cvt_pk_bf16_f32 v94, v94, v95
	v_cvt_pk_bf16_f32 v95, v96, v97
	v_cvt_pk_bf16_f32 v96, v90, v91
	v_cvt_pk_bf16_f32 v97, v92, v93
	global_store_dwordx4 v[98:99], v[94:97], off sc1
	s_cbranch_vccnz .LBB0_300
	v_and_b32_e32 v91, 0x7fffffff, v87
	v_and_b32_e32 v90, 0x7fffffff, v86
	v_pk_fma_f32 v[90:91], v[90:91], s[28:29], 1.0 op_sel_hi:[1,0,0]
	v_mov_b64_e32 v[92:93], s[68:69]
	v_rcp_f32_e32 v90, v90
	v_rcp_f32_e32 v91, v91
	v_pk_mul_f32 v[96:97], v[86:87], v[86:87]
	v_cmp_gt_f32_e32 vcc, 0, v86
	v_pk_mul_f32 v[96:97], v[96:97], s[88:89] op_sel_hi:[1,0]
	v_pk_fma_f32 v[94:95], v[90:91], s[38:39], v[92:93] op_sel_hi:[1,0,0]
	v_exp_f32_e32 v96, v96
	v_pk_fma_f32 v[94:95], v[90:91], v[94:95], s[72:73] op_sel_hi:[1,1,0]
	v_exp_f32_e32 v97, v97
	v_pk_fma_f32 v[94:95], v[90:91], v[94:95], s[76:77] op_sel_hi:[1,1,0]
	s_nop 0
	v_pk_fma_f32 v[94:95], v[90:91], v[94:95], s[82:83] op_sel_hi:[1,1,0]
	s_nop 0
	v_pk_mul_f32 v[90:91], v[90:91], v[94:95]
	v_pk_mul_f32 v[94:95], v[88:89], v[88:89]
	v_pk_mul_f32 v[90:91], v[96:97], v[90:91]
	v_pk_mul_f32 v[94:95], v[94:95], s[88:89] op_sel_hi:[1,0]
	v_pk_mul_f32 v[96:97], v[86:87], v[90:91]
	v_pk_fma_f32 v[90:91], v[86:87], v[90:91], v[86:87] neg_lo:[1,0,0] neg_hi:[1,0,0]
	v_exp_f32_e32 v94, v94
	v_cndmask_b32_e32 v86, v90, v96, vcc
	v_cmp_gt_f32_e32 vcc, 0, v87
	v_and_b32_e32 v90, 0x7fffffff, v88
	v_exp_f32_e32 v95, v95
	v_cndmask_b32_e32 v87, v91, v97, vcc
	v_and_b32_e32 v91, 0x7fffffff, v89
	v_pk_fma_f32 v[90:91], v[90:91], s[28:29], 1.0 op_sel_hi:[1,0,0]
	v_cmp_gt_f32_e32 vcc, 0, v88
	v_rcp_f32_e32 v90, v90
	v_rcp_f32_e32 v91, v91
	s_nop 0
	v_pk_fma_f32 v[96:97], v[90:91], s[38:39], v[92:93] op_sel_hi:[1,0,0]
	s_nop 0
	v_pk_fma_f32 v[96:97], v[90:91], v[96:97], s[72:73] op_sel_hi:[1,1,0]
	s_nop 0
	v_pk_fma_f32 v[96:97], v[90:91], v[96:97], s[76:77] op_sel_hi:[1,1,0]
	s_nop 0
	v_pk_fma_f32 v[96:97], v[90:91], v[96:97], s[82:83] op_sel_hi:[1,1,0]
	s_nop 0
	v_pk_mul_f32 v[90:91], v[90:91], v[96:97]
	v_pk_mul_f32 v[96:97], v[82:83], v[82:83]
	v_pk_mul_f32 v[90:91], v[94:95], v[90:91]
	v_pk_mul_f32 v[96:97], v[96:97], s[88:89] op_sel_hi:[1,0]
	v_pk_mul_f32 v[94:95], v[88:89], v[90:91]
	v_pk_fma_f32 v[90:91], v[88:89], v[90:91], v[88:89] neg_lo:[1,0,0] neg_hi:[1,0,0]
	v_exp_f32_e32 v96, v96
	v_cndmask_b32_e32 v88, v90, v94, vcc
	v_cmp_gt_f32_e32 vcc, 0, v89
	v_and_b32_e32 v90, 0x7fffffff, v82
	v_exp_f32_e32 v97, v97
	v_cndmask_b32_e32 v89, v91, v95, vcc
	v_and_b32_e32 v91, 0x7fffffff, v83
	v_pk_fma_f32 v[90:91], v[90:91], s[28:29], 1.0 op_sel_hi:[1,0,0]
	v_cmp_gt_f32_e32 vcc, 0, v82
	v_rcp_f32_e32 v90, v90
	v_rcp_f32_e32 v91, v91
	s_nop 0
	v_pk_fma_f32 v[94:95], v[90:91], s[38:39], v[92:93] op_sel_hi:[1,0,0]
	s_nop 0
	v_pk_fma_f32 v[94:95], v[90:91], v[94:95], s[72:73] op_sel_hi:[1,1,0]
	s_nop 0
	v_pk_fma_f32 v[94:95], v[90:91], v[94:95], s[76:77] op_sel_hi:[1,1,0]
	s_nop 0
	v_pk_fma_f32 v[94:95], v[90:91], v[94:95], s[82:83] op_sel_hi:[1,1,0]
	s_nop 0
	v_pk_mul_f32 v[90:91], v[90:91], v[94:95]
	v_pk_mul_f32 v[94:95], v[84:85], v[84:85]
	v_pk_mul_f32 v[90:91], v[96:97], v[90:91]
	s_nop 0
	v_pk_mul_f32 v[96:97], v[82:83], v[90:91]
	v_pk_fma_f32 v[90:91], v[82:83], v[90:91], v[82:83] neg_lo:[1,0,0] neg_hi:[1,0,0]
	s_nop 0
	v_cndmask_b32_e32 v82, v90, v96, vcc
	v_cmp_gt_f32_e32 vcc, 0, v83
	v_and_b32_e32 v90, 0x7fffffff, v84
	s_nop 0
	v_cndmask_b32_e32 v83, v91, v97, vcc
	v_and_b32_e32 v91, 0x7fffffff, v85
	v_pk_fma_f32 v[90:91], v[90:91], s[28:29], 1.0 op_sel_hi:[1,0,0]
	v_cmp_gt_f32_e32 vcc, 0, v84
	v_rcp_f32_e32 v90, v90
	v_rcp_f32_e32 v91, v91
	s_nop 0
	v_pk_fma_f32 v[92:93], v[90:91], s[38:39], v[92:93] op_sel_hi:[1,0,0]
	s_nop 0
	v_pk_fma_f32 v[92:93], v[90:91], v[92:93], s[72:73] op_sel_hi:[1,1,0]
	s_nop 0
	v_pk_fma_f32 v[92:93], v[90:91], v[92:93], s[76:77] op_sel_hi:[1,1,0]
	s_nop 0
	v_pk_fma_f32 v[92:93], v[90:91], v[92:93], s[82:83] op_sel_hi:[1,1,0]
	s_nop 0
	v_pk_mul_f32 v[90:91], v[90:91], v[92:93]
	v_pk_mul_f32 v[92:93], v[94:95], s[88:89] op_sel_hi:[1,0]
	s_nop 0
	v_exp_f32_e32 v92, v92
	v_exp_f32_e32 v93, v93
	s_nop 0
	v_pk_mul_f32 v[90:91], v[92:93], v[90:91]
	s_nop 0
	v_pk_mul_f32 v[92:93], v[84:85], v[90:91]
	v_pk_fma_f32 v[90:91], v[84:85], v[90:91], v[84:85] neg_lo:[1,0,0] neg_hi:[1,0,0]
	s_nop 0
	v_cndmask_b32_e32 v84, v90, v92, vcc
	v_cmp_gt_f32_e32 vcc, 0, v85
	s_nop 1
	v_cndmask_b32_e32 v85, v91, v93, vcc
.LBB0_300:
	s_and_b64 vcc, exec, s[10:11]
	v_cvt_pk_bf16_f32 v86, v86, v87
	v_cvt_pk_bf16_f32 v87, v88, v89
	v_cvt_pk_bf16_f32 v88, v82, v83
	v_cvt_pk_bf16_f32 v89, v84, v85
	global_store_dwordx4 v[98:99], v[86:89], off offset:256 sc1
	s_cbranch_vccnz .LBB0_302
	v_and_b32_e32 v83, 0x7fffffff, v79
	v_and_b32_e32 v82, 0x7fffffff, v78
	v_pk_fma_f32 v[82:83], v[82:83], s[28:29], 1.0 op_sel_hi:[1,0,0]
	v_mov_b64_e32 v[84:85], s[68:69]
	v_rcp_f32_e32 v82, v82
	v_rcp_f32_e32 v83, v83
	v_pk_mul_f32 v[88:89], v[78:79], v[78:79]
	v_cmp_gt_f32_e32 vcc, 0, v78
	v_pk_mul_f32 v[88:89], v[88:89], s[88:89] op_sel_hi:[1,0]
	v_pk_fma_f32 v[86:87], v[82:83], s[38:39], v[84:85] op_sel_hi:[1,0,0]
	v_exp_f32_e32 v88, v88
	v_pk_fma_f32 v[86:87], v[82:83], v[86:87], s[72:73] op_sel_hi:[1,1,0]
	v_exp_f32_e32 v89, v89
	v_pk_fma_f32 v[86:87], v[82:83], v[86:87], s[76:77] op_sel_hi:[1,1,0]
	s_nop 0
	v_pk_fma_f32 v[86:87], v[82:83], v[86:87], s[82:83] op_sel_hi:[1,1,0]
	s_nop 0
	v_pk_mul_f32 v[82:83], v[82:83], v[86:87]
	v_pk_mul_f32 v[86:87], v[80:81], v[80:81]
	v_pk_mul_f32 v[82:83], v[88:89], v[82:83]
	v_pk_mul_f32 v[86:87], v[86:87], s[88:89] op_sel_hi:[1,0]
	v_pk_mul_f32 v[88:89], v[78:79], v[82:83]
	v_pk_fma_f32 v[82:83], v[78:79], v[82:83], v[78:79] neg_lo:[1,0,0] neg_hi:[1,0,0]
	v_exp_f32_e32 v86, v86
	v_cndmask_b32_e32 v78, v82, v88, vcc
	v_cmp_gt_f32_e32 vcc, 0, v79
	v_and_b32_e32 v82, 0x7fffffff, v80
	v_exp_f32_e32 v87, v87
	v_cndmask_b32_e32 v79, v83, v89, vcc
	v_and_b32_e32 v83, 0x7fffffff, v81
	v_pk_fma_f32 v[82:83], v[82:83], s[28:29], 1.0 op_sel_hi:[1,0,0]
	v_cmp_gt_f32_e32 vcc, 0, v80
	v_rcp_f32_e32 v82, v82
	v_rcp_f32_e32 v83, v83
	s_nop 0
	v_pk_fma_f32 v[88:89], v[82:83], s[38:39], v[84:85] op_sel_hi:[1,0,0]
	s_nop 0
	v_pk_fma_f32 v[88:89], v[82:83], v[88:89], s[72:73] op_sel_hi:[1,1,0]
	s_nop 0
	v_pk_fma_f32 v[88:89], v[82:83], v[88:89], s[76:77] op_sel_hi:[1,1,0]
	s_nop 0
	v_pk_fma_f32 v[88:89], v[82:83], v[88:89], s[82:83] op_sel_hi:[1,1,0]
	s_nop 0
	v_pk_mul_f32 v[82:83], v[82:83], v[88:89]
	v_pk_mul_f32 v[88:89], v[74:75], v[74:75]
	v_pk_mul_f32 v[82:83], v[86:87], v[82:83]
	v_pk_mul_f32 v[88:89], v[88:89], s[88:89] op_sel_hi:[1,0]
	v_pk_mul_f32 v[86:87], v[80:81], v[82:83]
	v_pk_fma_f32 v[82:83], v[80:81], v[82:83], v[80:81] neg_lo:[1,0,0] neg_hi:[1,0,0]
	v_exp_f32_e32 v88, v88
	v_cndmask_b32_e32 v80, v82, v86, vcc
	v_cmp_gt_f32_e32 vcc, 0, v81
	v_and_b32_e32 v82, 0x7fffffff, v74
	v_exp_f32_e32 v89, v89
	v_cndmask_b32_e32 v81, v83, v87, vcc
	v_and_b32_e32 v83, 0x7fffffff, v75
	v_pk_fma_f32 v[82:83], v[82:83], s[28:29], 1.0 op_sel_hi:[1,0,0]
	v_cmp_gt_f32_e32 vcc, 0, v74
	v_rcp_f32_e32 v82, v82
	v_rcp_f32_e32 v83, v83
	s_nop 0
	v_pk_fma_f32 v[86:87], v[82:83], s[38:39], v[84:85] op_sel_hi:[1,0,0]
	s_nop 0
	v_pk_fma_f32 v[86:87], v[82:83], v[86:87], s[72:73] op_sel_hi:[1,1,0]
	s_nop 0
	v_pk_fma_f32 v[86:87], v[82:83], v[86:87], s[76:77] op_sel_hi:[1,1,0]
	s_nop 0
	v_pk_fma_f32 v[86:87], v[82:83], v[86:87], s[82:83] op_sel_hi:[1,1,0]
	s_nop 0
	v_pk_mul_f32 v[82:83], v[82:83], v[86:87]
	v_pk_mul_f32 v[86:87], v[76:77], v[76:77]
	v_pk_mul_f32 v[82:83], v[88:89], v[82:83]
	s_nop 0
	v_pk_mul_f32 v[88:89], v[74:75], v[82:83]
	v_pk_fma_f32 v[82:83], v[74:75], v[82:83], v[74:75] neg_lo:[1,0,0] neg_hi:[1,0,0]
	s_nop 0
	v_cndmask_b32_e32 v74, v82, v88, vcc
	v_cmp_gt_f32_e32 vcc, 0, v75
	v_and_b32_e32 v82, 0x7fffffff, v76
	s_nop 0
	v_cndmask_b32_e32 v75, v83, v89, vcc
	v_and_b32_e32 v83, 0x7fffffff, v77
	v_pk_fma_f32 v[82:83], v[82:83], s[28:29], 1.0 op_sel_hi:[1,0,0]
	v_cmp_gt_f32_e32 vcc, 0, v76
	v_rcp_f32_e32 v82, v82
	v_rcp_f32_e32 v83, v83
	s_nop 0
	v_pk_fma_f32 v[84:85], v[82:83], s[38:39], v[84:85] op_sel_hi:[1,0,0]
	s_nop 0
	v_pk_fma_f32 v[84:85], v[82:83], v[84:85], s[72:73] op_sel_hi:[1,1,0]
	s_nop 0
	v_pk_fma_f32 v[84:85], v[82:83], v[84:85], s[76:77] op_sel_hi:[1,1,0]
	s_nop 0
	v_pk_fma_f32 v[84:85], v[82:83], v[84:85], s[82:83] op_sel_hi:[1,1,0]
	s_nop 0
	v_pk_mul_f32 v[82:83], v[82:83], v[84:85]
	v_pk_mul_f32 v[84:85], v[86:87], s[88:89] op_sel_hi:[1,0]
	s_nop 0
	v_exp_f32_e32 v84, v84
	v_exp_f32_e32 v85, v85
	s_nop 0
	v_pk_mul_f32 v[82:83], v[84:85], v[82:83]
	s_nop 0
	v_pk_mul_f32 v[84:85], v[76:77], v[82:83]
	v_pk_fma_f32 v[82:83], v[76:77], v[82:83], v[76:77] neg_lo:[1,0,0] neg_hi:[1,0,0]
	s_nop 0
	v_cndmask_b32_e32 v76, v82, v84, vcc
	v_cmp_gt_f32_e32 vcc, 0, v77
	s_nop 1
	v_cndmask_b32_e32 v77, v83, v85, vcc
.LBB0_302:
	v_or_b32_e32 v84, 48, v167
	v_mov_b64_e32 v[82:83], s[74:75]
	v_mad_i64_i32 v[82:83], s[2:3], v84, s56, v[82:83]
	v_lshl_add_u64 v[82:83], v[202:203], 1, v[82:83]
	s_and_b64 vcc, exec, s[10:11]
	v_cvt_pk_bf16_f32 v78, v78, v79
	v_cvt_pk_bf16_f32 v79, v80, v81
	v_cvt_pk_bf16_f32 v80, v74, v75
	v_cvt_pk_bf16_f32 v81, v76, v77
	global_store_dwordx4 v[82:83], v[78:81], off sc1
	s_cbranch_vccnz .LBB0_304
	v_and_b32_e32 v75, 0x7fffffff, v71
	v_and_b32_e32 v74, 0x7fffffff, v70
	v_pk_fma_f32 v[74:75], v[74:75], s[28:29], 1.0 op_sel_hi:[1,0,0]
	v_mov_b64_e32 v[76:77], s[68:69]
	v_rcp_f32_e32 v74, v74
	v_rcp_f32_e32 v75, v75
	v_pk_mul_f32 v[80:81], v[70:71], v[70:71]
	v_cmp_gt_f32_e32 vcc, 0, v70
	v_pk_mul_f32 v[80:81], v[80:81], s[88:89] op_sel_hi:[1,0]
	v_pk_fma_f32 v[78:79], v[74:75], s[38:39], v[76:77] op_sel_hi:[1,0,0]
	v_exp_f32_e32 v80, v80
	v_pk_fma_f32 v[78:79], v[74:75], v[78:79], s[72:73] op_sel_hi:[1,1,0]
	v_exp_f32_e32 v81, v81
	v_pk_fma_f32 v[78:79], v[74:75], v[78:79], s[76:77] op_sel_hi:[1,1,0]
	s_nop 0
	v_pk_fma_f32 v[78:79], v[74:75], v[78:79], s[82:83] op_sel_hi:[1,1,0]
	s_nop 0
	v_pk_mul_f32 v[74:75], v[74:75], v[78:79]
	v_pk_mul_f32 v[78:79], v[72:73], v[72:73]
	v_pk_mul_f32 v[74:75], v[80:81], v[74:75]
	v_pk_mul_f32 v[78:79], v[78:79], s[88:89] op_sel_hi:[1,0]
	v_pk_mul_f32 v[80:81], v[70:71], v[74:75]
	v_pk_fma_f32 v[74:75], v[70:71], v[74:75], v[70:71] neg_lo:[1,0,0] neg_hi:[1,0,0]
	v_exp_f32_e32 v78, v78
	v_cndmask_b32_e32 v70, v74, v80, vcc
	v_cmp_gt_f32_e32 vcc, 0, v71
	v_and_b32_e32 v74, 0x7fffffff, v72
	v_exp_f32_e32 v79, v79
	v_cndmask_b32_e32 v71, v75, v81, vcc
	v_and_b32_e32 v75, 0x7fffffff, v73
	v_pk_fma_f32 v[74:75], v[74:75], s[28:29], 1.0 op_sel_hi:[1,0,0]
	v_cmp_gt_f32_e32 vcc, 0, v72
	v_rcp_f32_e32 v74, v74
	v_rcp_f32_e32 v75, v75
	s_nop 0
	v_pk_fma_f32 v[80:81], v[74:75], s[38:39], v[76:77] op_sel_hi:[1,0,0]
	s_nop 0
	v_pk_fma_f32 v[80:81], v[74:75], v[80:81], s[72:73] op_sel_hi:[1,1,0]
	s_nop 0
	v_pk_fma_f32 v[80:81], v[74:75], v[80:81], s[76:77] op_sel_hi:[1,1,0]
	s_nop 0
	v_pk_fma_f32 v[80:81], v[74:75], v[80:81], s[82:83] op_sel_hi:[1,1,0]
	s_nop 0
	v_pk_mul_f32 v[74:75], v[74:75], v[80:81]
	v_pk_mul_f32 v[80:81], v[66:67], v[66:67]
	v_pk_mul_f32 v[74:75], v[78:79], v[74:75]
	v_pk_mul_f32 v[80:81], v[80:81], s[88:89] op_sel_hi:[1,0]
	v_pk_mul_f32 v[78:79], v[72:73], v[74:75]
	v_pk_fma_f32 v[74:75], v[72:73], v[74:75], v[72:73] neg_lo:[1,0,0] neg_hi:[1,0,0]
	v_exp_f32_e32 v80, v80
	v_cndmask_b32_e32 v72, v74, v78, vcc
	v_cmp_gt_f32_e32 vcc, 0, v73
	v_and_b32_e32 v74, 0x7fffffff, v66
	v_exp_f32_e32 v81, v81
	v_cndmask_b32_e32 v73, v75, v79, vcc
	v_and_b32_e32 v75, 0x7fffffff, v67
	v_pk_fma_f32 v[74:75], v[74:75], s[28:29], 1.0 op_sel_hi:[1,0,0]
	v_cmp_gt_f32_e32 vcc, 0, v66
	v_rcp_f32_e32 v74, v74
	v_rcp_f32_e32 v75, v75
	s_nop 0
	v_pk_fma_f32 v[78:79], v[74:75], s[38:39], v[76:77] op_sel_hi:[1,0,0]
	s_nop 0
	v_pk_fma_f32 v[78:79], v[74:75], v[78:79], s[72:73] op_sel_hi:[1,1,0]
	s_nop 0
	v_pk_fma_f32 v[78:79], v[74:75], v[78:79], s[76:77] op_sel_hi:[1,1,0]
	s_nop 0
	v_pk_fma_f32 v[78:79], v[74:75], v[78:79], s[82:83] op_sel_hi:[1,1,0]
	s_nop 0
	v_pk_mul_f32 v[74:75], v[74:75], v[78:79]
	v_pk_mul_f32 v[78:79], v[68:69], v[68:69]
	v_pk_mul_f32 v[74:75], v[80:81], v[74:75]
	s_nop 0
	v_pk_mul_f32 v[80:81], v[66:67], v[74:75]
	v_pk_fma_f32 v[74:75], v[66:67], v[74:75], v[66:67] neg_lo:[1,0,0] neg_hi:[1,0,0]
	s_nop 0
	v_cndmask_b32_e32 v66, v74, v80, vcc
	v_cmp_gt_f32_e32 vcc, 0, v67
	v_and_b32_e32 v74, 0x7fffffff, v68
	s_nop 0
	v_cndmask_b32_e32 v67, v75, v81, vcc
	v_and_b32_e32 v75, 0x7fffffff, v69
	v_pk_fma_f32 v[74:75], v[74:75], s[28:29], 1.0 op_sel_hi:[1,0,0]
	v_cmp_gt_f32_e32 vcc, 0, v68
	v_rcp_f32_e32 v74, v74
	v_rcp_f32_e32 v75, v75
	s_nop 0
	v_pk_fma_f32 v[76:77], v[74:75], s[38:39], v[76:77] op_sel_hi:[1,0,0]
	s_nop 0
	v_pk_fma_f32 v[76:77], v[74:75], v[76:77], s[72:73] op_sel_hi:[1,1,0]
	s_nop 0
	v_pk_fma_f32 v[76:77], v[74:75], v[76:77], s[76:77] op_sel_hi:[1,1,0]
	s_nop 0
	v_pk_fma_f32 v[76:77], v[74:75], v[76:77], s[82:83] op_sel_hi:[1,1,0]
	s_nop 0
	v_pk_mul_f32 v[74:75], v[74:75], v[76:77]
	v_pk_mul_f32 v[76:77], v[78:79], s[88:89] op_sel_hi:[1,0]
	s_nop 0
	v_exp_f32_e32 v76, v76
	v_exp_f32_e32 v77, v77
	s_nop 0
	v_pk_mul_f32 v[74:75], v[76:77], v[74:75]
	s_nop 0
	v_pk_mul_f32 v[76:77], v[68:69], v[74:75]
	v_pk_fma_f32 v[74:75], v[68:69], v[74:75], v[68:69] neg_lo:[1,0,0] neg_hi:[1,0,0]
	s_nop 0
	v_cndmask_b32_e32 v68, v74, v76, vcc
	v_cmp_gt_f32_e32 vcc, 0, v69
	s_nop 1
	v_cndmask_b32_e32 v69, v75, v77, vcc
.LBB0_304:
	s_and_b64 vcc, exec, s[10:11]
	v_cvt_pk_bf16_f32 v70, v70, v71
	v_cvt_pk_bf16_f32 v71, v72, v73
	v_cvt_pk_bf16_f32 v72, v66, v67
	v_cvt_pk_bf16_f32 v73, v68, v69
	global_store_dwordx4 v[82:83], v[70:73], off offset:256 sc1
	s_cbranch_vccnz .LBB0_306
	v_and_b32_e32 v67, 0x7fffffff, v63
	v_and_b32_e32 v66, 0x7fffffff, v62
	v_pk_fma_f32 v[66:67], v[66:67], s[28:29], 1.0 op_sel_hi:[1,0,0]
	v_mov_b64_e32 v[68:69], s[68:69]
	v_rcp_f32_e32 v66, v66
	v_rcp_f32_e32 v67, v67
	v_pk_mul_f32 v[72:73], v[62:63], v[62:63]
	v_cmp_gt_f32_e32 vcc, 0, v62
	v_pk_mul_f32 v[72:73], v[72:73], s[88:89] op_sel_hi:[1,0]
	v_pk_fma_f32 v[70:71], v[66:67], s[38:39], v[68:69] op_sel_hi:[1,0,0]
	v_exp_f32_e32 v72, v72
	v_pk_fma_f32 v[70:71], v[66:67], v[70:71], s[72:73] op_sel_hi:[1,1,0]
	v_exp_f32_e32 v73, v73
	v_pk_fma_f32 v[70:71], v[66:67], v[70:71], s[76:77] op_sel_hi:[1,1,0]
	s_nop 0
	v_pk_fma_f32 v[70:71], v[66:67], v[70:71], s[82:83] op_sel_hi:[1,1,0]
	s_nop 0
	v_pk_mul_f32 v[66:67], v[66:67], v[70:71]
	v_pk_mul_f32 v[70:71], v[64:65], v[64:65]
	v_pk_mul_f32 v[66:67], v[72:73], v[66:67]
	v_pk_mul_f32 v[70:71], v[70:71], s[88:89] op_sel_hi:[1,0]
	v_pk_mul_f32 v[72:73], v[62:63], v[66:67]
	v_pk_fma_f32 v[66:67], v[62:63], v[66:67], v[62:63] neg_lo:[1,0,0] neg_hi:[1,0,0]
	v_exp_f32_e32 v70, v70
	v_cndmask_b32_e32 v62, v66, v72, vcc
	v_cmp_gt_f32_e32 vcc, 0, v63
	v_and_b32_e32 v66, 0x7fffffff, v64
	v_exp_f32_e32 v71, v71
	v_cndmask_b32_e32 v63, v67, v73, vcc
	v_and_b32_e32 v67, 0x7fffffff, v65
	v_pk_fma_f32 v[66:67], v[66:67], s[28:29], 1.0 op_sel_hi:[1,0,0]
	v_cmp_gt_f32_e32 vcc, 0, v64
	v_rcp_f32_e32 v66, v66
	v_rcp_f32_e32 v67, v67
	s_nop 0
	v_pk_fma_f32 v[72:73], v[66:67], s[38:39], v[68:69] op_sel_hi:[1,0,0]
	s_nop 0
	v_pk_fma_f32 v[72:73], v[66:67], v[72:73], s[72:73] op_sel_hi:[1,1,0]
	s_nop 0
	v_pk_fma_f32 v[72:73], v[66:67], v[72:73], s[76:77] op_sel_hi:[1,1,0]
	s_nop 0
	v_pk_fma_f32 v[72:73], v[66:67], v[72:73], s[82:83] op_sel_hi:[1,1,0]
	s_nop 0
	v_pk_mul_f32 v[66:67], v[66:67], v[72:73]
	v_pk_mul_f32 v[72:73], v[58:59], v[58:59]
	v_pk_mul_f32 v[66:67], v[70:71], v[66:67]
	v_pk_mul_f32 v[72:73], v[72:73], s[88:89] op_sel_hi:[1,0]
	v_pk_mul_f32 v[70:71], v[64:65], v[66:67]
	v_pk_fma_f32 v[66:67], v[64:65], v[66:67], v[64:65] neg_lo:[1,0,0] neg_hi:[1,0,0]
	v_exp_f32_e32 v72, v72
	v_cndmask_b32_e32 v64, v66, v70, vcc
	v_cmp_gt_f32_e32 vcc, 0, v65
	v_and_b32_e32 v66, 0x7fffffff, v58
	v_exp_f32_e32 v73, v73
	v_cndmask_b32_e32 v65, v67, v71, vcc
	v_and_b32_e32 v67, 0x7fffffff, v59
	v_pk_fma_f32 v[66:67], v[66:67], s[28:29], 1.0 op_sel_hi:[1,0,0]
	v_cmp_gt_f32_e32 vcc, 0, v58
	v_rcp_f32_e32 v66, v66
	v_rcp_f32_e32 v67, v67
	s_nop 0
	v_pk_fma_f32 v[70:71], v[66:67], s[38:39], v[68:69] op_sel_hi:[1,0,0]
	s_nop 0
	v_pk_fma_f32 v[70:71], v[66:67], v[70:71], s[72:73] op_sel_hi:[1,1,0]
	s_nop 0
	v_pk_fma_f32 v[70:71], v[66:67], v[70:71], s[76:77] op_sel_hi:[1,1,0]
	s_nop 0
	v_pk_fma_f32 v[70:71], v[66:67], v[70:71], s[82:83] op_sel_hi:[1,1,0]
	s_nop 0
	v_pk_mul_f32 v[66:67], v[66:67], v[70:71]
	v_pk_mul_f32 v[70:71], v[60:61], v[60:61]
	v_pk_mul_f32 v[66:67], v[72:73], v[66:67]
	s_nop 0
	v_pk_mul_f32 v[72:73], v[58:59], v[66:67]
	v_pk_fma_f32 v[66:67], v[58:59], v[66:67], v[58:59] neg_lo:[1,0,0] neg_hi:[1,0,0]
	s_nop 0
	v_cndmask_b32_e32 v58, v66, v72, vcc
	v_cmp_gt_f32_e32 vcc, 0, v59
	v_and_b32_e32 v66, 0x7fffffff, v60
	s_nop 0
	v_cndmask_b32_e32 v59, v67, v73, vcc
	v_and_b32_e32 v67, 0x7fffffff, v61
	v_pk_fma_f32 v[66:67], v[66:67], s[28:29], 1.0 op_sel_hi:[1,0,0]
	v_cmp_gt_f32_e32 vcc, 0, v60
	v_rcp_f32_e32 v66, v66
	v_rcp_f32_e32 v67, v67
	s_nop 0
	v_pk_fma_f32 v[68:69], v[66:67], s[38:39], v[68:69] op_sel_hi:[1,0,0]
	s_nop 0
	v_pk_fma_f32 v[68:69], v[66:67], v[68:69], s[72:73] op_sel_hi:[1,1,0]
	s_nop 0
	v_pk_fma_f32 v[68:69], v[66:67], v[68:69], s[76:77] op_sel_hi:[1,1,0]
	s_nop 0
	v_pk_fma_f32 v[68:69], v[66:67], v[68:69], s[82:83] op_sel_hi:[1,1,0]
	s_nop 0
	v_pk_mul_f32 v[66:67], v[66:67], v[68:69]
	v_pk_mul_f32 v[68:69], v[70:71], s[88:89] op_sel_hi:[1,0]
	s_nop 0
	v_exp_f32_e32 v68, v68
	v_exp_f32_e32 v69, v69
	s_nop 0
	v_pk_mul_f32 v[66:67], v[68:69], v[66:67]
	s_nop 0
	v_pk_mul_f32 v[68:69], v[60:61], v[66:67]
	v_pk_fma_f32 v[66:67], v[60:61], v[66:67], v[60:61] neg_lo:[1,0,0] neg_hi:[1,0,0]
	s_nop 0
	v_cndmask_b32_e32 v60, v66, v68, vcc
	v_cmp_gt_f32_e32 vcc, 0, v61
	s_nop 1
	v_cndmask_b32_e32 v61, v67, v69, vcc
.LBB0_306:
	v_add_u32_e32 v68, 0x80, v167
	v_mov_b64_e32 v[66:67], s[74:75]
	v_mad_i64_i32 v[66:67], s[2:3], v68, s56, v[66:67]
	v_lshl_add_u64 v[66:67], v[202:203], 1, v[66:67]
	s_and_b64 vcc, exec, s[10:11]
	v_cvt_pk_bf16_f32 v62, v62, v63
	v_cvt_pk_bf16_f32 v63, v64, v65
	v_cvt_pk_bf16_f32 v64, v58, v59
	v_cvt_pk_bf16_f32 v65, v60, v61
	global_store_dwordx4 v[66:67], v[62:65], off sc1
	s_cbranch_vccnz .LBB0_308
	v_and_b32_e32 v59, 0x7fffffff, v55
	v_and_b32_e32 v58, 0x7fffffff, v54
	v_pk_fma_f32 v[58:59], v[58:59], s[28:29], 1.0 op_sel_hi:[1,0,0]
	v_mov_b64_e32 v[60:61], s[68:69]
	v_rcp_f32_e32 v58, v58
	v_rcp_f32_e32 v59, v59
	v_pk_mul_f32 v[64:65], v[54:55], v[54:55]
	v_cmp_gt_f32_e32 vcc, 0, v54
	v_pk_mul_f32 v[64:65], v[64:65], s[88:89] op_sel_hi:[1,0]
	v_pk_fma_f32 v[62:63], v[58:59], s[38:39], v[60:61] op_sel_hi:[1,0,0]
	v_exp_f32_e32 v64, v64
	v_pk_fma_f32 v[62:63], v[58:59], v[62:63], s[72:73] op_sel_hi:[1,1,0]
	v_exp_f32_e32 v65, v65
	v_pk_fma_f32 v[62:63], v[58:59], v[62:63], s[76:77] op_sel_hi:[1,1,0]
	s_nop 0
	v_pk_fma_f32 v[62:63], v[58:59], v[62:63], s[82:83] op_sel_hi:[1,1,0]
	s_nop 0
	v_pk_mul_f32 v[58:59], v[58:59], v[62:63]
	v_pk_mul_f32 v[62:63], v[56:57], v[56:57]
	v_pk_mul_f32 v[58:59], v[64:65], v[58:59]
	v_pk_mul_f32 v[62:63], v[62:63], s[88:89] op_sel_hi:[1,0]
	v_pk_mul_f32 v[64:65], v[54:55], v[58:59]
	v_pk_fma_f32 v[58:59], v[54:55], v[58:59], v[54:55] neg_lo:[1,0,0] neg_hi:[1,0,0]
	v_exp_f32_e32 v62, v62
	v_cndmask_b32_e32 v54, v58, v64, vcc
	v_cmp_gt_f32_e32 vcc, 0, v55
	v_and_b32_e32 v58, 0x7fffffff, v56
	v_exp_f32_e32 v63, v63
	v_cndmask_b32_e32 v55, v59, v65, vcc
	v_and_b32_e32 v59, 0x7fffffff, v57
	v_pk_fma_f32 v[58:59], v[58:59], s[28:29], 1.0 op_sel_hi:[1,0,0]
	v_cmp_gt_f32_e32 vcc, 0, v56
	v_rcp_f32_e32 v58, v58
	v_rcp_f32_e32 v59, v59
	s_nop 0
	v_pk_fma_f32 v[64:65], v[58:59], s[38:39], v[60:61] op_sel_hi:[1,0,0]
	s_nop 0
	v_pk_fma_f32 v[64:65], v[58:59], v[64:65], s[72:73] op_sel_hi:[1,1,0]
	s_nop 0
	v_pk_fma_f32 v[64:65], v[58:59], v[64:65], s[76:77] op_sel_hi:[1,1,0]
	s_nop 0
	v_pk_fma_f32 v[64:65], v[58:59], v[64:65], s[82:83] op_sel_hi:[1,1,0]
	s_nop 0
	v_pk_mul_f32 v[58:59], v[58:59], v[64:65]
	v_pk_mul_f32 v[64:65], v[50:51], v[50:51]
	v_pk_mul_f32 v[58:59], v[62:63], v[58:59]
	v_pk_mul_f32 v[64:65], v[64:65], s[88:89] op_sel_hi:[1,0]
	v_pk_mul_f32 v[62:63], v[56:57], v[58:59]
	v_pk_fma_f32 v[58:59], v[56:57], v[58:59], v[56:57] neg_lo:[1,0,0] neg_hi:[1,0,0]
	v_exp_f32_e32 v64, v64
	v_cndmask_b32_e32 v56, v58, v62, vcc
	v_cmp_gt_f32_e32 vcc, 0, v57
	v_and_b32_e32 v58, 0x7fffffff, v50
	v_exp_f32_e32 v65, v65
	v_cndmask_b32_e32 v57, v59, v63, vcc
	v_and_b32_e32 v59, 0x7fffffff, v51
	v_pk_fma_f32 v[58:59], v[58:59], s[28:29], 1.0 op_sel_hi:[1,0,0]
	v_cmp_gt_f32_e32 vcc, 0, v50
	v_rcp_f32_e32 v58, v58
	v_rcp_f32_e32 v59, v59
	s_nop 0
	v_pk_fma_f32 v[62:63], v[58:59], s[38:39], v[60:61] op_sel_hi:[1,0,0]
	s_nop 0
	v_pk_fma_f32 v[62:63], v[58:59], v[62:63], s[72:73] op_sel_hi:[1,1,0]
	s_nop 0
	v_pk_fma_f32 v[62:63], v[58:59], v[62:63], s[76:77] op_sel_hi:[1,1,0]
	s_nop 0
	v_pk_fma_f32 v[62:63], v[58:59], v[62:63], s[82:83] op_sel_hi:[1,1,0]
	s_nop 0
	v_pk_mul_f32 v[58:59], v[58:59], v[62:63]
	v_pk_mul_f32 v[62:63], v[52:53], v[52:53]
	v_pk_mul_f32 v[58:59], v[64:65], v[58:59]
	s_nop 0
	v_pk_mul_f32 v[64:65], v[50:51], v[58:59]
	v_pk_fma_f32 v[58:59], v[50:51], v[58:59], v[50:51] neg_lo:[1,0,0] neg_hi:[1,0,0]
	s_nop 0
	v_cndmask_b32_e32 v50, v58, v64, vcc
	v_cmp_gt_f32_e32 vcc, 0, v51
	v_and_b32_e32 v58, 0x7fffffff, v52
	s_nop 0
	v_cndmask_b32_e32 v51, v59, v65, vcc
	v_and_b32_e32 v59, 0x7fffffff, v53
	v_pk_fma_f32 v[58:59], v[58:59], s[28:29], 1.0 op_sel_hi:[1,0,0]
	v_cmp_gt_f32_e32 vcc, 0, v52
	v_rcp_f32_e32 v58, v58
	v_rcp_f32_e32 v59, v59
	s_nop 0
	v_pk_fma_f32 v[60:61], v[58:59], s[38:39], v[60:61] op_sel_hi:[1,0,0]
	s_nop 0
	v_pk_fma_f32 v[60:61], v[58:59], v[60:61], s[72:73] op_sel_hi:[1,1,0]
	s_nop 0
	v_pk_fma_f32 v[60:61], v[58:59], v[60:61], s[76:77] op_sel_hi:[1,1,0]
	s_nop 0
	v_pk_fma_f32 v[60:61], v[58:59], v[60:61], s[82:83] op_sel_hi:[1,1,0]
	s_nop 0
	v_pk_mul_f32 v[58:59], v[58:59], v[60:61]
	v_pk_mul_f32 v[60:61], v[62:63], s[88:89] op_sel_hi:[1,0]
	s_nop 0
	v_exp_f32_e32 v60, v60
	v_exp_f32_e32 v61, v61
	s_nop 0
	v_pk_mul_f32 v[58:59], v[60:61], v[58:59]
	s_nop 0
	v_pk_mul_f32 v[60:61], v[52:53], v[58:59]
	v_pk_fma_f32 v[58:59], v[52:53], v[58:59], v[52:53] neg_lo:[1,0,0] neg_hi:[1,0,0]
	s_nop 0
	v_cndmask_b32_e32 v52, v58, v60, vcc
	v_cmp_gt_f32_e32 vcc, 0, v53
	s_nop 1
	v_cndmask_b32_e32 v53, v59, v61, vcc
.LBB0_308:
	s_and_b64 vcc, exec, s[10:11]
	v_cvt_pk_bf16_f32 v54, v54, v55
	v_cvt_pk_bf16_f32 v55, v56, v57
	v_cvt_pk_bf16_f32 v56, v50, v51
	v_cvt_pk_bf16_f32 v57, v52, v53
	global_store_dwordx4 v[66:67], v[54:57], off offset:256 sc1
	s_cbranch_vccnz .LBB0_310
	v_and_b32_e32 v51, 0x7fffffff, v47
	v_and_b32_e32 v50, 0x7fffffff, v46
	v_pk_fma_f32 v[50:51], v[50:51], s[28:29], 1.0 op_sel_hi:[1,0,0]
	v_mov_b64_e32 v[52:53], s[68:69]
	v_rcp_f32_e32 v50, v50
	v_rcp_f32_e32 v51, v51
	v_pk_mul_f32 v[56:57], v[46:47], v[46:47]
	v_cmp_gt_f32_e32 vcc, 0, v46
	v_pk_mul_f32 v[56:57], v[56:57], s[88:89] op_sel_hi:[1,0]
	v_pk_fma_f32 v[54:55], v[50:51], s[38:39], v[52:53] op_sel_hi:[1,0,0]
	v_exp_f32_e32 v56, v56
	v_pk_fma_f32 v[54:55], v[50:51], v[54:55], s[72:73] op_sel_hi:[1,1,0]
	v_exp_f32_e32 v57, v57
	v_pk_fma_f32 v[54:55], v[50:51], v[54:55], s[76:77] op_sel_hi:[1,1,0]
	s_nop 0
	v_pk_fma_f32 v[54:55], v[50:51], v[54:55], s[82:83] op_sel_hi:[1,1,0]
	s_nop 0
	v_pk_mul_f32 v[50:51], v[50:51], v[54:55]
	v_pk_mul_f32 v[54:55], v[48:49], v[48:49]
	v_pk_mul_f32 v[50:51], v[56:57], v[50:51]
	v_pk_mul_f32 v[54:55], v[54:55], s[88:89] op_sel_hi:[1,0]
	v_pk_mul_f32 v[56:57], v[46:47], v[50:51]
	v_pk_fma_f32 v[50:51], v[46:47], v[50:51], v[46:47] neg_lo:[1,0,0] neg_hi:[1,0,0]
	v_exp_f32_e32 v54, v54
	v_cndmask_b32_e32 v46, v50, v56, vcc
	v_cmp_gt_f32_e32 vcc, 0, v47
	v_and_b32_e32 v50, 0x7fffffff, v48
	v_exp_f32_e32 v55, v55
	v_cndmask_b32_e32 v47, v51, v57, vcc
	v_and_b32_e32 v51, 0x7fffffff, v49
	v_pk_fma_f32 v[50:51], v[50:51], s[28:29], 1.0 op_sel_hi:[1,0,0]
	v_cmp_gt_f32_e32 vcc, 0, v48
	v_rcp_f32_e32 v50, v50
	v_rcp_f32_e32 v51, v51
	s_nop 0
	v_pk_fma_f32 v[56:57], v[50:51], s[38:39], v[52:53] op_sel_hi:[1,0,0]
	s_nop 0
	v_pk_fma_f32 v[56:57], v[50:51], v[56:57], s[72:73] op_sel_hi:[1,1,0]
	s_nop 0
	v_pk_fma_f32 v[56:57], v[50:51], v[56:57], s[76:77] op_sel_hi:[1,1,0]
	s_nop 0
	v_pk_fma_f32 v[56:57], v[50:51], v[56:57], s[82:83] op_sel_hi:[1,1,0]
	s_nop 0
	v_pk_mul_f32 v[50:51], v[50:51], v[56:57]
	v_pk_mul_f32 v[56:57], v[42:43], v[42:43]
	v_pk_mul_f32 v[50:51], v[54:55], v[50:51]
	v_pk_mul_f32 v[56:57], v[56:57], s[88:89] op_sel_hi:[1,0]
	v_pk_mul_f32 v[54:55], v[48:49], v[50:51]
	v_pk_fma_f32 v[50:51], v[48:49], v[50:51], v[48:49] neg_lo:[1,0,0] neg_hi:[1,0,0]
	v_exp_f32_e32 v56, v56
	v_cndmask_b32_e32 v48, v50, v54, vcc
	v_cmp_gt_f32_e32 vcc, 0, v49
	v_and_b32_e32 v50, 0x7fffffff, v42
	v_exp_f32_e32 v57, v57
	v_cndmask_b32_e32 v49, v51, v55, vcc
	v_and_b32_e32 v51, 0x7fffffff, v43
	v_pk_fma_f32 v[50:51], v[50:51], s[28:29], 1.0 op_sel_hi:[1,0,0]
	v_cmp_gt_f32_e32 vcc, 0, v42
	v_rcp_f32_e32 v50, v50
	v_rcp_f32_e32 v51, v51
	s_nop 0
	v_pk_fma_f32 v[54:55], v[50:51], s[38:39], v[52:53] op_sel_hi:[1,0,0]
	s_nop 0
	v_pk_fma_f32 v[54:55], v[50:51], v[54:55], s[72:73] op_sel_hi:[1,1,0]
	s_nop 0
	v_pk_fma_f32 v[54:55], v[50:51], v[54:55], s[76:77] op_sel_hi:[1,1,0]
	s_nop 0
	v_pk_fma_f32 v[54:55], v[50:51], v[54:55], s[82:83] op_sel_hi:[1,1,0]
	s_nop 0
	v_pk_mul_f32 v[50:51], v[50:51], v[54:55]
	v_pk_mul_f32 v[54:55], v[44:45], v[44:45]
	v_pk_mul_f32 v[50:51], v[56:57], v[50:51]
	s_nop 0
	v_pk_mul_f32 v[56:57], v[42:43], v[50:51]
	v_pk_fma_f32 v[50:51], v[42:43], v[50:51], v[42:43] neg_lo:[1,0,0] neg_hi:[1,0,0]
	s_nop 0
	v_cndmask_b32_e32 v42, v50, v56, vcc
	v_cmp_gt_f32_e32 vcc, 0, v43
	v_and_b32_e32 v50, 0x7fffffff, v44
	s_nop 0
	v_cndmask_b32_e32 v43, v51, v57, vcc
	v_and_b32_e32 v51, 0x7fffffff, v45
	v_pk_fma_f32 v[50:51], v[50:51], s[28:29], 1.0 op_sel_hi:[1,0,0]
	v_cmp_gt_f32_e32 vcc, 0, v44
	v_rcp_f32_e32 v50, v50
	v_rcp_f32_e32 v51, v51
	s_nop 0
	v_pk_fma_f32 v[52:53], v[50:51], s[38:39], v[52:53] op_sel_hi:[1,0,0]
	s_nop 0
	v_pk_fma_f32 v[52:53], v[50:51], v[52:53], s[72:73] op_sel_hi:[1,1,0]
	s_nop 0
	v_pk_fma_f32 v[52:53], v[50:51], v[52:53], s[76:77] op_sel_hi:[1,1,0]
	s_nop 0
	v_pk_fma_f32 v[52:53], v[50:51], v[52:53], s[82:83] op_sel_hi:[1,1,0]
	s_nop 0
	v_pk_mul_f32 v[50:51], v[50:51], v[52:53]
	v_pk_mul_f32 v[52:53], v[54:55], s[88:89] op_sel_hi:[1,0]
	s_nop 0
	v_exp_f32_e32 v52, v52
	v_exp_f32_e32 v53, v53
	s_nop 0
	v_pk_mul_f32 v[50:51], v[52:53], v[50:51]
	s_nop 0
	v_pk_mul_f32 v[52:53], v[44:45], v[50:51]
	v_pk_fma_f32 v[50:51], v[44:45], v[50:51], v[44:45] neg_lo:[1,0,0] neg_hi:[1,0,0]
	s_nop 0
	v_cndmask_b32_e32 v44, v50, v52, vcc
	v_cmp_gt_f32_e32 vcc, 0, v45
	s_nop 1
	v_cndmask_b32_e32 v45, v51, v53, vcc
.LBB0_310:
	v_add_u32_e32 v52, 0x90, v167
	v_mov_b64_e32 v[50:51], s[74:75]
	v_mad_i64_i32 v[50:51], s[2:3], v52, s56, v[50:51]
	v_lshl_add_u64 v[50:51], v[202:203], 1, v[50:51]
	s_and_b64 vcc, exec, s[10:11]
	v_cvt_pk_bf16_f32 v46, v46, v47
	v_cvt_pk_bf16_f32 v47, v48, v49
	v_cvt_pk_bf16_f32 v48, v42, v43
	v_cvt_pk_bf16_f32 v49, v44, v45
	global_store_dwordx4 v[50:51], v[46:49], off sc1
	s_cbranch_vccnz .LBB0_312
	v_and_b32_e32 v43, 0x7fffffff, v39
	v_and_b32_e32 v42, 0x7fffffff, v38
	v_pk_fma_f32 v[42:43], v[42:43], s[28:29], 1.0 op_sel_hi:[1,0,0]
	v_mov_b64_e32 v[44:45], s[68:69]
	v_rcp_f32_e32 v42, v42
	v_rcp_f32_e32 v43, v43
	v_pk_mul_f32 v[48:49], v[38:39], v[38:39]
	v_cmp_gt_f32_e32 vcc, 0, v38
	v_pk_mul_f32 v[48:49], v[48:49], s[88:89] op_sel_hi:[1,0]
	v_pk_fma_f32 v[46:47], v[42:43], s[38:39], v[44:45] op_sel_hi:[1,0,0]
	v_exp_f32_e32 v48, v48
	v_pk_fma_f32 v[46:47], v[42:43], v[46:47], s[72:73] op_sel_hi:[1,1,0]
	v_exp_f32_e32 v49, v49
	v_pk_fma_f32 v[46:47], v[42:43], v[46:47], s[76:77] op_sel_hi:[1,1,0]
	s_nop 0
	v_pk_fma_f32 v[46:47], v[42:43], v[46:47], s[82:83] op_sel_hi:[1,1,0]
	s_nop 0
	v_pk_mul_f32 v[42:43], v[42:43], v[46:47]
	v_pk_mul_f32 v[46:47], v[40:41], v[40:41]
	v_pk_mul_f32 v[42:43], v[48:49], v[42:43]
	v_pk_mul_f32 v[46:47], v[46:47], s[88:89] op_sel_hi:[1,0]
	v_pk_mul_f32 v[48:49], v[38:39], v[42:43]
	v_pk_fma_f32 v[42:43], v[38:39], v[42:43], v[38:39] neg_lo:[1,0,0] neg_hi:[1,0,0]
	v_exp_f32_e32 v46, v46
	v_cndmask_b32_e32 v38, v42, v48, vcc
	v_cmp_gt_f32_e32 vcc, 0, v39
	v_and_b32_e32 v42, 0x7fffffff, v40
	v_exp_f32_e32 v47, v47
	v_cndmask_b32_e32 v39, v43, v49, vcc
	v_and_b32_e32 v43, 0x7fffffff, v41
	v_pk_fma_f32 v[42:43], v[42:43], s[28:29], 1.0 op_sel_hi:[1,0,0]
	v_cmp_gt_f32_e32 vcc, 0, v40
	v_rcp_f32_e32 v42, v42
	v_rcp_f32_e32 v43, v43
	s_nop 0
	v_pk_fma_f32 v[48:49], v[42:43], s[38:39], v[44:45] op_sel_hi:[1,0,0]
	s_nop 0
	v_pk_fma_f32 v[48:49], v[42:43], v[48:49], s[72:73] op_sel_hi:[1,1,0]
	s_nop 0
	v_pk_fma_f32 v[48:49], v[42:43], v[48:49], s[76:77] op_sel_hi:[1,1,0]
	s_nop 0
	v_pk_fma_f32 v[48:49], v[42:43], v[48:49], s[82:83] op_sel_hi:[1,1,0]
	s_nop 0
	v_pk_mul_f32 v[42:43], v[42:43], v[48:49]
	v_pk_mul_f32 v[48:49], v[34:35], v[34:35]
	v_pk_mul_f32 v[42:43], v[46:47], v[42:43]
	v_pk_mul_f32 v[48:49], v[48:49], s[88:89] op_sel_hi:[1,0]
	v_pk_mul_f32 v[46:47], v[40:41], v[42:43]
	v_pk_fma_f32 v[42:43], v[40:41], v[42:43], v[40:41] neg_lo:[1,0,0] neg_hi:[1,0,0]
	v_exp_f32_e32 v48, v48
	v_cndmask_b32_e32 v40, v42, v46, vcc
	v_cmp_gt_f32_e32 vcc, 0, v41
	v_and_b32_e32 v42, 0x7fffffff, v34
	v_exp_f32_e32 v49, v49
	v_cndmask_b32_e32 v41, v43, v47, vcc
	v_and_b32_e32 v43, 0x7fffffff, v35
	v_pk_fma_f32 v[42:43], v[42:43], s[28:29], 1.0 op_sel_hi:[1,0,0]
	v_cmp_gt_f32_e32 vcc, 0, v34
	v_rcp_f32_e32 v42, v42
	v_rcp_f32_e32 v43, v43
	s_nop 0
	v_pk_fma_f32 v[46:47], v[42:43], s[38:39], v[44:45] op_sel_hi:[1,0,0]
	s_nop 0
	v_pk_fma_f32 v[46:47], v[42:43], v[46:47], s[72:73] op_sel_hi:[1,1,0]
	s_nop 0
	v_pk_fma_f32 v[46:47], v[42:43], v[46:47], s[76:77] op_sel_hi:[1,1,0]
	s_nop 0
	v_pk_fma_f32 v[46:47], v[42:43], v[46:47], s[82:83] op_sel_hi:[1,1,0]
	s_nop 0
	v_pk_mul_f32 v[42:43], v[42:43], v[46:47]
	v_pk_mul_f32 v[46:47], v[36:37], v[36:37]
	v_pk_mul_f32 v[42:43], v[48:49], v[42:43]
	s_nop 0
	v_pk_mul_f32 v[48:49], v[34:35], v[42:43]
	v_pk_fma_f32 v[42:43], v[34:35], v[42:43], v[34:35] neg_lo:[1,0,0] neg_hi:[1,0,0]
	s_nop 0
	v_cndmask_b32_e32 v34, v42, v48, vcc
	v_cmp_gt_f32_e32 vcc, 0, v35
	v_and_b32_e32 v42, 0x7fffffff, v36
	s_nop 0
	v_cndmask_b32_e32 v35, v43, v49, vcc
	v_and_b32_e32 v43, 0x7fffffff, v37
	v_pk_fma_f32 v[42:43], v[42:43], s[28:29], 1.0 op_sel_hi:[1,0,0]
	v_cmp_gt_f32_e32 vcc, 0, v36
	v_rcp_f32_e32 v42, v42
	v_rcp_f32_e32 v43, v43
	s_nop 0
	v_pk_fma_f32 v[44:45], v[42:43], s[38:39], v[44:45] op_sel_hi:[1,0,0]
	s_nop 0
	v_pk_fma_f32 v[44:45], v[42:43], v[44:45], s[72:73] op_sel_hi:[1,1,0]
	s_nop 0
	v_pk_fma_f32 v[44:45], v[42:43], v[44:45], s[76:77] op_sel_hi:[1,1,0]
	s_nop 0
	v_pk_fma_f32 v[44:45], v[42:43], v[44:45], s[82:83] op_sel_hi:[1,1,0]
	s_nop 0
	v_pk_mul_f32 v[42:43], v[42:43], v[44:45]
	v_pk_mul_f32 v[44:45], v[46:47], s[88:89] op_sel_hi:[1,0]
	s_nop 0
	v_exp_f32_e32 v44, v44
	v_exp_f32_e32 v45, v45
	s_nop 0
	v_pk_mul_f32 v[42:43], v[44:45], v[42:43]
	s_nop 0
	v_pk_mul_f32 v[44:45], v[36:37], v[42:43]
	v_pk_fma_f32 v[42:43], v[36:37], v[42:43], v[36:37] neg_lo:[1,0,0] neg_hi:[1,0,0]
	s_nop 0
	v_cndmask_b32_e32 v36, v42, v44, vcc
	v_cmp_gt_f32_e32 vcc, 0, v37
	s_nop 1
	v_cndmask_b32_e32 v37, v43, v45, vcc
.LBB0_312:
	s_and_b64 vcc, exec, s[10:11]
	v_cvt_pk_bf16_f32 v38, v38, v39
	v_cvt_pk_bf16_f32 v39, v40, v41
	v_cvt_pk_bf16_f32 v40, v34, v35
	v_cvt_pk_bf16_f32 v41, v36, v37
	global_store_dwordx4 v[50:51], v[38:41], off offset:256 sc1
	s_cbranch_vccnz .LBB0_314
	v_and_b32_e32 v35, 0x7fffffff, v31
	v_and_b32_e32 v34, 0x7fffffff, v30
	v_pk_fma_f32 v[34:35], v[34:35], s[28:29], 1.0 op_sel_hi:[1,0,0]
	v_mov_b64_e32 v[36:37], s[68:69]
	v_rcp_f32_e32 v34, v34
	v_rcp_f32_e32 v35, v35
	v_pk_mul_f32 v[40:41], v[30:31], v[30:31]
	v_cmp_gt_f32_e32 vcc, 0, v30
	v_pk_mul_f32 v[40:41], v[40:41], s[88:89] op_sel_hi:[1,0]
	v_pk_fma_f32 v[38:39], v[34:35], s[38:39], v[36:37] op_sel_hi:[1,0,0]
	v_exp_f32_e32 v40, v40
	v_pk_fma_f32 v[38:39], v[34:35], v[38:39], s[72:73] op_sel_hi:[1,1,0]
	v_exp_f32_e32 v41, v41
	v_pk_fma_f32 v[38:39], v[34:35], v[38:39], s[76:77] op_sel_hi:[1,1,0]
	s_nop 0
	v_pk_fma_f32 v[38:39], v[34:35], v[38:39], s[82:83] op_sel_hi:[1,1,0]
	s_nop 0
	v_pk_mul_f32 v[34:35], v[34:35], v[38:39]
	v_pk_mul_f32 v[38:39], v[32:33], v[32:33]
	v_pk_mul_f32 v[34:35], v[40:41], v[34:35]
	v_pk_mul_f32 v[38:39], v[38:39], s[88:89] op_sel_hi:[1,0]
	v_pk_mul_f32 v[40:41], v[30:31], v[34:35]
	v_pk_fma_f32 v[34:35], v[30:31], v[34:35], v[30:31] neg_lo:[1,0,0] neg_hi:[1,0,0]
	v_exp_f32_e32 v38, v38
	v_cndmask_b32_e32 v30, v34, v40, vcc
	v_cmp_gt_f32_e32 vcc, 0, v31
	v_and_b32_e32 v34, 0x7fffffff, v32
	v_exp_f32_e32 v39, v39
	v_cndmask_b32_e32 v31, v35, v41, vcc
	v_and_b32_e32 v35, 0x7fffffff, v33
	v_pk_fma_f32 v[34:35], v[34:35], s[28:29], 1.0 op_sel_hi:[1,0,0]
	v_cmp_gt_f32_e32 vcc, 0, v32
	v_rcp_f32_e32 v34, v34
	v_rcp_f32_e32 v35, v35
	s_nop 0
	v_pk_fma_f32 v[40:41], v[34:35], s[38:39], v[36:37] op_sel_hi:[1,0,0]
	s_nop 0
	v_pk_fma_f32 v[40:41], v[34:35], v[40:41], s[72:73] op_sel_hi:[1,1,0]
	s_nop 0
	v_pk_fma_f32 v[40:41], v[34:35], v[40:41], s[76:77] op_sel_hi:[1,1,0]
	s_nop 0
	v_pk_fma_f32 v[40:41], v[34:35], v[40:41], s[82:83] op_sel_hi:[1,1,0]
	s_nop 0
	v_pk_mul_f32 v[34:35], v[34:35], v[40:41]
	v_pk_mul_f32 v[40:41], v[26:27], v[26:27]
	v_pk_mul_f32 v[34:35], v[38:39], v[34:35]
	v_pk_mul_f32 v[40:41], v[40:41], s[88:89] op_sel_hi:[1,0]
	v_pk_mul_f32 v[38:39], v[32:33], v[34:35]
	v_pk_fma_f32 v[34:35], v[32:33], v[34:35], v[32:33] neg_lo:[1,0,0] neg_hi:[1,0,0]
	v_exp_f32_e32 v40, v40
	v_cndmask_b32_e32 v32, v34, v38, vcc
	v_cmp_gt_f32_e32 vcc, 0, v33
	v_and_b32_e32 v34, 0x7fffffff, v26
	v_exp_f32_e32 v41, v41
	v_cndmask_b32_e32 v33, v35, v39, vcc
	v_and_b32_e32 v35, 0x7fffffff, v27
	v_pk_fma_f32 v[34:35], v[34:35], s[28:29], 1.0 op_sel_hi:[1,0,0]
	v_cmp_gt_f32_e32 vcc, 0, v26
	v_rcp_f32_e32 v34, v34
	v_rcp_f32_e32 v35, v35
	s_nop 0
	v_pk_fma_f32 v[38:39], v[34:35], s[38:39], v[36:37] op_sel_hi:[1,0,0]
	s_nop 0
	v_pk_fma_f32 v[38:39], v[34:35], v[38:39], s[72:73] op_sel_hi:[1,1,0]
	s_nop 0
	v_pk_fma_f32 v[38:39], v[34:35], v[38:39], s[76:77] op_sel_hi:[1,1,0]
	s_nop 0
	v_pk_fma_f32 v[38:39], v[34:35], v[38:39], s[82:83] op_sel_hi:[1,1,0]
	s_nop 0
	v_pk_mul_f32 v[34:35], v[34:35], v[38:39]
	v_pk_mul_f32 v[38:39], v[28:29], v[28:29]
	v_pk_mul_f32 v[34:35], v[40:41], v[34:35]
	s_nop 0
	v_pk_mul_f32 v[40:41], v[26:27], v[34:35]
	v_pk_fma_f32 v[34:35], v[26:27], v[34:35], v[26:27] neg_lo:[1,0,0] neg_hi:[1,0,0]
	s_nop 0
	v_cndmask_b32_e32 v26, v34, v40, vcc
	v_cmp_gt_f32_e32 vcc, 0, v27
	v_and_b32_e32 v34, 0x7fffffff, v28
	s_nop 0
	v_cndmask_b32_e32 v27, v35, v41, vcc
	v_and_b32_e32 v35, 0x7fffffff, v29
	v_pk_fma_f32 v[34:35], v[34:35], s[28:29], 1.0 op_sel_hi:[1,0,0]
	v_cmp_gt_f32_e32 vcc, 0, v28
	v_rcp_f32_e32 v34, v34
	v_rcp_f32_e32 v35, v35
	s_nop 0
	v_pk_fma_f32 v[36:37], v[34:35], s[38:39], v[36:37] op_sel_hi:[1,0,0]
	s_nop 0
	v_pk_fma_f32 v[36:37], v[34:35], v[36:37], s[72:73] op_sel_hi:[1,1,0]
	s_nop 0
	v_pk_fma_f32 v[36:37], v[34:35], v[36:37], s[76:77] op_sel_hi:[1,1,0]
	s_nop 0
	v_pk_fma_f32 v[36:37], v[34:35], v[36:37], s[82:83] op_sel_hi:[1,1,0]
	s_nop 0
	v_pk_mul_f32 v[34:35], v[34:35], v[36:37]
	v_pk_mul_f32 v[36:37], v[38:39], s[88:89] op_sel_hi:[1,0]
	s_nop 0
	v_exp_f32_e32 v36, v36
	v_exp_f32_e32 v37, v37
	s_nop 0
	v_pk_mul_f32 v[34:35], v[36:37], v[34:35]
	s_nop 0
	v_pk_mul_f32 v[36:37], v[28:29], v[34:35]
	v_pk_fma_f32 v[34:35], v[28:29], v[34:35], v[28:29] neg_lo:[1,0,0] neg_hi:[1,0,0]
	s_nop 0
	v_cndmask_b32_e32 v28, v34, v36, vcc
	v_cmp_gt_f32_e32 vcc, 0, v29
	s_nop 1
	v_cndmask_b32_e32 v29, v35, v37, vcc
.LBB0_314:
	v_add_u32_e32 v36, 0xa0, v167
	v_mov_b64_e32 v[34:35], s[74:75]
	v_mad_i64_i32 v[34:35], s[2:3], v36, s56, v[34:35]
	v_lshl_add_u64 v[34:35], v[202:203], 1, v[34:35]
	s_and_b64 vcc, exec, s[10:11]
	v_cvt_pk_bf16_f32 v30, v30, v31
	v_cvt_pk_bf16_f32 v31, v32, v33
	v_cvt_pk_bf16_f32 v32, v26, v27
	v_cvt_pk_bf16_f32 v33, v28, v29
	global_store_dwordx4 v[34:35], v[30:33], off sc1
	s_cbranch_vccnz .LBB0_316
	v_and_b32_e32 v27, 0x7fffffff, v23
	v_and_b32_e32 v26, 0x7fffffff, v22
	v_pk_fma_f32 v[26:27], v[26:27], s[28:29], 1.0 op_sel_hi:[1,0,0]
	v_mov_b64_e32 v[28:29], s[68:69]
	v_rcp_f32_e32 v26, v26
	v_rcp_f32_e32 v27, v27
	v_pk_mul_f32 v[32:33], v[22:23], v[22:23]
	v_cmp_gt_f32_e32 vcc, 0, v22
	v_pk_mul_f32 v[32:33], v[32:33], s[88:89] op_sel_hi:[1,0]
	v_pk_fma_f32 v[30:31], v[26:27], s[38:39], v[28:29] op_sel_hi:[1,0,0]
	v_exp_f32_e32 v32, v32
	v_pk_fma_f32 v[30:31], v[26:27], v[30:31], s[72:73] op_sel_hi:[1,1,0]
	v_exp_f32_e32 v33, v33
	v_pk_fma_f32 v[30:31], v[26:27], v[30:31], s[76:77] op_sel_hi:[1,1,0]
	s_nop 0
	v_pk_fma_f32 v[30:31], v[26:27], v[30:31], s[82:83] op_sel_hi:[1,1,0]
	s_nop 0
	v_pk_mul_f32 v[26:27], v[26:27], v[30:31]
	v_pk_mul_f32 v[30:31], v[24:25], v[24:25]
	v_pk_mul_f32 v[26:27], v[32:33], v[26:27]
	v_pk_mul_f32 v[30:31], v[30:31], s[88:89] op_sel_hi:[1,0]
	v_pk_mul_f32 v[32:33], v[22:23], v[26:27]
	v_pk_fma_f32 v[26:27], v[22:23], v[26:27], v[22:23] neg_lo:[1,0,0] neg_hi:[1,0,0]
	v_exp_f32_e32 v30, v30
	v_cndmask_b32_e32 v22, v26, v32, vcc
	v_cmp_gt_f32_e32 vcc, 0, v23
	v_and_b32_e32 v26, 0x7fffffff, v24
	v_exp_f32_e32 v31, v31
	v_cndmask_b32_e32 v23, v27, v33, vcc
	v_and_b32_e32 v27, 0x7fffffff, v25
	v_pk_fma_f32 v[26:27], v[26:27], s[28:29], 1.0 op_sel_hi:[1,0,0]
	v_cmp_gt_f32_e32 vcc, 0, v24
	v_rcp_f32_e32 v26, v26
	v_rcp_f32_e32 v27, v27
	s_nop 0
	v_pk_fma_f32 v[32:33], v[26:27], s[38:39], v[28:29] op_sel_hi:[1,0,0]
	s_nop 0
	v_pk_fma_f32 v[32:33], v[26:27], v[32:33], s[72:73] op_sel_hi:[1,1,0]
	s_nop 0
	v_pk_fma_f32 v[32:33], v[26:27], v[32:33], s[76:77] op_sel_hi:[1,1,0]
	s_nop 0
	v_pk_fma_f32 v[32:33], v[26:27], v[32:33], s[82:83] op_sel_hi:[1,1,0]
	s_nop 0
	v_pk_mul_f32 v[26:27], v[26:27], v[32:33]
	v_pk_mul_f32 v[32:33], v[18:19], v[18:19]
	v_pk_mul_f32 v[26:27], v[30:31], v[26:27]
	v_pk_mul_f32 v[32:33], v[32:33], s[88:89] op_sel_hi:[1,0]
	v_pk_mul_f32 v[30:31], v[24:25], v[26:27]
	v_pk_fma_f32 v[26:27], v[24:25], v[26:27], v[24:25] neg_lo:[1,0,0] neg_hi:[1,0,0]
	v_exp_f32_e32 v32, v32
	v_cndmask_b32_e32 v24, v26, v30, vcc
	v_cmp_gt_f32_e32 vcc, 0, v25
	v_and_b32_e32 v26, 0x7fffffff, v18
	v_exp_f32_e32 v33, v33
	v_cndmask_b32_e32 v25, v27, v31, vcc
	v_and_b32_e32 v27, 0x7fffffff, v19
	v_pk_fma_f32 v[26:27], v[26:27], s[28:29], 1.0 op_sel_hi:[1,0,0]
	v_cmp_gt_f32_e32 vcc, 0, v18
	v_rcp_f32_e32 v26, v26
	v_rcp_f32_e32 v27, v27
	s_nop 0
	v_pk_fma_f32 v[30:31], v[26:27], s[38:39], v[28:29] op_sel_hi:[1,0,0]
	s_nop 0
	v_pk_fma_f32 v[30:31], v[26:27], v[30:31], s[72:73] op_sel_hi:[1,1,0]
	s_nop 0
	v_pk_fma_f32 v[30:31], v[26:27], v[30:31], s[76:77] op_sel_hi:[1,1,0]
	s_nop 0
	v_pk_fma_f32 v[30:31], v[26:27], v[30:31], s[82:83] op_sel_hi:[1,1,0]
	s_nop 0
	v_pk_mul_f32 v[26:27], v[26:27], v[30:31]
	v_pk_mul_f32 v[30:31], v[20:21], v[20:21]
	v_pk_mul_f32 v[26:27], v[32:33], v[26:27]
	s_nop 0
	v_pk_mul_f32 v[32:33], v[18:19], v[26:27]
	v_pk_fma_f32 v[26:27], v[18:19], v[26:27], v[18:19] neg_lo:[1,0,0] neg_hi:[1,0,0]
	s_nop 0
	v_cndmask_b32_e32 v18, v26, v32, vcc
	v_cmp_gt_f32_e32 vcc, 0, v19
	v_and_b32_e32 v26, 0x7fffffff, v20
	s_nop 0
	v_cndmask_b32_e32 v19, v27, v33, vcc
	v_and_b32_e32 v27, 0x7fffffff, v21
	v_pk_fma_f32 v[26:27], v[26:27], s[28:29], 1.0 op_sel_hi:[1,0,0]
	v_cmp_gt_f32_e32 vcc, 0, v20
	v_rcp_f32_e32 v26, v26
	v_rcp_f32_e32 v27, v27
	s_nop 0
	v_pk_fma_f32 v[28:29], v[26:27], s[38:39], v[28:29] op_sel_hi:[1,0,0]
	s_nop 0
	v_pk_fma_f32 v[28:29], v[26:27], v[28:29], s[72:73] op_sel_hi:[1,1,0]
	s_nop 0
	v_pk_fma_f32 v[28:29], v[26:27], v[28:29], s[76:77] op_sel_hi:[1,1,0]
	s_nop 0
	v_pk_fma_f32 v[28:29], v[26:27], v[28:29], s[82:83] op_sel_hi:[1,1,0]
	s_nop 0
	v_pk_mul_f32 v[26:27], v[26:27], v[28:29]
	v_pk_mul_f32 v[28:29], v[30:31], s[88:89] op_sel_hi:[1,0]
	s_nop 0
	v_exp_f32_e32 v28, v28
	v_exp_f32_e32 v29, v29
	s_nop 0
	v_pk_mul_f32 v[26:27], v[28:29], v[26:27]
	s_nop 0
	v_pk_mul_f32 v[28:29], v[20:21], v[26:27]
	v_pk_fma_f32 v[26:27], v[20:21], v[26:27], v[20:21] neg_lo:[1,0,0] neg_hi:[1,0,0]
	s_nop 0
	v_cndmask_b32_e32 v20, v26, v28, vcc
	v_cmp_gt_f32_e32 vcc, 0, v21
	s_nop 1
	v_cndmask_b32_e32 v21, v27, v29, vcc
.LBB0_316:
	s_and_b64 vcc, exec, s[10:11]
	v_cvt_pk_bf16_f32 v22, v22, v23
	v_cvt_pk_bf16_f32 v23, v24, v25
	v_cvt_pk_bf16_f32 v24, v18, v19
	v_cvt_pk_bf16_f32 v25, v20, v21
	global_store_dwordx4 v[34:35], v[22:25], off offset:256 sc1
	s_cbranch_vccnz .LBB0_318
	v_and_b32_e32 v19, 0x7fffffff, v15
	v_and_b32_e32 v18, 0x7fffffff, v14
	v_pk_fma_f32 v[18:19], v[18:19], s[28:29], 1.0 op_sel_hi:[1,0,0]
	v_mov_b64_e32 v[20:21], s[68:69]
	v_rcp_f32_e32 v18, v18
	v_rcp_f32_e32 v19, v19
	v_pk_mul_f32 v[24:25], v[14:15], v[14:15]
	v_cmp_gt_f32_e32 vcc, 0, v14
	v_pk_mul_f32 v[24:25], v[24:25], s[88:89] op_sel_hi:[1,0]
	v_pk_fma_f32 v[22:23], v[18:19], s[38:39], v[20:21] op_sel_hi:[1,0,0]
	v_exp_f32_e32 v24, v24
	v_pk_fma_f32 v[22:23], v[18:19], v[22:23], s[72:73] op_sel_hi:[1,1,0]
	v_exp_f32_e32 v25, v25
	v_pk_fma_f32 v[22:23], v[18:19], v[22:23], s[76:77] op_sel_hi:[1,1,0]
	s_nop 0
	v_pk_fma_f32 v[22:23], v[18:19], v[22:23], s[82:83] op_sel_hi:[1,1,0]
	s_nop 0
	v_pk_mul_f32 v[18:19], v[18:19], v[22:23]
	v_pk_mul_f32 v[22:23], v[16:17], v[16:17]
	v_pk_mul_f32 v[18:19], v[24:25], v[18:19]
	v_pk_mul_f32 v[22:23], v[22:23], s[88:89] op_sel_hi:[1,0]
	v_pk_mul_f32 v[24:25], v[14:15], v[18:19]
	v_pk_fma_f32 v[18:19], v[14:15], v[18:19], v[14:15] neg_lo:[1,0,0] neg_hi:[1,0,0]
	v_exp_f32_e32 v22, v22
	v_cndmask_b32_e32 v14, v18, v24, vcc
	v_cmp_gt_f32_e32 vcc, 0, v15
	v_and_b32_e32 v18, 0x7fffffff, v16
	v_exp_f32_e32 v23, v23
	v_cndmask_b32_e32 v15, v19, v25, vcc
	v_and_b32_e32 v19, 0x7fffffff, v17
	v_pk_fma_f32 v[18:19], v[18:19], s[28:29], 1.0 op_sel_hi:[1,0,0]
	v_cmp_gt_f32_e32 vcc, 0, v16
	v_rcp_f32_e32 v18, v18
	v_rcp_f32_e32 v19, v19
	s_nop 0
	v_pk_fma_f32 v[24:25], v[18:19], s[38:39], v[20:21] op_sel_hi:[1,0,0]
	s_nop 0
	v_pk_fma_f32 v[24:25], v[18:19], v[24:25], s[72:73] op_sel_hi:[1,1,0]
	s_nop 0
	v_pk_fma_f32 v[24:25], v[18:19], v[24:25], s[76:77] op_sel_hi:[1,1,0]
	s_nop 0
	v_pk_fma_f32 v[24:25], v[18:19], v[24:25], s[82:83] op_sel_hi:[1,1,0]
	s_nop 0
	v_pk_mul_f32 v[18:19], v[18:19], v[24:25]
	v_pk_mul_f32 v[24:25], v[10:11], v[10:11]
	v_pk_mul_f32 v[18:19], v[22:23], v[18:19]
	v_pk_mul_f32 v[24:25], v[24:25], s[88:89] op_sel_hi:[1,0]
	v_pk_mul_f32 v[22:23], v[16:17], v[18:19]
	v_pk_fma_f32 v[18:19], v[16:17], v[18:19], v[16:17] neg_lo:[1,0,0] neg_hi:[1,0,0]
	v_exp_f32_e32 v24, v24
	v_cndmask_b32_e32 v16, v18, v22, vcc
	v_cmp_gt_f32_e32 vcc, 0, v17
	v_and_b32_e32 v18, 0x7fffffff, v10
	v_exp_f32_e32 v25, v25
	v_cndmask_b32_e32 v17, v19, v23, vcc
	v_and_b32_e32 v19, 0x7fffffff, v11
	v_pk_fma_f32 v[18:19], v[18:19], s[28:29], 1.0 op_sel_hi:[1,0,0]
	v_cmp_gt_f32_e32 vcc, 0, v10
	v_rcp_f32_e32 v18, v18
	v_rcp_f32_e32 v19, v19
	s_nop 0
	v_pk_fma_f32 v[22:23], v[18:19], s[38:39], v[20:21] op_sel_hi:[1,0,0]
	s_nop 0
	v_pk_fma_f32 v[22:23], v[18:19], v[22:23], s[72:73] op_sel_hi:[1,1,0]
	s_nop 0
	v_pk_fma_f32 v[22:23], v[18:19], v[22:23], s[76:77] op_sel_hi:[1,1,0]
	s_nop 0
	v_pk_fma_f32 v[22:23], v[18:19], v[22:23], s[82:83] op_sel_hi:[1,1,0]
	s_nop 0
	v_pk_mul_f32 v[18:19], v[18:19], v[22:23]
	v_pk_mul_f32 v[22:23], v[12:13], v[12:13]
	v_pk_mul_f32 v[18:19], v[24:25], v[18:19]
	s_nop 0
	v_pk_mul_f32 v[24:25], v[10:11], v[18:19]
	v_pk_fma_f32 v[18:19], v[10:11], v[18:19], v[10:11] neg_lo:[1,0,0] neg_hi:[1,0,0]
	s_nop 0
	v_cndmask_b32_e32 v10, v18, v24, vcc
	v_cmp_gt_f32_e32 vcc, 0, v11
	v_and_b32_e32 v18, 0x7fffffff, v12
	s_nop 0
	v_cndmask_b32_e32 v11, v19, v25, vcc
	v_and_b32_e32 v19, 0x7fffffff, v13
	v_pk_fma_f32 v[18:19], v[18:19], s[28:29], 1.0 op_sel_hi:[1,0,0]
	v_cmp_gt_f32_e32 vcc, 0, v12
	v_rcp_f32_e32 v18, v18
	v_rcp_f32_e32 v19, v19
	s_nop 0
	v_pk_fma_f32 v[20:21], v[18:19], s[38:39], v[20:21] op_sel_hi:[1,0,0]
	s_nop 0
	v_pk_fma_f32 v[20:21], v[18:19], v[20:21], s[72:73] op_sel_hi:[1,1,0]
	s_nop 0
	v_pk_fma_f32 v[20:21], v[18:19], v[20:21], s[76:77] op_sel_hi:[1,1,0]
	s_nop 0
	v_pk_fma_f32 v[20:21], v[18:19], v[20:21], s[82:83] op_sel_hi:[1,1,0]
	s_nop 0
	v_pk_mul_f32 v[18:19], v[18:19], v[20:21]
	v_pk_mul_f32 v[20:21], v[22:23], s[88:89] op_sel_hi:[1,0]
	s_nop 0
	v_exp_f32_e32 v20, v20
	v_exp_f32_e32 v21, v21
	s_nop 0
	v_pk_mul_f32 v[18:19], v[20:21], v[18:19]
	s_nop 0
	v_pk_mul_f32 v[20:21], v[12:13], v[18:19]
	v_pk_fma_f32 v[18:19], v[12:13], v[18:19], v[12:13] neg_lo:[1,0,0] neg_hi:[1,0,0]
	s_nop 0
	v_cndmask_b32_e32 v12, v18, v20, vcc
	v_cmp_gt_f32_e32 vcc, 0, v13
	s_nop 1
	v_cndmask_b32_e32 v13, v19, v21, vcc
.LBB0_318:
	v_add_u32_e32 v20, 0xb0, v167
	v_mov_b64_e32 v[18:19], s[74:75]
	v_mad_i64_i32 v[18:19], s[2:3], v20, s56, v[18:19]
	v_lshl_add_u64 v[18:19], v[202:203], 1, v[18:19]
	s_and_b64 vcc, exec, s[10:11]
	v_cvt_pk_bf16_f32 v14, v14, v15
	v_cvt_pk_bf16_f32 v15, v16, v17
	v_cvt_pk_bf16_f32 v16, v10, v11
	v_cvt_pk_bf16_f32 v17, v12, v13
	global_store_dwordx4 v[18:19], v[14:17], off sc1
	s_cbranch_vccnz .LBB0_320
	v_and_b32_e32 v11, 0x7fffffff, v7
	v_and_b32_e32 v10, 0x7fffffff, v6
	v_pk_fma_f32 v[10:11], v[10:11], s[28:29], 1.0 op_sel_hi:[1,0,0]
	v_mov_b64_e32 v[12:13], s[68:69]
	v_rcp_f32_e32 v10, v10
	v_rcp_f32_e32 v11, v11
	v_pk_mul_f32 v[16:17], v[6:7], v[6:7]
	v_cmp_gt_f32_e32 vcc, 0, v6
	v_pk_mul_f32 v[16:17], v[16:17], s[88:89] op_sel_hi:[1,0]
	v_pk_fma_f32 v[14:15], v[10:11], s[38:39], v[12:13] op_sel_hi:[1,0,0]
	v_exp_f32_e32 v16, v16
	v_pk_fma_f32 v[14:15], v[10:11], v[14:15], s[72:73] op_sel_hi:[1,1,0]
	v_exp_f32_e32 v17, v17
	v_pk_fma_f32 v[14:15], v[10:11], v[14:15], s[76:77] op_sel_hi:[1,1,0]
	s_nop 0
	v_pk_fma_f32 v[14:15], v[10:11], v[14:15], s[82:83] op_sel_hi:[1,1,0]
	s_nop 0
	v_pk_mul_f32 v[10:11], v[10:11], v[14:15]
	v_pk_mul_f32 v[14:15], v[8:9], v[8:9]
	v_pk_mul_f32 v[10:11], v[16:17], v[10:11]
	v_pk_mul_f32 v[14:15], v[14:15], s[88:89] op_sel_hi:[1,0]
	v_pk_mul_f32 v[16:17], v[6:7], v[10:11]
	v_pk_fma_f32 v[10:11], v[6:7], v[10:11], v[6:7] neg_lo:[1,0,0] neg_hi:[1,0,0]
	v_exp_f32_e32 v14, v14
	v_cndmask_b32_e32 v6, v10, v16, vcc
	v_cmp_gt_f32_e32 vcc, 0, v7
	v_and_b32_e32 v10, 0x7fffffff, v8
	v_exp_f32_e32 v15, v15
	v_cndmask_b32_e32 v7, v11, v17, vcc
	v_and_b32_e32 v11, 0x7fffffff, v9
	v_pk_fma_f32 v[10:11], v[10:11], s[28:29], 1.0 op_sel_hi:[1,0,0]
	v_cmp_gt_f32_e32 vcc, 0, v8
	v_rcp_f32_e32 v10, v10
	v_rcp_f32_e32 v11, v11
	s_nop 0
	v_pk_fma_f32 v[16:17], v[10:11], s[38:39], v[12:13] op_sel_hi:[1,0,0]
	s_nop 0
	v_pk_fma_f32 v[16:17], v[10:11], v[16:17], s[72:73] op_sel_hi:[1,1,0]
	s_nop 0
	v_pk_fma_f32 v[16:17], v[10:11], v[16:17], s[76:77] op_sel_hi:[1,1,0]
	s_nop 0
	v_pk_fma_f32 v[16:17], v[10:11], v[16:17], s[82:83] op_sel_hi:[1,1,0]
	s_nop 0
	v_pk_mul_f32 v[10:11], v[10:11], v[16:17]
	v_pk_mul_f32 v[16:17], v[2:3], v[2:3]
	v_pk_mul_f32 v[10:11], v[14:15], v[10:11]
	v_pk_mul_f32 v[16:17], v[16:17], s[88:89] op_sel_hi:[1,0]
	v_pk_mul_f32 v[14:15], v[8:9], v[10:11]
	v_pk_fma_f32 v[10:11], v[8:9], v[10:11], v[8:9] neg_lo:[1,0,0] neg_hi:[1,0,0]
	v_exp_f32_e32 v16, v16
	v_cndmask_b32_e32 v8, v10, v14, vcc
	v_cmp_gt_f32_e32 vcc, 0, v9
	v_and_b32_e32 v10, 0x7fffffff, v2
	v_exp_f32_e32 v17, v17
	v_cndmask_b32_e32 v9, v11, v15, vcc
	v_and_b32_e32 v11, 0x7fffffff, v3
	v_pk_fma_f32 v[10:11], v[10:11], s[28:29], 1.0 op_sel_hi:[1,0,0]
	v_cmp_gt_f32_e32 vcc, 0, v2
	v_rcp_f32_e32 v10, v10
	v_rcp_f32_e32 v11, v11
	s_nop 0
	v_pk_fma_f32 v[14:15], v[10:11], s[38:39], v[12:13] op_sel_hi:[1,0,0]
	s_nop 0
	v_pk_fma_f32 v[14:15], v[10:11], v[14:15], s[72:73] op_sel_hi:[1,1,0]
	s_nop 0
	v_pk_fma_f32 v[14:15], v[10:11], v[14:15], s[76:77] op_sel_hi:[1,1,0]
	s_nop 0
	v_pk_fma_f32 v[14:15], v[10:11], v[14:15], s[82:83] op_sel_hi:[1,1,0]
	s_nop 0
	v_pk_mul_f32 v[10:11], v[10:11], v[14:15]
	v_pk_mul_f32 v[14:15], v[4:5], v[4:5]
	v_pk_mul_f32 v[10:11], v[16:17], v[10:11]
	s_nop 0
	v_pk_mul_f32 v[16:17], v[2:3], v[10:11]
	v_pk_fma_f32 v[10:11], v[2:3], v[10:11], v[2:3] neg_lo:[1,0,0] neg_hi:[1,0,0]
	s_nop 0
	v_cndmask_b32_e32 v2, v10, v16, vcc
	v_cmp_gt_f32_e32 vcc, 0, v3
	v_and_b32_e32 v10, 0x7fffffff, v4
	s_nop 0
	v_cndmask_b32_e32 v3, v11, v17, vcc
	v_and_b32_e32 v11, 0x7fffffff, v5
	v_pk_fma_f32 v[10:11], v[10:11], s[28:29], 1.0 op_sel_hi:[1,0,0]
	v_cmp_gt_f32_e32 vcc, 0, v4
	v_rcp_f32_e32 v10, v10
	v_rcp_f32_e32 v11, v11
	s_nop 0
	v_pk_fma_f32 v[12:13], v[10:11], s[38:39], v[12:13] op_sel_hi:[1,0,0]
	s_nop 0
	v_pk_fma_f32 v[12:13], v[10:11], v[12:13], s[72:73] op_sel_hi:[1,1,0]
	s_nop 0
	v_pk_fma_f32 v[12:13], v[10:11], v[12:13], s[76:77] op_sel_hi:[1,1,0]
	s_nop 0
	v_pk_fma_f32 v[12:13], v[10:11], v[12:13], s[82:83] op_sel_hi:[1,1,0]
	s_nop 0
	v_pk_mul_f32 v[10:11], v[10:11], v[12:13]
	v_pk_mul_f32 v[12:13], v[14:15], s[88:89] op_sel_hi:[1,0]
	s_nop 0
	v_exp_f32_e32 v12, v12
	v_exp_f32_e32 v13, v13
	s_nop 0
	v_pk_mul_f32 v[10:11], v[12:13], v[10:11]
	s_nop 0
	v_pk_mul_f32 v[12:13], v[4:5], v[10:11]
	v_pk_fma_f32 v[10:11], v[4:5], v[10:11], v[4:5] neg_lo:[1,0,0] neg_hi:[1,0,0]
	s_nop 0
	v_cndmask_b32_e32 v4, v10, v12, vcc
	v_cmp_gt_f32_e32 vcc, 0, v5
	s_nop 1
	v_cndmask_b32_e32 v5, v11, v13, vcc
.LBB0_320:
	v_cvt_pk_bf16_f32 v6, v6, v7
	v_cvt_pk_bf16_f32 v7, v8, v9
	v_cvt_pk_bf16_f32 v8, v2, v3
	v_cvt_pk_bf16_f32 v9, v4, v5
	global_store_dwordx4 v[18:19], v[6:9], off offset:256 sc1
	s_andn2_b64 vcc, exec, s[80:81]
	s_mov_b64 s[2:3], -1
	s_cbranch_vccnz .LBB0_246

.LBB0_397:
	s_load_dwordx2 s[62:63], s[76:77], 0x0
	s_ashr_i32 s3, s2, 31
	v_add_u32_e32 v126, s38, v136
	s_lshl_b64 s[2:3], s[2:3], 2
	v_add_u32_e32 v106, 16, v126
	s_waitcnt lgkmcnt(0)
	s_add_u32 s2, s62, s2
	v_add_u32_e32 v114, 32, v126
	v_ashrrev_i32_e32 v98, 31, v126
	s_addc_u32 s3, s63, s3
	v_ashrrev_i32_e32 v107, 31, v106
	v_ashrrev_i32_e32 v115, 31, v114
	v_add_u32_e32 v124, 48, v126
	v_lshl_add_u64 v[122:123], s[2:3], 0, v[202:203]
	v_mul_lo_u32 v100, s68, v98
	v_mul_lo_u32 v101, s69, v126
	v_mad_u64_u32 v[98:99], s[2:3], s68, v126, 0
	v_mul_lo_u32 v108, s68, v107
	v_mul_lo_u32 v109, s69, v106
	v_mad_u64_u32 v[106:107], s[2:3], s68, v106, 0
	v_mul_lo_u32 v116, s68, v115
	v_mul_lo_u32 v117, s69, v114
	v_mad_u64_u32 v[114:115], s[2:3], s68, v114, 0
	v_ashrrev_i32_e32 v125, 31, v124
	v_add3_u32 v99, v99, v100, v101
	v_add_u32_e32 v100, 8, v126
	v_add3_u32 v107, v107, v108, v109
	v_add_u32_e32 v108, 24, v126
	v_add3_u32 v115, v115, v116, v117
	v_add_u32_e32 v116, 40, v126
	v_mul_lo_u32 v127, s68, v125
	v_mul_lo_u32 v128, s69, v124
	v_mad_u64_u32 v[124:125], s[2:3], s68, v124, 0
	v_add_u32_e32 v126, 56, v126
	v_ashrrev_i32_e32 v101, 31, v100
	v_ashrrev_i32_e32 v109, 31, v108
	v_ashrrev_i32_e32 v117, 31, v116
	v_add3_u32 v125, v125, v127, v128
	v_ashrrev_i32_e32 v127, 31, v126
	v_mul_lo_u32 v102, s68, v101
	v_mul_lo_u32 v103, s69, v100
	v_mad_u64_u32 v[100:101], s[2:3], s68, v100, 0
	v_mul_lo_u32 v110, s68, v109
	v_mul_lo_u32 v111, s69, v108
	v_mad_u64_u32 v[108:109], s[2:3], s68, v108, 0
	v_mul_lo_u32 v118, s68, v117
	v_mul_lo_u32 v119, s69, v116
	v_mad_u64_u32 v[116:117], s[2:3], s68, v116, 0
	v_mul_lo_u32 v128, s68, v127
	v_mul_lo_u32 v129, s69, v126
	v_mad_u64_u32 v[126:127], s[2:3], s68, v126, 0
	v_add3_u32 v101, v101, v102, v103
	v_add3_u32 v109, v109, v110, v111
	v_add3_u32 v117, v117, v118, v119
	v_add3_u32 v127, v127, v128, v129
	v_lshl_add_u64 v[98:99], v[98:99], 2, v[122:123]
	v_lshl_add_u64 v[100:101], v[100:101], 2, v[122:123]
	v_lshl_add_u64 v[106:107], v[106:107], 2, v[122:123]
	v_lshl_add_u64 v[108:109], v[108:109], 2, v[122:123]
	v_lshl_add_u64 v[114:115], v[114:115], 2, v[122:123]
	v_lshl_add_u64 v[116:117], v[116:117], 2, v[122:123]
	v_lshl_add_u64 v[124:125], v[124:125], 2, v[122:123]
	v_lshl_add_u64 v[122:123], v[126:127], 2, v[122:123]
	global_load_dwordx4 v[102:105], v[98:99], off nt
	s_nop 0
	global_load_dwordx4 v[98:101], v[100:101], off nt
	s_nop 0
	global_load_dwordx4 v[110:113], v[106:107], off nt
	s_nop 0
	global_load_dwordx4 v[106:109], v[108:109], off nt
	s_nop 0
	global_load_dwordx4 v[118:121], v[114:115], off nt
	s_nop 0
	global_load_dwordx4 v[114:117], v[116:117], off nt
	s_nop 0
	global_load_dwordx4 v[126:129], v[124:125], off nt
	s_nop 0
	global_load_dwordx4 v[122:125], v[122:123], off nt
	s_waitcnt vmcnt(31)
	ds_write2_b32 v143, v6, v7 offset1:1
	ds_write2_b32 v143, v8, v9 offset0:2 offset1:3
	v_add_u32_e32 v6, 0x420, v143
	s_waitcnt vmcnt(30)
	ds_write2_b32 v6, v2, v3 offset1:1
	v_add_u32_e32 v2, 0x428, v143
	ds_write2_b32 v2, v4, v5 offset1:1
	v_add_u32_e32 v3, 0x840, v143
	v_add_u32_e32 v5, 0xc60, v143
	v_add_u32_e32 v7, 0xc68, v143
	s_waitcnt vmcnt(29)
	ds_write2_b32 v3, v14, v15 offset1:1
	v_add_u32_e32 v4, 0x848, v143
	s_waitcnt vmcnt(28)
	ds_write2_b32 v5, v10, v11 offset1:1
	ds_write2_b32 v7, v12, v13 offset1:1
	v_add_u32_e32 v8, 0x1080, v143
	v_add_u32_e32 v9, 0x1088, v143
	v_add_u32_e32 v10, 0x14a0, v143
	v_add_u32_e32 v11, 0x14a8, v143
	v_add_u32_e32 v12, 0x18c0, v143
	v_add_u32_e32 v13, 0x18c8, v143
	v_add_u32_e32 v14, 0x1ce0, v143
	v_add_u32_e32 v15, 0x1ce8, v143
	ds_write2_b32 v4, v16, v17 offset1:1
	s_waitcnt vmcnt(27)
	ds_write2_b32 v8, v22, v23 offset1:1
	ds_write2_b32 v9, v24, v25 offset1:1
	s_waitcnt vmcnt(26)
	ds_write2_b32 v10, v18, v19 offset1:1
	ds_write2_b32 v11, v20, v21 offset1:1
	s_waitcnt vmcnt(25)
	ds_write2_b32 v12, v30, v31 offset1:1
	ds_write2_b32 v13, v32, v33 offset1:1
	s_waitcnt vmcnt(24)
	ds_write2_b32 v14, v26, v27 offset1:1
	ds_write2_b32 v15, v28, v29 offset1:1
	s_waitcnt lgkmcnt(0)
	ds_read2_b32 v[20:21], v141 offset1:8
	ds_read2_b32 v[24:25], v141 offset0:33 offset1:41
	ds_read2_b32 v[26:27], v141 offset0:66 offset1:74
	ds_read2_b32 v[28:29], v141 offset0:99 offset1:107
	ds_read2_b32 v[30:31], v141 offset0:132 offset1:140
	s_waitcnt lgkmcnt(4)
	v_bfe_u32 v16, v20, 16, 1
	v_add3_u32 v16, v20, v16, s57
	s_waitcnt lgkmcnt(3)
	v_bfe_u32 v17, v24, 16, 1
	v_lshrrev_b32_e32 v16, 16, v16
	v_add3_u32 v17, v24, v17, s57
	ds_read2_b32 v[32:33], v141 offset0:165 offset1:173
	v_and_or_b32 v16, v17, s53, v16
	s_waitcnt lgkmcnt(3)
	v_bfe_u32 v17, v26, 16, 1
	v_add3_u32 v17, v26, v17, s57
	s_waitcnt lgkmcnt(2)
	v_bfe_u32 v18, v28, 16, 1
	ds_read2_b32 v[146:147], v141 offset0:198 offset1:206
	v_lshrrev_b32_e32 v17, 16, v17
	v_add3_u32 v18, v28, v18, s57
	ds_read2_b32 v[148:149], v141 offset0:231 offset1:239
	v_and_or_b32 v17, v18, s53, v17
	s_waitcnt lgkmcnt(3)
	v_bfe_u32 v18, v30, 16, 1
	v_add3_u32 v18, v30, v18, s57
	s_waitcnt lgkmcnt(2)
	v_bfe_u32 v19, v32, 16, 1
	v_lshrrev_b32_e32 v18, 16, v18
	v_add3_u32 v19, v32, v19, s57
	v_and_or_b32 v18, v19, s53, v18
	s_waitcnt lgkmcnt(1)
	v_bfe_u32 v19, v146, 16, 1
	s_ashr_i32 s19, s18, 31
	v_add3_u32 v19, v146, v19, s57
	s_waitcnt lgkmcnt(0)
	v_bfe_u32 v20, v148, 16, 1
	s_lshl_b64 s[2:3], s[18:19], 1
	v_lshrrev_b32_e32 v19, 16, v19
	v_add3_u32 v20, v148, v20, s57
	s_add_u32 s2, s86, s2
	v_and_or_b32 v19, v20, s53, v19
	v_add_u32_e32 v20, s15, v136
	s_addc_u32 s3, s87, s3
	v_mov_b32_e32 v135, v203
	v_ashrrev_i32_e32 v24, 31, v20
	v_lshl_add_u64 v[22:23], s[2:3], 0, v[134:135]
	v_mul_lo_u32 v24, s6, v24
	v_mul_lo_u32 v26, s7, v20
	v_mad_u64_u32 v[150:151], s[2:3], s6, v20, 0
	v_add3_u32 v151, v151, v24, v26
	v_lshl_add_u64 v[150:151], v[150:151], 1, v[22:23]
	global_store_dwordx4 v[150:151], v[16:19], off sc1
	v_bfe_u32 v20, v149, 16, 1
	v_add3_u32 v20, v149, v20, s57
	v_bfe_u32 v16, v21, 16, 1
	v_add3_u32 v16, v21, v16, s57
	v_bfe_u32 v17, v25, 16, 1
	v_lshrrev_b32_e32 v16, 16, v16
	v_add3_u32 v17, v25, v17, s57
	v_and_or_b32 v16, v17, s53, v16
	v_bfe_u32 v17, v27, 16, 1
	v_add3_u32 v17, v27, v17, s57
	v_bfe_u32 v18, v29, 16, 1
	v_lshrrev_b32_e32 v17, 16, v17
	v_add3_u32 v18, v29, v18, s57
	v_and_or_b32 v17, v18, s53, v17
	v_bfe_u32 v18, v31, 16, 1
	v_add3_u32 v18, v31, v18, s57
	v_bfe_u32 v19, v33, 16, 1
	v_lshrrev_b32_e32 v18, 16, v18
	v_add3_u32 v19, v33, v19, s57
	v_and_or_b32 v18, v19, s53, v18
	v_bfe_u32 v19, v147, 16, 1
	v_add3_u32 v19, v147, v19, s57
	v_lshrrev_b32_e32 v19, 16, v19
	v_and_or_b32 v19, v20, s53, v19
	v_add_u32_e32 v20, s15, v138
	v_ashrrev_i32_e32 v21, 31, v20
	v_mul_lo_u32 v26, s6, v21
	v_mul_lo_u32 v27, s7, v20
	v_mad_u64_u32 v[20:21], s[2:3], s6, v20, 0
	v_add3_u32 v21, v21, v26, v27
	ds_read2_b32 v[24:25], v141 offset0:16 offset1:24
	v_lshl_add_u64 v[20:21], v[20:21], 1, v[22:23]
	global_store_dwordx4 v[20:21], v[16:19], off sc1
	ds_read2_b32 v[20:21], v141 offset0:49 offset1:57
	ds_read2_b32 v[26:27], v141 offset0:82 offset1:90
	ds_read2_b32 v[28:29], v141 offset0:115 offset1:123
	s_waitcnt lgkmcnt(3)
	v_bfe_u32 v16, v24, 16, 1
	v_add3_u32 v16, v24, v16, s57
	s_waitcnt lgkmcnt(2)
	v_bfe_u32 v17, v20, 16, 1
	ds_read2_b32 v[30:31], v141 offset0:148 offset1:156
	v_lshrrev_b32_e32 v16, 16, v16
	v_add3_u32 v17, v20, v17, s57
	ds_read2_b32 v[32:33], v141 offset0:181 offset1:189
	v_and_or_b32 v16, v17, s53, v16
	s_waitcnt lgkmcnt(3)
	v_bfe_u32 v17, v26, 16, 1
	v_add3_u32 v17, v26, v17, s57
	s_waitcnt lgkmcnt(2)
	v_bfe_u32 v18, v28, 16, 1
	ds_read2_b32 v[146:147], v141 offset0:214 offset1:222
	v_lshrrev_b32_e32 v17, 16, v17
	v_add3_u32 v18, v28, v18, s57
	ds_read2_b32 v[148:149], v141 offset0:247 offset1:255
	v_and_or_b32 v17, v18, s53, v17
	s_waitcnt lgkmcnt(3)
	v_bfe_u32 v18, v30, 16, 1
	v_add3_u32 v18, v30, v18, s57
	s_waitcnt lgkmcnt(2)
	v_bfe_u32 v19, v32, 16, 1
	v_lshrrev_b32_e32 v18, 16, v18
	v_add3_u32 v19, v32, v19, s57
	v_and_or_b32 v18, v19, s53, v18
	s_waitcnt lgkmcnt(1)
	v_bfe_u32 v19, v146, 16, 1
	v_add3_u32 v19, v146, v19, s57
	s_waitcnt lgkmcnt(0)
	v_bfe_u32 v20, v148, 16, 1
	v_lshrrev_b32_e32 v19, 16, v19
	v_add3_u32 v20, v148, v20, s57
	v_and_or_b32 v19, v20, s53, v19
	v_add_u32_e32 v20, s15, v139
	v_ashrrev_i32_e32 v24, 31, v20
	v_mul_lo_u32 v24, s6, v24
	v_mul_lo_u32 v26, s7, v20
	v_mad_u64_u32 v[150:151], s[2:3], s6, v20, 0
	v_add3_u32 v151, v151, v24, v26
	v_lshl_add_u64 v[150:151], v[150:151], 1, v[22:23]
	global_store_dwordx4 v[150:151], v[16:19], off sc1
	v_bfe_u32 v20, v149, 16, 1
	v_add3_u32 v20, v149, v20, s57
	v_bfe_u32 v16, v25, 16, 1
	v_add3_u32 v16, v25, v16, s57
	v_bfe_u32 v17, v21, 16, 1
	v_lshrrev_b32_e32 v16, 16, v16
	v_add3_u32 v17, v21, v17, s57
	v_and_or_b32 v16, v17, s53, v16
	v_bfe_u32 v17, v27, 16, 1
	v_add3_u32 v17, v27, v17, s57
	v_bfe_u32 v18, v29, 16, 1
	v_lshrrev_b32_e32 v17, 16, v17
	v_add3_u32 v18, v29, v18, s57
	v_and_or_b32 v17, v18, s53, v17
	v_bfe_u32 v18, v31, 16, 1
	v_add3_u32 v18, v31, v18, s57
	v_bfe_u32 v19, v33, 16, 1
	v_lshrrev_b32_e32 v18, 16, v18
	v_add3_u32 v19, v33, v19, s57
	v_and_or_b32 v18, v19, s53, v18
	v_bfe_u32 v19, v147, 16, 1
	v_add3_u32 v19, v147, v19, s57
	v_lshrrev_b32_e32 v19, 16, v19
	v_and_or_b32 v19, v20, s53, v19
	v_add_u32_e32 v20, s15, v140
	v_ashrrev_i32_e32 v21, 31, v20
	v_mul_lo_u32 v24, s6, v21
	v_mul_lo_u32 v25, s7, v20
	v_mad_u64_u32 v[20:21], s[2:3], s6, v20, 0
	v_add3_u32 v21, v21, v24, v25
	v_lshl_add_u64 v[20:21], v[20:21], 1, v[22:23]
	global_store_dwordx4 v[20:21], v[16:19], off sc1
	s_waitcnt lgkmcnt(0)
	s_waitcnt vmcnt(27)
	ds_write2_b32 v143, v38, v39 offset1:1
	ds_write2_b32 v143, v40, v41 offset0:2 offset1:3
	s_waitcnt vmcnt(26)
	ds_write2_b32 v6, v34, v35 offset1:1
	ds_write2_b32 v2, v36, v37 offset1:1
	s_waitcnt vmcnt(25)
	ds_write2_b32 v3, v46, v47 offset1:1
	ds_write2_b32 v4, v48, v49 offset1:1
	s_waitcnt vmcnt(24)
	ds_write2_b32 v5, v42, v43 offset1:1
	ds_write2_b32 v7, v44, v45 offset1:1
	s_waitcnt vmcnt(23)
	ds_write2_b32 v8, v54, v55 offset1:1
	ds_write2_b32 v9, v56, v57 offset1:1
	s_waitcnt vmcnt(22)
	ds_write2_b32 v10, v50, v51 offset1:1
	ds_write2_b32 v11, v52, v53 offset1:1
	s_waitcnt vmcnt(21)
	ds_write2_b32 v12, v62, v63 offset1:1
	ds_write2_b32 v13, v64, v65 offset1:1
	s_waitcnt vmcnt(20)
	ds_write2_b32 v14, v58, v59 offset1:1
	ds_write2_b32 v15, v60, v61 offset1:1
	s_waitcnt lgkmcnt(0)
	ds_read2_b32 v[20:21], v141 offset1:8
	ds_read2_b32 v[24:25], v141 offset0:33 offset1:41
	ds_read2_b32 v[26:27], v141 offset0:66 offset1:74
	ds_read2_b32 v[28:29], v141 offset0:99 offset1:107
	ds_read2_b32 v[30:31], v141 offset0:132 offset1:140
	s_waitcnt lgkmcnt(4)
	v_bfe_u32 v16, v20, 16, 1
	v_add3_u32 v16, v20, v16, s57
	s_waitcnt lgkmcnt(3)
	v_bfe_u32 v17, v24, 16, 1
	v_lshrrev_b32_e32 v16, 16, v16
	v_add3_u32 v17, v24, v17, s57
	ds_read2_b32 v[32:33], v141 offset0:165 offset1:173
	v_and_or_b32 v16, v17, s53, v16
	s_waitcnt lgkmcnt(3)
	v_bfe_u32 v17, v26, 16, 1
	v_add3_u32 v17, v26, v17, s57
	s_waitcnt lgkmcnt(2)
	v_bfe_u32 v18, v28, 16, 1
	ds_read2_b32 v[34:35], v141 offset0:198 offset1:206
	v_lshrrev_b32_e32 v17, 16, v17
	v_add3_u32 v18, v28, v18, s57
	ds_read2_b32 v[36:37], v141 offset0:231 offset1:239
	v_and_or_b32 v17, v18, s53, v17
	s_waitcnt lgkmcnt(3)
	v_bfe_u32 v18, v30, 16, 1
	v_add3_u32 v18, v30, v18, s57
	s_waitcnt lgkmcnt(2)
	v_bfe_u32 v19, v32, 16, 1
	v_lshrrev_b32_e32 v18, 16, v18
	v_add3_u32 v19, v32, v19, s57
	v_and_or_b32 v18, v19, s53, v18
	s_waitcnt lgkmcnt(1)
	v_bfe_u32 v19, v34, 16, 1
	s_ashr_i32 s9, s8, 31
	v_add3_u32 v19, v34, v19, s57
	s_waitcnt lgkmcnt(0)
	v_bfe_u32 v20, v36, 16, 1
	s_lshl_b64 s[2:3], s[8:9], 1
	v_lshrrev_b32_e32 v19, 16, v19
	v_add3_u32 v20, v36, v20, s57
	s_add_u32 s2, s96, s2
	v_and_or_b32 v19, v20, s53, v19
	v_add_u32_e32 v20, s22, v136
	s_addc_u32 s3, s97, s3
	v_ashrrev_i32_e32 v24, 31, v20
	v_lshl_add_u64 v[22:23], s[2:3], 0, v[134:135]
	v_mul_lo_u32 v24, s16, v24
	v_mul_lo_u32 v26, s17, v20
	v_mad_u64_u32 v[38:39], s[2:3], s16, v20, 0
	v_add3_u32 v39, v39, v24, v26
	v_lshl_add_u64 v[38:39], v[38:39], 1, v[22:23]
	global_store_dwordx4 v[38:39], v[16:19], off sc1
	v_bfe_u32 v20, v37, 16, 1
	v_add3_u32 v20, v37, v20, s57
	v_bfe_u32 v16, v21, 16, 1
	v_add3_u32 v16, v21, v16, s57
	v_bfe_u32 v17, v25, 16, 1
	v_lshrrev_b32_e32 v16, 16, v16
	v_add3_u32 v17, v25, v17, s57
	v_and_or_b32 v16, v17, s53, v16
	v_bfe_u32 v17, v27, 16, 1
	v_add3_u32 v17, v27, v17, s57
	v_bfe_u32 v18, v29, 16, 1
	v_lshrrev_b32_e32 v17, 16, v17
	v_add3_u32 v18, v29, v18, s57
	v_and_or_b32 v17, v18, s53, v17
	v_bfe_u32 v18, v31, 16, 1
	v_add3_u32 v18, v31, v18, s57
	v_bfe_u32 v19, v33, 16, 1
	v_lshrrev_b32_e32 v18, 16, v18
	v_add3_u32 v19, v33, v19, s57
	v_and_or_b32 v18, v19, s53, v18
	v_bfe_u32 v19, v35, 16, 1
	v_add3_u32 v19, v35, v19, s57
	v_lshrrev_b32_e32 v19, 16, v19
	v_and_or_b32 v19, v20, s53, v19
	v_add_u32_e32 v20, s22, v138
	v_ashrrev_i32_e32 v21, 31, v20
	v_mul_lo_u32 v26, s16, v21
	v_mul_lo_u32 v27, s17, v20
	v_mad_u64_u32 v[20:21], s[2:3], s16, v20, 0
	v_add3_u32 v21, v21, v26, v27
	ds_read2_b32 v[24:25], v141 offset0:16 offset1:24
	v_lshl_add_u64 v[20:21], v[20:21], 1, v[22:23]
	global_store_dwordx4 v[20:21], v[16:19], off sc1
	ds_read2_b32 v[20:21], v141 offset0:49 offset1:57
	ds_read2_b32 v[26:27], v141 offset0:82 offset1:90
	ds_read2_b32 v[28:29], v141 offset0:115 offset1:123
	s_waitcnt lgkmcnt(3)
	v_bfe_u32 v16, v24, 16, 1
	v_add3_u32 v16, v24, v16, s57
	s_waitcnt lgkmcnt(2)
	v_bfe_u32 v17, v20, 16, 1
	ds_read2_b32 v[30:31], v141 offset0:148 offset1:156
	v_lshrrev_b32_e32 v16, 16, v16
	v_add3_u32 v17, v20, v17, s57
	ds_read2_b32 v[32:33], v141 offset0:181 offset1:189
	v_and_or_b32 v16, v17, s53, v16
	s_waitcnt lgkmcnt(3)
	v_bfe_u32 v17, v26, 16, 1
	v_add3_u32 v17, v26, v17, s57
	s_waitcnt lgkmcnt(2)
	v_bfe_u32 v18, v28, 16, 1
	ds_read2_b32 v[34:35], v141 offset0:214 offset1:222
	v_lshrrev_b32_e32 v17, 16, v17
	v_add3_u32 v18, v28, v18, s57
	ds_read2_b32 v[36:37], v141 offset0:247 offset1:255
	v_and_or_b32 v17, v18, s53, v17
	s_waitcnt lgkmcnt(3)
	v_bfe_u32 v18, v30, 16, 1
	v_add3_u32 v18, v30, v18, s57
	s_waitcnt lgkmcnt(2)
	v_bfe_u32 v19, v32, 16, 1
	v_lshrrev_b32_e32 v18, 16, v18
	v_add3_u32 v19, v32, v19, s57
	v_and_or_b32 v18, v19, s53, v18
	s_waitcnt lgkmcnt(1)
	v_bfe_u32 v19, v34, 16, 1
	v_add3_u32 v19, v34, v19, s57
	s_waitcnt lgkmcnt(0)
	v_bfe_u32 v20, v36, 16, 1
	v_lshrrev_b32_e32 v19, 16, v19
	v_add3_u32 v20, v36, v20, s57
	v_and_or_b32 v19, v20, s53, v19
	v_add_u32_e32 v20, s22, v139
	v_ashrrev_i32_e32 v24, 31, v20
	v_mul_lo_u32 v24, s16, v24
	v_mul_lo_u32 v26, s17, v20
	v_mad_u64_u32 v[38:39], s[2:3], s16, v20, 0
	v_add3_u32 v39, v39, v24, v26
	v_lshl_add_u64 v[38:39], v[38:39], 1, v[22:23]
	global_store_dwordx4 v[38:39], v[16:19], off sc1
	v_bfe_u32 v20, v37, 16, 1
	v_add3_u32 v20, v37, v20, s57
	v_bfe_u32 v16, v25, 16, 1
	v_add3_u32 v16, v25, v16, s57
	v_bfe_u32 v17, v21, 16, 1
	v_lshrrev_b32_e32 v16, 16, v16
	v_add3_u32 v17, v21, v17, s57
	v_and_or_b32 v16, v17, s53, v16
	v_bfe_u32 v17, v27, 16, 1
	v_add3_u32 v17, v27, v17, s57
	v_bfe_u32 v18, v29, 16, 1
	v_lshrrev_b32_e32 v17, 16, v17
	v_add3_u32 v18, v29, v18, s57
	v_and_or_b32 v17, v18, s53, v17
	v_bfe_u32 v18, v31, 16, 1
	v_add3_u32 v18, v31, v18, s57
	v_bfe_u32 v19, v33, 16, 1
	v_lshrrev_b32_e32 v18, 16, v18
	v_add3_u32 v19, v33, v19, s57
	v_and_or_b32 v18, v19, s53, v18
	v_bfe_u32 v19, v35, 16, 1
	v_add3_u32 v19, v35, v19, s57
	v_lshrrev_b32_e32 v19, 16, v19
	v_and_or_b32 v19, v20, s53, v19
	v_add_u32_e32 v20, s22, v140
	v_ashrrev_i32_e32 v21, 31, v20
	v_mul_lo_u32 v24, s16, v21
	v_mul_lo_u32 v25, s17, v20
	v_mad_u64_u32 v[20:21], s[2:3], s16, v20, 0
	v_add3_u32 v21, v21, v24, v25
	v_lshl_add_u64 v[20:21], v[20:21], 1, v[22:23]
	global_store_dwordx4 v[20:21], v[16:19], off sc1
	s_waitcnt lgkmcnt(0)
	s_waitcnt vmcnt(23)
	ds_write2_b32 v143, v70, v71 offset1:1
	ds_write2_b32 v143, v72, v73 offset0:2 offset1:3
	s_waitcnt vmcnt(22)
	ds_write2_b32 v6, v66, v67 offset1:1
	ds_write2_b32 v2, v68, v69 offset1:1
	s_waitcnt vmcnt(21)
	ds_write2_b32 v3, v78, v79 offset1:1
	ds_write2_b32 v4, v80, v81 offset1:1
	s_waitcnt vmcnt(20)
	ds_write2_b32 v5, v74, v75 offset1:1
	ds_write2_b32 v7, v76, v77 offset1:1
	s_waitcnt vmcnt(19)
	ds_write2_b32 v8, v86, v87 offset1:1
	ds_write2_b32 v9, v88, v89 offset1:1
	s_waitcnt vmcnt(18)
	ds_write2_b32 v10, v82, v83 offset1:1
	ds_write2_b32 v11, v84, v85 offset1:1
	s_waitcnt vmcnt(17)
	ds_write2_b32 v12, v94, v95 offset1:1
	ds_write2_b32 v13, v96, v97 offset1:1
	s_waitcnt vmcnt(16)
	ds_write2_b32 v14, v90, v91 offset1:1
	ds_write2_b32 v15, v92, v93 offset1:1
	s_waitcnt lgkmcnt(0)
	ds_read2_b32 v[20:21], v141 offset1:8
	ds_read2_b32 v[24:25], v141 offset0:33 offset1:41
	ds_read2_b32 v[26:27], v141 offset0:66 offset1:74
	ds_read2_b32 v[28:29], v141 offset0:99 offset1:107
	ds_read2_b32 v[30:31], v141 offset0:132 offset1:140
	s_waitcnt lgkmcnt(4)
	v_bfe_u32 v16, v20, 16, 1
	v_add3_u32 v16, v20, v16, s57
	s_waitcnt lgkmcnt(3)
	v_bfe_u32 v17, v24, 16, 1
	v_lshrrev_b32_e32 v16, 16, v16
	v_add3_u32 v17, v24, v17, s57
	ds_read2_b32 v[32:33], v141 offset0:165 offset1:173
	v_and_or_b32 v16, v17, s53, v16
	s_waitcnt lgkmcnt(3)
	v_bfe_u32 v17, v26, 16, 1
	v_add3_u32 v17, v26, v17, s57
	s_waitcnt lgkmcnt(2)
	v_bfe_u32 v18, v28, 16, 1
	ds_read2_b32 v[34:35], v141 offset0:198 offset1:206
	v_lshrrev_b32_e32 v17, 16, v17
	v_add3_u32 v18, v28, v18, s57
	ds_read2_b32 v[36:37], v141 offset0:231 offset1:239
	v_and_or_b32 v17, v18, s53, v17
	s_waitcnt lgkmcnt(3)
	v_bfe_u32 v18, v30, 16, 1
	v_add3_u32 v18, v30, v18, s57
	s_waitcnt lgkmcnt(2)
	v_bfe_u32 v19, v32, 16, 1
	v_lshrrev_b32_e32 v18, 16, v18
	v_add3_u32 v19, v32, v19, s57
	v_and_or_b32 v18, v19, s53, v18
	s_waitcnt lgkmcnt(1)
	v_bfe_u32 v19, v34, 16, 1
	s_ashr_i32 s91, s90, 31
	v_add3_u32 v19, v34, v19, s57
	s_waitcnt lgkmcnt(0)
	v_bfe_u32 v20, v36, 16, 1
	s_lshl_b64 s[2:3], s[90:91], 1
	v_lshrrev_b32_e32 v19, 16, v19
	v_add3_u32 v20, v36, v20, s57
	s_add_u32 s2, s72, s2
	v_and_or_b32 v19, v20, s53, v19
	v_add_u32_e32 v20, s46, v136
	s_addc_u32 s3, s73, s3
	v_ashrrev_i32_e32 v24, 31, v20
	v_lshl_add_u64 v[22:23], s[2:3], 0, v[134:135]
	v_mul_lo_u32 v24, s34, v24
	v_mul_lo_u32 v26, s35, v20
	v_mad_u64_u32 v[38:39], s[2:3], s34, v20, 0
	v_add3_u32 v39, v39, v24, v26
	v_lshl_add_u64 v[38:39], v[38:39], 1, v[22:23]
	global_store_dwordx4 v[38:39], v[16:19], off sc1
	v_bfe_u32 v20, v37, 16, 1
	v_add3_u32 v20, v37, v20, s57
	v_bfe_u32 v16, v21, 16, 1
	v_add3_u32 v16, v21, v16, s57
	v_bfe_u32 v17, v25, 16, 1
	v_lshrrev_b32_e32 v16, 16, v16
	v_add3_u32 v17, v25, v17, s57
	v_and_or_b32 v16, v17, s53, v16
	v_bfe_u32 v17, v27, 16, 1
	v_add3_u32 v17, v27, v17, s57
	v_bfe_u32 v18, v29, 16, 1
	v_lshrrev_b32_e32 v17, 16, v17
	v_add3_u32 v18, v29, v18, s57
	v_and_or_b32 v17, v18, s53, v17
	v_bfe_u32 v18, v31, 16, 1
	v_add3_u32 v18, v31, v18, s57
	v_bfe_u32 v19, v33, 16, 1
	v_lshrrev_b32_e32 v18, 16, v18
	v_add3_u32 v19, v33, v19, s57
	v_and_or_b32 v18, v19, s53, v18
	v_bfe_u32 v19, v35, 16, 1
	v_add3_u32 v19, v35, v19, s57
	v_lshrrev_b32_e32 v19, 16, v19
	v_and_or_b32 v19, v20, s53, v19
	v_add_u32_e32 v20, s46, v138
	v_ashrrev_i32_e32 v21, 31, v20
	v_mul_lo_u32 v26, s34, v21
	v_mul_lo_u32 v27, s35, v20
	v_mad_u64_u32 v[20:21], s[2:3], s34, v20, 0
	v_add3_u32 v21, v21, v26, v27
	ds_read2_b32 v[24:25], v141 offset0:16 offset1:24
	v_lshl_add_u64 v[20:21], v[20:21], 1, v[22:23]
	global_store_dwordx4 v[20:21], v[16:19], off sc1
	ds_read2_b32 v[20:21], v141 offset0:49 offset1:57
	ds_read2_b32 v[26:27], v141 offset0:82 offset1:90
	ds_read2_b32 v[28:29], v141 offset0:115 offset1:123
	s_waitcnt lgkmcnt(3)
	v_bfe_u32 v16, v24, 16, 1
	v_add3_u32 v16, v24, v16, s57
	s_waitcnt lgkmcnt(2)
	v_bfe_u32 v17, v20, 16, 1
	ds_read2_b32 v[30:31], v141 offset0:148 offset1:156
	v_lshrrev_b32_e32 v16, 16, v16
	v_add3_u32 v17, v20, v17, s57
	ds_read2_b32 v[32:33], v141 offset0:181 offset1:189
	v_and_or_b32 v16, v17, s53, v16
	s_waitcnt lgkmcnt(3)
	v_bfe_u32 v17, v26, 16, 1
	v_add3_u32 v17, v26, v17, s57
	s_waitcnt lgkmcnt(2)
	v_bfe_u32 v18, v28, 16, 1
	ds_read2_b32 v[34:35], v141 offset0:214 offset1:222
	v_lshrrev_b32_e32 v17, 16, v17
	v_add3_u32 v18, v28, v18, s57
	ds_read2_b32 v[36:37], v141 offset0:247 offset1:255
	v_and_or_b32 v17, v18, s53, v17
	s_waitcnt lgkmcnt(3)
	v_bfe_u32 v18, v30, 16, 1
	v_add3_u32 v18, v30, v18, s57
	s_waitcnt lgkmcnt(2)
	v_bfe_u32 v19, v32, 16, 1
	v_lshrrev_b32_e32 v18, 16, v18
	v_add3_u32 v19, v32, v19, s57
	v_and_or_b32 v18, v19, s53, v18
	s_waitcnt lgkmcnt(1)
	v_bfe_u32 v19, v34, 16, 1
	v_add3_u32 v19, v34, v19, s57
	s_waitcnt lgkmcnt(0)
	v_bfe_u32 v20, v36, 16, 1
	v_lshrrev_b32_e32 v19, 16, v19
	v_add3_u32 v20, v36, v20, s57
	v_and_or_b32 v19, v20, s53, v19
	v_add_u32_e32 v20, s46, v139
	v_ashrrev_i32_e32 v24, 31, v20
	v_mul_lo_u32 v24, s34, v24
	v_mul_lo_u32 v26, s35, v20
	v_mad_u64_u32 v[38:39], s[2:3], s34, v20, 0
	v_add3_u32 v39, v39, v24, v26
	v_lshl_add_u64 v[38:39], v[38:39], 1, v[22:23]
	global_store_dwordx4 v[38:39], v[16:19], off sc1
	v_bfe_u32 v20, v37, 16, 1
	v_add3_u32 v20, v37, v20, s57
	v_bfe_u32 v16, v25, 16, 1
	v_add3_u32 v16, v25, v16, s57
	v_bfe_u32 v17, v21, 16, 1
	v_lshrrev_b32_e32 v16, 16, v16
	v_add3_u32 v17, v21, v17, s57
	v_and_or_b32 v16, v17, s53, v16
	v_bfe_u32 v17, v27, 16, 1
	v_add3_u32 v17, v27, v17, s57
	v_bfe_u32 v18, v29, 16, 1
	v_lshrrev_b32_e32 v17, 16, v17
	v_add3_u32 v18, v29, v18, s57
	v_and_or_b32 v17, v18, s53, v17
	v_bfe_u32 v18, v31, 16, 1
	v_add3_u32 v18, v31, v18, s57
	v_bfe_u32 v19, v33, 16, 1
	v_lshrrev_b32_e32 v18, 16, v18
	v_add3_u32 v19, v33, v19, s57
	v_and_or_b32 v18, v19, s53, v18
	v_bfe_u32 v19, v35, 16, 1
	v_add3_u32 v19, v35, v19, s57
	v_lshrrev_b32_e32 v19, 16, v19
	v_and_or_b32 v19, v20, s53, v19
	v_add_u32_e32 v20, s46, v140
	v_ashrrev_i32_e32 v21, 31, v20
	v_mul_lo_u32 v24, s34, v21
	v_mul_lo_u32 v25, s35, v20
	v_mad_u64_u32 v[20:21], s[2:3], s34, v20, 0
	v_add3_u32 v21, v21, v24, v25
	v_lshl_add_u64 v[20:21], v[20:21], 1, v[22:23]
	global_store_dwordx4 v[20:21], v[16:19], off sc1
	s_waitcnt lgkmcnt(0)
	s_waitcnt vmcnt(19)
	ds_write2_b32 v143, v102, v103 offset1:1
	ds_write2_b32 v143, v104, v105 offset0:2 offset1:3
	s_waitcnt vmcnt(18)
	ds_write2_b32 v6, v98, v99 offset1:1
	ds_write2_b32 v2, v100, v101 offset1:1
	s_waitcnt vmcnt(17)
	ds_write2_b32 v3, v110, v111 offset1:1
	ds_write2_b32 v4, v112, v113 offset1:1
	s_waitcnt vmcnt(16)
	ds_write2_b32 v5, v106, v107 offset1:1
	ds_write2_b32 v7, v108, v109 offset1:1
	s_waitcnt vmcnt(15)
	ds_write2_b32 v8, v118, v119 offset1:1
	ds_write2_b32 v9, v120, v121 offset1:1
	s_waitcnt vmcnt(14)
	ds_write2_b32 v10, v114, v115 offset1:1
	ds_write2_b32 v11, v116, v117 offset1:1
	s_waitcnt vmcnt(13)
	ds_write2_b32 v12, v126, v127 offset1:1
	ds_write2_b32 v13, v128, v129 offset1:1
	s_waitcnt vmcnt(12)
	ds_write2_b32 v14, v122, v123 offset1:1
	ds_write2_b32 v15, v124, v125 offset1:1
	s_waitcnt lgkmcnt(0)
	ds_read2_b32 v[6:7], v141 offset1:8
	ds_read2_b32 v[10:11], v141 offset0:33 offset1:41
	ds_read2_b32 v[12:13], v141 offset0:66 offset1:74
	ds_read2_b32 v[14:15], v141 offset0:99 offset1:107
	ds_read2_b32 v[16:17], v141 offset0:132 offset1:140
	s_waitcnt lgkmcnt(4)
	v_bfe_u32 v2, v6, 16, 1
	v_add3_u32 v2, v6, v2, s57
	s_waitcnt lgkmcnt(3)
	v_bfe_u32 v3, v10, 16, 1
	v_lshrrev_b32_e32 v2, 16, v2
	v_add3_u32 v3, v10, v3, s57
	ds_read2_b32 v[18:19], v141 offset0:165 offset1:173
	v_and_or_b32 v2, v3, s53, v2
	s_waitcnt lgkmcnt(3)
	v_bfe_u32 v3, v12, 16, 1
	v_add3_u32 v3, v12, v3, s57
	s_waitcnt lgkmcnt(2)
	v_bfe_u32 v4, v14, 16, 1
	ds_read2_b32 v[20:21], v141 offset0:198 offset1:206
	v_lshrrev_b32_e32 v3, 16, v3
	v_add3_u32 v4, v14, v4, s57
	ds_read2_b32 v[22:23], v141 offset0:231 offset1:239
	v_and_or_b32 v3, v4, s53, v3
	s_waitcnt lgkmcnt(3)
	v_bfe_u32 v4, v16, 16, 1
	v_add3_u32 v4, v16, v4, s57
	s_waitcnt lgkmcnt(2)
	v_bfe_u32 v5, v18, 16, 1
	v_lshrrev_b32_e32 v4, 16, v4
	v_add3_u32 v5, v18, v5, s57
	v_and_or_b32 v4, v5, s53, v4
	s_waitcnt lgkmcnt(1)
	v_bfe_u32 v5, v20, 16, 1
	s_ashr_i32 s39, s38, 31
	v_add3_u32 v5, v20, v5, s57
	s_waitcnt lgkmcnt(0)
	v_bfe_u32 v6, v22, 16, 1
	s_lshl_b64 s[2:3], s[38:39], 1
	v_lshrrev_b32_e32 v5, 16, v5
	v_add3_u32 v6, v22, v6, s57
	s_add_u32 s2, s28, s2
	v_and_or_b32 v5, v6, s53, v5
	v_add_u32_e32 v6, s48, v136
	s_addc_u32 s3, s29, s3
	v_ashrrev_i32_e32 v10, 31, v6
	v_lshl_add_u64 v[8:9], s[2:3], 0, v[134:135]
	v_mul_lo_u32 v10, s82, v10
	v_mul_lo_u32 v12, s83, v6
	v_mad_u64_u32 v[24:25], s[2:3], s82, v6, 0
	v_add3_u32 v25, v25, v10, v12
	v_lshl_add_u64 v[24:25], v[24:25], 1, v[8:9]
	global_store_dwordx4 v[24:25], v[2:5], off sc1
	v_bfe_u32 v6, v23, 16, 1
	v_add3_u32 v6, v23, v6, s57
	v_bfe_u32 v2, v7, 16, 1
	v_add3_u32 v2, v7, v2, s57
	v_bfe_u32 v3, v11, 16, 1
	v_lshrrev_b32_e32 v2, 16, v2
	v_add3_u32 v3, v11, v3, s57
	v_and_or_b32 v2, v3, s53, v2
	v_bfe_u32 v3, v13, 16, 1
	v_add3_u32 v3, v13, v3, s57
	v_bfe_u32 v4, v15, 16, 1
	v_lshrrev_b32_e32 v3, 16, v3
	v_add3_u32 v4, v15, v4, s57
	v_and_or_b32 v3, v4, s53, v3
	v_bfe_u32 v4, v17, 16, 1
	v_add3_u32 v4, v17, v4, s57
	v_bfe_u32 v5, v19, 16, 1
	v_lshrrev_b32_e32 v4, 16, v4
	v_add3_u32 v5, v19, v5, s57
	v_and_or_b32 v4, v5, s53, v4
	v_bfe_u32 v5, v21, 16, 1
	v_add3_u32 v5, v21, v5, s57
	v_lshrrev_b32_e32 v5, 16, v5
	v_and_or_b32 v5, v6, s53, v5
	v_add_u32_e32 v6, s48, v138
	v_ashrrev_i32_e32 v7, 31, v6
	v_mul_lo_u32 v12, s82, v7
	v_mul_lo_u32 v13, s83, v6
	v_mad_u64_u32 v[6:7], s[2:3], s82, v6, 0
	v_add3_u32 v7, v7, v12, v13
	ds_read2_b32 v[10:11], v141 offset0:16 offset1:24
	v_lshl_add_u64 v[6:7], v[6:7], 1, v[8:9]
	global_store_dwordx4 v[6:7], v[2:5], off sc1
	ds_read2_b32 v[6:7], v141 offset0:49 offset1:57
	ds_read2_b32 v[12:13], v141 offset0:82 offset1:90
	ds_read2_b32 v[14:15], v141 offset0:115 offset1:123
	s_waitcnt lgkmcnt(3)
	v_bfe_u32 v2, v10, 16, 1
	v_add3_u32 v2, v10, v2, s57
	s_waitcnt lgkmcnt(2)
	v_bfe_u32 v3, v6, 16, 1
	ds_read2_b32 v[16:17], v141 offset0:148 offset1:156
	v_lshrrev_b32_e32 v2, 16, v2
	v_add3_u32 v3, v6, v3, s57
	ds_read2_b32 v[18:19], v141 offset0:181 offset1:189
	v_and_or_b32 v2, v3, s53, v2
	s_waitcnt lgkmcnt(3)
	v_bfe_u32 v3, v12, 16, 1
	v_add3_u32 v3, v12, v3, s57
	s_waitcnt lgkmcnt(2)
	v_bfe_u32 v4, v14, 16, 1
	ds_read2_b32 v[20:21], v141 offset0:214 offset1:222
	v_lshrrev_b32_e32 v3, 16, v3
	v_add3_u32 v4, v14, v4, s57
	ds_read2_b32 v[22:23], v141 offset0:247 offset1:255
	v_and_or_b32 v3, v4, s53, v3
	s_waitcnt lgkmcnt(3)
	v_bfe_u32 v4, v16, 16, 1
	v_add3_u32 v4, v16, v4, s57
	s_waitcnt lgkmcnt(2)
	v_bfe_u32 v5, v18, 16, 1
	v_lshrrev_b32_e32 v4, 16, v4
	v_add3_u32 v5, v18, v5, s57
	v_and_or_b32 v4, v5, s53, v4
	s_waitcnt lgkmcnt(1)
	v_bfe_u32 v5, v20, 16, 1
	v_add3_u32 v5, v20, v5, s57
	s_waitcnt lgkmcnt(0)
	v_bfe_u32 v6, v22, 16, 1
	v_lshrrev_b32_e32 v5, 16, v5
	v_add3_u32 v6, v22, v6, s57
	v_and_or_b32 v5, v6, s53, v5
	v_add_u32_e32 v6, s48, v139
	v_ashrrev_i32_e32 v10, 31, v6
	v_mul_lo_u32 v10, s82, v10
	v_mul_lo_u32 v12, s83, v6
	v_mad_u64_u32 v[24:25], s[2:3], s82, v6, 0
	v_add3_u32 v25, v25, v10, v12
	v_lshl_add_u64 v[24:25], v[24:25], 1, v[8:9]
	global_store_dwordx4 v[24:25], v[2:5], off sc1
	v_bfe_u32 v6, v23, 16, 1
	v_add3_u32 v6, v23, v6, s57
	v_bfe_u32 v2, v11, 16, 1
	v_add3_u32 v2, v11, v2, s57
	v_bfe_u32 v3, v7, 16, 1
	v_lshrrev_b32_e32 v2, 16, v2
	v_add3_u32 v3, v7, v3, s57
	v_and_or_b32 v2, v3, s53, v2
	v_bfe_u32 v3, v13, 16, 1
	v_add3_u32 v3, v13, v3, s57
	v_bfe_u32 v4, v15, 16, 1
	v_lshrrev_b32_e32 v3, 16, v3
	v_add3_u32 v4, v15, v4, s57
	v_and_or_b32 v3, v4, s53, v3
	v_bfe_u32 v4, v17, 16, 1
	v_add3_u32 v4, v17, v4, s57
	v_bfe_u32 v5, v19, 16, 1
	v_lshrrev_b32_e32 v4, 16, v4
	v_add3_u32 v5, v19, v5, s57
	v_and_or_b32 v4, v5, s53, v4
	v_bfe_u32 v5, v21, 16, 1
	v_add3_u32 v5, v21, v5, s57
	v_lshrrev_b32_e32 v5, 16, v5
	v_and_or_b32 v5, v6, s53, v5
	v_add_u32_e32 v6, s48, v140
	v_ashrrev_i32_e32 v7, 31, v6
	v_mul_lo_u32 v10, s82, v7
	v_mul_lo_u32 v11, s83, v6
	v_mad_u64_u32 v[6:7], s[2:3], s82, v6, 0
	v_add3_u32 v7, v7, v10, v11
	v_lshl_add_u64 v[6:7], v[6:7], 1, v[8:9]
	global_store_dwordx4 v[6:7], v[2:5], off sc1
	s_waitcnt lgkmcnt(0)
	s_mov_b64 s[2:3], 0
	s_movk_i32 s54, 0x1000
	s_movk_i32 s56, 0x1800
	v_readlane_b32 s97, v254, 19
	s_movk_i32 s58, 0x2ff

.LBB0_467:
	s_or_b64 exec, exec, s[2:3]
	s_waitcnt lgkmcnt(0)
	v_add_u32_e32 v74, v179, v178
	ds_read_b128 v[66:69], v74
	ds_read_b128 v[70:73], v74 offset:32
	ds_read_b128 v[76:79], v74 offset:64
	ds_read_b128 v[80:83], v74 offset:96
	s_ashr_i32 s27, s26, 31
	s_lshl_b64 s[2:3], s[26:27], 12
	s_add_u32 s6, s14, s2
	s_addc_u32 s7, s15, s3
	s_lshl_b64 s[2:3], s[30:31], 1
	s_add_u32 s2, s6, s2
	s_addc_u32 s3, s7, s3
	s_lshl_b32 s6, s9, 13
	v_lshlrev_b32_e32 v84, 10, v180
	v_lshl_add_u32 v84, v181, 1, v84
	v_add_u32_e32 v84, s6, v84
	v_lshl_add_u32 v85, v180, 5, v181
	v_lshlrev_b32_e32 v86, 4, v85
	v_add_u32_e32 v86, s6, v86
	v_lshrrev_b32_e32 v87, 4, v85
	v_lshlrev_b32_e32 v87, 12, v87
	v_and_b32_e32 v88, 15, v85
	v_lshl_add_u32 v87, v88, 4, v87
	v_add_u32_e32 v88, 0x4000, v87
	v_add_u32_e32 v89, 0x8000, v87
	v_add_u32_e32 v90, 0xc000, v87
	v_add_u32_e32 v91, 0x10000, v87
	v_add_u32_e32 v92, 0x14000, v87
	v_add_u32_e32 v93, 0x18000, v87
	v_add_u32_e32 v94, 0x1c000, v87
	s_waitcnt lgkmcnt(0)
	v_rcp_f32_e32 v66, v66
	v_rcp_f32_e32 v67, v67
	v_rcp_f32_e32 v68, v68
	v_rcp_f32_e32 v69, v69
	v_rcp_f32_e32 v70, v70
	v_rcp_f32_e32 v71, v71
	v_rcp_f32_e32 v72, v72
	v_rcp_f32_e32 v73, v73
	v_rcp_f32_e32 v76, v76
	v_rcp_f32_e32 v77, v77
	v_rcp_f32_e32 v78, v78
	v_rcp_f32_e32 v79, v79
	v_rcp_f32_e32 v80, v80
	v_rcp_f32_e32 v81, v81
	v_rcp_f32_e32 v82, v82
	v_rcp_f32_e32 v83, v83
	s_barrier
	v_mul_f32_e32 v2, v2, v66
	v_mul_f32_e32 v50, v50, v66
	v_cvt_pk_bf16_f32 v2, v2, v50
	ds_write_b16 v84, v2 offset:0
	ds_write_b16_d16_hi v84, v2 offset:64
	v_mul_f32_e32 v34, v34, v66
	v_mul_f32_e32 v18, v18, v66
	v_cvt_pk_bf16_f32 v34, v34, v18
	ds_write_b16 v84, v34 offset:128
	ds_write_b16_d16_hi v84, v34 offset:192
	v_mul_f32_e32 v3, v3, v67
	v_mul_f32_e32 v51, v51, v67
	v_cvt_pk_bf16_f32 v3, v3, v51
	ds_write_b16 v84, v3 offset:256
	ds_write_b16_d16_hi v84, v3 offset:320
	v_mul_f32_e32 v35, v35, v67
	v_mul_f32_e32 v19, v19, v67
	v_cvt_pk_bf16_f32 v35, v35, v19
	ds_write_b16 v84, v35 offset:384
	ds_write_b16_d16_hi v84, v35 offset:448
	v_mul_f32_e32 v4, v4, v68
	v_mul_f32_e32 v52, v52, v68
	v_cvt_pk_bf16_f32 v4, v4, v52
	ds_write_b16 v84, v4 offset:512
	ds_write_b16_d16_hi v84, v4 offset:576
	v_mul_f32_e32 v36, v36, v68
	v_mul_f32_e32 v20, v20, v68
	v_cvt_pk_bf16_f32 v36, v36, v20
	ds_write_b16 v84, v36 offset:640
	ds_write_b16_d16_hi v84, v36 offset:704
	v_mul_f32_e32 v5, v5, v69
	v_mul_f32_e32 v53, v53, v69
	v_cvt_pk_bf16_f32 v5, v5, v53
	ds_write_b16 v84, v5 offset:768
	ds_write_b16_d16_hi v84, v5 offset:832
	v_mul_f32_e32 v37, v37, v69
	v_mul_f32_e32 v21, v21, v69
	v_cvt_pk_bf16_f32 v37, v37, v21
	ds_write_b16 v84, v37 offset:896
	ds_write_b16_d16_hi v84, v37 offset:960
	v_mul_f32_e32 v6, v6, v70
	v_mul_f32_e32 v54, v54, v70
	v_cvt_pk_bf16_f32 v6, v6, v54
	ds_write_b16 v84, v6 offset:2048
	ds_write_b16_d16_hi v84, v6 offset:2112
	v_mul_f32_e32 v38, v38, v70
	v_mul_f32_e32 v22, v22, v70
	v_cvt_pk_bf16_f32 v38, v38, v22
	ds_write_b16 v84, v38 offset:2176
	ds_write_b16_d16_hi v84, v38 offset:2240
	v_mul_f32_e32 v7, v7, v71
	v_mul_f32_e32 v55, v55, v71
	v_cvt_pk_bf16_f32 v7, v7, v55
	ds_write_b16 v84, v7 offset:2304
	ds_write_b16_d16_hi v84, v7 offset:2368
	v_mul_f32_e32 v39, v39, v71
	v_mul_f32_e32 v23, v23, v71
	v_cvt_pk_bf16_f32 v39, v39, v23
	ds_write_b16 v84, v39 offset:2432
	ds_write_b16_d16_hi v84, v39 offset:2496
	v_mul_f32_e32 v8, v8, v72
	v_mul_f32_e32 v56, v56, v72
	v_cvt_pk_bf16_f32 v8, v8, v56
	ds_write_b16 v84, v8 offset:2560
	ds_write_b16_d16_hi v84, v8 offset:2624
	v_mul_f32_e32 v40, v40, v72
	v_mul_f32_e32 v24, v24, v72
	v_cvt_pk_bf16_f32 v40, v40, v24
	ds_write_b16 v84, v40 offset:2688
	ds_write_b16_d16_hi v84, v40 offset:2752
	v_mul_f32_e32 v9, v9, v73
	v_mul_f32_e32 v57, v57, v73
	v_cvt_pk_bf16_f32 v9, v9, v57
	ds_write_b16 v84, v9 offset:2816
	ds_write_b16_d16_hi v84, v9 offset:2880
	v_mul_f32_e32 v41, v41, v73
	v_mul_f32_e32 v25, v25, v73
	v_cvt_pk_bf16_f32 v41, v41, v25
	ds_write_b16 v84, v41 offset:2944
	ds_write_b16_d16_hi v84, v41 offset:3008
	v_mul_f32_e32 v10, v10, v76
	v_mul_f32_e32 v58, v58, v76
	v_cvt_pk_bf16_f32 v10, v10, v58
	ds_write_b16 v84, v10 offset:4096
	ds_write_b16_d16_hi v84, v10 offset:4160
	v_mul_f32_e32 v42, v42, v76
	v_mul_f32_e32 v26, v26, v76
	v_cvt_pk_bf16_f32 v42, v42, v26
	ds_write_b16 v84, v42 offset:4224
	ds_write_b16_d16_hi v84, v42 offset:4288
	v_mul_f32_e32 v11, v11, v77
	v_mul_f32_e32 v59, v59, v77
	v_cvt_pk_bf16_f32 v11, v11, v59
	ds_write_b16 v84, v11 offset:4352
	ds_write_b16_d16_hi v84, v11 offset:4416
	v_mul_f32_e32 v43, v43, v77
	v_mul_f32_e32 v27, v27, v77
	v_cvt_pk_bf16_f32 v43, v43, v27
	ds_write_b16 v84, v43 offset:4480
	ds_write_b16_d16_hi v84, v43 offset:4544
	v_mul_f32_e32 v12, v12, v78
	v_mul_f32_e32 v60, v60, v78
	v_cvt_pk_bf16_f32 v12, v12, v60
	ds_write_b16 v84, v12 offset:4608
	ds_write_b16_d16_hi v84, v12 offset:4672
	v_mul_f32_e32 v44, v44, v78
	v_mul_f32_e32 v28, v28, v78
	v_cvt_pk_bf16_f32 v44, v44, v28
	ds_write_b16 v84, v44 offset:4736
	ds_write_b16_d16_hi v84, v44 offset:4800
	v_mul_f32_e32 v13, v13, v79
	v_mul_f32_e32 v61, v61, v79
	v_cvt_pk_bf16_f32 v13, v13, v61
	ds_write_b16 v84, v13 offset:4864
	ds_write_b16_d16_hi v84, v13 offset:4928
	v_mul_f32_e32 v45, v45, v79
	v_mul_f32_e32 v29, v29, v79
	v_cvt_pk_bf16_f32 v45, v45, v29
	ds_write_b16 v84, v45 offset:4992
	ds_write_b16_d16_hi v84, v45 offset:5056
	v_mul_f32_e32 v14, v14, v80
	v_mul_f32_e32 v62, v62, v80
	v_cvt_pk_bf16_f32 v14, v14, v62
	ds_write_b16 v84, v14 offset:6144
	ds_write_b16_d16_hi v84, v14 offset:6208
	v_mul_f32_e32 v46, v46, v80
	v_mul_f32_e32 v30, v30, v80
	v_cvt_pk_bf16_f32 v46, v46, v30
	ds_write_b16 v84, v46 offset:6272
	ds_write_b16_d16_hi v84, v46 offset:6336
	v_mul_f32_e32 v15, v15, v81
	v_mul_f32_e32 v63, v63, v81
	v_cvt_pk_bf16_f32 v15, v15, v63
	ds_write_b16 v84, v15 offset:6400
	ds_write_b16_d16_hi v84, v15 offset:6464
	v_mul_f32_e32 v47, v47, v81
	v_mul_f32_e32 v31, v31, v81
	v_cvt_pk_bf16_f32 v47, v47, v31
	ds_write_b16 v84, v47 offset:6528
	ds_write_b16_d16_hi v84, v47 offset:6592
	v_mul_f32_e32 v16, v16, v82
	v_mul_f32_e32 v64, v64, v82
	v_cvt_pk_bf16_f32 v16, v16, v64
	ds_write_b16 v84, v16 offset:6656
	ds_write_b16_d16_hi v84, v16 offset:6720
	v_mul_f32_e32 v48, v48, v82
	v_mul_f32_e32 v32, v32, v82
	v_cvt_pk_bf16_f32 v48, v48, v32
	ds_write_b16 v84, v48 offset:6784
	ds_write_b16_d16_hi v84, v48 offset:6848
	v_mul_f32_e32 v17, v17, v83
	v_mul_f32_e32 v65, v65, v83
	v_cvt_pk_bf16_f32 v17, v17, v65
	ds_write_b16 v84, v17 offset:6912
	ds_write_b16_d16_hi v84, v17 offset:6976
	v_mul_f32_e32 v49, v49, v83
	v_mul_f32_e32 v33, v33, v83
	v_cvt_pk_bf16_f32 v49, v49, v33
	ds_write_b16 v84, v49 offset:7040
	ds_write_b16_d16_hi v84, v49 offset:7104
	s_waitcnt lgkmcnt(0)
	ds_read_b128 v[2:5], v86 offset:0
	ds_read_b128 v[6:9], v86 offset:1024
	ds_read_b128 v[10:13], v86 offset:2048
	ds_read_b128 v[14:17], v86 offset:3072
	ds_read_b128 v[18:21], v86 offset:4096
	ds_read_b128 v[22:25], v86 offset:5120
	ds_read_b128 v[26:29], v86 offset:6144
	ds_read_b128 v[30:33], v86 offset:7168
	s_waitcnt lgkmcnt(7)
	global_store_dwordx4 v87, v[2:5], s[2:3] sc1
	s_waitcnt lgkmcnt(6)
	global_store_dwordx4 v88, v[6:9], s[2:3] sc1
	s_waitcnt lgkmcnt(5)
	global_store_dwordx4 v89, v[10:13], s[2:3] sc1
	s_waitcnt lgkmcnt(4)
	global_store_dwordx4 v90, v[14:17], s[2:3] sc1
	s_waitcnt lgkmcnt(3)
	global_store_dwordx4 v91, v[18:21], s[2:3] sc1
	s_waitcnt lgkmcnt(2)
	global_store_dwordx4 v92, v[22:25], s[2:3] sc1
	s_waitcnt lgkmcnt(1)
	global_store_dwordx4 v93, v[26:29], s[2:3] sc1
	s_waitcnt lgkmcnt(0)
	global_store_dwordx4 v94, v[30:33], s[2:3] sc1
	s_waitcnt vmcnt(63) expcnt(7) lgkmcnt(15)
	s_barrier

.LBB0_509:
	s_waitcnt lgkmcnt(0)
	s_andn2_b64 vcc, exec, s[34:35]
	s_waitcnt lgkmcnt(0)
	s_barrier
	s_cbranch_vccnz .LBB0_506
	s_lshl_b32 s22, s14, 15
	v_lshl_add_u64 v[2:3], v[88:89], 0, s[22:23]
	v_add_co_u32_e32 v4, vcc, 0x1000, v2
	v_or_b32_e32 v94, s9, v97
	s_nop 0
	v_addc_co_u32_e32 v5, vcc, 0, v3, vcc
	global_load_dwordx4 v[46:49], v[2:3], off
	global_load_dwordx4 v[50:53], v[2:3], off offset:64
	global_load_dwordx4 v[58:61], v[4:5], off
	global_load_dwordx4 v[62:65], v[4:5], off offset:64
	global_load_dwordx4 v[42:45], v[2:3], off offset:128
	global_load_dwordx4 v[30:33], v[2:3], off offset:192
	global_load_dwordx4 v[38:41], v[4:5], off offset:128
	global_load_dwordx4 v[26:29], v[4:5], off offset:192
	v_lshlrev_b32_e32 v2, 2, v97
	v_lshl_or_b32 v8, s14, 9, v2
	v_mov_b64_e32 v[2:3], s[18:19]
	v_mad_i64_i32 v[4:5], s[10:11], v94, s56, v[2:3]
	s_lshl_b32 s22, s14, 8
	v_lshl_add_u64 v[4:5], v[4:5], 0, s[22:23]
	v_mov_b32_e32 v91, v203
	v_lshl_add_u64 v[4:5], v[4:5], 0, v[90:91]
	s_mov_b64 s[14:15], 0x1000
	v_lshl_add_u64 v[6:7], v[4:5], 0, s[14:15]
	v_add_co_u32_e32 v4, vcc, s54, v4
	v_ashrrev_i32_e32 v95, 31, v94
	s_nop 0
	v_addc_co_u32_e32 v5, vcc, 0, v5, vcc
	global_load_dwordx4 v[34:37], v[6:7], off offset:64
	global_load_dwordx4 v[22:25], v[6:7], off offset:128
	global_load_dwordx4 v[54:57], v[4:5], off
	global_load_dwordx4 v[18:21], v[6:7], off offset:192
	global_load_dword v96, v8, s[30:31]
	global_load_dword v92, v8, s[30:31] offset:64
	v_or_b32_e32 v4, s9, v98
	v_mad_i64_i32 v[2:3], s[10:11], v4, s56, v[2:3]
	v_lshl_add_u64 v[2:3], v[2:3], 0, s[22:23]
	v_lshl_add_u64 v[2:3], v[2:3], 0, v[90:91]
	v_lshl_add_u64 v[4:5], v[2:3], 0, s[14:15]
	v_add_co_u32_e32 v2, vcc, s54, v2
	s_nop 1
	v_addc_co_u32_e32 v3, vcc, 0, v3, vcc
	global_load_dwordx4 v[10:13], v[4:5], off offset:64
	global_load_dwordx4 v[6:9], v[4:5], off offset:128
	global_load_dwordx4 v[14:17], v[2:3], off
	s_nop 0
	global_load_dwordx4 v[2:5], v[4:5], off offset:192
	ds_read_b128 v[66:69], v99
	ds_read_b128 v[70:73], v99 offset:1088
	ds_read_b128 v[74:77], v99 offset:8704
	ds_read_b128 v[78:81], v99 offset:9792
	ds_read_b128 v[82:85], v99 offset:17408
	ds_read_b128 v[100:103], v99 offset:18496
	ds_read_b128 v[104:107], v99 offset:26112
	ds_read_b128 v[108:111], v99 offset:27200
	s_waitcnt vmcnt(17) lgkmcnt(7)
	v_mfma_f32_16x16x32_bf16 v[112:115], v[66:69], v[46:49], 0
	s_waitcnt lgkmcnt(6)
	v_mfma_f32_16x16x32_bf16 v[116:119], v[70:73], v[46:49], 0
	s_waitcnt lgkmcnt(5)
	v_mfma_f32_16x16x32_bf16 v[120:123], v[74:77], v[46:49], 0
	s_waitcnt lgkmcnt(4)
	v_mfma_f32_16x16x32_bf16 v[124:127], v[78:81], v[46:49], 0
	s_waitcnt lgkmcnt(3)
	v_mfma_f32_16x16x32_bf16 v[128:131], v[82:85], v[46:49], 0
	s_waitcnt lgkmcnt(2)
	v_mfma_f32_16x16x32_bf16 v[132:135], v[100:103], v[46:49], 0
	s_waitcnt lgkmcnt(1)
	v_mfma_f32_16x16x32_bf16 v[136:139], v[104:107], v[46:49], 0
	s_waitcnt lgkmcnt(0)
	v_mfma_f32_16x16x32_bf16 v[46:49], v[108:111], v[46:49], 0
	s_waitcnt vmcnt(15)
	v_mfma_f32_16x16x32_bf16 v[66:69], v[66:69], v[58:61], 0
	v_mfma_f32_16x16x32_bf16 v[70:73], v[70:73], v[58:61], 0
	v_mfma_f32_16x16x32_bf16 v[74:77], v[74:77], v[58:61], 0
	v_mfma_f32_16x16x32_bf16 v[78:81], v[78:81], v[58:61], 0
	v_mfma_f32_16x16x32_bf16 v[82:85], v[82:85], v[58:61], 0
	v_mfma_f32_16x16x32_bf16 v[100:103], v[100:103], v[58:61], 0
	v_mfma_f32_16x16x32_bf16 v[104:107], v[104:107], v[58:61], 0
	v_mfma_f32_16x16x32_bf16 v[58:61], v[108:111], v[58:61], 0
	ds_read_b128 v[108:111], v99 offset:64
	ds_read_b128 v[140:143], v99 offset:1152
	ds_read_b128 v[144:147], v99 offset:8768
	ds_read_b128 v[148:151], v99 offset:9856
	ds_read_b128 v[152:155], v99 offset:17472
	ds_read_b128 v[156:159], v99 offset:18560
	ds_read_b128 v[160:163], v99 offset:26176
	ds_read_b128 v[164:167], v99 offset:27264
	s_waitcnt lgkmcnt(7)
	v_mfma_f32_16x16x32_bf16 v[112:115], v[108:111], v[50:53], v[112:115]
	s_waitcnt lgkmcnt(6)
	v_mfma_f32_16x16x32_bf16 v[116:119], v[140:143], v[50:53], v[116:119]
	s_waitcnt lgkmcnt(5)
	v_mfma_f32_16x16x32_bf16 v[120:123], v[144:147], v[50:53], v[120:123]
	s_waitcnt lgkmcnt(4)
	v_mfma_f32_16x16x32_bf16 v[124:127], v[148:151], v[50:53], v[124:127]
	s_waitcnt lgkmcnt(3)
	v_mfma_f32_16x16x32_bf16 v[128:131], v[152:155], v[50:53], v[128:131]
	s_waitcnt lgkmcnt(2)
	v_mfma_f32_16x16x32_bf16 v[132:135], v[156:159], v[50:53], v[132:135]
	s_waitcnt lgkmcnt(1)
	v_mfma_f32_16x16x32_bf16 v[136:139], v[160:163], v[50:53], v[136:139]
	s_waitcnt lgkmcnt(0)
	v_mfma_f32_16x16x32_bf16 v[46:49], v[164:167], v[50:53], v[46:49]
	s_waitcnt vmcnt(14)
	v_mfma_f32_16x16x32_bf16 v[50:53], v[108:111], v[62:65], v[66:69]
	v_mfma_f32_16x16x32_bf16 v[66:69], v[140:143], v[62:65], v[70:73]
	v_mfma_f32_16x16x32_bf16 v[70:73], v[144:147], v[62:65], v[74:77]
	v_mfma_f32_16x16x32_bf16 v[74:77], v[148:151], v[62:65], v[78:81]
	v_mfma_f32_16x16x32_bf16 v[78:81], v[152:155], v[62:65], v[82:85]
	v_mfma_f32_16x16x32_bf16 v[82:85], v[156:159], v[62:65], v[100:103]
	v_mfma_f32_16x16x32_bf16 v[100:103], v[160:163], v[62:65], v[104:107]
	v_mfma_f32_16x16x32_bf16 v[58:61], v[164:167], v[62:65], v[58:61]
	ds_read_b128 v[62:65], v99 offset:128
	s_nop 0
	ds_read_b128 v[104:107], v99 offset:1216
	ds_read_b128 v[108:111], v99 offset:8832
	ds_read_b128 v[140:143], v99 offset:9920
	ds_read_b128 v[144:147], v99 offset:17536
	ds_read_b128 v[148:151], v99 offset:18624
	ds_read_b128 v[152:155], v99 offset:26240
	ds_read_b128 v[156:159], v99 offset:27328
	s_waitcnt vmcnt(13) lgkmcnt(7)
	v_mfma_f32_16x16x32_bf16 v[112:115], v[62:65], v[42:45], v[112:115]
	s_waitcnt lgkmcnt(6)
	v_mfma_f32_16x16x32_bf16 v[116:119], v[104:107], v[42:45], v[116:119]
	s_waitcnt lgkmcnt(5)
	v_mfma_f32_16x16x32_bf16 v[120:123], v[108:111], v[42:45], v[120:123]
	s_waitcnt lgkmcnt(4)
	v_mfma_f32_16x16x32_bf16 v[124:127], v[140:143], v[42:45], v[124:127]
	s_waitcnt lgkmcnt(3)
	v_mfma_f32_16x16x32_bf16 v[128:131], v[144:147], v[42:45], v[128:131]
	s_waitcnt lgkmcnt(2)
	v_mfma_f32_16x16x32_bf16 v[132:135], v[148:151], v[42:45], v[132:135]
	s_waitcnt lgkmcnt(1)
	v_mfma_f32_16x16x32_bf16 v[136:139], v[152:155], v[42:45], v[136:139]
	s_waitcnt lgkmcnt(0)
	v_mfma_f32_16x16x32_bf16 v[42:45], v[156:159], v[42:45], v[46:49]
	s_waitcnt vmcnt(11)
	v_mfma_f32_16x16x32_bf16 v[46:49], v[62:65], v[38:41], v[50:53]
	v_mfma_f32_16x16x32_bf16 v[50:53], v[104:107], v[38:41], v[66:69]
	v_mfma_f32_16x16x32_bf16 v[104:107], v[108:111], v[38:41], v[70:73]
	v_mfma_f32_16x16x32_bf16 v[108:111], v[140:143], v[38:41], v[74:77]
	v_mfma_f32_16x16x32_bf16 v[140:143], v[144:147], v[38:41], v[78:81]
	v_mfma_f32_16x16x32_bf16 v[144:147], v[148:151], v[38:41], v[82:85]
	v_mfma_f32_16x16x32_bf16 v[100:103], v[152:155], v[38:41], v[100:103]
	v_mfma_f32_16x16x32_bf16 v[148:151], v[156:159], v[38:41], v[58:61]
	ds_read_b128 v[38:41], v99 offset:192
	s_nop 1
	ds_read_b128 v[58:61], v99 offset:1280
	ds_read_b128 v[152:155], v99 offset:8896
	ds_read_b128 v[156:159], v99 offset:9984
	ds_read_b128 v[160:163], v99 offset:17600
	ds_read_b128 v[164:167], v99 offset:18688
	ds_read_b128 v[168:171], v99 offset:26304
	ds_read_b128 v[172:175], v99 offset:27392
	s_waitcnt lgkmcnt(7)
	v_mfma_f32_16x16x32_bf16 v[112:115], v[38:41], v[30:33], v[112:115]
	s_waitcnt lgkmcnt(6)
	v_mfma_f32_16x16x32_bf16 v[116:119], v[58:61], v[30:33], v[116:119]
	s_waitcnt lgkmcnt(5)
	v_mfma_f32_16x16x32_bf16 v[120:123], v[152:155], v[30:33], v[120:123]
	s_waitcnt lgkmcnt(4)
	v_mfma_f32_16x16x32_bf16 v[82:85], v[156:159], v[30:33], v[124:127]
	s_waitcnt lgkmcnt(3)
	v_mfma_f32_16x16x32_bf16 v[78:81], v[160:163], v[30:33], v[128:131]
	s_waitcnt lgkmcnt(2)
	v_mfma_f32_16x16x32_bf16 v[74:77], v[164:167], v[30:33], v[132:135]
	s_waitcnt vmcnt(5)
	s_nop 2
	v_pk_add_f32 v[82:83], v[96:97], v[82:83] op_sel_hi:[0,1]
	s_waitcnt lgkmcnt(1)
	v_mfma_f32_16x16x32_bf16 v[70:73], v[168:171], v[30:33], v[136:139]
	s_waitcnt lgkmcnt(0)
	v_mfma_f32_16x16x32_bf16 v[66:69], v[172:175], v[30:33], v[42:45]
	v_mfma_f32_16x16x32_bf16 v[30:33], v[168:171], v[26:29], v[100:103]
	s_nop 2
	v_lshlrev_b64 v[100:101], 12, v[94:95]
	v_lshl_add_u64 v[100:101], s[26:27], 0, v[100:101]
	v_mfma_f32_16x16x32_bf16 v[58:61], v[58:61], v[26:29], v[50:53]
	v_add_f32_e64 v102, v96, v112
	v_add_f32_e64 v103, v96, v113
	v_mfma_f32_16x16x32_bf16 v[50:53], v[152:155], v[26:29], v[104:107]
	s_nop 2
	v_lshl_add_u64 v[104:105], v[100:101], 0, s[22:23]
	v_pk_add_f32 v[100:101], v[96:97], v[114:115] op_sel_hi:[0,1]
	v_lshlrev_b32_e32 v106, 16, v54
	v_and_b32_e32 v107, 0xffff0000, v54
	v_lshlrev_b32_e32 v54, 16, v55
	v_and_b32_e32 v55, 0xffff0000, v55
	v_pk_mul_f32 v[54:55], v[100:101], v[54:55]
	v_pk_mul_f32 v[100:101], v[102:103], v[106:107]
	v_pk_add_f32 v[102:103], v[96:97], v[116:117] op_sel_hi:[0,1]
	v_bfe_u32 v95, v100, 16, 1
	v_add3_u32 v95, v100, v95, s57
	v_bfe_u32 v100, v101, 16, 1
	v_lshrrev_b32_e32 v95, 16, v95
	v_add3_u32 v100, v101, v100, s57
	v_and_or_b32 v100, v100, s53, v95
	v_bfe_u32 v95, v54, 16, 1
	v_add3_u32 v54, v54, v95, s57
	v_bfe_u32 v95, v55, 16, 1
	v_lshrrev_b32_e32 v54, 16, v54
	v_add3_u32 v55, v55, v95, s57
	v_and_or_b32 v101, v55, s53, v54
	v_pk_add_f32 v[54:55], v[96:97], v[118:119] op_sel_hi:[0,1]
	v_lshlrev_b32_e32 v106, 16, v56
	v_and_b32_e32 v107, 0xffff0000, v56
	v_lshlrev_b32_e32 v56, 16, v57
	v_and_b32_e32 v57, 0xffff0000, v57
	v_pk_mul_f32 v[54:55], v[54:55], v[56:57]
	v_pk_mul_f32 v[56:57], v[102:103], v[106:107]
	v_mfma_f32_16x16x32_bf16 v[62:65], v[38:41], v[26:29], v[46:49]
	v_bfe_u32 v95, v57, 16, 1
	v_add3_u32 v57, v57, v95, s57
	v_bfe_u32 v95, v56, 16, 1
	v_add3_u32 v56, v56, v95, s57
	v_lshrrev_b32_e32 v56, 16, v56
	v_and_or_b32 v102, v57, s53, v56
	v_bfe_u32 v56, v55, 16, 1
	v_add3_u32 v55, v55, v56, s57
	v_bfe_u32 v56, v54, 16, 1
	v_add3_u32 v54, v54, v56, s57
	v_lshrrev_b32_e32 v54, 16, v54
	v_and_or_b32 v103, v55, s53, v54
	v_lshl_add_u64 v[54:55], v[104:105], 0, v[90:91]
	global_store_dwordx4 v[54:55], v[100:103], off offset:3072 sc1
	v_pk_add_f32 v[56:57], v[96:97], v[122:123] op_sel_hi:[0,1]
	v_mfma_f32_16x16x32_bf16 v[46:49], v[156:159], v[26:29], v[108:111]
	v_add_f32_e64 v100, v96, v120
	v_add_f32_e64 v101, v96, v121
	v_lshlrev_b32_e32 v102, 16, v34
	v_and_b32_e32 v103, 0xffff0000, v34
	v_lshlrev_b32_e32 v34, 16, v35
	v_and_b32_e32 v35, 0xffff0000, v35
	v_pk_mul_f32 v[56:57], v[56:57], v[34:35]
	v_pk_mul_f32 v[34:35], v[100:101], v[102:103]
	v_mfma_f32_16x16x32_bf16 v[42:45], v[160:163], v[26:29], v[140:143]
	v_bfe_u32 v95, v34, 16, 1
	v_add3_u32 v34, v34, v95, s57
	v_bfe_u32 v95, v35, 16, 1
	v_lshrrev_b32_e32 v34, 16, v34
	v_add3_u32 v35, v35, v95, s57
	v_and_or_b32 v34, v35, s53, v34
	v_bfe_u32 v35, v56, 16, 1
	v_add3_u32 v35, v56, v35, s57
	v_bfe_u32 v56, v57, 16, 1
	v_lshrrev_b32_e32 v35, 16, v35
	v_add3_u32 v56, v57, v56, s57
	v_and_or_b32 v35, v56, s53, v35
	v_pk_add_f32 v[56:57], v[96:97], v[84:85] op_sel_hi:[0,1]
	v_lshlrev_b32_e32 v84, 16, v36
	v_and_b32_e32 v85, 0xffff0000, v36
	v_lshlrev_b32_e32 v36, 16, v37
	v_and_b32_e32 v37, 0xffff0000, v37
	v_pk_mul_f32 v[56:57], v[56:57], v[36:37]
	v_pk_mul_f32 v[36:37], v[82:83], v[84:85]
	v_mfma_f32_16x16x32_bf16 v[38:41], v[164:167], v[26:29], v[144:147]
	v_bfe_u32 v82, v37, 16, 1
	v_add3_u32 v37, v37, v82, s57
	v_bfe_u32 v82, v36, 16, 1
	v_add3_u32 v36, v36, v82, s57
	v_lshrrev_b32_e32 v36, 16, v36
	v_and_or_b32 v36, v37, s53, v36
	v_bfe_u32 v37, v57, 16, 1
	v_add3_u32 v37, v57, v37, s57
	v_bfe_u32 v57, v56, 16, 1
	v_add3_u32 v56, v56, v57, s57
	v_lshrrev_b32_e32 v56, 16, v56
	v_and_or_b32 v37, v37, s53, v56
	global_store_dwordx4 v[54:55], v[34:37], off offset:3136 sc1
	v_lshlrev_b32_e32 v56, 16, v22
	v_and_b32_e32 v57, 0xffff0000, v22
	v_pk_add_f32 v[34:35], v[96:97], v[80:81] op_sel_hi:[0,1]
	v_pk_add_f32 v[36:37], v[96:97], v[78:79] op_sel_hi:[0,1]
	v_lshlrev_b32_e32 v22, 16, v23
	v_and_b32_e32 v23, 0xffff0000, v23
	v_pk_mul_f32 v[34:35], v[34:35], v[22:23]
	v_pk_mul_f32 v[22:23], v[36:37], v[56:57]
	v_lshlrev_b32_e32 v56, 16, v24
	v_bfe_u32 v36, v22, 16, 1
	v_add3_u32 v22, v22, v36, s57
	v_bfe_u32 v36, v23, 16, 1
	v_lshrrev_b32_e32 v22, 16, v22
	v_add3_u32 v23, v23, v36, s57
	v_and_or_b32 v22, v23, s53, v22
	v_bfe_u32 v23, v34, 16, 1
	v_add3_u32 v23, v34, v23, s57
	v_bfe_u32 v34, v35, 16, 1
	v_lshrrev_b32_e32 v23, 16, v23
	v_add3_u32 v34, v35, v34, s57
	v_and_or_b32 v23, v34, s53, v23
	v_pk_add_f32 v[34:35], v[96:97], v[76:77] op_sel_hi:[0,1]
	v_pk_add_f32 v[36:37], v[96:97], v[74:75] op_sel_hi:[0,1]
	v_and_b32_e32 v57, 0xffff0000, v24
	v_lshlrev_b32_e32 v24, 16, v25
	v_and_b32_e32 v25, 0xffff0000, v25
	v_pk_mul_f32 v[34:35], v[34:35], v[24:25]
	v_pk_mul_f32 v[24:25], v[36:37], v[56:57]
	v_mfma_f32_16x16x32_bf16 v[26:29], v[172:175], v[26:29], v[148:151]
	v_bfe_u32 v36, v25, 16, 1
	v_add3_u32 v25, v25, v36, s57
	v_bfe_u32 v36, v24, 16, 1
	v_add3_u32 v24, v24, v36, s57
	v_lshrrev_b32_e32 v24, 16, v24
	v_and_or_b32 v24, v25, s53, v24
	v_bfe_u32 v25, v35, 16, 1
	v_add3_u32 v25, v35, v25, s57
	v_bfe_u32 v35, v34, 16, 1
	v_add3_u32 v34, v34, v35, s57
	v_lshrrev_b32_e32 v34, 16, v34
	v_and_or_b32 v25, v25, s53, v34
	global_store_dwordx4 v[54:55], v[22:25], off offset:3200 sc1
	v_lshlrev_b32_e32 v34, 16, v18
	v_and_b32_e32 v35, 0xffff0000, v18
	v_pk_add_f32 v[22:23], v[96:97], v[72:73] op_sel_hi:[0,1]
	v_pk_add_f32 v[24:25], v[96:97], v[70:71] op_sel_hi:[0,1]
	v_lshlrev_b32_e32 v18, 16, v19
	v_and_b32_e32 v19, 0xffff0000, v19
	v_pk_mul_f32 v[22:23], v[22:23], v[18:19]
	v_pk_mul_f32 v[18:19], v[24:25], v[34:35]
	v_lshlrev_b32_e32 v34, 16, v20
	v_bfe_u32 v24, v18, 16, 1
	v_add3_u32 v18, v18, v24, s57
	v_bfe_u32 v24, v19, 16, 1
	v_lshrrev_b32_e32 v18, 16, v18
	v_add3_u32 v19, v19, v24, s57
	v_and_or_b32 v18, v19, s53, v18
	v_bfe_u32 v19, v22, 16, 1
	v_add3_u32 v19, v22, v19, s57
	v_bfe_u32 v22, v23, 16, 1
	v_lshrrev_b32_e32 v19, 16, v19
	v_add3_u32 v22, v23, v22, s57
	v_and_or_b32 v19, v22, s53, v19
	v_pk_add_f32 v[22:23], v[96:97], v[68:69] op_sel_hi:[0,1]
	v_pk_add_f32 v[24:25], v[96:97], v[66:67] op_sel_hi:[0,1]
	v_and_b32_e32 v35, 0xffff0000, v20
	v_lshlrev_b32_e32 v20, 16, v21
	v_and_b32_e32 v21, 0xffff0000, v21
	v_pk_mul_f32 v[22:23], v[22:23], v[20:21]
	v_pk_mul_f32 v[20:21], v[24:25], v[34:35]
	s_waitcnt vmcnt(4)
	v_and_b32_e32 v25, 0xffff0000, v14
	v_bfe_u32 v24, v21, 16, 1
	v_add3_u32 v21, v21, v24, s57
	v_bfe_u32 v24, v20, 16, 1
	v_add3_u32 v20, v20, v24, s57
	v_lshrrev_b32_e32 v20, 16, v20
	v_and_or_b32 v20, v21, s53, v20
	v_bfe_u32 v21, v23, 16, 1
	v_add3_u32 v21, v23, v21, s57
	v_bfe_u32 v23, v22, 16, 1
	v_add3_u32 v22, v22, v23, s57
	v_lshrrev_b32_e32 v22, 16, v22
	v_and_or_b32 v21, v21, s53, v22
	global_store_dwordx4 v[54:55], v[18:21], off offset:3264 sc1
	v_pk_add_f32 v[22:23], v[92:93], v[62:63] op_sel_hi:[0,1]
	v_lshlrev_b32_e32 v24, 16, v14
	v_pk_add_f32 v[20:21], v[92:93], v[64:65] op_sel_hi:[0,1]
	v_lshlrev_b32_e32 v14, 16, v15
	v_and_b32_e32 v15, 0xffff0000, v15
	v_pk_mul_f32 v[20:21], v[20:21], v[14:15]
	v_pk_mul_f32 v[14:15], v[22:23], v[24:25]
	v_lshlrev_b32_e32 v24, 16, v16
	v_bfe_u32 v22, v14, 16, 1
	v_add3_u32 v14, v14, v22, s57
	v_bfe_u32 v22, v15, 16, 1
	v_lshrrev_b32_e32 v14, 16, v14
	v_add3_u32 v15, v15, v22, s57
	v_and_or_b32 v14, v15, s53, v14
	v_bfe_u32 v15, v20, 16, 1
	v_add3_u32 v15, v20, v15, s57
	v_bfe_u32 v20, v21, 16, 1
	v_lshrrev_b32_e32 v15, 16, v15
	v_add3_u32 v20, v21, v20, s57
	v_and_or_b32 v15, v20, s53, v15
	v_pk_add_f32 v[20:21], v[92:93], v[60:61] op_sel_hi:[0,1]
	v_pk_add_f32 v[22:23], v[92:93], v[58:59] op_sel_hi:[0,1]
	v_and_b32_e32 v25, 0xffff0000, v16
	v_lshlrev_b32_e32 v16, 16, v17
	v_and_b32_e32 v17, 0xffff0000, v17
	v_pk_mul_f32 v[20:21], v[20:21], v[16:17]
	v_pk_mul_f32 v[16:17], v[22:23], v[24:25]
	v_or_b32_e32 v18, 16, v94
	v_bfe_u32 v22, v17, 16, 1
	v_add3_u32 v17, v17, v22, s57
	v_bfe_u32 v22, v16, 16, 1
	v_add3_u32 v16, v16, v22, s57
	v_lshrrev_b32_e32 v16, 16, v16
	v_ashrrev_i32_e32 v19, 31, v18
	v_and_or_b32 v16, v17, s53, v16
	v_bfe_u32 v17, v21, 16, 1
	v_lshlrev_b64 v[18:19], 12, v[18:19]
	v_add3_u32 v17, v21, v17, s57
	v_bfe_u32 v21, v20, 16, 1
	v_lshl_add_u64 v[18:19], s[26:27], 0, v[18:19]
	v_add3_u32 v20, v20, v21, s57
	v_lshl_add_u64 v[18:19], v[18:19], 0, s[22:23]
	v_lshrrev_b32_e32 v20, 16, v20
	v_and_or_b32 v17, v17, s53, v20
	v_lshl_add_u64 v[18:19], v[18:19], 0, v[90:91]
	global_store_dwordx4 v[18:19], v[14:17], off offset:3072 sc1
	v_lshlrev_b32_e32 v20, 16, v10
	v_and_b32_e32 v21, 0xffff0000, v10
	v_pk_add_f32 v[14:15], v[92:93], v[52:53] op_sel_hi:[0,1]
	v_pk_add_f32 v[16:17], v[92:93], v[50:51] op_sel_hi:[0,1]
	v_lshlrev_b32_e32 v10, 16, v11
	v_and_b32_e32 v11, 0xffff0000, v11
	v_pk_mul_f32 v[14:15], v[14:15], v[10:11]
	v_pk_mul_f32 v[10:11], v[16:17], v[20:21]
	v_lshlrev_b32_e32 v20, 16, v12
	v_bfe_u32 v16, v10, 16, 1
	v_add3_u32 v10, v10, v16, s57
	v_bfe_u32 v16, v11, 16, 1
	v_lshrrev_b32_e32 v10, 16, v10
	v_add3_u32 v11, v11, v16, s57
	v_and_or_b32 v10, v11, s53, v10
	v_bfe_u32 v11, v14, 16, 1
	v_add3_u32 v11, v14, v11, s57
	v_bfe_u32 v14, v15, 16, 1
	v_lshrrev_b32_e32 v11, 16, v11
	v_add3_u32 v14, v15, v14, s57
	v_and_or_b32 v11, v14, s53, v11
	v_pk_add_f32 v[14:15], v[92:93], v[48:49] op_sel_hi:[0,1]
	v_pk_add_f32 v[16:17], v[92:93], v[46:47] op_sel_hi:[0,1]
	v_and_b32_e32 v21, 0xffff0000, v12
	v_lshlrev_b32_e32 v12, 16, v13
	v_and_b32_e32 v13, 0xffff0000, v13
	v_pk_mul_f32 v[14:15], v[14:15], v[12:13]
	v_pk_mul_f32 v[12:13], v[16:17], v[20:21]
	s_nop 0
	v_bfe_u32 v16, v13, 16, 1
	v_add3_u32 v13, v13, v16, s57
	v_bfe_u32 v16, v12, 16, 1
	v_add3_u32 v12, v12, v16, s57
	v_lshrrev_b32_e32 v12, 16, v12
	v_and_or_b32 v12, v13, s53, v12
	v_bfe_u32 v13, v15, 16, 1
	v_add3_u32 v13, v15, v13, s57
	v_bfe_u32 v15, v14, 16, 1
	v_add3_u32 v14, v14, v15, s57
	v_lshrrev_b32_e32 v14, 16, v14
	v_and_or_b32 v13, v13, s53, v14
	global_store_dwordx4 v[18:19], v[10:13], off offset:3136 sc1
	v_lshlrev_b32_e32 v14, 16, v6
	v_and_b32_e32 v15, 0xffff0000, v6
	v_pk_add_f32 v[10:11], v[92:93], v[44:45] op_sel_hi:[0,1]
	v_pk_add_f32 v[12:13], v[92:93], v[42:43] op_sel_hi:[0,1]
	v_lshlrev_b32_e32 v6, 16, v7
	v_and_b32_e32 v7, 0xffff0000, v7
	v_pk_mul_f32 v[10:11], v[10:11], v[6:7]
	v_pk_mul_f32 v[6:7], v[12:13], v[14:15]
	v_lshlrev_b32_e32 v14, 16, v8
	v_bfe_u32 v12, v6, 16, 1
	v_add3_u32 v6, v6, v12, s57
	v_bfe_u32 v12, v7, 16, 1
	v_lshrrev_b32_e32 v6, 16, v6
	v_add3_u32 v7, v7, v12, s57
	v_and_or_b32 v6, v7, s53, v6
	v_bfe_u32 v7, v10, 16, 1
	v_add3_u32 v7, v10, v7, s57
	v_bfe_u32 v10, v11, 16, 1
	v_lshrrev_b32_e32 v7, 16, v7
	v_add3_u32 v10, v11, v10, s57
	v_and_or_b32 v7, v10, s53, v7
	v_pk_add_f32 v[10:11], v[92:93], v[40:41] op_sel_hi:[0,1]
	v_pk_add_f32 v[12:13], v[92:93], v[38:39] op_sel_hi:[0,1]
	v_and_b32_e32 v15, 0xffff0000, v8
	v_lshlrev_b32_e32 v8, 16, v9
	v_and_b32_e32 v9, 0xffff0000, v9
	v_pk_mul_f32 v[10:11], v[10:11], v[8:9]
	v_pk_mul_f32 v[8:9], v[12:13], v[14:15]
	s_nop 0
	v_bfe_u32 v12, v9, 16, 1
	v_add3_u32 v9, v9, v12, s57
	v_bfe_u32 v12, v8, 16, 1
	v_add3_u32 v8, v8, v12, s57
	v_lshrrev_b32_e32 v8, 16, v8
	v_and_or_b32 v8, v9, s53, v8
	v_bfe_u32 v9, v11, 16, 1
	v_add3_u32 v9, v11, v9, s57
	v_bfe_u32 v11, v10, 16, 1
	v_add3_u32 v10, v10, v11, s57
	v_lshrrev_b32_e32 v10, 16, v10
	v_and_or_b32 v9, v9, s53, v10
	global_store_dwordx4 v[18:19], v[6:9], off offset:3200 sc1
	s_waitcnt vmcnt(7)
	v_lshlrev_b32_e32 v10, 16, v2
	v_and_b32_e32 v11, 0xffff0000, v2
	v_pk_add_f32 v[6:7], v[92:93], v[32:33] op_sel_hi:[0,1]
	v_pk_add_f32 v[8:9], v[92:93], v[30:31] op_sel_hi:[0,1]
	v_lshlrev_b32_e32 v2, 16, v3
	v_and_b32_e32 v3, 0xffff0000, v3
	v_pk_mul_f32 v[6:7], v[6:7], v[2:3]
	v_pk_mul_f32 v[2:3], v[8:9], v[10:11]
	v_lshlrev_b32_e32 v10, 16, v4
	v_bfe_u32 v8, v2, 16, 1
	v_add3_u32 v2, v2, v8, s57
	v_bfe_u32 v8, v3, 16, 1
	v_lshrrev_b32_e32 v2, 16, v2
	v_add3_u32 v3, v3, v8, s57
	v_and_or_b32 v2, v3, s53, v2
	v_bfe_u32 v3, v6, 16, 1
	v_add3_u32 v3, v6, v3, s57
	v_bfe_u32 v6, v7, 16, 1
	v_lshrrev_b32_e32 v3, 16, v3
	v_add3_u32 v6, v7, v6, s57
	v_and_or_b32 v3, v6, s53, v3
	v_pk_add_f32 v[6:7], v[92:93], v[28:29] op_sel_hi:[0,1]
	v_pk_add_f32 v[8:9], v[92:93], v[26:27] op_sel_hi:[0,1]
	v_and_b32_e32 v11, 0xffff0000, v4
	v_lshlrev_b32_e32 v4, 16, v5
	v_and_b32_e32 v5, 0xffff0000, v5
	v_pk_mul_f32 v[6:7], v[6:7], v[4:5]
	v_pk_mul_f32 v[4:5], v[8:9], v[10:11]
	s_nop 0
	v_bfe_u32 v8, v5, 16, 1
	v_add3_u32 v5, v5, v8, s57
	v_bfe_u32 v8, v4, 16, 1
	v_add3_u32 v4, v4, v8, s57
	v_lshrrev_b32_e32 v4, 16, v4
	v_and_or_b32 v4, v5, s53, v4
	v_bfe_u32 v5, v7, 16, 1
	v_add3_u32 v5, v7, v5, s57
	v_bfe_u32 v7, v6, 16, 1
	v_add3_u32 v6, v6, v7, s57
	v_lshrrev_b32_e32 v6, 16, v6
	v_and_or_b32 v5, v5, s53, v6
	global_store_dwordx4 v[18:19], v[2:5], off offset:3264 sc1
	s_branch .LBB0_506

.LBB0_513:
	v_lshlrev_b32_e32 v202, 1, v144
	v_lshlrev_b32_e32 v6, 2, v142
	v_lshl_add_u64 v[98:99], s[10:11], 0, v[202:203]
	v_lshlrev_b32_e32 v202, 1, v146
	global_load_dwordx4 v[26:29], v6, s[12:13] offset:16
	global_load_dwordx4 v[30:33], v6, s[12:13]
	global_load_dwordx4 v[18:21], v6, s[12:13] offset:144
	global_load_dwordx4 v[22:25], v6, s[12:13] offset:128
	global_load_dwordx4 v[10:13], v6, s[12:13] offset:272
	global_load_dwordx4 v[14:17], v6, s[12:13] offset:256
	global_load_dwordx4 v[2:5], v6, s[12:13] offset:400
	s_nop 0
	global_load_dwordx4 v[6:9], v6, s[12:13] offset:384
	v_lshl_add_u64 v[102:103], v[98:99], 0, v[202:203]
	v_lshlrev_b32_e32 v202, 1, v148
	v_lshlrev_b32_e32 v110, 1, v150
	v_mov_b32_e32 v111, v203
	v_lshl_add_u64 v[34:35], v[98:99], 0, v[202:203]
	v_lshl_add_u64 v[36:37], v[98:99], 0, v[110:111]
	v_lshlrev_b32_e32 v114, 1, v152
	v_mov_b32_e32 v115, v203
	v_lshlrev_b32_e32 v118, 1, v154
	v_mov_b32_e32 v119, v203
	global_load_dwordx4 v[66:69], v[34:35], off
	global_load_dwordx4 v[70:73], v[36:37], off
	v_lshl_add_u64 v[34:35], v[98:99], 0, v[114:115]
	v_lshl_add_u64 v[36:37], v[98:99], 0, v[118:119]
	v_lshlrev_b32_e32 v122, 1, v156
	v_mov_b32_e32 v123, v203
	v_lshlrev_b32_e32 v126, 1, v158
	v_mov_b32_e32 v127, v203
	global_load_dwordx4 v[74:77], v[34:35], off
	global_load_dwordx4 v[78:81], v[36:37], off
	v_lshl_add_u64 v[34:35], v[98:99], 0, v[122:123]
	v_lshl_add_u64 v[36:37], v[98:99], 0, v[126:127]
	global_load_dwordx4 v[82:85], v[34:35], off
	global_load_dwordx4 v[86:89], v[36:37], off
	v_lshl_add_u64 v[58:59], v[98:99], 0, 64
	global_load_dwordx4 v[90:93], v[102:103], off
	global_load_dwordx4 v[34:37], v[102:103], off offset:64
	global_load_dwordx4 v[94:97], v[102:103], off offset:1024
	global_load_dwordx4 v[38:41], v[102:103], off offset:1088
	v_lshl_add_u64 v[42:43], v[58:59], 0, v[202:203]
	v_lshl_add_u64 v[46:47], v[58:59], 0, v[110:111]
	v_lshl_add_u64 v[50:51], v[58:59], 0, v[114:115]
	v_lshl_add_u64 v[54:55], v[58:59], 0, v[118:119]
	v_lshl_add_u64 v[60:61], v[58:59], 0, v[122:123]
	v_lshl_add_u64 v[62:63], v[58:59], 0, v[126:127]
	global_load_dwordx4 v[42:45], v[42:43], off
	s_nop 0
	global_load_dwordx4 v[46:49], v[46:47], off
	s_nop 0
	global_load_dwordx4 v[50:53], v[50:51], off
	s_nop 0
	global_load_dwordx4 v[54:57], v[54:55], off
	s_nop 0
	global_load_dwordx4 v[58:61], v[60:61], off
	s_nop 0
	global_load_dwordx4 v[62:65], v[62:63], off
	s_waitcnt vmcnt(24)
	v_lshlrev_b32_e32 v170, 16, v117
	v_and_b32_e32 v171, 0xffff0000, v117
	s_min_u32 s10, s77, s17
	v_sub_u32_e64 v117, s38, 1 clamp
	v_sub_u32_e32 v117, s10, v117
	v_cvt_f32_i32_e32 v117, v117
	v_lshlrev_b32_e32 v168, 16, v166
	v_and_b32_e32 v169, 0xffff0000, v166
	v_pk_add_f32 v[166:167], v[168:169], 0 op_sel_hi:[1,0]
	s_add_i32 s38, s38, 32
	v_pk_add_f32 v[172:173], v[166:167], v[170:171]
	v_div_scale_f32 v166, s[10:11], v117, v117, 1.0
	v_rcp_f32_e32 v167, v166
	s_min_u32 s10, s76, s17
	s_sub_i32 s10, s10, s77
	s_add_i32 s10, s10, 1
	v_fma_f32 v174, -v166, v167, 1.0
	v_fmac_f32_e32 v167, v174, v167
	v_div_scale_f32 v174, vcc, 1.0, v117, 1.0
	v_mul_f32_e32 v175, v174, v167
	v_fma_f32 v182, -v166, v175, v174
	v_fmac_f32_e32 v175, v182, v167
	v_fma_f32 v166, -v166, v175, v174
	v_div_fmas_f32 v166, v166, v167, v175
	v_div_fixup_f32 v166, v166, v117, 1.0
	v_lshlrev_b32_e32 v174, 16, v120
	v_and_b32_e32 v175, 0xffff0000, v120
	v_cvt_f32_i32_e32 v120, s10
	v_pk_fma_f32 v[166:167], v[166:167], v[172:173], v[170:171] op_sel_hi:[0,1,1] neg_lo:[0,0,1] neg_hi:[0,0,1]
	v_bfe_u32 v117, v166, 16, 1
	v_add3_u32 v117, v166, v117, s57
	v_bfe_u32 v166, v167, 16, 1
	v_add3_u32 v166, v167, v166, s57
	v_pk_add_f32 v[168:169], v[174:175], v[168:169] neg_lo:[0,1] neg_hi:[0,1]
	v_div_scale_f32 v167, s[10:11], v120, v120, 1.0
	v_pk_add_f32 v[168:169], v[172:173], v[168:169]
	v_rcp_f32_e32 v172, v167
	s_min_u32 s10, s75, s17
	s_sub_i32 s10, s10, s76
	s_add_i32 s10, s10, 1
	v_fma_f32 v173, -v167, v172, 1.0
	v_fmac_f32_e32 v172, v173, v172
	v_div_scale_f32 v173, vcc, 1.0, v120, 1.0
	v_mul_f32_e32 v182, v173, v172
	v_fma_f32 v183, -v167, v182, v173
	v_fmac_f32_e32 v182, v183, v172
	v_fma_f32 v167, -v167, v182, v173
	v_div_fmas_f32 v167, v167, v172, v182
	v_div_fixup_f32 v120, v167, v120, 1.0
	v_pk_fma_f32 v[172:173], v[120:121], v[168:169], v[174:175] op_sel_hi:[0,1,1] neg_lo:[0,0,1] neg_hi:[0,0,1]
	v_bfe_u32 v120, v172, 16, 1
	v_bfe_u32 v167, v173, 16, 1
	v_add3_u32 v120, v172, v120, s57
	v_add3_u32 v167, v173, v167, s57
	v_lshlrev_b32_e32 v172, 16, v121
	v_and_b32_e32 v173, 0xffff0000, v121
	v_cvt_f32_i32_e32 v121, s10
	v_pk_add_f32 v[170:171], v[172:173], v[170:171] neg_lo:[0,1] neg_hi:[0,1]
	v_lshrrev_b32_e32 v117, 16, v117
	v_pk_add_f32 v[170:171], v[168:169], v[170:171]
	v_div_scale_f32 v168, s[10:11], v121, v121, 1.0
	v_rcp_f32_e32 v169, v168
	s_min_u32 s10, s74, s17
	s_sub_i32 s10, s10, s75
	s_add_i32 s10, s10, 1
	v_fma_f32 v182, -v168, v169, 1.0
	v_fmac_f32_e32 v169, v182, v169
	v_div_scale_f32 v182, vcc, 1.0, v121, 1.0
	v_mul_f32_e32 v183, v182, v169
	v_fma_f32 v184, -v168, v183, v182
	v_fmac_f32_e32 v183, v184, v169
	v_fma_f32 v168, -v168, v183, v182
	v_div_fmas_f32 v168, v168, v169, v183
	v_div_fixup_f32 v168, v168, v121, 1.0
	v_lshlrev_b32_e32 v182, 16, v124
	v_and_b32_e32 v183, 0xffff0000, v124
	v_cvt_f32_i32_e32 v124, s10
	v_pk_fma_f32 v[168:169], v[168:169], v[170:171], v[172:173] op_sel_hi:[0,1,1] neg_lo:[0,0,1] neg_hi:[0,0,1]
	v_bfe_u32 v121, v168, 16, 1
	v_add3_u32 v121, v168, v121, s57
	v_bfe_u32 v168, v169, 16, 1
	v_add3_u32 v168, v169, v168, s57
	v_pk_add_f32 v[174:175], v[182:183], v[174:175] neg_lo:[0,1] neg_hi:[0,1]
	v_div_scale_f32 v169, s[10:11], v124, v124, 1.0
	v_pk_add_f32 v[170:171], v[170:171], v[174:175]
	v_rcp_f32_e32 v174, v169
	s_min_u32 s10, s73, s17
	s_sub_i32 s10, s10, s74
	s_add_i32 s10, s10, 1
	v_fma_f32 v175, -v169, v174, 1.0
	v_fmac_f32_e32 v174, v175, v174
	v_div_scale_f32 v175, vcc, 1.0, v124, 1.0
	v_mul_f32_e32 v184, v175, v174
	v_fma_f32 v185, -v169, v184, v175
	v_fmac_f32_e32 v184, v185, v174
	v_fma_f32 v169, -v169, v184, v175
	v_div_fmas_f32 v169, v169, v174, v184
	v_div_fixup_f32 v124, v169, v124, 1.0
	v_pk_fma_f32 v[174:175], v[124:125], v[170:171], v[182:183] op_sel_hi:[0,1,1] neg_lo:[0,0,1] neg_hi:[0,0,1]
	v_bfe_u32 v124, v174, 16, 1
	v_bfe_u32 v169, v175, 16, 1
	v_add3_u32 v124, v174, v124, s57
	v_add3_u32 v169, v175, v169, s57
	v_lshlrev_b32_e32 v174, 16, v125
	v_and_b32_e32 v175, 0xffff0000, v125
	v_cvt_f32_i32_e32 v125, s10
	v_pk_add_f32 v[172:173], v[174:175], v[172:173] neg_lo:[0,1] neg_hi:[0,1]
	v_and_or_b32 v166, v166, s53, v117
	v_pk_add_f32 v[172:173], v[170:171], v[172:173]
	v_div_scale_f32 v170, s[10:11], v125, v125, 1.0
	v_rcp_f32_e32 v171, v170
	s_min_u32 s10, s72, s17
	s_sub_i32 s10, s10, s73
	s_add_i32 s10, s10, 1
	v_fma_f32 v184, -v170, v171, 1.0
	v_fmac_f32_e32 v171, v184, v171
	v_div_scale_f32 v184, vcc, 1.0, v125, 1.0
	v_mul_f32_e32 v185, v184, v171
	v_fma_f32 v186, -v170, v185, v184
	v_fmac_f32_e32 v185, v186, v171
	v_fma_f32 v170, -v170, v185, v184
	v_div_fmas_f32 v170, v170, v171, v185
	v_div_fixup_f32 v170, v170, v125, 1.0
	v_lshlrev_b32_e32 v184, 16, v128
	v_and_b32_e32 v185, 0xffff0000, v128
	v_cvt_f32_i32_e32 v128, s10
	v_pk_fma_f32 v[170:171], v[170:171], v[172:173], v[174:175] op_sel_hi:[0,1,1] neg_lo:[0,0,1] neg_hi:[0,0,1]
	v_bfe_u32 v125, v170, 16, 1
	v_add3_u32 v125, v170, v125, s57
	v_bfe_u32 v170, v171, 16, 1
	v_add3_u32 v170, v171, v170, s57
	v_pk_add_f32 v[182:183], v[184:185], v[182:183] neg_lo:[0,1] neg_hi:[0,1]
	v_div_scale_f32 v171, s[10:11], v128, v128, 1.0
	v_pk_add_f32 v[172:173], v[172:173], v[182:183]
	v_rcp_f32_e32 v182, v171
	s_min_u32 s10, s69, s17
	s_sub_i32 s10, s10, s72
	s_add_i32 s10, s10, 1
	v_fma_f32 v183, -v171, v182, 1.0
	v_fmac_f32_e32 v182, v183, v182
	v_div_scale_f32 v183, vcc, 1.0, v128, 1.0
	v_mul_f32_e32 v186, v183, v182
	v_fma_f32 v187, -v171, v186, v183
	v_fmac_f32_e32 v186, v187, v182
	v_fma_f32 v171, -v171, v186, v183
	v_div_fmas_f32 v171, v171, v182, v186
	v_div_fixup_f32 v128, v171, v128, 1.0
	v_pk_fma_f32 v[182:183], v[128:129], v[172:173], v[184:185] op_sel_hi:[0,1,1] neg_lo:[0,0,1] neg_hi:[0,0,1]
	v_bfe_u32 v128, v182, 16, 1
	v_bfe_u32 v171, v183, 16, 1
	v_add3_u32 v128, v182, v128, s57
	v_add3_u32 v171, v183, v171, s57
	v_lshlrev_b32_e32 v182, 16, v129
	v_and_b32_e32 v183, 0xffff0000, v129
	v_cvt_f32_i32_e32 v129, s10
	v_pk_add_f32 v[174:175], v[182:183], v[174:175] neg_lo:[0,1] neg_hi:[0,1]
	v_add_u32_e32 v117, v147, v145
	v_pk_add_f32 v[174:175], v[172:173], v[174:175]
	v_div_scale_f32 v172, s[10:11], v129, v129, 1.0
	v_rcp_f32_e32 v173, v172
	s_min_u32 s10, s68, s17
	s_sub_i32 s10, s10, s69
	s_add_i32 s10, s10, 1
	v_fma_f32 v186, -v172, v173, 1.0
	v_fmac_f32_e32 v173, v186, v173
	v_div_scale_f32 v186, vcc, 1.0, v129, 1.0
	v_mul_f32_e32 v187, v186, v173
	v_fma_f32 v188, -v172, v187, v186
	v_fmac_f32_e32 v187, v188, v173
	v_fma_f32 v172, -v172, v187, v186
	v_div_fmas_f32 v172, v172, v173, v187
	v_div_fixup_f32 v172, v172, v129, 1.0
	v_lshlrev_b32_e32 v186, 16, v116
	v_and_b32_e32 v187, 0xffff0000, v116
	v_cvt_f32_i32_e32 v116, s10
	v_pk_fma_f32 v[172:173], v[172:173], v[174:175], v[182:183] op_sel_hi:[0,1,1] neg_lo:[0,0,1] neg_hi:[0,0,1]
	v_bfe_u32 v129, v172, 16, 1
	v_add3_u32 v129, v172, v129, s57
	v_bfe_u32 v172, v173, 16, 1
	v_add3_u32 v172, v173, v172, s57
	v_pk_add_f32 v[184:185], v[186:187], v[184:185] neg_lo:[0,1] neg_hi:[0,1]
	v_div_scale_f32 v173, s[10:11], v116, v116, 1.0
	v_pk_add_f32 v[174:175], v[174:175], v[184:185]
	v_rcp_f32_e32 v184, v173
	s_min_u32 s10, s58, s17
	s_sub_i32 s10, s10, s68
	s_add_i32 s10, s10, 1
	v_fma_f32 v185, -v173, v184, 1.0
	v_fmac_f32_e32 v184, v185, v184
	v_div_scale_f32 v185, vcc, 1.0, v116, 1.0
	v_mul_f32_e32 v188, v185, v184
	v_fma_f32 v189, -v173, v188, v185
	v_fmac_f32_e32 v188, v189, v184
	v_fma_f32 v173, -v173, v188, v185
	v_div_fmas_f32 v173, v173, v184, v188
	v_div_fixup_f32 v116, v173, v116, 1.0
	v_pk_fma_f32 v[184:185], v[116:117], v[174:175], v[186:187] op_sel_hi:[0,1,1] neg_lo:[0,0,1] neg_hi:[0,0,1]
	v_bfe_u32 v116, v184, 16, 1
	v_bfe_u32 v173, v185, 16, 1
	v_add3_u32 v116, v184, v116, s57
	v_add3_u32 v173, v185, v173, s57
	v_lshlrev_b32_e32 v184, 16, v165
	v_and_b32_e32 v185, 0xffff0000, v165
	v_cvt_f32_i32_e32 v165, s10
	v_pk_add_f32 v[182:183], v[184:185], v[182:183] neg_lo:[0,1] neg_hi:[0,1]
	v_lshrrev_b32_e32 v120, 16, v120
	v_pk_add_f32 v[174:175], v[174:175], v[182:183]
	v_div_scale_f32 v182, s[10:11], v165, v165, 1.0
	v_rcp_f32_e32 v183, v182
	s_min_u32 s10, s63, s17
	s_sub_i32 s10, s10, s58
	s_add_i32 s10, s10, 1
	v_fma_f32 v188, -v182, v183, 1.0
	v_fmac_f32_e32 v183, v188, v183
	v_div_scale_f32 v188, vcc, 1.0, v165, 1.0
	v_mul_f32_e32 v189, v188, v183
	v_fma_f32 v190, -v182, v189, v188
	v_fmac_f32_e32 v189, v190, v183
	v_fma_f32 v182, -v182, v189, v188
	v_div_fmas_f32 v182, v182, v183, v189
	v_div_fixup_f32 v182, v182, v165, 1.0
	v_pk_fma_f32 v[182:183], v[182:183], v[174:175], v[184:185] op_sel_hi:[0,1,1] neg_lo:[0,0,1] neg_hi:[0,0,1]
	v_bfe_u32 v165, v182, 16, 1
	v_add3_u32 v165, v182, v165, s57
	v_bfe_u32 v182, v183, 16, 1
	v_lshrrev_b32_e32 v165, 16, v165
	v_add3_u32 v182, v183, v182, s57
	v_and_or_b32 v165, v182, s53, v165
	ds_write2st64_b32 v117, v166, v165 offset1:8
	v_cvt_f32_i32_e32 v166, s10
	v_lshlrev_b32_e32 v182, 16, v164
	v_and_b32_e32 v183, 0xffff0000, v164
	v_pk_add_f32 v[164:165], v[182:183], v[186:187] neg_lo:[0,1] neg_hi:[0,1]
	v_and_or_b32 v167, v167, s53, v120
	v_pk_add_f32 v[164:165], v[174:175], v[164:165]
	v_div_scale_f32 v174, s[10:11], v166, v166, 1.0
	v_rcp_f32_e32 v175, v174
	s_min_u32 s10, s62, s17
	s_sub_i32 s10, s10, s63
	v_add_u32_e32 v120, v149, v145
	v_fma_f32 v186, -v174, v175, 1.0
	v_fmac_f32_e32 v175, v186, v175
	v_div_scale_f32 v186, vcc, 1.0, v166, 1.0
	v_mul_f32_e32 v187, v186, v175
	v_fma_f32 v188, -v174, v187, v186
	v_fmac_f32_e32 v187, v188, v175
	v_fma_f32 v174, -v174, v187, v186
	v_div_fmas_f32 v174, v174, v175, v187
	v_div_fixup_f32 v166, v174, v166, 1.0
	v_pk_fma_f32 v[174:175], v[166:167], v[164:165], v[182:183] op_sel_hi:[0,1,1] neg_lo:[0,0,1] neg_hi:[0,0,1]
	v_bfe_u32 v166, v174, 16, 1
	v_add3_u32 v166, v174, v166, s57
	v_bfe_u32 v174, v175, 16, 1
	v_lshrrev_b32_e32 v166, 16, v166
	v_add3_u32 v174, v175, v174, s57
	v_and_or_b32 v166, v174, s53, v166
	s_add_i32 s10, s10, 1
	ds_write2st64_b32 v120, v167, v166 offset0:1 offset1:9
	v_lshlrev_b32_e32 v166, 16, v141
	v_and_b32_e32 v167, 0xffff0000, v141
	v_cvt_f32_i32_e32 v141, s10
	v_pk_add_f32 v[174:175], v[166:167], v[184:185] neg_lo:[0,1] neg_hi:[0,1]
	v_lshrrev_b32_e32 v121, 16, v121
	v_pk_add_f32 v[164:165], v[164:165], v[174:175]
	v_div_scale_f32 v174, s[10:11], v141, v141, 1.0
	v_rcp_f32_e32 v175, v174
	s_min_u32 s10, s56, s17
	v_and_or_b32 v168, v168, s53, v121
	v_add_u32_e32 v121, v151, v145
	v_fma_f32 v184, -v174, v175, 1.0
	v_fmac_f32_e32 v175, v184, v175
	v_div_scale_f32 v184, vcc, 1.0, v141, 1.0
	v_mul_f32_e32 v185, v184, v175
	v_fma_f32 v186, -v174, v185, v184
	v_fmac_f32_e32 v185, v186, v175
	v_fma_f32 v174, -v174, v185, v184
	v_div_fmas_f32 v174, v174, v175, v185
	v_div_fixup_f32 v174, v174, v141, 1.0
	v_pk_fma_f32 v[174:175], v[174:175], v[164:165], v[166:167] op_sel_hi:[0,1,1] neg_lo:[0,0,1] neg_hi:[0,0,1]
	v_bfe_u32 v141, v174, 16, 1
	v_add3_u32 v141, v174, v141, s57
	v_bfe_u32 v174, v175, 16, 1
	v_lshrrev_b32_e32 v141, 16, v141
	v_add3_u32 v174, v175, v174, s57
	v_and_or_b32 v141, v174, s53, v141
	v_lshlrev_b32_e32 v174, 16, v140
	v_and_b32_e32 v175, 0xffff0000, v140
	s_sub_i32 s10, s10, s62
	ds_write2st64_b32 v121, v168, v141 offset0:2 offset1:10
	v_pk_add_f32 v[140:141], v[174:175], v[182:183] neg_lo:[0,1] neg_hi:[0,1]
	s_add_i32 s10, s10, 1
	v_pk_add_f32 v[140:141], v[164:165], v[140:141]
	v_cvt_f32_i32_e32 v164, s10
	v_lshrrev_b32_e32 v124, 16, v124
	v_and_or_b32 v169, v169, s53, v124
	v_add_u32_e32 v124, v153, v145
	v_div_scale_f32 v165, s[10:11], v164, v164, 1.0
	v_rcp_f32_e32 v168, v165
	s_min_u32 s10, s54, s17
	s_sub_i32 s10, s10, s56
	s_add_i32 s10, s10, 1
	v_fma_f32 v182, -v165, v168, 1.0
	v_fmac_f32_e32 v168, v182, v168
	v_div_scale_f32 v182, vcc, 1.0, v164, 1.0
	v_mul_f32_e32 v183, v182, v168
	v_fma_f32 v184, -v165, v183, v182
	v_fmac_f32_e32 v183, v184, v168
	v_fma_f32 v165, -v165, v183, v182
	v_div_fmas_f32 v165, v165, v168, v183
	v_div_fixup_f32 v164, v165, v164, 1.0
	v_pk_fma_f32 v[164:165], v[164:165], v[140:141], v[174:175] op_sel_hi:[0,1,1] neg_lo:[0,0,1] neg_hi:[0,0,1]
	v_bfe_u32 v168, v164, 16, 1
	v_add3_u32 v164, v164, v168, s57
	v_bfe_u32 v168, v165, 16, 1
	v_lshrrev_b32_e32 v164, 16, v164
	v_add3_u32 v165, v165, v168, s57
	v_and_or_b32 v164, v165, s53, v164
	ds_write2st64_b32 v124, v169, v164 offset0:3 offset1:11
	v_lshlrev_b32_e32 v164, 16, v139
	v_and_b32_e32 v165, 0xffff0000, v139
	v_cvt_f32_i32_e32 v139, s10
	v_pk_add_f32 v[166:167], v[164:165], v[166:167] neg_lo:[0,1] neg_hi:[0,1]
	v_lshrrev_b32_e32 v125, 16, v125
	v_pk_add_f32 v[140:141], v[140:141], v[166:167]
	v_div_scale_f32 v166, s[10:11], v139, v139, 1.0
	v_rcp_f32_e32 v167, v166
	s_min_u32 s10, s52, s17
	v_and_or_b32 v170, v170, s53, v125
	v_add_u32_e32 v125, v155, v145
	v_fma_f32 v168, -v166, v167, 1.0
	v_fmac_f32_e32 v167, v168, v167
	v_div_scale_f32 v168, vcc, 1.0, v139, 1.0
	v_mul_f32_e32 v169, v168, v167
	v_fma_f32 v182, -v166, v169, v168
	v_fmac_f32_e32 v169, v182, v167
	v_fma_f32 v166, -v166, v169, v168
	v_div_fmas_f32 v166, v166, v167, v169
	v_div_fixup_f32 v166, v166, v139, 1.0
	v_pk_fma_f32 v[166:167], v[166:167], v[140:141], v[164:165] op_sel_hi:[0,1,1] neg_lo:[0,0,1] neg_hi:[0,0,1]
	v_bfe_u32 v139, v166, 16, 1
	v_add3_u32 v139, v166, v139, s57
	v_bfe_u32 v166, v167, 16, 1
	v_lshrrev_b32_e32 v139, 16, v139
	v_add3_u32 v166, v167, v166, s57
	v_and_or_b32 v139, v166, s53, v139
	v_lshlrev_b32_e32 v166, 16, v138
	v_and_b32_e32 v167, 0xffff0000, v138
	s_sub_i32 s10, s10, s54
	ds_write2st64_b32 v125, v170, v139 offset0:4 offset1:12
	v_pk_add_f32 v[138:139], v[166:167], v[174:175] neg_lo:[0,1] neg_hi:[0,1]
	s_add_i32 s10, s10, 1
	v_pk_add_f32 v[138:139], v[140:141], v[138:139]
	v_cvt_f32_i32_e32 v140, s10
	v_lshrrev_b32_e32 v128, 16, v128
	v_and_or_b32 v171, v171, s53, v128
	v_add_u32_e32 v128, v157, v145
	v_div_scale_f32 v141, s[10:11], v140, v140, 1.0
	v_rcp_f32_e32 v168, v141
	s_min_u32 s10, s51, s17
	s_sub_i32 s10, s10, s52
	s_add_i32 s10, s10, 1
	v_fma_f32 v169, -v141, v168, 1.0
	v_fmac_f32_e32 v168, v169, v168
	v_div_scale_f32 v169, vcc, 1.0, v140, 1.0
	v_mul_f32_e32 v170, v169, v168
	v_fma_f32 v174, -v141, v170, v169
	v_fmac_f32_e32 v170, v174, v168
	v_fma_f32 v141, -v141, v170, v169
	v_div_fmas_f32 v141, v141, v168, v170
	v_div_fixup_f32 v140, v141, v140, 1.0
	v_pk_fma_f32 v[140:141], v[140:141], v[138:139], v[166:167] op_sel_hi:[0,1,1] neg_lo:[0,0,1] neg_hi:[0,0,1]
	v_bfe_u32 v168, v140, 16, 1
	v_add3_u32 v140, v140, v168, s57
	v_bfe_u32 v168, v141, 16, 1
	v_lshrrev_b32_e32 v140, 16, v140
	v_add3_u32 v141, v141, v168, s57
	v_and_or_b32 v140, v141, s53, v140
	ds_write2st64_b32 v128, v171, v140 offset0:5 offset1:13
	v_lshlrev_b32_e32 v140, 16, v137
	v_and_b32_e32 v141, 0xffff0000, v137
	v_cvt_f32_i32_e32 v137, s10
	v_pk_add_f32 v[164:165], v[140:141], v[164:165] neg_lo:[0,1] neg_hi:[0,1]
	v_lshrrev_b32_e32 v129, 16, v129
	v_pk_add_f32 v[138:139], v[138:139], v[164:165]
	v_div_scale_f32 v164, s[10:11], v137, v137, 1.0
	v_rcp_f32_e32 v165, v164
	s_min_u32 s10, s48, s17
	v_and_or_b32 v172, v172, s53, v129
	v_add_u32_e32 v129, v159, v145
	v_fma_f32 v168, -v164, v165, 1.0
	v_fmac_f32_e32 v165, v168, v165
	v_div_scale_f32 v168, vcc, 1.0, v137, 1.0
	v_mul_f32_e32 v169, v168, v165
	v_fma_f32 v170, -v164, v169, v168
	v_fmac_f32_e32 v169, v170, v165
	v_fma_f32 v164, -v164, v169, v168
	v_div_fmas_f32 v164, v164, v165, v169
	v_div_fixup_f32 v164, v164, v137, 1.0
	v_pk_fma_f32 v[164:165], v[164:165], v[138:139], v[140:141] op_sel_hi:[0,1,1] neg_lo:[0,0,1] neg_hi:[0,0,1]
	v_bfe_u32 v137, v164, 16, 1
	v_add3_u32 v137, v164, v137, s57
	v_bfe_u32 v164, v165, 16, 1
	v_lshrrev_b32_e32 v137, 16, v137
	v_add3_u32 v164, v165, v164, s57
	v_and_or_b32 v137, v164, s53, v137
	v_lshlrev_b32_e32 v164, 16, v136
	v_and_b32_e32 v165, 0xffff0000, v136
	s_sub_i32 s10, s10, s51
	ds_write2st64_b32 v129, v172, v137 offset0:6 offset1:14
	v_pk_add_f32 v[136:137], v[164:165], v[166:167] neg_lo:[0,1] neg_hi:[0,1]
	s_add_i32 s10, s10, 1
	v_pk_add_f32 v[136:137], v[138:139], v[136:137]
	v_cvt_f32_i32_e32 v138, s10
	v_lshrrev_b32_e32 v116, 16, v116
	v_and_or_b32 v173, v173, s53, v116
	v_add_u32_e32 v116, v176, v145
	v_div_scale_f32 v139, s[10:11], v138, v138, 1.0
	v_rcp_f32_e32 v166, v139
	s_min_u32 s10, s46, s17
	s_sub_i32 s10, s10, s48
	s_add_i32 s10, s10, 1
	v_fma_f32 v167, -v139, v166, 1.0
	v_fmac_f32_e32 v166, v167, v166
	v_div_scale_f32 v167, vcc, 1.0, v138, 1.0
	v_mul_f32_e32 v168, v167, v166
	v_fma_f32 v169, -v139, v168, v167
	v_fmac_f32_e32 v168, v169, v166
	v_fma_f32 v139, -v139, v168, v167
	v_div_fmas_f32 v139, v139, v166, v168
	v_div_fixup_f32 v138, v139, v138, 1.0
	v_pk_fma_f32 v[138:139], v[138:139], v[136:137], v[164:165] op_sel_hi:[0,1,1] neg_lo:[0,0,1] neg_hi:[0,0,1]
	v_bfe_u32 v166, v138, 16, 1
	v_add3_u32 v138, v138, v166, s57
	v_bfe_u32 v166, v139, 16, 1
	v_lshrrev_b32_e32 v138, 16, v138
	v_add3_u32 v139, v139, v166, s57
	v_and_or_b32 v138, v139, s53, v138
	ds_write2st64_b32 v116, v173, v138 offset0:7 offset1:15
	v_lshlrev_b32_e32 v138, 16, v135
	v_and_b32_e32 v139, 0xffff0000, v135
	v_cvt_f32_i32_e32 v135, s10
	v_pk_add_f32 v[140:141], v[138:139], v[140:141] neg_lo:[0,1] neg_hi:[0,1]
	s_nop 0
	v_pk_add_f32 v[136:137], v[136:137], v[140:141]
	v_div_scale_f32 v140, s[10:11], v135, v135, 1.0
	v_rcp_f32_e32 v141, v140
	s_min_u32 s10, s45, s17
	s_sub_i32 s10, s10, s46
	s_add_i32 s10, s10, 1
	v_fma_f32 v166, -v140, v141, 1.0
	v_fmac_f32_e32 v141, v166, v141
	v_div_scale_f32 v166, vcc, 1.0, v135, 1.0
	v_mul_f32_e32 v167, v166, v141
	v_fma_f32 v168, -v140, v167, v166
	v_fmac_f32_e32 v167, v168, v141
	v_fma_f32 v140, -v140, v167, v166
	v_div_fmas_f32 v140, v140, v141, v167
	v_div_fixup_f32 v140, v140, v135, 1.0
	v_pk_fma_f32 v[140:141], v[140:141], v[136:137], v[138:139] op_sel_hi:[0,1,1] neg_lo:[0,0,1] neg_hi:[0,0,1]
	v_bfe_u32 v135, v140, 16, 1
	v_add3_u32 v135, v140, v135, s57
	v_bfe_u32 v140, v141, 16, 1
	v_lshrrev_b32_e32 v135, 16, v135
	v_add3_u32 v140, v141, v140, s57
	v_and_or_b32 v135, v140, s53, v135
	v_lshlrev_b32_e32 v140, 16, v134
	v_and_b32_e32 v141, 0xffff0000, v134
	v_cvt_f32_i32_e32 v134, s10
	v_pk_add_f32 v[164:165], v[140:141], v[164:165] neg_lo:[0,1] neg_hi:[0,1]
	s_nop 0
	v_pk_add_f32 v[136:137], v[136:137], v[164:165]
	v_div_scale_f32 v164, s[10:11], v134, v134, 1.0
	v_rcp_f32_e32 v165, v164
	s_min_u32 s10, s44, s17
	s_sub_i32 s10, s10, s45
	s_add_i32 s10, s10, 1
	v_fma_f32 v166, -v164, v165, 1.0
	v_fmac_f32_e32 v165, v166, v165
	v_div_scale_f32 v166, vcc, 1.0, v134, 1.0
	v_mul_f32_e32 v167, v166, v165
	v_fma_f32 v168, -v164, v167, v166
	v_fmac_f32_e32 v167, v168, v165
	v_fma_f32 v164, -v164, v167, v166
	v_div_fmas_f32 v164, v164, v165, v167
	v_div_fixup_f32 v134, v164, v134, 1.0
	v_pk_fma_f32 v[164:165], v[134:135], v[136:137], v[140:141] op_sel_hi:[0,1,1] neg_lo:[0,0,1] neg_hi:[0,0,1]
	v_bfe_u32 v134, v164, 16, 1
	v_add3_u32 v134, v164, v134, s57
	v_bfe_u32 v164, v165, 16, 1
	v_lshrrev_b32_e32 v134, 16, v134
	v_add3_u32 v164, v165, v164, s57
	v_and_or_b32 v134, v164, s53, v134
	v_lshlrev_b32_e32 v164, 16, v133
	v_and_b32_e32 v165, 0xffff0000, v133
	v_cvt_f32_i32_e32 v133, s10
	v_pk_add_f32 v[138:139], v[164:165], v[138:139] neg_lo:[0,1] neg_hi:[0,1]
	s_nop 0
	v_pk_add_f32 v[136:137], v[136:137], v[138:139]
	v_div_scale_f32 v138, s[10:11], v133, v133, 1.0
	v_rcp_f32_e32 v139, v138
	s_min_u32 s10, s39, s17
	s_sub_i32 s10, s10, s44
	s_add_i32 s10, s10, 1
	v_fma_f32 v166, -v138, v139, 1.0
	v_fmac_f32_e32 v139, v166, v139
	v_div_scale_f32 v166, vcc, 1.0, v133, 1.0
	v_mul_f32_e32 v167, v166, v139
	v_fma_f32 v168, -v138, v167, v166
	v_fmac_f32_e32 v167, v168, v139
	v_fma_f32 v138, -v138, v167, v166
	v_div_fmas_f32 v138, v138, v139, v167
	v_div_fixup_f32 v138, v138, v133, 1.0
	v_pk_fma_f32 v[138:139], v[138:139], v[136:137], v[164:165] op_sel_hi:[0,1,1] neg_lo:[0,0,1] neg_hi:[0,0,1]
	v_bfe_u32 v133, v138, 16, 1
	v_add3_u32 v133, v138, v133, s57
	v_bfe_u32 v138, v139, 16, 1
	v_lshrrev_b32_e32 v133, 16, v133
	v_add3_u32 v138, v139, v138, s57
	v_and_or_b32 v133, v138, s53, v133
	v_lshlrev_b32_e32 v138, 16, v132
	v_and_b32_e32 v139, 0xffff0000, v132
	v_cvt_f32_i32_e32 v132, s10
	v_pk_add_f32 v[140:141], v[138:139], v[140:141] neg_lo:[0,1] neg_hi:[0,1]
	s_nop 0
	v_pk_add_f32 v[136:137], v[136:137], v[140:141]
	v_div_scale_f32 v140, s[10:11], v132, v132, 1.0
	v_rcp_f32_e32 v141, v140
	s_min_u32 s10, s27, s17
	s_sub_i32 s10, s10, s39
	s_add_i32 s10, s10, 1
	v_fma_f32 v166, -v140, v141, 1.0
	v_fmac_f32_e32 v141, v166, v141
	v_div_scale_f32 v166, vcc, 1.0, v132, 1.0
	v_mul_f32_e32 v167, v166, v141
	v_fma_f32 v168, -v140, v167, v166
	v_fmac_f32_e32 v167, v168, v141
	v_fma_f32 v140, -v140, v167, v166
	v_div_fmas_f32 v140, v140, v141, v167
	v_div_fixup_f32 v132, v140, v132, 1.0
	v_pk_fma_f32 v[140:141], v[132:133], v[136:137], v[138:139] op_sel_hi:[0,1,1] neg_lo:[0,0,1] neg_hi:[0,0,1]
	v_bfe_u32 v132, v140, 16, 1
	v_add3_u32 v132, v140, v132, s57
	v_bfe_u32 v140, v141, 16, 1
	v_lshrrev_b32_e32 v132, 16, v132
	v_add3_u32 v140, v141, v140, s57
	v_and_or_b32 v132, v140, s53, v132
	v_lshlrev_b32_e32 v140, 16, v131
	v_and_b32_e32 v141, 0xffff0000, v131
	v_cvt_f32_i32_e32 v131, s10
	v_pk_add_f32 v[164:165], v[140:141], v[164:165] neg_lo:[0,1] neg_hi:[0,1]
	s_nop 0
	v_pk_add_f32 v[136:137], v[136:137], v[164:165]
	v_div_scale_f32 v164, s[10:11], v131, v131, 1.0
	v_rcp_f32_e32 v165, v164
	s_min_u32 s10, s26, s17
	s_sub_i32 s10, s10, s27
	s_add_i32 s10, s10, 1
	v_fma_f32 v166, -v164, v165, 1.0
	v_fmac_f32_e32 v165, v166, v165
	v_div_scale_f32 v166, vcc, 1.0, v131, 1.0
	v_mul_f32_e32 v167, v166, v165
	v_fma_f32 v168, -v164, v167, v166
	v_fmac_f32_e32 v167, v168, v165
	v_fma_f32 v164, -v164, v167, v166
	v_div_fmas_f32 v164, v164, v165, v167
	v_div_fixup_f32 v164, v164, v131, 1.0
	v_pk_fma_f32 v[164:165], v[164:165], v[136:137], v[140:141] op_sel_hi:[0,1,1] neg_lo:[0,0,1] neg_hi:[0,0,1]
	v_bfe_u32 v131, v164, 16, 1
	v_add3_u32 v131, v164, v131, s57
	v_bfe_u32 v164, v165, 16, 1
	v_lshrrev_b32_e32 v131, 16, v131
	v_add3_u32 v164, v165, v164, s57
	v_and_or_b32 v131, v164, s53, v131
	v_lshlrev_b32_e32 v164, 16, v130
	v_and_b32_e32 v165, 0xffff0000, v130
	v_cvt_f32_i32_e32 v130, s10
	v_pk_add_f32 v[138:139], v[164:165], v[138:139] neg_lo:[0,1] neg_hi:[0,1]
	s_nop 0
	v_pk_add_f32 v[136:137], v[136:137], v[138:139]
	v_div_scale_f32 v138, s[10:11], v130, v130, 1.0
	v_rcp_f32_e32 v139, v138
	s_min_u32 s10, s19, s17
	s_sub_i32 s10, s10, s26
	s_add_i32 s10, s10, 1
	v_fma_f32 v166, -v138, v139, 1.0
	v_fmac_f32_e32 v139, v166, v139
	v_div_scale_f32 v166, vcc, 1.0, v130, 1.0
	v_mul_f32_e32 v167, v166, v139
	v_fma_f32 v168, -v138, v167, v166
	v_fmac_f32_e32 v167, v168, v139
	v_fma_f32 v138, -v138, v167, v166
	v_div_fmas_f32 v138, v138, v139, v167
	v_div_fixup_f32 v130, v138, v130, 1.0
	v_pk_fma_f32 v[138:139], v[130:131], v[136:137], v[164:165] op_sel_hi:[0,1,1] neg_lo:[0,0,1] neg_hi:[0,0,1]
	v_bfe_u32 v130, v138, 16, 1
	v_add3_u32 v130, v138, v130, s57
	v_bfe_u32 v138, v139, 16, 1
	v_lshrrev_b32_e32 v130, 16, v130
	v_add3_u32 v138, v139, v138, s57
	v_and_or_b32 v130, v138, s53, v130
	v_lshlrev_b32_e32 v138, 16, v113
	v_and_b32_e32 v139, 0xffff0000, v113
	v_cvt_f32_i32_e32 v113, s10
	v_pk_add_f32 v[140:141], v[138:139], v[140:141] neg_lo:[0,1] neg_hi:[0,1]
	s_nop 0
	v_pk_add_f32 v[136:137], v[136:137], v[140:141]
	v_div_scale_f32 v140, s[10:11], v113, v113, 1.0
	v_rcp_f32_e32 v141, v140
	s_min_u32 s10, s18, s17
	s_sub_i32 s10, s10, s19
	s_add_i32 s10, s10, 1
	v_fma_f32 v166, -v140, v141, 1.0
	v_fmac_f32_e32 v141, v166, v141
	v_div_scale_f32 v166, vcc, 1.0, v113, 1.0
	v_mul_f32_e32 v167, v166, v141
	v_fma_f32 v168, -v140, v167, v166
	v_fmac_f32_e32 v167, v168, v141
	v_fma_f32 v140, -v140, v167, v166
	v_div_fmas_f32 v140, v140, v141, v167
	v_div_fixup_f32 v140, v140, v113, 1.0
	v_pk_fma_f32 v[140:141], v[140:141], v[136:137], v[138:139] op_sel_hi:[0,1,1] neg_lo:[0,0,1] neg_hi:[0,0,1]
	v_bfe_u32 v113, v140, 16, 1
	v_add3_u32 v113, v140, v113, s57
	v_bfe_u32 v140, v141, 16, 1
	v_lshrrev_b32_e32 v113, 16, v113
	v_add3_u32 v140, v141, v140, s57
	v_and_or_b32 v113, v140, s53, v113
	v_lshlrev_b32_e32 v140, 16, v112
	v_and_b32_e32 v141, 0xffff0000, v112
	v_cvt_f32_i32_e32 v112, s10
	v_pk_add_f32 v[164:165], v[140:141], v[164:165] neg_lo:[0,1] neg_hi:[0,1]
	s_nop 0
	v_pk_add_f32 v[136:137], v[136:137], v[164:165]
	v_div_scale_f32 v164, s[10:11], v112, v112, 1.0
	v_rcp_f32_e32 v165, v164
	s_min_u32 s10, s16, s17
	s_sub_i32 s10, s10, s18
	s_add_i32 s10, s10, 1
	v_fma_f32 v166, -v164, v165, 1.0
	v_fmac_f32_e32 v165, v166, v165
	v_div_scale_f32 v166, vcc, 1.0, v112, 1.0
	v_mul_f32_e32 v167, v166, v165
	v_fma_f32 v168, -v164, v167, v166
	v_fmac_f32_e32 v167, v168, v165
	v_fma_f32 v164, -v164, v167, v166
	v_div_fmas_f32 v164, v164, v165, v167
	v_div_fixup_f32 v112, v164, v112, 1.0
	v_pk_fma_f32 v[164:165], v[112:113], v[136:137], v[140:141] op_sel_hi:[0,1,1] neg_lo:[0,0,1] neg_hi:[0,0,1]
	v_bfe_u32 v112, v164, 16, 1
	v_add3_u32 v112, v164, v112, s57
	v_bfe_u32 v164, v165, 16, 1
	v_lshrrev_b32_e32 v112, 16, v112
	v_add3_u32 v164, v165, v164, s57
	v_and_or_b32 v112, v164, s53, v112
	v_lshlrev_b32_e32 v164, 16, v109
	v_and_b32_e32 v165, 0xffff0000, v109
	v_cvt_f32_i32_e32 v109, s10
	v_pk_add_f32 v[138:139], v[164:165], v[138:139] neg_lo:[0,1] neg_hi:[0,1]
	s_nop 0
	v_pk_add_f32 v[136:137], v[136:137], v[138:139]
	v_div_scale_f32 v138, s[10:11], v109, v109, 1.0
	v_rcp_f32_e32 v139, v138
	s_min_u32 s10, s15, s17
	s_sub_i32 s10, s10, s16
	s_add_i32 s10, s10, 1
	v_fma_f32 v166, -v138, v139, 1.0
	v_fmac_f32_e32 v139, v166, v139
	v_div_scale_f32 v166, vcc, 1.0, v109, 1.0
	v_mul_f32_e32 v167, v166, v139
	v_fma_f32 v168, -v138, v167, v166
	v_fmac_f32_e32 v167, v168, v139
	v_fma_f32 v138, -v138, v167, v166
	v_div_fmas_f32 v138, v138, v139, v167
	v_div_fixup_f32 v138, v138, v109, 1.0
	v_pk_fma_f32 v[138:139], v[138:139], v[136:137], v[164:165] op_sel_hi:[0,1,1] neg_lo:[0,0,1] neg_hi:[0,0,1]
	v_bfe_u32 v109, v138, 16, 1
	v_add3_u32 v109, v138, v109, s57
	v_bfe_u32 v138, v139, 16, 1
	v_lshrrev_b32_e32 v109, 16, v109
	v_add3_u32 v138, v139, v138, s57
	v_and_or_b32 v109, v138, s53, v109
	ds_write2st64_b32 v117, v135, v109 offset0:16 offset1:24
	v_cvt_f32_i32_e32 v117, s10
	v_lshlrev_b32_e32 v138, 16, v108
	v_and_b32_e32 v139, 0xffff0000, v108
	v_pk_add_f32 v[108:109], v[138:139], v[140:141] neg_lo:[0,1] neg_hi:[0,1]
	v_div_scale_f32 v135, s[10:11], v117, v117, 1.0
	v_pk_add_f32 v[108:109], v[136:137], v[108:109]
	v_rcp_f32_e32 v136, v135
	s_min_u32 s10, s14, s17
	s_sub_i32 s10, s10, s15
	s_add_i32 s10, s10, 1
	v_fma_f32 v137, -v135, v136, 1.0
	v_fmac_f32_e32 v136, v137, v136
	v_div_scale_f32 v137, vcc, 1.0, v117, 1.0
	v_mul_f32_e32 v140, v137, v136
	v_fma_f32 v141, -v135, v140, v137
	v_fmac_f32_e32 v140, v141, v136
	v_fma_f32 v135, -v135, v140, v137
	v_div_fmas_f32 v135, v135, v136, v140
	v_div_fixup_f32 v136, v135, v117, 1.0
	v_pk_fma_f32 v[136:137], v[136:137], v[108:109], v[138:139] op_sel_hi:[0,1,1] neg_lo:[0,0,1] neg_hi:[0,0,1]
	v_bfe_u32 v117, v136, 16, 1
	v_add3_u32 v117, v136, v117, s57
	v_bfe_u32 v135, v137, 16, 1
	v_lshrrev_b32_e32 v117, 16, v117
	v_add3_u32 v135, v137, v135, s57
	v_and_or_b32 v117, v135, s53, v117
	ds_write2st64_b32 v120, v134, v117 offset0:17 offset1:25
	v_lshlrev_b32_e32 v134, 16, v107
	v_and_b32_e32 v135, 0xffff0000, v107
	v_cvt_f32_i32_e32 v107, s10
	v_pk_add_f32 v[136:137], v[134:135], v[164:165] neg_lo:[0,1] neg_hi:[0,1]
	v_div_scale_f32 v117, s[10:11], v107, v107, 1.0
	v_rcp_f32_e32 v120, v117
	v_pk_add_f32 v[108:109], v[108:109], v[136:137]
	s_min_u32 s10, s3, s17
	s_sub_i32 s10, s10, s14
	v_fma_f32 v136, -v117, v120, 1.0
	v_fmac_f32_e32 v120, v136, v120
	v_div_scale_f32 v136, vcc, 1.0, v107, 1.0
	v_mul_f32_e32 v137, v136, v120
	v_fma_f32 v140, -v117, v137, v136
	v_fmac_f32_e32 v137, v140, v120
	v_fma_f32 v117, -v117, v137, v136
	v_div_fmas_f32 v117, v117, v120, v137
	v_div_fixup_f32 v120, v117, v107, 1.0
	v_pk_fma_f32 v[136:137], v[120:121], v[108:109], v[134:135] op_sel_hi:[0,1,1] neg_lo:[0,0,1] neg_hi:[0,0,1]
	v_bfe_u32 v107, v136, 16, 1
	v_add3_u32 v107, v136, v107, s57
	v_bfe_u32 v117, v137, 16, 1
	v_lshrrev_b32_e32 v107, 16, v107
	v_add3_u32 v117, v137, v117, s57
	v_and_or_b32 v107, v117, s53, v107
	ds_write2st64_b32 v121, v133, v107 offset0:18 offset1:26
	v_lshlrev_b32_e32 v120, 16, v106
	v_and_b32_e32 v121, 0xffff0000, v106
	v_pk_add_f32 v[106:107], v[120:121], v[138:139] neg_lo:[0,1] neg_hi:[0,1]
	s_add_i32 s10, s10, 1
	v_pk_add_f32 v[106:107], v[108:109], v[106:107]
	v_cvt_f32_i32_e32 v108, s10
	v_div_scale_f32 v109, s[10:11], v108, v108, 1.0
	v_rcp_f32_e32 v117, v109
	s_min_u32 s10, s2, s17
	s_sub_i32 s3, s10, s3
	s_add_i32 s3, s3, 1
	v_fma_f32 v133, -v109, v117, 1.0
	v_fmac_f32_e32 v117, v133, v117
	v_div_scale_f32 v133, vcc, 1.0, v108, 1.0
	v_mul_f32_e32 v136, v133, v117
	v_fma_f32 v137, -v109, v136, v133
	v_fmac_f32_e32 v136, v137, v117
	v_fma_f32 v109, -v109, v136, v133
	v_div_fmas_f32 v109, v109, v117, v136
	v_div_fixup_f32 v108, v109, v108, 1.0
	v_pk_fma_f32 v[108:109], v[108:109], v[106:107], v[120:121] op_sel_hi:[0,1,1] neg_lo:[0,0,1] neg_hi:[0,0,1]
	v_bfe_u32 v117, v108, 16, 1
	v_add3_u32 v108, v108, v117, s57
	v_bfe_u32 v117, v109, 16, 1
	v_lshrrev_b32_e32 v108, 16, v108
	v_add3_u32 v109, v109, v117, s57
	v_and_or_b32 v108, v109, s53, v108
	ds_write2st64_b32 v124, v132, v108 offset0:19 offset1:27
	v_lshlrev_b32_e32 v108, 16, v105
	v_and_b32_e32 v109, 0xffff0000, v105
	v_cvt_f32_i32_e32 v105, s3
	v_pk_add_f32 v[132:133], v[108:109], v[134:135] neg_lo:[0,1] neg_hi:[0,1]
	s_min_u32 s3, s1, s17
	v_pk_add_f32 v[106:107], v[106:107], v[132:133]
	v_div_scale_f32 v117, s[10:11], v105, v105, 1.0
	v_rcp_f32_e32 v124, v117
	s_sub_i32 s2, s3, s2
	s_add_i32 s2, s2, 1
	v_fma_f32 v132, -v117, v124, 1.0
	v_fmac_f32_e32 v124, v132, v124
	v_div_scale_f32 v132, vcc, 1.0, v105, 1.0
	v_mul_f32_e32 v133, v132, v124
	v_fma_f32 v134, -v117, v133, v132
	v_fmac_f32_e32 v133, v134, v124
	v_fma_f32 v117, -v117, v133, v132
	v_div_fmas_f32 v117, v117, v124, v133
	v_div_fixup_f32 v124, v117, v105, 1.0
	v_pk_fma_f32 v[132:133], v[124:125], v[106:107], v[108:109] op_sel_hi:[0,1,1] neg_lo:[0,0,1] neg_hi:[0,0,1]
	v_bfe_u32 v105, v132, 16, 1
	v_add3_u32 v105, v132, v105, s57
	v_bfe_u32 v117, v133, 16, 1
	v_lshrrev_b32_e32 v105, 16, v105
	v_add3_u32 v117, v133, v117, s57
	v_and_or_b32 v105, v117, s53, v105
	ds_write2st64_b32 v125, v131, v105 offset0:20 offset1:28
	v_lshlrev_b32_e32 v124, 16, v104
	v_and_b32_e32 v125, 0xffff0000, v104
	v_pk_add_f32 v[104:105], v[124:125], v[120:121] neg_lo:[0,1] neg_hi:[0,1]
	s_nop 0
	v_pk_add_f32 v[104:105], v[106:107], v[104:105]
	v_cvt_f32_i32_e32 v106, s2
	v_div_scale_f32 v107, s[2:3], v106, v106, 1.0
	v_rcp_f32_e32 v117, v107
	s_min_u32 s2, s0, s17
	s_sub_i32 s1, s2, s1
	s_add_i32 s1, s1, 1
	v_fma_f32 v120, -v107, v117, 1.0
	v_fmac_f32_e32 v117, v120, v117
	v_div_scale_f32 v120, vcc, 1.0, v106, 1.0
	v_mul_f32_e32 v121, v120, v117
	v_fma_f32 v131, -v107, v121, v120
	v_fmac_f32_e32 v121, v131, v117
	v_fma_f32 v107, -v107, v121, v120
	v_div_fmas_f32 v107, v107, v117, v121
	v_div_fixup_f32 v106, v107, v106, 1.0
	v_pk_fma_f32 v[106:107], v[106:107], v[104:105], v[124:125] op_sel_hi:[0,1,1] neg_lo:[0,0,1] neg_hi:[0,0,1]
	v_bfe_u32 v117, v106, 16, 1
	v_add3_u32 v106, v106, v117, s57
	v_bfe_u32 v117, v107, 16, 1
	v_lshrrev_b32_e32 v106, 16, v106
	v_add3_u32 v107, v107, v117, s57
	v_and_or_b32 v106, v107, s53, v106
	ds_write2st64_b32 v128, v130, v106 offset0:21 offset1:29
	v_lshlrev_b32_e32 v106, 16, v101
	v_and_b32_e32 v107, 0xffff0000, v101
	v_cvt_f32_i32_e32 v101, s1
	v_pk_add_f32 v[108:109], v[106:107], v[108:109] neg_lo:[0,1] neg_hi:[0,1]
	s_min_u32 s1, s38, s17
	v_pk_add_f32 v[104:105], v[104:105], v[108:109]
	v_div_scale_f32 v108, s[2:3], v101, v101, 1.0
	v_rcp_f32_e32 v109, v108
	s_sub_i32 s0, s1, s0
	s_add_i32 s0, s0, 1
	v_fma_f32 v117, -v108, v109, 1.0
	v_fmac_f32_e32 v109, v117, v109
	v_div_scale_f32 v117, vcc, 1.0, v101, 1.0
	v_mul_f32_e32 v120, v117, v109
	v_fma_f32 v121, -v108, v120, v117
	v_fmac_f32_e32 v120, v121, v109
	v_fma_f32 v108, -v108, v120, v117
	v_div_fmas_f32 v108, v108, v109, v120
	v_div_fixup_f32 v108, v108, v101, 1.0
	v_pk_fma_f32 v[106:107], v[108:109], v[104:105], v[106:107] op_sel_hi:[0,1,1] neg_lo:[0,0,1] neg_hi:[0,0,1]
	v_bfe_u32 v101, v106, 16, 1
	v_add3_u32 v101, v106, v101, s57
	v_bfe_u32 v106, v107, 16, 1
	v_lshrrev_b32_e32 v101, 16, v101
	v_add3_u32 v106, v107, v106, s57
	v_and_or_b32 v101, v106, s53, v101
	v_lshlrev_b32_e32 v106, 16, v100
	v_and_b32_e32 v107, 0xffff0000, v100
	ds_write2st64_b32 v129, v113, v101 offset0:22 offset1:30
	v_pk_add_f32 v[100:101], v[106:107], v[124:125] neg_lo:[0,1] neg_hi:[0,1]
	s_nop 0
	v_pk_add_f32 v[100:101], v[104:105], v[100:101]
	v_cvt_f32_i32_e32 v104, s0
	v_div_scale_f32 v105, s[0:1], v104, v104, 1.0
	v_rcp_f32_e32 v108, v105
	s_mov_b64 s[0:1], 0xc0
	v_lshl_add_u64 v[128:129], v[98:99], 0, s[0:1]
	v_fma_f32 v109, -v105, v108, 1.0
	v_fmac_f32_e32 v108, v109, v108
	v_div_scale_f32 v109, vcc, 1.0, v104, 1.0
	v_mul_f32_e32 v113, v109, v108
	v_fma_f32 v117, -v105, v113, v109
	v_fmac_f32_e32 v113, v117, v108
	v_fma_f32 v105, -v105, v113, v109
	v_div_fmas_f32 v105, v105, v108, v113
	v_div_fixup_f32 v104, v105, v104, 1.0
	v_pk_fma_f32 v[100:101], v[104:105], v[100:101], v[106:107] op_sel_hi:[0,1,1] neg_lo:[0,0,1] neg_hi:[0,0,1]
	v_bfe_u32 v104, v100, 16, 1
	v_add3_u32 v100, v100, v104, s57
	v_bfe_u32 v104, v101, 16, 1
	v_lshrrev_b32_e32 v100, 16, v100
	v_add3_u32 v101, v101, v104, s57
	v_and_or_b32 v100, v101, s53, v100
	ds_write2st64_b32 v116, v112, v100 offset0:23 offset1:31
	v_lshl_add_u64 v[100:101], v[98:99], 0, s[42:43]
	v_lshl_add_u64 v[104:105], v[100:101], 0, v[202:203]
	s_waitcnt lgkmcnt(0)
	global_load_dwordx4 v[130:133], v[102:103], off offset:128
	global_load_dwordx4 v[134:137], v[102:103], off offset:1152
	global_load_dwordx4 v[138:141], v[104:105], off
	v_lshl_add_u64 v[104:105], v[100:101], 0, v[110:111]
	global_load_dwordx4 v[164:167], v[104:105], off
	v_lshl_add_u64 v[104:105], v[100:101], 0, v[114:115]
	global_load_dwordx4 v[168:171], v[104:105], off
	v_lshl_add_u64 v[104:105], v[100:101], 0, v[118:119]
	global_load_dwordx4 v[172:175], v[104:105], off
	v_lshl_add_u64 v[104:105], v[100:101], 0, v[122:123]
	v_lshl_add_u64 v[100:101], v[100:101], 0, v[126:127]
	global_load_dwordx4 v[182:185], v[104:105], off
	global_load_dwordx4 v[186:189], v[100:101], off
	s_nop 0
	global_load_dwordx4 v[98:101], v[102:103], off offset:192
	s_nop 0
	global_load_dwordx4 v[102:105], v[102:103], off offset:1216
	v_lshl_add_u64 v[106:107], v[128:129], 0, v[202:203]
	v_lshl_add_u64 v[110:111], v[128:129], 0, v[110:111]
	v_lshl_add_u64 v[114:115], v[128:129], 0, v[114:115]
	v_lshl_add_u64 v[118:119], v[128:129], 0, v[118:119]
	v_lshl_add_u64 v[122:123], v[128:129], 0, v[122:123]
	v_lshl_add_u64 v[126:127], v[128:129], 0, v[126:127]
	global_load_dwordx4 v[106:109], v[106:107], off
	s_nop 0
	global_load_dwordx4 v[110:113], v[110:111], off
	s_nop 0
	global_load_dwordx4 v[114:117], v[114:115], off
	s_nop 0
	global_load_dwordx4 v[118:121], v[118:119], off
	s_nop 0
	global_load_dwordx4 v[122:125], v[122:123], off
	s_nop 0
	global_load_dwordx4 v[126:129], v[126:127], off
	v_add_u32_e32 v194, v177, v178
	ds_read_b128 v[190:193], v194
	ds_read_b128 v[194:197], v194 offset:4096
	v_add_u32_e32 v202, v177, v179
	s_waitcnt vmcnt(25) lgkmcnt(1)
	v_mfma_f32_16x16x32_bf16 v[198:201], v[90:93], v[190:193], 0
	s_waitcnt vmcnt(23)
	v_mfma_f32_16x16x32_bf16 v[226:229], v[94:97], v[190:193], 0
	v_mfma_f32_16x16x32_bf16 v[230:233], v[66:69], v[190:193], 0
	v_mfma_f32_16x16x32_bf16 v[234:237], v[70:73], v[190:193], 0
	v_mfma_f32_16x16x32_bf16 v[238:241], v[74:77], v[190:193], 0
	v_mfma_f32_16x16x32_bf16 v[242:245], v[78:81], v[190:193], 0
	v_mfma_f32_16x16x32_bf16 v[246:249], v[82:85], v[190:193], 0
	v_mfma_f32_16x16x32_bf16 v[190:193], v[86:89], v[190:193], 0
	s_waitcnt lgkmcnt(0)
	v_mfma_f32_16x16x32_bf16 v[90:93], v[90:93], v[194:197], 0
	v_mfma_f32_16x16x32_bf16 v[94:97], v[94:97], v[194:197], 0
	v_mfma_f32_16x16x32_bf16 v[66:69], v[66:69], v[194:197], 0
	v_mfma_f32_16x16x32_bf16 v[70:73], v[70:73], v[194:197], 0
	v_mfma_f32_16x16x32_bf16 v[74:77], v[74:77], v[194:197], 0
	v_mfma_f32_16x16x32_bf16 v[78:81], v[78:81], v[194:197], 0
	v_mfma_f32_16x16x32_bf16 v[82:85], v[82:85], v[194:197], 0
	v_mfma_f32_16x16x32_bf16 v[86:89], v[86:89], v[194:197], 0
	ds_read_b128 v[194:197], v202
	ds_read_b128 v[250:253], v202 offset:4096
	s_waitcnt vmcnt(20) lgkmcnt(1)
	v_mfma_f32_16x16x32_bf16 v[234:237], v[46:49], v[194:197], v[234:237]
	s_waitcnt lgkmcnt(0)
	v_mfma_f32_16x16x32_bf16 v[46:49], v[46:49], v[250:253], v[70:73]
	s_nop 2
	v_add_u32_e32 v70, v177, v180
	v_mfma_f32_16x16x32_bf16 v[230:233], v[42:45], v[194:197], v[230:233]
	v_mfma_f32_16x16x32_bf16 v[42:45], v[42:45], v[250:253], v[66:69]
	s_nop 2
	ds_read_b128 v[66:69], v70
	ds_read_b128 v[70:73], v70 offset:4096
	v_mfma_f32_16x16x32_bf16 v[226:229], v[38:41], v[194:197], v[226:229]
	v_mfma_f32_16x16x32_bf16 v[38:41], v[38:41], v[250:253], v[94:97]
	v_mfma_f32_16x16x32_bf16 v[198:201], v[34:37], v[194:197], v[198:201]
	s_waitcnt vmcnt(18)
	v_mfma_f32_16x16x32_bf16 v[242:245], v[54:57], v[194:197], v[242:245]
	v_mfma_f32_16x16x32_bf16 v[34:37], v[34:37], v[250:253], v[90:93]
	v_mfma_f32_16x16x32_bf16 v[54:57], v[54:57], v[250:253], v[78:81]
	v_mfma_f32_16x16x32_bf16 v[238:241], v[50:53], v[194:197], v[238:241]
	s_waitcnt vmcnt(14) lgkmcnt(1)
	v_mfma_f32_16x16x32_bf16 v[78:81], v[134:137], v[66:69], v[226:229]
	s_waitcnt lgkmcnt(0)
	v_mfma_f32_16x16x32_bf16 v[38:41], v[134:137], v[70:73], v[38:41]
	s_waitcnt vmcnt(12)
	v_mfma_f32_16x16x32_bf16 v[134:137], v[164:167], v[70:73], v[46:49]
	s_nop 2
	v_add_u32_e32 v46, v177, v181
	v_mfma_f32_16x16x32_bf16 v[246:249], v[58:61], v[194:197], v[246:249]
	v_mfma_f32_16x16x32_bf16 v[50:53], v[50:53], v[250:253], v[74:77]
	v_mfma_f32_16x16x32_bf16 v[58:61], v[58:61], v[250:253], v[82:85]
	v_mfma_f32_16x16x32_bf16 v[74:77], v[130:133], v[66:69], v[198:201]
	v_mfma_f32_16x16x32_bf16 v[82:85], v[138:141], v[66:69], v[230:233]
	s_waitcnt vmcnt(10)
	v_mfma_f32_16x16x32_bf16 v[94:97], v[172:175], v[66:69], v[242:245]
	v_mfma_f32_16x16x32_bf16 v[34:37], v[130:133], v[70:73], v[34:37]
	v_mfma_f32_16x16x32_bf16 v[130:133], v[138:141], v[70:73], v[42:45]
	v_mfma_f32_16x16x32_bf16 v[138:141], v[172:175], v[70:73], v[54:57]
	s_nop 1
	ds_read_b128 v[42:45], v46
	ds_read_b128 v[172:175], v46 offset:4096
	v_mfma_f32_16x16x32_bf16 v[190:193], v[62:65], v[194:197], v[190:193]
	v_mfma_f32_16x16x32_bf16 v[62:65], v[62:65], v[250:253], v[86:89]
	v_mfma_f32_16x16x32_bf16 v[86:89], v[164:167], v[66:69], v[234:237]
	v_mfma_f32_16x16x32_bf16 v[90:93], v[168:171], v[66:69], v[238:241]
	s_waitcnt vmcnt(9)
	v_mfma_f32_16x16x32_bf16 v[194:197], v[182:185], v[66:69], v[246:249]
	s_waitcnt vmcnt(8)
	v_mfma_f32_16x16x32_bf16 v[66:69], v[186:189], v[66:69], v[190:193]
	v_mfma_f32_16x16x32_bf16 v[50:53], v[168:171], v[70:73], v[50:53]
	v_mfma_f32_16x16x32_bf16 v[164:167], v[182:185], v[70:73], v[58:61]
	v_mfma_f32_16x16x32_bf16 v[168:171], v[186:189], v[70:73], v[62:65]
	s_waitcnt vmcnt(7) lgkmcnt(1)
	v_mfma_f32_16x16x32_bf16 v[182:185], v[98:101], v[42:45], v[74:77]
	s_waitcnt vmcnt(6)
	v_mfma_f32_16x16x32_bf16 v[186:189], v[102:105], v[42:45], v[78:81]
	s_waitcnt vmcnt(5)
	v_mfma_f32_16x16x32_bf16 v[78:81], v[106:109], v[42:45], v[82:85]
	s_waitcnt vmcnt(4)
	v_mfma_f32_16x16x32_bf16 v[74:77], v[110:113], v[42:45], v[86:89]
	s_waitcnt lgkmcnt(0)
	v_mfma_f32_16x16x32_bf16 v[84:87], v[98:101], v[172:175], v[34:37]
	s_nop 1
	v_mul_f32_e64 v98, v26, v186
	v_mul_f32_e64 v99, v27, v187
	v_add_u32_e32 v100, s35, v143
	s_nop 0
	v_pk_mul_f32 v[74:75], v[18:19], v[74:75]
	s_waitcnt vmcnt(3)
	v_mfma_f32_16x16x32_bf16 v[62:65], v[114:117], v[42:45], v[90:93]
	v_add_u32_e32 v82, 8, v100
	v_mfma_f32_16x16x32_bf16 v[88:91], v[102:105], v[172:175], v[38:41]
	s_nop 0
	v_mul_f32_e64 v92, v30, v182
	v_mul_f32_e64 v93, v31, v183
	v_pk_mul_f32 v[30:31], v[30:31], v[84:85]
	v_bfe_u32 v83, v92, 16, 1
	s_waitcnt vmcnt(2)
	v_mfma_f32_16x16x32_bf16 v[58:61], v[118:121], v[42:45], v[94:97]
	v_add3_u32 v83, v92, v83, s57
	v_pk_mul_f32 v[84:85], v[28:29], v[90:91]
	v_pk_mul_f32 v[26:27], v[26:27], v[88:89]
	v_pk_mul_f32 v[96:97], v[28:29], v[188:189]
	v_bfe_u32 v28, v30, 16, 1
	v_add3_u32 v28, v30, v28, s57
	v_bfe_u32 v29, v31, 16, 1
	v_pk_mul_f32 v[94:95], v[32:33], v[184:185]
	v_pk_mul_f32 v[32:33], v[32:33], v[86:87]
	v_lshrrev_b32_e32 v28, 16, v28
	v_add3_u32 v29, v31, v29, s57
	v_and_or_b32 v28, v29, s53, v28
	v_bfe_u32 v29, v32, 16, 1
	v_add3_u32 v29, v32, v29, s57
	v_bfe_u32 v30, v33, 16, 1
	v_lshrrev_b32_e32 v29, 16, v29
	v_add3_u32 v30, v33, v30, s57
	v_and_or_b32 v29, v30, s53, v29
	v_bfe_u32 v30, v26, 16, 1
	v_add3_u32 v26, v26, v30, s57
	v_bfe_u32 v30, v27, 16, 1
	v_lshrrev_b32_e32 v26, 16, v26
	v_add3_u32 v27, v27, v30, s57
	v_and_or_b32 v30, v27, s53, v26
	v_bfe_u32 v26, v84, 16, 1
	v_add3_u32 v26, v84, v26, s57
	v_bfe_u32 v27, v85, 16, 1
	v_lshrrev_b32_e32 v26, 16, v26
	v_add3_u32 v27, v85, v27, s57
	v_and_or_b32 v31, v27, s53, v26
	v_add_u32_e32 v26, 24, v100
	v_ashrrev_i32_e32 v27, 31, v26
	v_lshlrev_b64 v[26:27], 12, v[26:27]
	v_lshl_add_u64 v[26:27], v[162:163], 0, v[26:27]
	v_bfe_u32 v92, v93, 16, 1
	global_store_dwordx4 v[26:27], v[28:31], off offset:2048 sc1
	v_lshrrev_b32_e32 v83, 16, v83
	v_add3_u32 v92, v93, v92, s57
	v_pk_mul_f32 v[28:29], v[22:23], v[78:79]
	v_pk_mul_f32 v[32:33], v[20:21], v[76:77]
	v_bfe_u32 v76, v28, 16, 1
	v_and_or_b32 v92, v92, s53, v83
	v_bfe_u32 v83, v94, 16, 1
	v_add3_u32 v28, v28, v76, s57
	v_bfe_u32 v76, v29, 16, 1
	v_add3_u32 v83, v94, v83, s57
	v_bfe_u32 v93, v95, 16, 1
	v_pk_mul_f32 v[30:31], v[24:25], v[80:81]
	v_lshrrev_b32_e32 v28, 16, v28
	v_add3_u32 v29, v29, v76, s57
	v_lshrrev_b32_e32 v83, 16, v83
	v_add3_u32 v93, v95, v93, s57
	v_and_or_b32 v28, v29, s53, v28
	v_bfe_u32 v29, v30, 16, 1
	v_and_or_b32 v93, v93, s53, v83
	v_bfe_u32 v83, v98, 16, 1
	v_add3_u32 v29, v30, v29, s57
	v_bfe_u32 v30, v31, 16, 1
	v_add3_u32 v83, v98, v83, s57
	v_bfe_u32 v94, v99, 16, 1
	v_lshrrev_b32_e32 v29, 16, v29
	v_add3_u32 v30, v31, v30, s57
	v_lshrrev_b32_e32 v83, 16, v83
	v_add3_u32 v94, v99, v94, s57
	v_and_or_b32 v29, v30, s53, v29
	v_bfe_u32 v30, v74, 16, 1
	v_and_or_b32 v94, v94, s53, v83
	v_bfe_u32 v83, v96, 16, 1
	v_add3_u32 v30, v74, v30, s57
	v_bfe_u32 v31, v75, 16, 1
	v_mfma_f32_16x16x32_bf16 v[70:73], v[106:109], v[172:175], v[130:133]
	v_add3_u32 v83, v96, v83, s57
	v_bfe_u32 v95, v97, 16, 1
	v_lshrrev_b32_e32 v30, 16, v30
	v_add3_u32 v31, v75, v31, s57
	s_waitcnt vmcnt(2)
	v_mfma_f32_16x16x32_bf16 v[46:49], v[122:125], v[42:45], v[194:197]
	v_lshrrev_b32_e32 v83, 16, v83
	v_add3_u32 v95, v97, v95, s57
	v_and_or_b32 v30, v31, s53, v30
	s_waitcnt vmcnt(1)
	v_mfma_f32_16x16x32_bf16 v[42:45], v[126:129], v[42:45], v[66:69]
	v_bfe_u32 v31, v32, 16, 1
	v_and_or_b32 v95, v95, s53, v83
	v_ashrrev_i32_e32 v83, 31, v82
	v_mfma_f32_16x16x32_bf16 v[66:69], v[110:113], v[172:175], v[134:137]
	v_add3_u32 v31, v32, v31, s57
	v_bfe_u32 v32, v33, 16, 1
	v_lshlrev_b64 v[82:83], 12, v[82:83]
	v_lshrrev_b32_e32 v31, 16, v31
	v_add3_u32 v32, v33, v32, s57
	v_lshl_add_u64 v[82:83], v[162:163], 0, v[82:83]
	v_and_or_b32 v31, v32, s53, v31
	v_pk_mul_f32 v[22:23], v[22:23], v[70:71]
	global_store_dwordx4 v[82:83], v[28:31], off offset:2112 sc1
	v_pk_mul_f32 v[24:25], v[24:25], v[72:73]
	v_mfma_f32_16x16x32_bf16 v[54:57], v[114:117], v[172:175], v[50:53]
	v_mul_f32_e64 v28, v20, v68
	v_mul_f32_e64 v29, v21, v69
	v_pk_mul_f32 v[20:21], v[18:19], v[66:67]
	v_bfe_u32 v18, v22, 16, 1
	v_add3_u32 v18, v22, v18, s57
	v_bfe_u32 v19, v23, 16, 1
	v_lshrrev_b32_e32 v18, 16, v18
	v_add3_u32 v19, v23, v19, s57
	v_and_or_b32 v18, v19, s53, v18
	v_bfe_u32 v19, v24, 16, 1
	v_add3_u32 v19, v24, v19, s57
	v_bfe_u32 v22, v25, 16, 1
	v_lshrrev_b32_e32 v19, 16, v19
	v_add3_u32 v22, v25, v22, s57
	v_and_or_b32 v19, v22, s53, v19
	v_bfe_u32 v22, v20, 16, 1
	v_add3_u32 v20, v20, v22, s57
	v_bfe_u32 v22, v21, 16, 1
	v_lshrrev_b32_e32 v20, 16, v20
	v_add3_u32 v21, v21, v22, s57
	v_and_or_b32 v20, v21, s53, v20
	v_bfe_u32 v21, v28, 16, 1
	v_add3_u32 v21, v28, v21, s57
	v_bfe_u32 v22, v29, 16, 1
	v_lshrrev_b32_e32 v21, 16, v21
	v_add3_u32 v22, v29, v22, s57
	v_and_or_b32 v21, v22, s53, v21
	global_store_dwordx4 v[26:27], v[18:21], off offset:2112 sc1
	v_pk_mul_f32 v[24:25], v[10:11], v[58:59]
	v_pk_mul_f32 v[22:23], v[12:13], v[60:61]
	v_pk_mul_f32 v[18:19], v[14:15], v[62:63]
	v_pk_mul_f32 v[20:21], v[16:17], v[64:65]
	v_bfe_u32 v28, v18, 16, 1
	v_add3_u32 v18, v18, v28, s57
	v_bfe_u32 v28, v19, 16, 1
	v_lshrrev_b32_e32 v18, 16, v18
	v_add3_u32 v19, v19, v28, s57
	v_and_or_b32 v18, v19, s53, v18
	v_bfe_u32 v19, v20, 16, 1
	v_add3_u32 v19, v20, v19, s57
	v_bfe_u32 v20, v21, 16, 1
	v_lshrrev_b32_e32 v19, 16, v19
	v_add3_u32 v20, v21, v20, s57
	v_and_or_b32 v19, v20, s53, v19
	v_bfe_u32 v20, v24, 16, 1
	v_add3_u32 v20, v24, v20, s57
	v_bfe_u32 v21, v25, 16, 1
	v_lshrrev_b32_e32 v20, 16, v20
	v_add3_u32 v21, v25, v21, s57
	v_mfma_f32_16x16x32_bf16 v[50:53], v[118:121], v[172:175], v[138:141]
	v_and_or_b32 v20, v21, s53, v20
	v_bfe_u32 v21, v22, 16, 1
	v_add3_u32 v21, v22, v21, s57
	v_bfe_u32 v22, v23, 16, 1
	v_lshrrev_b32_e32 v21, 16, v21
	v_add3_u32 v22, v23, v22, s57
	v_and_or_b32 v21, v22, s53, v21
	v_pk_mul_f32 v[14:15], v[14:15], v[54:55]
	global_store_dwordx4 v[82:83], v[18:21], off offset:2176 sc1
	v_pk_mul_f32 v[16:17], v[16:17], v[56:57]
	v_mfma_f32_16x16x32_bf16 v[38:41], v[122:125], v[172:175], v[164:167]
	v_mul_f32_e64 v18, v12, v52
	v_mul_f32_e64 v19, v13, v53
	v_pk_mul_f32 v[12:13], v[10:11], v[50:51]
	v_bfe_u32 v10, v14, 16, 1
	v_add3_u32 v10, v14, v10, s57
	v_bfe_u32 v11, v15, 16, 1
	v_lshrrev_b32_e32 v10, 16, v10
	v_add3_u32 v11, v15, v11, s57
	v_and_or_b32 v10, v11, s53, v10
	v_bfe_u32 v11, v16, 16, 1
	v_add3_u32 v11, v16, v11, s57
	v_bfe_u32 v14, v17, 16, 1
	v_lshrrev_b32_e32 v11, 16, v11
	v_add3_u32 v14, v17, v14, s57
	v_and_or_b32 v11, v14, s53, v11
	v_bfe_u32 v14, v12, 16, 1
	v_add3_u32 v12, v12, v14, s57
	v_bfe_u32 v14, v13, 16, 1
	v_lshrrev_b32_e32 v12, 16, v12
	v_add3_u32 v13, v13, v14, s57
	v_and_or_b32 v12, v13, s53, v12
	v_bfe_u32 v13, v18, 16, 1
	v_add3_u32 v13, v18, v13, s57
	v_bfe_u32 v14, v19, 16, 1
	v_lshrrev_b32_e32 v13, 16, v13
	v_add3_u32 v14, v19, v14, s57
	v_and_or_b32 v13, v14, s53, v13
	global_store_dwordx4 v[26:27], v[10:13], off offset:2176 sc1
	v_pk_mul_f32 v[16:17], v[2:3], v[42:43]
	v_pk_mul_f32 v[14:15], v[4:5], v[44:45]
	v_pk_mul_f32 v[10:11], v[6:7], v[46:47]
	v_pk_mul_f32 v[12:13], v[8:9], v[48:49]
	v_bfe_u32 v18, v10, 16, 1
	v_add3_u32 v10, v10, v18, s57
	v_bfe_u32 v18, v11, 16, 1
	v_lshrrev_b32_e32 v10, 16, v10
	v_add3_u32 v11, v11, v18, s57
	v_and_or_b32 v10, v11, s53, v10
	v_bfe_u32 v11, v12, 16, 1
	v_add3_u32 v11, v12, v11, s57
	v_bfe_u32 v12, v13, 16, 1
	v_lshrrev_b32_e32 v11, 16, v11
	v_add3_u32 v12, v13, v12, s57
	v_and_or_b32 v11, v12, s53, v11
	v_bfe_u32 v12, v16, 16, 1
	v_add3_u32 v12, v16, v12, s57
	v_bfe_u32 v13, v17, 16, 1
	v_lshrrev_b32_e32 v12, 16, v12
	v_add3_u32 v13, v17, v13, s57
	v_mfma_f32_16x16x32_bf16 v[34:37], v[126:129], v[172:175], v[168:171]
	v_and_or_b32 v12, v13, s53, v12
	v_bfe_u32 v13, v14, 16, 1
	v_add3_u32 v13, v14, v13, s57
	v_bfe_u32 v14, v15, 16, 1
	v_lshrrev_b32_e32 v13, 16, v13
	v_add3_u32 v14, v15, v14, s57
	v_and_or_b32 v13, v14, s53, v13
	v_pk_mul_f32 v[6:7], v[6:7], v[38:39]
	global_store_dwordx4 v[82:83], v[10:13], off offset:2240 sc1
	v_pk_mul_f32 v[8:9], v[8:9], v[40:41]
	global_store_dwordx4 v[82:83], v[92:95], off offset:2048 sc1
	v_pk_mul_f32 v[10:11], v[4:5], v[36:37]
	v_pk_mul_f32 v[4:5], v[2:3], v[34:35]
	v_bfe_u32 v2, v6, 16, 1
	v_add3_u32 v2, v6, v2, s57
	v_bfe_u32 v3, v7, 16, 1
	v_lshrrev_b32_e32 v2, 16, v2
	v_add3_u32 v3, v7, v3, s57
	v_and_or_b32 v2, v3, s53, v2
	v_bfe_u32 v3, v8, 16, 1
	v_add3_u32 v3, v8, v3, s57
	v_bfe_u32 v6, v9, 16, 1
	v_lshrrev_b32_e32 v3, 16, v3
	v_add3_u32 v6, v9, v6, s57
	v_and_or_b32 v3, v6, s53, v3
	v_bfe_u32 v6, v4, 16, 1
	v_add3_u32 v4, v4, v6, s57
	v_bfe_u32 v6, v5, 16, 1
	v_lshrrev_b32_e32 v4, 16, v4
	v_add3_u32 v5, v5, v6, s57
	v_and_or_b32 v4, v5, s53, v4
	v_bfe_u32 v5, v10, 16, 1
	v_add3_u32 v5, v10, v5, s57
	v_bfe_u32 v6, v11, 16, 1
	v_lshrrev_b32_e32 v5, 16, v5
	v_add3_u32 v6, v11, v6, s57
	v_and_or_b32 v5, v6, s53, v5
	global_store_dwordx4 v[26:27], v[2:5], off offset:2240 sc1
	s_waitcnt lgkmcnt(0)

.LBB0_601:
	v_lshlrev_b32_e32 v202, 1, v144
	v_lshlrev_b32_e32 v6, 2, v142
	v_lshl_add_u64 v[98:99], s[10:11], 0, v[202:203]
	v_lshlrev_b32_e32 v202, 1, v146
	global_load_dwordx4 v[26:29], v6, s[12:13] offset:16
	global_load_dwordx4 v[30:33], v6, s[12:13]
	global_load_dwordx4 v[18:21], v6, s[12:13] offset:144
	global_load_dwordx4 v[22:25], v6, s[12:13] offset:128
	global_load_dwordx4 v[10:13], v6, s[12:13] offset:272
	global_load_dwordx4 v[14:17], v6, s[12:13] offset:256
	global_load_dwordx4 v[2:5], v6, s[12:13] offset:400
	s_nop 0
	global_load_dwordx4 v[6:9], v6, s[12:13] offset:384
	v_lshl_add_u64 v[102:103], v[98:99], 0, v[202:203]
	v_lshlrev_b32_e32 v202, 1, v148
	v_lshlrev_b32_e32 v110, 1, v150
	v_mov_b32_e32 v111, v203
	v_lshl_add_u64 v[34:35], v[98:99], 0, v[202:203]
	v_lshl_add_u64 v[36:37], v[98:99], 0, v[110:111]
	v_lshlrev_b32_e32 v114, 1, v152
	v_mov_b32_e32 v115, v203
	v_lshlrev_b32_e32 v118, 1, v154
	v_mov_b32_e32 v119, v203
	global_load_dwordx4 v[66:69], v[34:35], off
	global_load_dwordx4 v[70:73], v[36:37], off
	v_lshl_add_u64 v[34:35], v[98:99], 0, v[114:115]
	v_lshl_add_u64 v[36:37], v[98:99], 0, v[118:119]
	v_lshlrev_b32_e32 v122, 1, v156
	v_mov_b32_e32 v123, v203
	v_lshlrev_b32_e32 v126, 1, v158
	v_mov_b32_e32 v127, v203
	global_load_dwordx4 v[74:77], v[34:35], off
	global_load_dwordx4 v[78:81], v[36:37], off
	v_lshl_add_u64 v[34:35], v[98:99], 0, v[122:123]
	v_lshl_add_u64 v[36:37], v[98:99], 0, v[126:127]
	global_load_dwordx4 v[82:85], v[34:35], off
	global_load_dwordx4 v[86:89], v[36:37], off
	v_lshl_add_u64 v[58:59], v[98:99], 0, 64
	global_load_dwordx4 v[90:93], v[102:103], off
	global_load_dwordx4 v[34:37], v[102:103], off offset:64
	global_load_dwordx4 v[94:97], v[102:103], off offset:1024
	global_load_dwordx4 v[38:41], v[102:103], off offset:1088
	v_lshl_add_u64 v[42:43], v[58:59], 0, v[202:203]
	v_lshl_add_u64 v[46:47], v[58:59], 0, v[110:111]
	v_lshl_add_u64 v[50:51], v[58:59], 0, v[114:115]
	v_lshl_add_u64 v[54:55], v[58:59], 0, v[118:119]
	v_lshl_add_u64 v[60:61], v[58:59], 0, v[122:123]
	v_lshl_add_u64 v[62:63], v[58:59], 0, v[126:127]
	global_load_dwordx4 v[42:45], v[42:43], off
	s_nop 0
	global_load_dwordx4 v[46:49], v[46:47], off
	s_nop 0
	global_load_dwordx4 v[50:53], v[50:51], off
	s_nop 0
	global_load_dwordx4 v[54:57], v[54:55], off
	s_nop 0
	global_load_dwordx4 v[58:61], v[60:61], off
	s_nop 0
	global_load_dwordx4 v[62:65], v[62:63], off
	s_waitcnt vmcnt(24)
	v_lshlrev_b32_e32 v182, 16, v101
	v_and_b32_e32 v183, 0xffff0000, v101
	v_pk_add_f32 v[108:109], v[182:183], 0 op_sel_hi:[1,0]
	v_lshlrev_b32_e32 v184, 16, v100
	v_and_b32_e32 v185, 0xffff0000, v100
	v_pk_add_f32 v[100:101], v[108:109], v[184:185]
	v_lshlrev_b32_e32 v194, 16, v105
	v_and_b32_e32 v195, 0xffff0000, v105
	v_pk_add_f32 v[100:101], v[100:101], v[194:195]
	v_lshlrev_b32_e32 v112, 16, v104
	v_and_b32_e32 v113, 0xffff0000, v104
	v_pk_add_f32 v[100:101], v[100:101], v[112:113]
	v_lshlrev_b32_e32 v108, 16, v106
	v_and_b32_e32 v109, 0xffff0000, v106
	v_pk_add_f32 v[100:101], v[100:101], v[108:109]
	v_lshlrev_b32_e32 v106, 16, v107
	v_and_b32_e32 v107, 0xffff0000, v107
	v_pk_add_f32 v[100:101], v[100:101], v[106:107]
	v_lshlrev_b32_e32 v104, 16, v125
	v_and_b32_e32 v105, 0xffff0000, v125
	v_pk_add_f32 v[128:129], v[100:101], v[104:105]
	v_lshlrev_b32_e32 v100, 16, v124
	v_and_b32_e32 v101, 0xffff0000, v124
	v_pk_add_f32 v[124:125], v[128:129], v[100:101]
	s_min_u32 s2, s87, s17
	v_sub_u32_e64 v128, s38, 4 clamp
	v_sub_u32_e32 v128, s2, v128
	v_cvt_f32_i32_e32 v128, v128
	v_div_scale_f32 v129, s[2:3], v128, v128, 1.0
	v_rcp_f32_e32 v175, v129
	s_min_u32 s2, s86, s17
	v_fma_f32 v190, -v129, v175, 1.0
	v_fmac_f32_e32 v175, v190, v175
	v_div_scale_f32 v190, vcc, 1.0, v128, 1.0
	v_mul_f32_e32 v191, v190, v175
	v_fma_f32 v192, -v129, v191, v190
	v_fmac_f32_e32 v191, v192, v175
	v_fma_f32 v129, -v129, v191, v190
	v_div_fmas_f32 v129, v129, v175, v191
	v_div_fixup_f32 v128, v129, v128, 1.0
	v_pk_fma_f32 v[128:129], v[128:129], v[124:125], v[108:109] op_sel_hi:[0,1,1] neg_lo:[0,0,1] neg_hi:[0,0,1]
	v_bfe_u32 v175, v128, 16, 1
	v_add3_u32 v128, v128, v175, s57
	v_bfe_u32 v175, v129, 16, 1
	v_lshrrev_b32_e32 v128, 16, v128
	v_add3_u32 v129, v129, v175, s57
	v_and_or_b32 v190, v129, s53, v128
	v_lshlrev_b32_e32 v128, 16, v121
	v_and_b32_e32 v129, 0xffff0000, v121
	v_sub_u32_e64 v121, s91, 4 clamp
	v_sub_u32_e32 v121, s2, v121
	v_cvt_f32_i32_e32 v121, v121
	v_pk_add_f32 v[182:183], v[128:129], v[182:183] neg_lo:[0,1] neg_hi:[0,1]
	v_add_u32_e32 v175, v147, v145
	v_pk_add_f32 v[192:193], v[124:125], v[182:183]
	v_div_scale_f32 v124, s[2:3], v121, v121, 1.0
	v_rcp_f32_e32 v125, v124
	s_min_u32 s2, s83, s17
	v_fma_f32 v182, -v124, v125, 1.0
	v_fmac_f32_e32 v125, v182, v125
	v_div_scale_f32 v182, vcc, 1.0, v121, 1.0
	v_mul_f32_e32 v183, v182, v125
	v_fma_f32 v191, -v124, v183, v182
	v_fmac_f32_e32 v183, v191, v125
	v_fma_f32 v124, -v124, v183, v182
	v_div_fmas_f32 v124, v124, v125, v183
	v_div_fixup_f32 v124, v124, v121, 1.0
	v_pk_fma_f32 v[124:125], v[124:125], v[192:193], v[106:107] op_sel_hi:[0,1,1] neg_lo:[0,0,1] neg_hi:[0,0,1]
	v_bfe_u32 v121, v124, 16, 1
	v_add3_u32 v121, v124, v121, s57
	v_bfe_u32 v124, v125, 16, 1
	v_lshrrev_b32_e32 v121, 16, v121
	v_add3_u32 v124, v125, v124, s57
	v_and_or_b32 v191, v124, s53, v121
	v_lshlrev_b32_e32 v124, 16, v120
	v_and_b32_e32 v125, 0xffff0000, v120
	v_pk_add_f32 v[120:121], v[124:125], v[184:185] neg_lo:[0,1] neg_hi:[0,1]
	v_add_u32_e32 v182, v149, v145
	v_pk_add_f32 v[184:185], v[192:193], v[120:121]
	v_sub_u32_e64 v120, s89, 4 clamp
	v_sub_u32_e32 v120, s2, v120
	v_cvt_f32_i32_e32 v120, v120
	v_div_scale_f32 v121, s[2:3], v120, v120, 1.0
	v_rcp_f32_e32 v183, v121
	s_min_u32 s2, s58, s17
	v_fma_f32 v192, -v121, v183, 1.0
	v_fmac_f32_e32 v183, v192, v183
	v_div_scale_f32 v192, vcc, 1.0, v120, 1.0
	v_mul_f32_e32 v193, v192, v183
	v_fma_f32 v196, -v121, v193, v192
	v_fmac_f32_e32 v193, v196, v183
	v_fma_f32 v121, -v121, v193, v192
	v_div_fmas_f32 v121, v121, v183, v193
	v_div_fixup_f32 v120, v121, v120, 1.0
	v_pk_fma_f32 v[120:121], v[120:121], v[184:185], v[104:105] op_sel_hi:[0,1,1] neg_lo:[0,0,1] neg_hi:[0,0,1]
	v_bfe_u32 v183, v120, 16, 1
	v_add3_u32 v120, v120, v183, s57
	v_bfe_u32 v183, v121, 16, 1
	v_lshrrev_b32_e32 v120, 16, v120
	v_add3_u32 v121, v121, v183, s57
	v_and_or_b32 v192, v121, s53, v120
	v_lshlrev_b32_e32 v120, 16, v116
	v_and_b32_e32 v121, 0xffff0000, v116
	v_sub_u32_e64 v116, s88, 4 clamp
	v_sub_u32_e32 v116, s2, v116
	v_cvt_f32_i32_e32 v116, v116
	v_pk_add_f32 v[194:195], v[120:121], v[194:195] neg_lo:[0,1] neg_hi:[0,1]
	v_add_u32_e32 v183, v151, v145
	v_pk_add_f32 v[194:195], v[184:185], v[194:195]
	v_div_scale_f32 v184, s[2:3], v116, v116, 1.0
	v_rcp_f32_e32 v185, v184
	s_min_u32 s2, s82, s17
	s_sub_i32 s2, s2, s87
	s_add_i32 s2, s2, 4
	v_fma_f32 v193, -v184, v185, 1.0
	v_fmac_f32_e32 v185, v193, v185
	v_div_scale_f32 v193, vcc, 1.0, v116, 1.0
	v_mul_f32_e32 v196, v193, v185
	v_fma_f32 v197, -v184, v196, v193
	v_fmac_f32_e32 v196, v197, v185
	v_fma_f32 v184, -v184, v196, v193
	v_div_fmas_f32 v184, v184, v185, v196
	v_div_fixup_f32 v116, v184, v116, 1.0
	v_pk_fma_f32 v[184:185], v[116:117], v[194:195], v[100:101] op_sel_hi:[0,1,1] neg_lo:[0,0,1] neg_hi:[0,0,1]
	v_bfe_u32 v116, v184, 16, 1
	v_add3_u32 v116, v184, v116, s57
	v_bfe_u32 v184, v185, 16, 1
	v_lshrrev_b32_e32 v116, 16, v116
	v_add3_u32 v184, v185, v184, s57
	v_and_or_b32 v193, v184, s53, v116
	v_lshlrev_b32_e32 v116, 16, v117
	v_and_b32_e32 v117, 0xffff0000, v117
	v_pk_add_f32 v[112:113], v[116:117], v[112:113] neg_lo:[0,1] neg_hi:[0,1]
	v_add_u32_e32 v184, v153, v145
	v_pk_add_f32 v[196:197], v[194:195], v[112:113]
	v_cvt_f32_i32_e32 v112, s2
	v_div_scale_f32 v113, s[2:3], v112, v112, 1.0
	v_rcp_f32_e32 v185, v113
	s_min_u32 s2, s81, s17
	s_sub_i32 s2, s2, s86
	s_add_i32 s2, s2, 4
	v_fma_f32 v194, -v113, v185, 1.0
	v_fmac_f32_e32 v185, v194, v185
	v_div_scale_f32 v194, vcc, 1.0, v112, 1.0
	v_mul_f32_e32 v195, v194, v185
	v_fma_f32 v198, -v113, v195, v194
	v_fmac_f32_e32 v195, v198, v185
	v_fma_f32 v113, -v113, v195, v194
	v_div_fmas_f32 v113, v113, v185, v195
	v_div_fixup_f32 v112, v113, v112, 1.0
	v_pk_fma_f32 v[112:113], v[112:113], v[196:197], v[128:129] op_sel_hi:[0,1,1] neg_lo:[0,0,1] neg_hi:[0,0,1]
	v_bfe_u32 v185, v112, 16, 1
	v_add3_u32 v112, v112, v185, s57
	v_bfe_u32 v185, v113, 16, 1
	v_lshrrev_b32_e32 v112, 16, v112
	v_add3_u32 v113, v113, v185, s57
	v_and_or_b32 v194, v113, s53, v112
	v_lshlrev_b32_e32 v112, 16, v186
	v_and_b32_e32 v113, 0xffff0000, v186
	v_pk_add_f32 v[108:109], v[112:113], v[108:109] neg_lo:[0,1] neg_hi:[0,1]
	v_add_u32_e32 v185, v155, v145
	v_pk_add_f32 v[196:197], v[196:197], v[108:109]
	v_cvt_f32_i32_e32 v108, s2
	v_div_scale_f32 v109, s[2:3], v108, v108, 1.0
	v_rcp_f32_e32 v186, v109
	s_min_u32 s2, s80, s17
	s_sub_i32 s2, s2, s83
	s_add_i32 s2, s2, 4
	v_fma_f32 v195, -v109, v186, 1.0
	v_fmac_f32_e32 v186, v195, v186
	v_div_scale_f32 v195, vcc, 1.0, v108, 1.0
	v_mul_f32_e32 v198, v195, v186
	v_fma_f32 v199, -v109, v198, v195
	v_fmac_f32_e32 v198, v199, v186
	v_fma_f32 v109, -v109, v198, v195
	v_div_fmas_f32 v109, v109, v186, v198
	v_div_fixup_f32 v108, v109, v108, 1.0
	v_pk_fma_f32 v[108:109], v[108:109], v[196:197], v[124:125] op_sel_hi:[0,1,1] neg_lo:[0,0,1] neg_hi:[0,0,1]
	v_bfe_u32 v186, v108, 16, 1
	v_add3_u32 v108, v108, v186, s57
	v_bfe_u32 v186, v109, 16, 1
	v_lshrrev_b32_e32 v108, 16, v108
	v_add3_u32 v109, v109, v186, s57
	v_and_or_b32 v195, v109, s53, v108
	v_lshlrev_b32_e32 v108, 16, v187
	v_and_b32_e32 v109, 0xffff0000, v187
	v_pk_add_f32 v[106:107], v[108:109], v[106:107] neg_lo:[0,1] neg_hi:[0,1]
	v_add_u32_e32 v186, v157, v145
	v_pk_add_f32 v[198:199], v[196:197], v[106:107]
	v_cvt_f32_i32_e32 v106, s2
	v_div_scale_f32 v107, s[2:3], v106, v106, 1.0
	v_rcp_f32_e32 v187, v107
	s_min_u32 s2, s79, s17
	s_sub_i32 s2, s2, s58
	s_add_i32 s2, s2, 4
	v_fma_f32 v196, -v107, v187, 1.0
	v_fmac_f32_e32 v187, v196, v187
	v_div_scale_f32 v196, vcc, 1.0, v106, 1.0
	v_mul_f32_e32 v197, v196, v187
	v_fma_f32 v200, -v107, v197, v196
	v_fmac_f32_e32 v197, v200, v187
	v_fma_f32 v107, -v107, v197, v196
	v_div_fmas_f32 v107, v107, v187, v197
	v_div_fixup_f32 v106, v107, v106, 1.0
	v_pk_fma_f32 v[106:107], v[106:107], v[198:199], v[120:121] op_sel_hi:[0,1,1] neg_lo:[0,0,1] neg_hi:[0,0,1]
	v_bfe_u32 v187, v106, 16, 1
	v_add3_u32 v106, v106, v187, s57
	v_bfe_u32 v187, v107, 16, 1
	v_lshrrev_b32_e32 v106, 16, v106
	v_add3_u32 v107, v107, v187, s57
	v_and_or_b32 v196, v107, s53, v106
	v_lshlrev_b32_e32 v106, 16, v174
	v_and_b32_e32 v107, 0xffff0000, v174
	v_pk_add_f32 v[104:105], v[106:107], v[104:105] neg_lo:[0,1] neg_hi:[0,1]
	v_add_u32_e32 v187, v159, v145
	v_pk_add_f32 v[198:199], v[198:199], v[104:105]
	v_cvt_f32_i32_e32 v104, s2
	v_div_scale_f32 v105, s[2:3], v104, v104, 1.0
	v_rcp_f32_e32 v174, v105
	s_min_u32 s2, s78, s17
	s_sub_i32 s2, s2, s82
	s_add_i32 s2, s2, 4
	v_fma_f32 v197, -v105, v174, 1.0
	v_fmac_f32_e32 v174, v197, v174
	v_div_scale_f32 v197, vcc, 1.0, v104, 1.0
	v_mul_f32_e32 v200, v197, v174
	v_fma_f32 v201, -v105, v200, v197
	v_fmac_f32_e32 v200, v201, v174
	v_fma_f32 v105, -v105, v200, v197
	v_div_fmas_f32 v105, v105, v174, v200
	v_div_fixup_f32 v104, v105, v104, 1.0
	v_pk_fma_f32 v[104:105], v[104:105], v[198:199], v[116:117] op_sel_hi:[0,1,1] neg_lo:[0,0,1] neg_hi:[0,0,1]
	v_bfe_u32 v174, v104, 16, 1
	v_add3_u32 v104, v104, v174, s57
	v_bfe_u32 v174, v105, 16, 1
	v_lshrrev_b32_e32 v104, 16, v104
	v_add3_u32 v105, v105, v174, s57
	v_and_or_b32 v197, v105, s53, v104
	v_lshlrev_b32_e32 v104, 16, v189
	v_and_b32_e32 v105, 0xffff0000, v189
	v_pk_add_f32 v[100:101], v[104:105], v[100:101] neg_lo:[0,1] neg_hi:[0,1]
	v_add_u32_e32 v174, v176, v145
	v_pk_add_f32 v[198:199], v[198:199], v[100:101]
	v_cvt_f32_i32_e32 v100, s2
	v_div_scale_f32 v101, s[2:3], v100, v100, 1.0
	v_rcp_f32_e32 v189, v101
	s_min_u32 s2, s77, s17
	s_sub_i32 s2, s2, s81
	s_add_i32 s2, s2, 4
	v_fma_f32 v200, -v101, v189, 1.0
	v_fmac_f32_e32 v189, v200, v189
	v_div_scale_f32 v200, vcc, 1.0, v100, 1.0
	v_mul_f32_e32 v201, v200, v189
	v_fma_f32 v206, -v101, v201, v200
	v_fmac_f32_e32 v201, v206, v189
	v_fma_f32 v101, -v101, v201, v200
	v_div_fmas_f32 v101, v101, v189, v201
	v_div_fixup_f32 v100, v101, v100, 1.0
	v_pk_fma_f32 v[100:101], v[100:101], v[198:199], v[112:113] op_sel_hi:[0,1,1] neg_lo:[0,0,1] neg_hi:[0,0,1]
	v_bfe_u32 v189, v100, 16, 1
	v_add3_u32 v100, v100, v189, s57
	v_bfe_u32 v189, v101, 16, 1
	v_lshrrev_b32_e32 v100, 16, v100
	v_add3_u32 v101, v101, v189, s57
	v_and_or_b32 v100, v101, s53, v100
	ds_write2st64_b32 v175, v190, v100 offset1:8
	v_lshlrev_b32_e32 v100, 16, v139
	v_and_b32_e32 v101, 0xffff0000, v139
	v_pk_add_f32 v[128:129], v[100:101], v[128:129] neg_lo:[0,1] neg_hi:[0,1]
	s_nop 0
	v_pk_add_f32 v[198:199], v[198:199], v[128:129]
	v_cvt_f32_i32_e32 v128, s2
	v_div_scale_f32 v129, s[2:3], v128, v128, 1.0
	v_rcp_f32_e32 v139, v129
	s_min_u32 s2, s76, s17
	s_sub_i32 s2, s2, s80
	s_add_i32 s2, s2, 4
	v_fma_f32 v189, -v129, v139, 1.0
	v_fmac_f32_e32 v139, v189, v139
	v_div_scale_f32 v189, vcc, 1.0, v128, 1.0
	v_mul_f32_e32 v190, v189, v139
	v_fma_f32 v200, -v129, v190, v189
	v_fmac_f32_e32 v190, v200, v139
	v_fma_f32 v129, -v129, v190, v189
	v_div_fmas_f32 v129, v129, v139, v190
	v_div_fixup_f32 v128, v129, v128, 1.0
	v_pk_fma_f32 v[128:129], v[128:129], v[198:199], v[108:109] op_sel_hi:[0,1,1] neg_lo:[0,0,1] neg_hi:[0,0,1]
	v_bfe_u32 v139, v128, 16, 1
	v_add3_u32 v128, v128, v139, s57
	v_bfe_u32 v139, v129, 16, 1
	v_lshrrev_b32_e32 v128, 16, v128
	v_add3_u32 v129, v129, v139, s57
	v_and_or_b32 v128, v129, s53, v128
	ds_write2st64_b32 v182, v191, v128 offset0:1 offset1:9
	v_lshlrev_b32_e32 v128, 16, v138
	v_and_b32_e32 v129, 0xffff0000, v138
	v_pk_add_f32 v[124:125], v[128:129], v[124:125] neg_lo:[0,1] neg_hi:[0,1]
	s_nop 0
	v_pk_add_f32 v[138:139], v[198:199], v[124:125]
	v_cvt_f32_i32_e32 v124, s2
	v_div_scale_f32 v125, s[2:3], v124, v124, 1.0
	v_rcp_f32_e32 v189, v125
	s_min_u32 s2, s75, s17
	s_sub_i32 s2, s2, s79
	s_add_i32 s2, s2, 4
	v_fma_f32 v190, -v125, v189, 1.0
	v_fmac_f32_e32 v189, v190, v189
	v_div_scale_f32 v190, vcc, 1.0, v124, 1.0
	v_mul_f32_e32 v191, v190, v189
	v_fma_f32 v198, -v125, v191, v190
	v_fmac_f32_e32 v191, v198, v189
	v_fma_f32 v125, -v125, v191, v190
	v_div_fmas_f32 v125, v125, v189, v191
	v_div_fixup_f32 v124, v125, v124, 1.0
	v_pk_fma_f32 v[124:125], v[124:125], v[138:139], v[106:107] op_sel_hi:[0,1,1] neg_lo:[0,0,1] neg_hi:[0,0,1]
	v_bfe_u32 v189, v124, 16, 1
	v_add3_u32 v124, v124, v189, s57
	v_bfe_u32 v189, v125, 16, 1
	v_lshrrev_b32_e32 v124, 16, v124
	v_add3_u32 v125, v125, v189, s57
	v_and_or_b32 v124, v125, s53, v124
	ds_write2st64_b32 v183, v192, v124 offset0:2 offset1:10
	v_lshlrev_b32_e32 v124, 16, v137
	v_and_b32_e32 v125, 0xffff0000, v137
	v_pk_add_f32 v[120:121], v[124:125], v[120:121] neg_lo:[0,1] neg_hi:[0,1]
	s_nop 0
	v_pk_add_f32 v[138:139], v[138:139], v[120:121]
	v_cvt_f32_i32_e32 v120, s2
	v_div_scale_f32 v121, s[2:3], v120, v120, 1.0
	v_rcp_f32_e32 v137, v121
	s_min_u32 s2, s74, s17
	s_sub_i32 s2, s2, s78
	s_add_i32 s2, s2, 4
	v_fma_f32 v189, -v121, v137, 1.0
	v_fmac_f32_e32 v137, v189, v137
	v_div_scale_f32 v189, vcc, 1.0, v120, 1.0
	v_mul_f32_e32 v190, v189, v137
	v_fma_f32 v191, -v121, v190, v189
	v_fmac_f32_e32 v190, v191, v137
	v_fma_f32 v121, -v121, v190, v189
	v_div_fmas_f32 v121, v121, v137, v190
	v_div_fixup_f32 v120, v121, v120, 1.0
	v_pk_fma_f32 v[120:121], v[120:121], v[138:139], v[104:105] op_sel_hi:[0,1,1] neg_lo:[0,0,1] neg_hi:[0,0,1]
	v_bfe_u32 v137, v120, 16, 1
	v_add3_u32 v120, v120, v137, s57
	v_bfe_u32 v137, v121, 16, 1
	v_lshrrev_b32_e32 v120, 16, v120
	v_add3_u32 v121, v121, v137, s57
	v_and_or_b32 v120, v121, s53, v120
	ds_write2st64_b32 v184, v193, v120 offset0:3 offset1:11
	v_lshlrev_b32_e32 v120, 16, v136
	v_and_b32_e32 v121, 0xffff0000, v136
	v_pk_add_f32 v[116:117], v[120:121], v[116:117] neg_lo:[0,1] neg_hi:[0,1]
	s_nop 0
	v_pk_add_f32 v[136:137], v[138:139], v[116:117]
	v_cvt_f32_i32_e32 v116, s2
	v_div_scale_f32 v117, s[2:3], v116, v116, 1.0
	v_rcp_f32_e32 v138, v117
	s_min_u32 s2, s73, s17
	s_sub_i32 s2, s2, s77
	s_add_i32 s2, s2, 4
	v_fma_f32 v139, -v117, v138, 1.0
	v_fmac_f32_e32 v138, v139, v138
	v_div_scale_f32 v139, vcc, 1.0, v116, 1.0
	v_mul_f32_e32 v189, v139, v138
	v_fma_f32 v190, -v117, v189, v139
	v_fmac_f32_e32 v189, v190, v138
	v_fma_f32 v117, -v117, v189, v139
	v_div_fmas_f32 v117, v117, v138, v189
	v_div_fixup_f32 v116, v117, v116, 1.0
	v_pk_fma_f32 v[116:117], v[116:117], v[136:137], v[100:101] op_sel_hi:[0,1,1] neg_lo:[0,0,1] neg_hi:[0,0,1]
	v_bfe_u32 v138, v116, 16, 1
	v_add3_u32 v116, v116, v138, s57
	v_bfe_u32 v138, v117, 16, 1
	v_lshrrev_b32_e32 v116, 16, v116
	v_add3_u32 v117, v117, v138, s57
	v_and_or_b32 v116, v117, s53, v116
	ds_write2st64_b32 v185, v194, v116 offset0:4 offset1:12
	v_lshlrev_b32_e32 v116, 16, v132
	v_and_b32_e32 v117, 0xffff0000, v132
	v_cvt_f32_i32_e32 v132, s2
	v_pk_add_f32 v[112:113], v[116:117], v[112:113] neg_lo:[0,1] neg_hi:[0,1]
	s_nop 0
	v_pk_add_f32 v[112:113], v[136:137], v[112:113]
	v_div_scale_f32 v136, s[2:3], v132, v132, 1.0
	v_rcp_f32_e32 v137, v136
	s_min_u32 s2, s72, s17
	s_sub_i32 s2, s2, s76
	s_add_i32 s2, s2, 4
	v_fma_f32 v138, -v136, v137, 1.0
	v_fmac_f32_e32 v137, v138, v137
	v_div_scale_f32 v138, vcc, 1.0, v132, 1.0
	v_mul_f32_e32 v139, v138, v137
	v_fma_f32 v189, -v136, v139, v138
	v_fmac_f32_e32 v139, v189, v137
	v_fma_f32 v136, -v136, v139, v138
	v_div_fmas_f32 v136, v136, v137, v139
	v_div_fixup_f32 v132, v136, v132, 1.0
	v_pk_fma_f32 v[136:137], v[132:133], v[112:113], v[128:129] op_sel_hi:[0,1,1] neg_lo:[0,0,1] neg_hi:[0,0,1]
	v_bfe_u32 v132, v136, 16, 1
	v_add3_u32 v132, v136, v132, s57
	v_bfe_u32 v136, v137, 16, 1
	v_lshrrev_b32_e32 v132, 16, v132
	v_add3_u32 v136, v137, v136, s57
	v_and_or_b32 v132, v136, s53, v132
	ds_write2st64_b32 v186, v195, v132 offset0:5 offset1:13
	v_lshlrev_b32_e32 v132, 16, v133
	v_and_b32_e32 v133, 0xffff0000, v133
	v_pk_add_f32 v[108:109], v[132:133], v[108:109] neg_lo:[0,1] neg_hi:[0,1]
	s_nop 0
	v_pk_add_f32 v[108:109], v[112:113], v[108:109]
	v_cvt_f32_i32_e32 v112, s2
	v_div_scale_f32 v113, s[2:3], v112, v112, 1.0
	v_rcp_f32_e32 v136, v113
	s_min_u32 s2, s69, s17
	s_sub_i32 s2, s2, s75
	s_add_i32 s2, s2, 4
	v_fma_f32 v137, -v113, v136, 1.0
	v_fmac_f32_e32 v136, v137, v136
	v_div_scale_f32 v137, vcc, 1.0, v112, 1.0
	v_mul_f32_e32 v138, v137, v136
	v_fma_f32 v139, -v113, v138, v137
	v_fmac_f32_e32 v138, v139, v136
	v_fma_f32 v113, -v113, v138, v137
	v_div_fmas_f32 v113, v113, v136, v138
	v_div_fixup_f32 v112, v113, v112, 1.0
	v_pk_fma_f32 v[112:113], v[112:113], v[108:109], v[124:125] op_sel_hi:[0,1,1] neg_lo:[0,0,1] neg_hi:[0,0,1]
	v_bfe_u32 v136, v112, 16, 1
	v_add3_u32 v112, v112, v136, s57
	v_bfe_u32 v136, v113, 16, 1
	v_add3_u32 v113, v113, v136, s57
	v_lshlrev_b32_e32 v136, 16, v135
	v_and_b32_e32 v137, 0xffff0000, v135
	v_pk_add_f32 v[106:107], v[136:137], v[106:107] neg_lo:[0,1] neg_hi:[0,1]
	v_lshrrev_b32_e32 v112, 16, v112
	v_pk_add_f32 v[106:107], v[108:109], v[106:107]
	v_cvt_f32_i32_e32 v108, s2
	v_and_or_b32 v112, v113, s53, v112
	ds_write2st64_b32 v187, v196, v112 offset0:6 offset1:14
	v_and_b32_e32 v139, 0xffff0000, v134
	v_div_scale_f32 v109, s[2:3], v108, v108, 1.0
	v_rcp_f32_e32 v112, v109
	s_min_u32 s2, s68, s17
	s_sub_i32 s2, s2, s74
	s_add_i32 s2, s2, 4
	v_fma_f32 v113, -v109, v112, 1.0
	v_fmac_f32_e32 v112, v113, v112
	v_div_scale_f32 v113, vcc, 1.0, v108, 1.0
	v_mul_f32_e32 v135, v113, v112
	v_fma_f32 v138, -v109, v135, v113
	v_fmac_f32_e32 v135, v138, v112
	v_fma_f32 v109, -v109, v135, v113
	v_div_fmas_f32 v109, v109, v112, v135
	v_lshlrev_b32_e32 v138, 16, v134
	v_div_fixup_f32 v108, v109, v108, 1.0
	v_pk_add_f32 v[104:105], v[138:139], v[104:105] neg_lo:[0,1] neg_hi:[0,1]
	v_pk_fma_f32 v[108:109], v[108:109], v[106:107], v[120:121] op_sel_hi:[0,1,1] neg_lo:[0,0,1] neg_hi:[0,0,1]
	v_pk_add_f32 v[104:105], v[106:107], v[104:105]
	v_cvt_f32_i32_e32 v106, s2
	v_bfe_u32 v112, v108, 16, 1
	v_add3_u32 v108, v108, v112, s57
	v_bfe_u32 v112, v109, 16, 1
	v_lshrrev_b32_e32 v108, 16, v108
	v_add3_u32 v109, v109, v112, s57
	v_and_or_b32 v108, v109, s53, v108
	v_div_scale_f32 v107, s[2:3], v106, v106, 1.0
	ds_write2st64_b32 v174, v197, v108 offset0:7 offset1:15
	v_rcp_f32_e32 v108, v107
	s_min_u32 s2, s63, s17
	v_lshlrev_b32_e32 v134, 16, v130
	v_and_b32_e32 v135, 0xffff0000, v130
	v_fma_f32 v109, -v107, v108, 1.0
	v_fmac_f32_e32 v108, v109, v108
	v_div_scale_f32 v109, vcc, 1.0, v106, 1.0
	v_mul_f32_e32 v112, v109, v108
	v_fma_f32 v113, -v107, v112, v109
	v_fmac_f32_e32 v112, v113, v108
	v_fma_f32 v107, -v107, v112, v109
	v_div_fmas_f32 v107, v107, v108, v112
	s_sub_i32 s2, s2, s73
	v_div_fixup_f32 v106, v107, v106, 1.0
	v_pk_add_f32 v[100:101], v[134:135], v[100:101] neg_lo:[0,1] neg_hi:[0,1]
	s_add_i32 s2, s2, 4
	v_pk_fma_f32 v[106:107], v[106:107], v[104:105], v[116:117] op_sel_hi:[0,1,1] neg_lo:[0,0,1] neg_hi:[0,0,1]
	v_pk_add_f32 v[100:101], v[104:105], v[100:101]
	v_cvt_f32_i32_e32 v104, s2
	v_bfe_u32 v108, v106, 16, 1
	v_add3_u32 v106, v106, v108, s57
	v_bfe_u32 v108, v107, 16, 1
	v_lshrrev_b32_e32 v106, 16, v106
	v_add3_u32 v107, v107, v108, s57
	v_div_scale_f32 v105, s[2:3], v104, v104, 1.0
	v_and_or_b32 v191, v107, s53, v106
	v_rcp_f32_e32 v106, v105
	s_min_u32 s2, s62, s17
	v_lshlrev_b32_e32 v130, 16, v131
	v_and_b32_e32 v131, 0xffff0000, v131
	v_fma_f32 v107, -v105, v106, 1.0
	v_fmac_f32_e32 v106, v107, v106
	v_div_scale_f32 v107, vcc, 1.0, v104, 1.0
	v_mul_f32_e32 v108, v107, v106
	v_fma_f32 v109, -v105, v108, v107
	v_fmac_f32_e32 v108, v109, v106
	v_fma_f32 v105, -v105, v108, v107
	v_div_fmas_f32 v105, v105, v106, v108
	v_div_fixup_f32 v104, v105, v104, 1.0
	v_pk_fma_f32 v[104:105], v[104:105], v[100:101], v[132:133] op_sel_hi:[0,1,1] neg_lo:[0,0,1] neg_hi:[0,0,1]
	v_bfe_u32 v106, v104, 16, 1
	v_add3_u32 v104, v104, v106, s57
	v_bfe_u32 v106, v105, 16, 1
	v_lshrrev_b32_e32 v104, 16, v104
	v_add3_u32 v105, v105, v106, s57
	s_sub_i32 s2, s2, s72
	v_and_or_b32 v190, v105, s53, v104
	v_pk_add_f32 v[104:105], v[130:131], v[128:129] neg_lo:[0,1] neg_hi:[0,1]
	s_add_i32 s2, s2, 4
	v_pk_add_f32 v[100:101], v[100:101], v[104:105]
	v_cvt_f32_i32_e32 v104, s2
	v_lshlrev_b32_e32 v112, 16, v188
	v_and_b32_e32 v113, 0xffff0000, v188
	v_div_scale_f32 v105, s[2:3], v104, v104, 1.0
	v_rcp_f32_e32 v106, v105
	s_min_u32 s2, s56, s17
	s_sub_i32 s2, s2, s69
	s_add_i32 s2, s2, 4
	v_fma_f32 v107, -v105, v106, 1.0
	v_fmac_f32_e32 v106, v107, v106
	v_div_scale_f32 v107, vcc, 1.0, v104, 1.0
	v_mul_f32_e32 v108, v107, v106
	v_fma_f32 v109, -v105, v108, v107
	v_fmac_f32_e32 v108, v109, v106
	v_fma_f32 v105, -v105, v108, v107
	v_div_fmas_f32 v105, v105, v106, v108
	v_div_fixup_f32 v104, v105, v104, 1.0
	v_pk_fma_f32 v[104:105], v[104:105], v[100:101], v[136:137] op_sel_hi:[0,1,1] neg_lo:[0,0,1] neg_hi:[0,0,1]
	v_bfe_u32 v106, v104, 16, 1
	v_add3_u32 v104, v104, v106, s57
	v_bfe_u32 v106, v105, 16, 1
	v_lshrrev_b32_e32 v104, 16, v104
	v_add3_u32 v105, v105, v106, s57
	v_and_or_b32 v189, v105, s53, v104
	v_pk_add_f32 v[104:105], v[112:113], v[124:125] neg_lo:[0,1] neg_hi:[0,1]
	s_nop 0
	v_pk_add_f32 v[100:101], v[100:101], v[104:105]
	v_cvt_f32_i32_e32 v104, s2
	v_div_scale_f32 v105, s[2:3], v104, v104, 1.0
	v_rcp_f32_e32 v106, v105
	s_min_u32 s2, s54, s17
	s_sub_i32 s2, s2, s68
	s_add_i32 s2, s2, 4
	v_fma_f32 v107, -v105, v106, 1.0
	v_fmac_f32_e32 v106, v107, v106
	v_div_scale_f32 v107, vcc, 1.0, v104, 1.0
	v_mul_f32_e32 v108, v107, v106
	v_fma_f32 v109, -v105, v108, v107
	v_fmac_f32_e32 v108, v109, v106
	v_fma_f32 v105, -v105, v108, v107
	v_div_fmas_f32 v105, v105, v106, v108
	v_div_fixup_f32 v104, v105, v104, 1.0
	v_pk_fma_f32 v[104:105], v[104:105], v[100:101], v[138:139] op_sel_hi:[0,1,1] neg_lo:[0,0,1] neg_hi:[0,0,1]
	v_bfe_u32 v106, v104, 16, 1
	v_add3_u32 v104, v104, v106, s57
	v_bfe_u32 v106, v105, 16, 1
	v_lshrrev_b32_e32 v104, 16, v104
	v_add3_u32 v105, v105, v106, s57
	v_lshlrev_b32_e32 v108, 16, v173
	v_and_b32_e32 v109, 0xffff0000, v173
	v_and_or_b32 v188, v105, s53, v104
	v_pk_add_f32 v[104:105], v[108:109], v[120:121] neg_lo:[0,1] neg_hi:[0,1]
	s_nop 0
	v_pk_add_f32 v[100:101], v[100:101], v[104:105]
	v_cvt_f32_i32_e32 v104, s2
	v_div_scale_f32 v105, s[2:3], v104, v104, 1.0
	v_rcp_f32_e32 v106, v105
	s_min_u32 s2, s52, s17
	s_sub_i32 s2, s2, s63
	s_add_i32 s2, s2, 4
	v_fma_f32 v107, -v105, v106, 1.0
	v_fmac_f32_e32 v106, v107, v106
	v_div_scale_f32 v107, vcc, 1.0, v104, 1.0
	v_mul_f32_e32 v120, v107, v106
	v_fma_f32 v121, -v105, v120, v107
	v_fmac_f32_e32 v120, v121, v106
	v_fma_f32 v105, -v105, v120, v107
	v_div_fmas_f32 v105, v105, v106, v120
	v_div_fixup_f32 v104, v105, v104, 1.0
	v_pk_fma_f32 v[104:105], v[104:105], v[100:101], v[134:135] op_sel_hi:[0,1,1] neg_lo:[0,0,1] neg_hi:[0,0,1]
	v_bfe_u32 v106, v104, 16, 1
	v_add3_u32 v104, v104, v106, s57
	v_bfe_u32 v106, v105, 16, 1
	v_lshrrev_b32_e32 v104, 16, v104
	v_add3_u32 v105, v105, v106, s57
	v_lshlrev_b32_e32 v106, 16, v172
	v_and_b32_e32 v107, 0xffff0000, v172
	v_and_or_b32 v173, v105, s53, v104
	v_pk_add_f32 v[104:105], v[106:107], v[116:117] neg_lo:[0,1] neg_hi:[0,1]
	s_nop 0
	v_pk_add_f32 v[100:101], v[100:101], v[104:105]
	v_cvt_f32_i32_e32 v104, s2
	v_div_scale_f32 v105, s[2:3], v104, v104, 1.0
	v_rcp_f32_e32 v116, v105
	s_min_u32 s2, s51, s17
	s_sub_i32 s2, s2, s62
	s_add_i32 s2, s2, 4
	v_fma_f32 v117, -v105, v116, 1.0
	v_fmac_f32_e32 v116, v117, v116
	v_div_scale_f32 v117, vcc, 1.0, v104, 1.0
	v_mul_f32_e32 v120, v117, v116
	v_fma_f32 v121, -v105, v120, v117
	v_fmac_f32_e32 v120, v121, v116
	v_fma_f32 v105, -v105, v120, v117
	v_div_fmas_f32 v105, v105, v116, v120
	v_div_fixup_f32 v104, v105, v104, 1.0
	v_pk_fma_f32 v[104:105], v[104:105], v[100:101], v[130:131] op_sel_hi:[0,1,1] neg_lo:[0,0,1] neg_hi:[0,0,1]
	v_bfe_u32 v116, v104, 16, 1
	v_add3_u32 v104, v104, v116, s57
	v_bfe_u32 v116, v105, 16, 1
	v_lshrrev_b32_e32 v104, 16, v104
	v_add3_u32 v105, v105, v116, s57
	v_and_or_b32 v172, v105, s53, v104
	v_lshlrev_b32_e32 v104, 16, v171
	v_and_b32_e32 v105, 0xffff0000, v171
	v_pk_add_f32 v[116:117], v[104:105], v[132:133] neg_lo:[0,1] neg_hi:[0,1]
	s_nop 0
	v_pk_add_f32 v[116:117], v[100:101], v[116:117]
	v_cvt_f32_i32_e32 v100, s2
	v_div_scale_f32 v101, s[2:3], v100, v100, 1.0
	v_rcp_f32_e32 v120, v101
	s_min_u32 s2, s46, s17
	s_sub_i32 s2, s2, s56
	s_add_i32 s2, s2, 4
	v_fma_f32 v121, -v101, v120, 1.0
	v_fmac_f32_e32 v120, v121, v120
	v_div_scale_f32 v121, vcc, 1.0, v100, 1.0
	v_mul_f32_e32 v124, v121, v120
	v_fma_f32 v125, -v101, v124, v121
	v_fmac_f32_e32 v124, v125, v120
	v_fma_f32 v101, -v101, v124, v121
	v_div_fmas_f32 v101, v101, v120, v124
	v_div_fixup_f32 v100, v101, v100, 1.0
	v_pk_fma_f32 v[100:101], v[100:101], v[116:117], v[112:113] op_sel_hi:[0,1,1] neg_lo:[0,0,1] neg_hi:[0,0,1]
	v_bfe_u32 v120, v100, 16, 1
	v_add3_u32 v100, v100, v120, s57
	v_bfe_u32 v120, v101, 16, 1
	v_lshrrev_b32_e32 v100, 16, v100
	v_add3_u32 v101, v101, v120, s57
	v_and_or_b32 v133, v101, s53, v100
	v_lshlrev_b32_e32 v100, 16, v170
	v_and_b32_e32 v101, 0xffff0000, v170
	v_pk_add_f32 v[120:121], v[100:101], v[136:137] neg_lo:[0,1] neg_hi:[0,1]
	s_nop 0
	v_pk_add_f32 v[116:117], v[116:117], v[120:121]
	v_cvt_f32_i32_e32 v120, s2
	v_div_scale_f32 v121, s[2:3], v120, v120, 1.0
	v_rcp_f32_e32 v124, v121
	s_min_u32 s2, s27, s17
	s_sub_i32 s2, s2, s54
	s_add_i32 s2, s2, 4
	v_fma_f32 v125, -v121, v124, 1.0
	v_fmac_f32_e32 v124, v125, v124
	v_div_scale_f32 v125, vcc, 1.0, v120, 1.0
	v_mul_f32_e32 v128, v125, v124
	v_fma_f32 v129, -v121, v128, v125
	v_fmac_f32_e32 v128, v129, v124
	v_fma_f32 v121, -v121, v128, v125
	v_div_fmas_f32 v121, v121, v124, v128
	v_div_fixup_f32 v120, v121, v120, 1.0
	v_pk_fma_f32 v[120:121], v[120:121], v[116:117], v[108:109] op_sel_hi:[0,1,1] neg_lo:[0,0,1] neg_hi:[0,0,1]
	v_bfe_u32 v124, v120, 16, 1
	v_add3_u32 v120, v120, v124, s57
	v_bfe_u32 v124, v121, 16, 1
	v_lshrrev_b32_e32 v120, 16, v120
	v_add3_u32 v121, v121, v124, s57
	v_lshlrev_b32_e32 v128, 16, v169
	v_and_b32_e32 v129, 0xffff0000, v169
	v_and_or_b32 v132, v121, s53, v120
	v_pk_add_f32 v[120:121], v[128:129], v[138:139] neg_lo:[0,1] neg_hi:[0,1]
	s_nop 0
	v_pk_add_f32 v[116:117], v[116:117], v[120:121]
	v_cvt_f32_i32_e32 v120, s2
	v_div_scale_f32 v121, s[2:3], v120, v120, 1.0
	v_rcp_f32_e32 v124, v121
	s_min_u32 s2, s15, s17
	s_sub_i32 s2, s2, s52
	s_add_i32 s2, s2, 4
	v_fma_f32 v125, -v121, v124, 1.0
	v_fmac_f32_e32 v124, v125, v124
	v_div_scale_f32 v125, vcc, 1.0, v120, 1.0
	v_mul_f32_e32 v136, v125, v124
	v_fma_f32 v137, -v121, v136, v125
	v_fmac_f32_e32 v136, v137, v124
	v_fma_f32 v121, -v121, v136, v125
	v_div_fmas_f32 v121, v121, v124, v136
	v_div_fixup_f32 v120, v121, v120, 1.0
	v_pk_fma_f32 v[120:121], v[120:121], v[116:117], v[106:107] op_sel_hi:[0,1,1] neg_lo:[0,0,1] neg_hi:[0,0,1]
	v_bfe_u32 v124, v120, 16, 1
	v_add3_u32 v120, v120, v124, s57
	v_bfe_u32 v124, v121, 16, 1
	v_lshrrev_b32_e32 v120, 16, v120
	v_add3_u32 v121, v121, v124, s57
	v_and_or_b32 v120, v121, s53, v120
	v_lshlrev_b32_e32 v124, 16, v168
	v_and_b32_e32 v125, 0xffff0000, v168
	ds_write2st64_b32 v175, v191, v120 offset0:16 offset1:24
	v_pk_add_f32 v[120:121], v[124:125], v[134:135] neg_lo:[0,1] neg_hi:[0,1]
	s_nop 0
	v_pk_add_f32 v[116:117], v[116:117], v[120:121]
	v_cvt_f32_i32_e32 v120, s2
	v_div_scale_f32 v121, s[2:3], v120, v120, 1.0
	v_rcp_f32_e32 v134, v121
	s_min_u32 s2, s14, s17
	s_sub_i32 s2, s2, s51
	s_add_i32 s2, s2, 4
	v_fma_f32 v135, -v121, v134, 1.0
	v_fmac_f32_e32 v134, v135, v134
	v_div_scale_f32 v135, vcc, 1.0, v120, 1.0
	v_mul_f32_e32 v136, v135, v134
	v_fma_f32 v137, -v121, v136, v135
	v_fmac_f32_e32 v136, v137, v134
	v_fma_f32 v121, -v121, v136, v135
	v_div_fmas_f32 v121, v121, v134, v136
	v_div_fixup_f32 v120, v121, v120, 1.0
	v_pk_fma_f32 v[120:121], v[120:121], v[116:117], v[104:105] op_sel_hi:[0,1,1] neg_lo:[0,0,1] neg_hi:[0,0,1]
	v_bfe_u32 v134, v120, 16, 1
	v_add3_u32 v120, v120, v134, s57
	v_bfe_u32 v134, v121, 16, 1
	v_lshrrev_b32_e32 v120, 16, v120
	v_add3_u32 v121, v121, v134, s57
	v_and_or_b32 v120, v121, s53, v120
	ds_write2st64_b32 v182, v190, v120 offset0:17 offset1:25
	v_lshlrev_b32_e32 v120, 16, v167
	v_and_b32_e32 v121, 0xffff0000, v167
	v_pk_add_f32 v[130:131], v[120:121], v[130:131] neg_lo:[0,1] neg_hi:[0,1]
	s_nop 0
	v_pk_add_f32 v[130:131], v[116:117], v[130:131]
	v_cvt_f32_i32_e32 v116, s2
	v_div_scale_f32 v117, s[2:3], v116, v116, 1.0
	v_rcp_f32_e32 v134, v117
	s_min_u32 s2, s1, s17
	s_sub_i32 s2, s2, s46
	s_add_i32 s2, s2, 4
	v_fma_f32 v135, -v117, v134, 1.0
	v_fmac_f32_e32 v134, v135, v134
	v_div_scale_f32 v135, vcc, 1.0, v116, 1.0
	v_mul_f32_e32 v136, v135, v134
	v_fma_f32 v137, -v117, v136, v135
	v_fmac_f32_e32 v136, v137, v134
	v_fma_f32 v117, -v117, v136, v135
	v_div_fmas_f32 v117, v117, v134, v136
	v_div_fixup_f32 v116, v117, v116, 1.0
	v_pk_fma_f32 v[116:117], v[116:117], v[130:131], v[100:101] op_sel_hi:[0,1,1] neg_lo:[0,0,1] neg_hi:[0,0,1]
	v_bfe_u32 v134, v116, 16, 1
	v_add3_u32 v116, v116, v134, s57
	v_bfe_u32 v134, v117, 16, 1
	v_lshrrev_b32_e32 v116, 16, v116
	v_add3_u32 v117, v117, v134, s57
	v_and_or_b32 v116, v117, s53, v116
	ds_write2st64_b32 v183, v189, v116 offset0:18 offset1:26
	v_lshlrev_b32_e32 v116, 16, v166
	v_and_b32_e32 v117, 0xffff0000, v166
	v_pk_add_f32 v[112:113], v[116:117], v[112:113] neg_lo:[0,1] neg_hi:[0,1]
	s_nop 0
	v_pk_add_f32 v[130:131], v[130:131], v[112:113]
	v_cvt_f32_i32_e32 v112, s2
	v_div_scale_f32 v113, s[2:3], v112, v112, 1.0
	v_rcp_f32_e32 v134, v113
	s_min_u32 s2, s48, s17
	s_sub_i32 s2, s2, s27
	s_add_i32 s2, s2, 4
	v_fma_f32 v135, -v113, v134, 1.0
	v_fmac_f32_e32 v134, v135, v134
	v_div_scale_f32 v135, vcc, 1.0, v112, 1.0
	v_mul_f32_e32 v136, v135, v134
	v_fma_f32 v137, -v113, v136, v135
	v_fmac_f32_e32 v136, v137, v134
	v_fma_f32 v113, -v113, v136, v135
	v_div_fmas_f32 v113, v113, v134, v136
	v_div_fixup_f32 v112, v113, v112, 1.0
	v_pk_fma_f32 v[112:113], v[112:113], v[130:131], v[128:129] op_sel_hi:[0,1,1] neg_lo:[0,0,1] neg_hi:[0,0,1]
	v_bfe_u32 v128, v112, 16, 1
	v_add3_u32 v112, v112, v128, s57
	v_bfe_u32 v128, v113, 16, 1
	v_add3_u32 v113, v113, v128, s57
	v_cvt_f32_i32_e32 v128, s2
	v_lshrrev_b32_e32 v112, 16, v112
	v_and_or_b32 v112, v113, s53, v112
	ds_write2st64_b32 v184, v188, v112 offset0:19 offset1:27
	v_lshlrev_b32_e32 v112, 16, v165
	v_and_b32_e32 v113, 0xffff0000, v165
	v_pk_add_f32 v[108:109], v[112:113], v[108:109] neg_lo:[0,1] neg_hi:[0,1]
	v_div_scale_f32 v129, s[2:3], v128, v128, 1.0
	v_pk_add_f32 v[108:109], v[130:131], v[108:109]
	v_rcp_f32_e32 v130, v129
	s_min_u32 s2, s45, s17
	s_sub_i32 s2, s2, s15
	s_add_i32 s2, s2, 4
	v_fma_f32 v131, -v129, v130, 1.0
	v_fmac_f32_e32 v130, v131, v130
	v_div_scale_f32 v131, vcc, 1.0, v128, 1.0
	v_mul_f32_e32 v134, v131, v130
	v_fma_f32 v135, -v129, v134, v131
	v_fmac_f32_e32 v134, v135, v130
	v_fma_f32 v129, -v129, v134, v131
	v_div_fmas_f32 v129, v129, v130, v134
	v_div_fixup_f32 v128, v129, v128, 1.0
	v_pk_fma_f32 v[124:125], v[128:129], v[108:109], v[124:125] op_sel_hi:[0,1,1] neg_lo:[0,0,1] neg_hi:[0,0,1]
	v_bfe_u32 v128, v124, 16, 1
	v_add3_u32 v124, v124, v128, s57
	v_bfe_u32 v128, v125, 16, 1
	v_lshrrev_b32_e32 v124, 16, v124
	v_add3_u32 v125, v125, v128, s57
	v_and_or_b32 v124, v125, s53, v124
	ds_write2st64_b32 v185, v173, v124 offset0:20 offset1:28
	v_lshlrev_b32_e32 v124, 16, v164
	v_and_b32_e32 v125, 0xffff0000, v164
	v_pk_add_f32 v[106:107], v[124:125], v[106:107] neg_lo:[0,1] neg_hi:[0,1]
	s_nop 0
	v_pk_add_f32 v[106:107], v[108:109], v[106:107]
	v_cvt_f32_i32_e32 v108, s2
	v_div_scale_f32 v109, s[2:3], v108, v108, 1.0
	v_rcp_f32_e32 v124, v109
	s_min_u32 s2, s26, s17
	s_sub_i32 s2, s2, s14
	s_add_i32 s2, s2, 4
	v_fma_f32 v125, -v109, v124, 1.0
	v_fmac_f32_e32 v124, v125, v124
	v_div_scale_f32 v125, vcc, 1.0, v108, 1.0
	v_mul_f32_e32 v128, v125, v124
	v_fma_f32 v129, -v109, v128, v125
	v_fmac_f32_e32 v128, v129, v124
	v_fma_f32 v109, -v109, v128, v125
	v_div_fmas_f32 v109, v109, v124, v128
	v_div_fixup_f32 v108, v109, v108, 1.0
	v_pk_fma_f32 v[108:109], v[108:109], v[106:107], v[120:121] op_sel_hi:[0,1,1] neg_lo:[0,0,1] neg_hi:[0,0,1]
	v_bfe_u32 v120, v108, 16, 1
	v_add3_u32 v108, v108, v120, s57
	v_bfe_u32 v120, v109, 16, 1
	v_lshrrev_b32_e32 v108, 16, v108
	v_add3_u32 v109, v109, v120, s57
	v_and_or_b32 v108, v109, s53, v108
	ds_write2st64_b32 v186, v172, v108 offset0:21 offset1:29
	v_lshlrev_b32_e32 v108, 16, v141
	v_and_b32_e32 v109, 0xffff0000, v141
	v_pk_add_f32 v[104:105], v[108:109], v[104:105] neg_lo:[0,1] neg_hi:[0,1]
	s_nop 0
	v_pk_add_f32 v[104:105], v[106:107], v[104:105]
	v_cvt_f32_i32_e32 v106, s2
	v_div_scale_f32 v107, s[2:3], v106, v106, 1.0
	v_rcp_f32_e32 v108, v107
	s_add_i32 s2, s38, 35
	s_min_u32 s2, s2, s17
	s_sub_i32 s1, s2, s1
	v_fma_f32 v109, -v107, v108, 1.0
	v_fmac_f32_e32 v108, v109, v108
	v_div_scale_f32 v109, vcc, 1.0, v106, 1.0
	v_mul_f32_e32 v120, v109, v108
	v_fma_f32 v121, -v107, v120, v109
	v_fmac_f32_e32 v120, v121, v108
	v_fma_f32 v107, -v107, v120, v109
	v_div_fmas_f32 v107, v107, v108, v120
	v_div_fixup_f32 v106, v107, v106, 1.0
	v_pk_fma_f32 v[106:107], v[106:107], v[104:105], v[116:117] op_sel_hi:[0,1,1] neg_lo:[0,0,1] neg_hi:[0,0,1]
	v_bfe_u32 v108, v106, 16, 1
	v_add3_u32 v106, v106, v108, s57
	v_bfe_u32 v108, v107, 16, 1
	v_lshrrev_b32_e32 v106, 16, v106
	v_add3_u32 v107, v107, v108, s57
	v_and_or_b32 v106, v107, s53, v106
	ds_write2st64_b32 v187, v133, v106 offset0:22 offset1:30
	v_lshlrev_b32_e32 v106, 16, v140
	v_and_b32_e32 v107, 0xffff0000, v140
	v_pk_add_f32 v[100:101], v[106:107], v[100:101] neg_lo:[0,1] neg_hi:[0,1]
	s_add_i32 s1, s1, 4
	v_pk_add_f32 v[100:101], v[104:105], v[100:101]
	v_cvt_f32_i32_e32 v104, s1
	v_div_scale_f32 v105, s[2:3], v104, v104, 1.0
	v_rcp_f32_e32 v106, v105
	s_mov_b64 s[2:3], 0xc0
	v_lshl_add_u64 v[128:129], v[98:99], 0, s[2:3]
	v_fma_f32 v107, -v105, v106, 1.0
	v_fmac_f32_e32 v106, v107, v106
	v_div_scale_f32 v107, vcc, 1.0, v104, 1.0
	v_mul_f32_e32 v108, v107, v106
	v_fma_f32 v109, -v105, v108, v107
	v_fmac_f32_e32 v108, v109, v106
	v_fma_f32 v105, -v105, v108, v107
	v_div_fmas_f32 v105, v105, v106, v108
	v_div_fixup_f32 v104, v105, v104, 1.0
	v_pk_fma_f32 v[100:101], v[104:105], v[100:101], v[112:113] op_sel_hi:[0,1,1] neg_lo:[0,0,1] neg_hi:[0,0,1]
	v_bfe_u32 v104, v100, 16, 1
	v_add3_u32 v100, v100, v104, s57
	v_bfe_u32 v104, v101, 16, 1
	v_lshrrev_b32_e32 v100, 16, v100
	v_add3_u32 v101, v101, v104, s57
	v_and_or_b32 v100, v101, s53, v100
	ds_write2st64_b32 v174, v132, v100 offset0:23 offset1:31
	v_lshl_add_u64 v[100:101], v[98:99], 0, s[42:43]
	v_lshl_add_u64 v[104:105], v[100:101], 0, v[202:203]
	s_waitcnt lgkmcnt(0)
	global_load_dwordx4 v[130:133], v[102:103], off offset:128
	global_load_dwordx4 v[134:137], v[102:103], off offset:1152
	global_load_dwordx4 v[138:141], v[104:105], off
	v_lshl_add_u64 v[104:105], v[100:101], 0, v[110:111]
	global_load_dwordx4 v[164:167], v[104:105], off
	v_lshl_add_u64 v[104:105], v[100:101], 0, v[114:115]
	global_load_dwordx4 v[168:171], v[104:105], off
	v_lshl_add_u64 v[104:105], v[100:101], 0, v[118:119]
	global_load_dwordx4 v[172:175], v[104:105], off
	v_lshl_add_u64 v[104:105], v[100:101], 0, v[122:123]
	v_lshl_add_u64 v[100:101], v[100:101], 0, v[126:127]
	global_load_dwordx4 v[182:185], v[104:105], off
	global_load_dwordx4 v[186:189], v[100:101], off
	s_nop 0
	global_load_dwordx4 v[98:101], v[102:103], off offset:192
	s_nop 0
	global_load_dwordx4 v[102:105], v[102:103], off offset:1216
	v_lshl_add_u64 v[106:107], v[128:129], 0, v[202:203]
	v_lshl_add_u64 v[110:111], v[128:129], 0, v[110:111]
	v_lshl_add_u64 v[114:115], v[128:129], 0, v[114:115]
	v_lshl_add_u64 v[118:119], v[128:129], 0, v[118:119]
	v_lshl_add_u64 v[122:123], v[128:129], 0, v[122:123]
	v_lshl_add_u64 v[126:127], v[128:129], 0, v[126:127]
	global_load_dwordx4 v[106:109], v[106:107], off
	s_nop 0
	global_load_dwordx4 v[110:113], v[110:111], off
	s_nop 0
	global_load_dwordx4 v[114:117], v[114:115], off
	s_nop 0
	global_load_dwordx4 v[118:121], v[118:119], off
	s_nop 0
	global_load_dwordx4 v[122:125], v[122:123], off
	s_nop 0
	global_load_dwordx4 v[126:129], v[126:127], off
	v_add_u32_e32 v194, v177, v178
	ds_read_b128 v[190:193], v194
	ds_read_b128 v[194:197], v194 offset:4096
	v_add_u32_e32 v202, v177, v179
	s_add_i32 s0, s0, s35
	s_mov_b64 s[26:27], 0
	s_waitcnt vmcnt(25) lgkmcnt(1)
	v_mfma_f32_16x16x32_bf16 v[198:201], v[90:93], v[190:193], 0
	s_waitcnt vmcnt(23)
	v_mfma_f32_16x16x32_bf16 v[226:229], v[94:97], v[190:193], 0
	v_mfma_f32_16x16x32_bf16 v[230:233], v[66:69], v[190:193], 0
	v_mfma_f32_16x16x32_bf16 v[234:237], v[70:73], v[190:193], 0
	v_mfma_f32_16x16x32_bf16 v[238:241], v[74:77], v[190:193], 0
	v_mfma_f32_16x16x32_bf16 v[242:245], v[78:81], v[190:193], 0
	v_mfma_f32_16x16x32_bf16 v[246:249], v[82:85], v[190:193], 0
	v_mfma_f32_16x16x32_bf16 v[190:193], v[86:89], v[190:193], 0
	s_waitcnt lgkmcnt(0)
	v_mfma_f32_16x16x32_bf16 v[90:93], v[90:93], v[194:197], 0
	v_mfma_f32_16x16x32_bf16 v[94:97], v[94:97], v[194:197], 0
	v_mfma_f32_16x16x32_bf16 v[66:69], v[66:69], v[194:197], 0
	v_mfma_f32_16x16x32_bf16 v[70:73], v[70:73], v[194:197], 0
	v_mfma_f32_16x16x32_bf16 v[74:77], v[74:77], v[194:197], 0
	v_mfma_f32_16x16x32_bf16 v[78:81], v[78:81], v[194:197], 0
	v_mfma_f32_16x16x32_bf16 v[82:85], v[82:85], v[194:197], 0
	v_mfma_f32_16x16x32_bf16 v[86:89], v[86:89], v[194:197], 0
	ds_read_b128 v[194:197], v202
	ds_read_b128 v[250:253], v202 offset:4096
	s_waitcnt vmcnt(20) lgkmcnt(1)
	v_mfma_f32_16x16x32_bf16 v[234:237], v[46:49], v[194:197], v[234:237]
	s_waitcnt lgkmcnt(0)
	v_mfma_f32_16x16x32_bf16 v[46:49], v[46:49], v[250:253], v[70:73]
	s_nop 2
	v_add_u32_e32 v70, v177, v180
	v_mfma_f32_16x16x32_bf16 v[230:233], v[42:45], v[194:197], v[230:233]
	v_mfma_f32_16x16x32_bf16 v[42:45], v[42:45], v[250:253], v[66:69]
	s_nop 2
	ds_read_b128 v[66:69], v70
	ds_read_b128 v[70:73], v70 offset:4096
	v_mfma_f32_16x16x32_bf16 v[226:229], v[38:41], v[194:197], v[226:229]
	v_mfma_f32_16x16x32_bf16 v[38:41], v[38:41], v[250:253], v[94:97]
	v_mfma_f32_16x16x32_bf16 v[198:201], v[34:37], v[194:197], v[198:201]
	s_waitcnt vmcnt(18)
	v_mfma_f32_16x16x32_bf16 v[242:245], v[54:57], v[194:197], v[242:245]
	v_mfma_f32_16x16x32_bf16 v[34:37], v[34:37], v[250:253], v[90:93]
	v_mfma_f32_16x16x32_bf16 v[54:57], v[54:57], v[250:253], v[78:81]
	v_mfma_f32_16x16x32_bf16 v[238:241], v[50:53], v[194:197], v[238:241]
	s_waitcnt vmcnt(14) lgkmcnt(1)
	v_mfma_f32_16x16x32_bf16 v[78:81], v[134:137], v[66:69], v[226:229]
	s_waitcnt lgkmcnt(0)
	v_mfma_f32_16x16x32_bf16 v[38:41], v[134:137], v[70:73], v[38:41]
	s_waitcnt vmcnt(12)
	v_mfma_f32_16x16x32_bf16 v[134:137], v[164:167], v[70:73], v[46:49]
	s_nop 2
	v_add_u32_e32 v46, v177, v181
	v_mfma_f32_16x16x32_bf16 v[246:249], v[58:61], v[194:197], v[246:249]
	v_mfma_f32_16x16x32_bf16 v[50:53], v[50:53], v[250:253], v[74:77]
	v_mfma_f32_16x16x32_bf16 v[58:61], v[58:61], v[250:253], v[82:85]
	v_mfma_f32_16x16x32_bf16 v[74:77], v[130:133], v[66:69], v[198:201]
	v_mfma_f32_16x16x32_bf16 v[82:85], v[138:141], v[66:69], v[230:233]
	s_waitcnt vmcnt(10)
	v_mfma_f32_16x16x32_bf16 v[94:97], v[172:175], v[66:69], v[242:245]
	v_mfma_f32_16x16x32_bf16 v[34:37], v[130:133], v[70:73], v[34:37]
	v_mfma_f32_16x16x32_bf16 v[130:133], v[138:141], v[70:73], v[42:45]
	v_mfma_f32_16x16x32_bf16 v[138:141], v[172:175], v[70:73], v[54:57]
	s_nop 1
	ds_read_b128 v[42:45], v46
	ds_read_b128 v[172:175], v46 offset:4096
	v_mfma_f32_16x16x32_bf16 v[190:193], v[62:65], v[194:197], v[190:193]
	v_mfma_f32_16x16x32_bf16 v[62:65], v[62:65], v[250:253], v[86:89]
	v_mfma_f32_16x16x32_bf16 v[86:89], v[164:167], v[66:69], v[234:237]
	v_mfma_f32_16x16x32_bf16 v[90:93], v[168:171], v[66:69], v[238:241]
	s_waitcnt vmcnt(9)
	v_mfma_f32_16x16x32_bf16 v[194:197], v[182:185], v[66:69], v[246:249]
	s_waitcnt vmcnt(8)
	v_mfma_f32_16x16x32_bf16 v[66:69], v[186:189], v[66:69], v[190:193]
	v_mfma_f32_16x16x32_bf16 v[50:53], v[168:171], v[70:73], v[50:53]
	v_mfma_f32_16x16x32_bf16 v[164:167], v[182:185], v[70:73], v[58:61]
	v_mfma_f32_16x16x32_bf16 v[168:171], v[186:189], v[70:73], v[62:65]
	s_waitcnt vmcnt(7) lgkmcnt(1)
	v_mfma_f32_16x16x32_bf16 v[182:185], v[98:101], v[42:45], v[74:77]
	s_waitcnt vmcnt(6)
	v_mfma_f32_16x16x32_bf16 v[186:189], v[102:105], v[42:45], v[78:81]
	s_waitcnt vmcnt(5)
	v_mfma_f32_16x16x32_bf16 v[78:81], v[106:109], v[42:45], v[82:85]
	s_waitcnt vmcnt(4)
	v_mfma_f32_16x16x32_bf16 v[74:77], v[110:113], v[42:45], v[86:89]
	s_waitcnt lgkmcnt(0)
	v_mfma_f32_16x16x32_bf16 v[84:87], v[98:101], v[172:175], v[34:37]
	s_nop 1
	v_mul_f32_e64 v98, v26, v186
	v_mul_f32_e64 v99, v27, v187
	v_add_u32_e32 v100, s0, v143
	s_nop 0
	v_pk_mul_f32 v[74:75], v[18:19], v[74:75]
	s_waitcnt vmcnt(3)
	v_mfma_f32_16x16x32_bf16 v[62:65], v[114:117], v[42:45], v[90:93]
	v_add_u32_e32 v82, 8, v100
	v_mfma_f32_16x16x32_bf16 v[88:91], v[102:105], v[172:175], v[38:41]
	s_nop 0
	v_mul_f32_e64 v92, v30, v182
	v_mul_f32_e64 v93, v31, v183
	v_pk_mul_f32 v[30:31], v[30:31], v[84:85]
	v_bfe_u32 v83, v92, 16, 1
	s_waitcnt vmcnt(2)
	v_mfma_f32_16x16x32_bf16 v[58:61], v[118:121], v[42:45], v[94:97]
	v_add3_u32 v83, v92, v83, s57
	v_pk_mul_f32 v[84:85], v[28:29], v[90:91]
	v_pk_mul_f32 v[26:27], v[26:27], v[88:89]
	v_pk_mul_f32 v[96:97], v[28:29], v[188:189]
	v_bfe_u32 v28, v30, 16, 1
	v_add3_u32 v28, v30, v28, s57
	v_bfe_u32 v29, v31, 16, 1
	v_pk_mul_f32 v[94:95], v[32:33], v[184:185]
	v_pk_mul_f32 v[32:33], v[32:33], v[86:87]
	v_lshrrev_b32_e32 v28, 16, v28
	v_add3_u32 v29, v31, v29, s57
	v_and_or_b32 v28, v29, s53, v28
	v_bfe_u32 v29, v32, 16, 1
	v_add3_u32 v29, v32, v29, s57
	v_bfe_u32 v30, v33, 16, 1
	v_lshrrev_b32_e32 v29, 16, v29
	v_add3_u32 v30, v33, v30, s57
	v_and_or_b32 v29, v30, s53, v29
	v_bfe_u32 v30, v26, 16, 1
	v_add3_u32 v26, v26, v30, s57
	v_bfe_u32 v30, v27, 16, 1
	v_lshrrev_b32_e32 v26, 16, v26
	v_add3_u32 v27, v27, v30, s57
	v_and_or_b32 v30, v27, s53, v26
	v_bfe_u32 v26, v84, 16, 1
	v_add3_u32 v26, v84, v26, s57
	v_bfe_u32 v27, v85, 16, 1
	v_lshrrev_b32_e32 v26, 16, v26
	v_add3_u32 v27, v85, v27, s57
	v_and_or_b32 v31, v27, s53, v26
	v_add_u32_e32 v26, 24, v100
	v_ashrrev_i32_e32 v27, 31, v26
	v_lshlrev_b64 v[26:27], 12, v[26:27]
	v_lshl_add_u64 v[26:27], v[162:163], 0, v[26:27]
	v_bfe_u32 v92, v93, 16, 1
	global_store_dwordx4 v[26:27], v[28:31], off offset:2560 sc1
	v_lshrrev_b32_e32 v83, 16, v83
	v_add3_u32 v92, v93, v92, s57
	v_pk_mul_f32 v[28:29], v[22:23], v[78:79]
	v_pk_mul_f32 v[32:33], v[20:21], v[76:77]
	v_bfe_u32 v76, v28, 16, 1
	v_and_or_b32 v92, v92, s53, v83
	v_bfe_u32 v83, v94, 16, 1
	v_add3_u32 v28, v28, v76, s57
	v_bfe_u32 v76, v29, 16, 1
	v_add3_u32 v83, v94, v83, s57
	v_bfe_u32 v93, v95, 16, 1
	v_pk_mul_f32 v[30:31], v[24:25], v[80:81]
	v_lshrrev_b32_e32 v28, 16, v28
	v_add3_u32 v29, v29, v76, s57
	v_lshrrev_b32_e32 v83, 16, v83
	v_add3_u32 v93, v95, v93, s57
	v_and_or_b32 v28, v29, s53, v28
	v_bfe_u32 v29, v30, 16, 1
	v_and_or_b32 v93, v93, s53, v83
	v_bfe_u32 v83, v98, 16, 1
	v_add3_u32 v29, v30, v29, s57
	v_bfe_u32 v30, v31, 16, 1
	v_add3_u32 v83, v98, v83, s57
	v_bfe_u32 v94, v99, 16, 1
	v_lshrrev_b32_e32 v29, 16, v29
	v_add3_u32 v30, v31, v30, s57
	v_lshrrev_b32_e32 v83, 16, v83
	v_add3_u32 v94, v99, v94, s57
	v_and_or_b32 v29, v30, s53, v29
	v_bfe_u32 v30, v74, 16, 1
	v_and_or_b32 v94, v94, s53, v83
	v_bfe_u32 v83, v96, 16, 1
	v_add3_u32 v30, v74, v30, s57
	v_bfe_u32 v31, v75, 16, 1
	v_mfma_f32_16x16x32_bf16 v[70:73], v[106:109], v[172:175], v[130:133]
	v_add3_u32 v83, v96, v83, s57
	v_bfe_u32 v95, v97, 16, 1
	v_lshrrev_b32_e32 v30, 16, v30
	v_add3_u32 v31, v75, v31, s57
	s_waitcnt vmcnt(2)
	v_mfma_f32_16x16x32_bf16 v[46:49], v[122:125], v[42:45], v[194:197]
	v_lshrrev_b32_e32 v83, 16, v83
	v_add3_u32 v95, v97, v95, s57
	v_and_or_b32 v30, v31, s53, v30
	s_waitcnt vmcnt(1)
	v_mfma_f32_16x16x32_bf16 v[42:45], v[126:129], v[42:45], v[66:69]
	v_bfe_u32 v31, v32, 16, 1
	v_and_or_b32 v95, v95, s53, v83
	v_ashrrev_i32_e32 v83, 31, v82
	v_mfma_f32_16x16x32_bf16 v[66:69], v[110:113], v[172:175], v[134:137]
	v_add3_u32 v31, v32, v31, s57
	v_bfe_u32 v32, v33, 16, 1
	v_lshlrev_b64 v[82:83], 12, v[82:83]
	v_lshrrev_b32_e32 v31, 16, v31
	v_add3_u32 v32, v33, v32, s57
	v_lshl_add_u64 v[82:83], v[162:163], 0, v[82:83]
	v_and_or_b32 v31, v32, s53, v31
	v_pk_mul_f32 v[22:23], v[22:23], v[70:71]
	global_store_dwordx4 v[82:83], v[28:31], off offset:2624 sc1
	v_pk_mul_f32 v[24:25], v[24:25], v[72:73]
	v_mfma_f32_16x16x32_bf16 v[54:57], v[114:117], v[172:175], v[50:53]
	v_mul_f32_e64 v28, v20, v68
	v_mul_f32_e64 v29, v21, v69
	v_pk_mul_f32 v[20:21], v[18:19], v[66:67]
	v_bfe_u32 v18, v22, 16, 1
	v_add3_u32 v18, v22, v18, s57
	v_bfe_u32 v19, v23, 16, 1
	v_lshrrev_b32_e32 v18, 16, v18
	v_add3_u32 v19, v23, v19, s57
	v_and_or_b32 v18, v19, s53, v18
	v_bfe_u32 v19, v24, 16, 1
	v_add3_u32 v19, v24, v19, s57
	v_bfe_u32 v22, v25, 16, 1
	v_lshrrev_b32_e32 v19, 16, v19
	v_add3_u32 v22, v25, v22, s57
	v_and_or_b32 v19, v22, s53, v19
	v_bfe_u32 v22, v20, 16, 1
	v_add3_u32 v20, v20, v22, s57
	v_bfe_u32 v22, v21, 16, 1
	v_lshrrev_b32_e32 v20, 16, v20
	v_add3_u32 v21, v21, v22, s57
	v_and_or_b32 v20, v21, s53, v20
	v_bfe_u32 v21, v28, 16, 1
	v_add3_u32 v21, v28, v21, s57
	v_bfe_u32 v22, v29, 16, 1
	v_lshrrev_b32_e32 v21, 16, v21
	v_add3_u32 v22, v29, v22, s57
	v_and_or_b32 v21, v22, s53, v21
	global_store_dwordx4 v[26:27], v[18:21], off offset:2624 sc1
	v_pk_mul_f32 v[24:25], v[10:11], v[58:59]
	v_pk_mul_f32 v[22:23], v[12:13], v[60:61]
	v_pk_mul_f32 v[18:19], v[14:15], v[62:63]
	v_pk_mul_f32 v[20:21], v[16:17], v[64:65]
	v_bfe_u32 v28, v18, 16, 1
	v_add3_u32 v18, v18, v28, s57
	v_bfe_u32 v28, v19, 16, 1
	v_lshrrev_b32_e32 v18, 16, v18
	v_add3_u32 v19, v19, v28, s57
	v_and_or_b32 v18, v19, s53, v18
	v_bfe_u32 v19, v20, 16, 1
	v_add3_u32 v19, v20, v19, s57
	v_bfe_u32 v20, v21, 16, 1
	v_lshrrev_b32_e32 v19, 16, v19
	v_add3_u32 v20, v21, v20, s57
	v_and_or_b32 v19, v20, s53, v19
	v_bfe_u32 v20, v24, 16, 1
	v_add3_u32 v20, v24, v20, s57
	v_bfe_u32 v21, v25, 16, 1
	v_lshrrev_b32_e32 v20, 16, v20
	v_add3_u32 v21, v25, v21, s57
	v_mfma_f32_16x16x32_bf16 v[50:53], v[118:121], v[172:175], v[138:141]
	v_and_or_b32 v20, v21, s53, v20
	v_bfe_u32 v21, v22, 16, 1
	v_add3_u32 v21, v22, v21, s57
	v_bfe_u32 v22, v23, 16, 1
	v_lshrrev_b32_e32 v21, 16, v21
	v_add3_u32 v22, v23, v22, s57
	v_and_or_b32 v21, v22, s53, v21
	v_pk_mul_f32 v[14:15], v[14:15], v[54:55]
	global_store_dwordx4 v[82:83], v[18:21], off offset:2688 sc1
	v_pk_mul_f32 v[16:17], v[16:17], v[56:57]
	v_mfma_f32_16x16x32_bf16 v[38:41], v[122:125], v[172:175], v[164:167]
	v_mul_f32_e64 v18, v12, v52
	v_mul_f32_e64 v19, v13, v53
	v_pk_mul_f32 v[12:13], v[10:11], v[50:51]
	v_bfe_u32 v10, v14, 16, 1
	v_add3_u32 v10, v14, v10, s57
	v_bfe_u32 v11, v15, 16, 1
	v_lshrrev_b32_e32 v10, 16, v10
	v_add3_u32 v11, v15, v11, s57
	v_and_or_b32 v10, v11, s53, v10
	v_bfe_u32 v11, v16, 16, 1
	v_add3_u32 v11, v16, v11, s57
	v_bfe_u32 v14, v17, 16, 1
	v_lshrrev_b32_e32 v11, 16, v11
	v_add3_u32 v14, v17, v14, s57
	v_and_or_b32 v11, v14, s53, v11
	v_bfe_u32 v14, v12, 16, 1
	v_add3_u32 v12, v12, v14, s57
	v_bfe_u32 v14, v13, 16, 1
	v_lshrrev_b32_e32 v12, 16, v12
	v_add3_u32 v13, v13, v14, s57
	v_and_or_b32 v12, v13, s53, v12
	v_bfe_u32 v13, v18, 16, 1
	v_add3_u32 v13, v18, v13, s57
	v_bfe_u32 v14, v19, 16, 1
	v_lshrrev_b32_e32 v13, 16, v13
	v_add3_u32 v14, v19, v14, s57
	v_and_or_b32 v13, v14, s53, v13
	global_store_dwordx4 v[26:27], v[10:13], off offset:2688 sc1
	v_pk_mul_f32 v[16:17], v[2:3], v[42:43]
	v_pk_mul_f32 v[14:15], v[4:5], v[44:45]
	v_pk_mul_f32 v[10:11], v[6:7], v[46:47]
	v_pk_mul_f32 v[12:13], v[8:9], v[48:49]
	v_bfe_u32 v18, v10, 16, 1
	v_add3_u32 v10, v10, v18, s57
	v_bfe_u32 v18, v11, 16, 1
	v_lshrrev_b32_e32 v10, 16, v10
	v_add3_u32 v11, v11, v18, s57
	v_and_or_b32 v10, v11, s53, v10
	v_bfe_u32 v11, v12, 16, 1
	v_add3_u32 v11, v12, v11, s57
	v_bfe_u32 v12, v13, 16, 1
	v_lshrrev_b32_e32 v11, 16, v11
	v_add3_u32 v12, v13, v12, s57
	v_and_or_b32 v11, v12, s53, v11
	v_bfe_u32 v12, v16, 16, 1
	v_add3_u32 v12, v16, v12, s57
	v_bfe_u32 v13, v17, 16, 1
	v_lshrrev_b32_e32 v12, 16, v12
	v_add3_u32 v13, v17, v13, s57
	v_mfma_f32_16x16x32_bf16 v[34:37], v[126:129], v[172:175], v[168:171]
	v_and_or_b32 v12, v13, s53, v12
	v_bfe_u32 v13, v14, 16, 1
	v_add3_u32 v13, v14, v13, s57
	v_bfe_u32 v14, v15, 16, 1
	v_lshrrev_b32_e32 v13, 16, v13
	v_add3_u32 v14, v15, v14, s57
	v_and_or_b32 v13, v14, s53, v13
	v_pk_mul_f32 v[6:7], v[6:7], v[38:39]
	global_store_dwordx4 v[82:83], v[10:13], off offset:2752 sc1
	v_pk_mul_f32 v[8:9], v[8:9], v[40:41]
	global_store_dwordx4 v[82:83], v[92:95], off offset:2560 sc1
	v_pk_mul_f32 v[10:11], v[4:5], v[36:37]
	v_pk_mul_f32 v[4:5], v[2:3], v[34:35]
	v_bfe_u32 v2, v6, 16, 1
	v_add3_u32 v2, v6, v2, s57
	v_bfe_u32 v3, v7, 16, 1
	v_lshrrev_b32_e32 v2, 16, v2
	v_add3_u32 v3, v7, v3, s57
	v_and_or_b32 v2, v3, s53, v2
	v_bfe_u32 v3, v8, 16, 1
	v_add3_u32 v3, v8, v3, s57
	v_bfe_u32 v6, v9, 16, 1
	v_lshrrev_b32_e32 v3, 16, v3
	v_add3_u32 v6, v9, v6, s57
	v_and_or_b32 v3, v6, s53, v3
	v_bfe_u32 v6, v4, 16, 1
	v_add3_u32 v4, v4, v6, s57
	v_bfe_u32 v6, v5, 16, 1
	v_lshrrev_b32_e32 v4, 16, v4
	v_add3_u32 v5, v5, v6, s57
	v_and_or_b32 v4, v5, s53, v4
	v_bfe_u32 v5, v10, 16, 1
	v_add3_u32 v5, v10, v5, s57
	v_bfe_u32 v6, v11, 16, 1
	v_lshrrev_b32_e32 v5, 16, v5
	v_add3_u32 v6, v11, v6, s57
	v_and_or_b32 v5, v6, s53, v5
	global_store_dwordx4 v[26:27], v[2:5], off offset:2752 sc1
	s_waitcnt lgkmcnt(0)

.LBB0_672:
	v_lshlrev_b32_e32 v202, 1, v144
	v_lshlrev_b32_e32 v6, 2, v142
	v_lshl_add_u64 v[98:99], s[10:11], 0, v[202:203]
	v_lshlrev_b32_e32 v202, 1, v146
	global_load_dwordx4 v[26:29], v6, s[12:13] offset:16
	global_load_dwordx4 v[30:33], v6, s[12:13]
	global_load_dwordx4 v[18:21], v6, s[12:13] offset:144
	global_load_dwordx4 v[22:25], v6, s[12:13] offset:128
	global_load_dwordx4 v[10:13], v6, s[12:13] offset:272
	global_load_dwordx4 v[14:17], v6, s[12:13] offset:256
	global_load_dwordx4 v[2:5], v6, s[12:13] offset:400
	s_nop 0
	global_load_dwordx4 v[6:9], v6, s[12:13] offset:384
	v_lshl_add_u64 v[102:103], v[98:99], 0, v[202:203]
	v_lshlrev_b32_e32 v202, 1, v148
	v_lshlrev_b32_e32 v110, 1, v150
	v_mov_b32_e32 v111, v203
	v_lshl_add_u64 v[34:35], v[98:99], 0, v[202:203]
	v_lshl_add_u64 v[36:37], v[98:99], 0, v[110:111]
	v_lshlrev_b32_e32 v114, 1, v152
	v_mov_b32_e32 v115, v203
	v_lshlrev_b32_e32 v118, 1, v154
	v_mov_b32_e32 v119, v203
	global_load_dwordx4 v[66:69], v[34:35], off
	global_load_dwordx4 v[70:73], v[36:37], off
	v_lshl_add_u64 v[34:35], v[98:99], 0, v[114:115]
	v_lshl_add_u64 v[36:37], v[98:99], 0, v[118:119]
	v_lshlrev_b32_e32 v122, 1, v156
	v_mov_b32_e32 v123, v203
	v_lshlrev_b32_e32 v126, 1, v158
	v_mov_b32_e32 v127, v203
	global_load_dwordx4 v[74:77], v[34:35], off
	global_load_dwordx4 v[78:81], v[36:37], off
	v_lshl_add_u64 v[34:35], v[98:99], 0, v[122:123]
	v_lshl_add_u64 v[36:37], v[98:99], 0, v[126:127]
	global_load_dwordx4 v[82:85], v[34:35], off
	global_load_dwordx4 v[86:89], v[36:37], off
	v_lshl_add_u64 v[58:59], v[98:99], 0, 64
	global_load_dwordx4 v[90:93], v[102:103], off
	global_load_dwordx4 v[34:37], v[102:103], off offset:64
	global_load_dwordx4 v[94:97], v[102:103], off offset:1024
	global_load_dwordx4 v[38:41], v[102:103], off offset:1088
	v_lshl_add_u64 v[42:43], v[58:59], 0, v[202:203]
	v_lshl_add_u64 v[46:47], v[58:59], 0, v[110:111]
	v_lshl_add_u64 v[50:51], v[58:59], 0, v[114:115]
	v_lshl_add_u64 v[54:55], v[58:59], 0, v[118:119]
	v_lshl_add_u64 v[60:61], v[58:59], 0, v[122:123]
	v_lshl_add_u64 v[62:63], v[58:59], 0, v[126:127]
	global_load_dwordx4 v[42:45], v[42:43], off
	s_nop 0
	global_load_dwordx4 v[46:49], v[46:47], off
	s_nop 0
	global_load_dwordx4 v[50:53], v[50:51], off
	s_nop 0
	global_load_dwordx4 v[54:57], v[54:55], off
	s_nop 0
	global_load_dwordx4 v[58:61], v[60:61], off
	s_nop 0
	global_load_dwordx4 v[62:65], v[62:63], off
	s_waitcnt vmcnt(24)
	v_lshlrev_b32_e32 v116, 16, v101
	v_and_b32_e32 v117, 0xffff0000, v101
	v_pk_add_f32 v[136:137], v[116:117], 0 op_sel_hi:[1,0]
	v_lshlrev_b32_e32 v138, 16, v100
	v_and_b32_e32 v139, 0xffff0000, v100
	v_pk_add_f32 v[100:101], v[136:137], v[138:139]
	v_lshlrev_b32_e32 v188, 16, v112
	v_and_b32_e32 v189, 0xffff0000, v112
	v_pk_add_f32 v[112:113], v[100:101], v[188:189]
	v_lshlrev_b32_e32 v100, 16, v104
	v_and_b32_e32 v101, 0xffff0000, v104
	s_min_u32 s88, s86, s17
	v_sub_u32_e64 v104, s38, 2 clamp
	v_sub_u32_e32 v104, s88, v104
	v_cvt_f32_i32_e32 v104, v104
	v_pk_add_f32 v[112:113], v[112:113], v[100:101]
	s_min_u32 s2, s2, s17
	v_div_scale_f32 v135, s[88:89], v104, v104, 1.0
	v_rcp_f32_e32 v136, v135
	s_min_u32 s88, s83, s17
	v_fma_f32 v137, -v135, v136, 1.0
	v_fmac_f32_e32 v136, v137, v136
	v_div_scale_f32 v137, vcc, 1.0, v104, 1.0
	v_mul_f32_e32 v140, v137, v136
	v_fma_f32 v184, -v135, v140, v137
	v_fmac_f32_e32 v140, v184, v136
	v_fma_f32 v135, -v135, v140, v137
	v_div_fmas_f32 v135, v135, v136, v140
	v_div_fixup_f32 v104, v135, v104, 1.0
	v_pk_fma_f32 v[136:137], v[104:105], v[112:113], v[188:189] op_sel_hi:[0,1,1] neg_lo:[0,0,1] neg_hi:[0,0,1]
	v_bfe_u32 v104, v136, 16, 1
	v_add3_u32 v104, v136, v104, s57
	v_bfe_u32 v135, v137, 16, 1
	v_lshrrev_b32_e32 v104, 16, v104
	v_add3_u32 v135, v137, v135, s57
	v_and_or_b32 v184, v135, s53, v104
	v_lshlrev_b32_e32 v104, 16, v105
	v_and_b32_e32 v105, 0xffff0000, v105
	v_pk_add_f32 v[116:117], v[104:105], v[116:117] neg_lo:[0,1] neg_hi:[0,1]
	v_add_u32_e32 v135, v147, v145
	v_pk_add_f32 v[112:113], v[112:113], v[116:117]
	v_sub_u32_e64 v116, s87, 2 clamp
	v_sub_u32_e32 v116, s88, v116
	v_cvt_f32_i32_e32 v116, v116
	s_min_u32 s87, s82, s17
	s_sub_i32 s86, s87, s86
	s_add_i32 s86, s86, 2
	v_div_scale_f32 v117, s[88:89], v116, v116, 1.0
	v_rcp_f32_e32 v136, v117
	s_nop 0
	v_fma_f32 v137, -v117, v136, 1.0
	v_fmac_f32_e32 v136, v137, v136
	v_div_scale_f32 v137, vcc, 1.0, v116, 1.0
	v_mul_f32_e32 v140, v137, v136
	v_fma_f32 v185, -v117, v140, v137
	v_fmac_f32_e32 v140, v185, v136
	v_fma_f32 v117, -v117, v140, v137
	v_div_fmas_f32 v117, v117, v136, v140
	v_div_fixup_f32 v116, v117, v116, 1.0
	v_pk_fma_f32 v[116:117], v[116:117], v[112:113], v[100:101] op_sel_hi:[0,1,1] neg_lo:[0,0,1] neg_hi:[0,0,1]
	v_bfe_u32 v136, v116, 16, 1
	v_add3_u32 v116, v116, v136, s57
	v_bfe_u32 v136, v117, 16, 1
	v_lshrrev_b32_e32 v116, 16, v116
	v_add3_u32 v117, v117, v136, s57
	v_and_or_b32 v185, v117, s53, v116
	v_lshlrev_b32_e32 v116, 16, v109
	v_and_b32_e32 v117, 0xffff0000, v109
	v_cvt_f32_i32_e32 v109, s86
	v_pk_add_f32 v[138:139], v[116:117], v[138:139] neg_lo:[0,1] neg_hi:[0,1]
	v_add_u32_e32 v136, v149, v145
	v_pk_add_f32 v[138:139], v[112:113], v[138:139]
	v_div_scale_f32 v112, s[86:87], v109, v109, 1.0
	v_rcp_f32_e32 v113, v112
	s_min_u32 s86, s81, s17
	s_sub_i32 s83, s86, s83
	s_add_i32 s83, s83, 2
	v_fma_f32 v137, -v112, v113, 1.0
	v_fmac_f32_e32 v113, v137, v113
	v_div_scale_f32 v137, vcc, 1.0, v109, 1.0
	v_mul_f32_e32 v140, v137, v113
	v_fma_f32 v186, -v112, v140, v137
	v_fmac_f32_e32 v140, v186, v113
	v_fma_f32 v112, -v112, v140, v137
	v_div_fmas_f32 v112, v112, v113, v140
	v_div_fixup_f32 v112, v112, v109, 1.0
	v_pk_fma_f32 v[112:113], v[112:113], v[138:139], v[104:105] op_sel_hi:[0,1,1] neg_lo:[0,0,1] neg_hi:[0,0,1]
	v_bfe_u32 v109, v112, 16, 1
	v_add3_u32 v109, v112, v109, s57
	v_bfe_u32 v112, v113, 16, 1
	v_lshrrev_b32_e32 v109, 16, v109
	v_add3_u32 v112, v113, v112, s57
	v_and_or_b32 v186, v112, s53, v109
	v_lshlrev_b32_e32 v112, 16, v108
	v_and_b32_e32 v113, 0xffff0000, v108
	v_pk_add_f32 v[108:109], v[112:113], v[188:189] neg_lo:[0,1] neg_hi:[0,1]
	v_add_u32_e32 v137, v151, v145
	v_pk_add_f32 v[188:189], v[138:139], v[108:109]
	v_cvt_f32_i32_e32 v108, s83
	s_min_u32 s83, s80, s17
	s_sub_i32 s82, s83, s82
	s_add_i32 s82, s82, 2
	v_div_scale_f32 v109, s[86:87], v108, v108, 1.0
	v_rcp_f32_e32 v138, v109
	s_nop 0
	v_fma_f32 v139, -v109, v138, 1.0
	v_fmac_f32_e32 v138, v139, v138
	v_div_scale_f32 v139, vcc, 1.0, v108, 1.0
	v_mul_f32_e32 v140, v139, v138
	v_fma_f32 v187, -v109, v140, v139
	v_fmac_f32_e32 v140, v187, v138
	v_fma_f32 v109, -v109, v140, v139
	v_div_fmas_f32 v109, v109, v138, v140
	v_div_fixup_f32 v108, v109, v108, 1.0
	v_pk_fma_f32 v[108:109], v[108:109], v[188:189], v[116:117] op_sel_hi:[0,1,1] neg_lo:[0,0,1] neg_hi:[0,0,1]
	v_bfe_u32 v138, v108, 16, 1
	v_add3_u32 v108, v108, v138, s57
	v_bfe_u32 v138, v109, 16, 1
	v_lshrrev_b32_e32 v108, 16, v108
	v_add3_u32 v109, v109, v138, s57
	v_and_or_b32 v187, v109, s53, v108
	v_lshlrev_b32_e32 v108, 16, v106
	v_and_b32_e32 v109, 0xffff0000, v106
	v_cvt_f32_i32_e32 v106, s82
	v_pk_add_f32 v[100:101], v[108:109], v[100:101] neg_lo:[0,1] neg_hi:[0,1]
	v_add_u32_e32 v138, v153, v145
	v_pk_add_f32 v[100:101], v[188:189], v[100:101]
	v_div_scale_f32 v139, s[82:83], v106, v106, 1.0
	v_rcp_f32_e32 v140, v139
	s_min_u32 s82, s79, s17
	s_sub_i32 s81, s82, s81
	s_add_i32 s81, s81, 2
	v_fma_f32 v188, -v139, v140, 1.0
	v_fmac_f32_e32 v140, v188, v140
	v_div_scale_f32 v188, vcc, 1.0, v106, 1.0
	v_mul_f32_e32 v189, v188, v140
	v_fma_f32 v190, -v139, v189, v188
	v_fmac_f32_e32 v189, v190, v140
	v_fma_f32 v139, -v139, v189, v188
	v_div_fmas_f32 v139, v139, v140, v189
	v_div_fixup_f32 v106, v139, v106, 1.0
	v_pk_fma_f32 v[188:189], v[106:107], v[100:101], v[112:113] op_sel_hi:[0,1,1] neg_lo:[0,0,1] neg_hi:[0,0,1]
	v_bfe_u32 v106, v188, 16, 1
	v_add3_u32 v106, v188, v106, s57
	v_bfe_u32 v139, v189, 16, 1
	v_lshrrev_b32_e32 v106, 16, v106
	v_add3_u32 v139, v189, v139, s57
	v_and_or_b32 v188, v139, s53, v106
	v_lshlrev_b32_e32 v106, 16, v107
	v_and_b32_e32 v107, 0xffff0000, v107
	v_pk_add_f32 v[104:105], v[106:107], v[104:105] neg_lo:[0,1] neg_hi:[0,1]
	v_add_u32_e32 v139, v155, v145
	v_pk_add_f32 v[100:101], v[100:101], v[104:105]
	v_cvt_f32_i32_e32 v104, s81
	s_min_u32 s81, s58, s17
	s_sub_i32 s80, s81, s80
	s_add_i32 s80, s80, 2
	v_div_scale_f32 v105, s[82:83], v104, v104, 1.0
	v_rcp_f32_e32 v140, v105
	s_nop 0
	v_fma_f32 v189, -v105, v140, 1.0
	v_fmac_f32_e32 v140, v189, v140
	v_div_scale_f32 v189, vcc, 1.0, v104, 1.0
	v_mul_f32_e32 v190, v189, v140
	v_fma_f32 v191, -v105, v190, v189
	v_fmac_f32_e32 v190, v191, v140
	v_fma_f32 v105, -v105, v190, v189
	v_div_fmas_f32 v105, v105, v140, v190
	v_div_fixup_f32 v104, v105, v104, 1.0
	v_pk_fma_f32 v[104:105], v[104:105], v[100:101], v[108:109] op_sel_hi:[0,1,1] neg_lo:[0,0,1] neg_hi:[0,0,1]
	v_bfe_u32 v140, v104, 16, 1
	v_add3_u32 v104, v104, v140, s57
	v_bfe_u32 v140, v105, 16, 1
	v_lshrrev_b32_e32 v104, 16, v104
	v_add3_u32 v105, v105, v140, s57
	v_and_or_b32 v189, v105, s53, v104
	v_lshlrev_b32_e32 v104, 16, v183
	v_and_b32_e32 v105, 0xffff0000, v183
	v_pk_add_f32 v[116:117], v[104:105], v[116:117] neg_lo:[0,1] neg_hi:[0,1]
	v_add_u32_e32 v140, v157, v145
	v_pk_add_f32 v[190:191], v[100:101], v[116:117]
	v_cvt_f32_i32_e32 v100, s80
	v_div_scale_f32 v101, s[80:81], v100, v100, 1.0
	v_rcp_f32_e32 v116, v101
	s_min_u32 s80, s78, s17
	s_sub_i32 s79, s80, s79
	s_add_i32 s79, s79, 2
	v_fma_f32 v117, -v101, v116, 1.0
	v_fmac_f32_e32 v116, v117, v116
	v_div_scale_f32 v117, vcc, 1.0, v100, 1.0
	v_mul_f32_e32 v183, v117, v116
	v_fma_f32 v192, -v101, v183, v117
	v_fmac_f32_e32 v183, v192, v116
	v_fma_f32 v101, -v101, v183, v117
	v_div_fmas_f32 v101, v101, v116, v183
	v_div_fixup_f32 v100, v101, v100, 1.0
	v_pk_fma_f32 v[100:101], v[100:101], v[190:191], v[106:107] op_sel_hi:[0,1,1] neg_lo:[0,0,1] neg_hi:[0,0,1]
	v_bfe_u32 v116, v100, 16, 1
	v_add3_u32 v100, v100, v116, s57
	v_bfe_u32 v116, v101, 16, 1
	v_lshrrev_b32_e32 v100, 16, v100
	v_add3_u32 v101, v101, v116, s57
	v_and_or_b32 v183, v101, s53, v100
	v_lshlrev_b32_e32 v100, 16, v182
	v_and_b32_e32 v101, 0xffff0000, v182
	v_pk_add_f32 v[112:113], v[100:101], v[112:113] neg_lo:[0,1] neg_hi:[0,1]
	v_add_u32_e32 v117, v159, v145
	v_pk_add_f32 v[190:191], v[190:191], v[112:113]
	v_cvt_f32_i32_e32 v112, s79
	s_min_u32 s79, s77, s17
	s_sub_i32 s58, s79, s58
	s_add_i32 s58, s58, 2
	v_div_scale_f32 v113, s[80:81], v112, v112, 1.0
	v_rcp_f32_e32 v116, v113
	s_nop 0
	v_fma_f32 v182, -v113, v116, 1.0
	v_fmac_f32_e32 v116, v182, v116
	v_div_scale_f32 v182, vcc, 1.0, v112, 1.0
	v_mul_f32_e32 v192, v182, v116
	v_fma_f32 v193, -v113, v192, v182
	v_fmac_f32_e32 v192, v193, v116
	v_fma_f32 v113, -v113, v192, v182
	v_div_fmas_f32 v113, v113, v116, v192
	v_div_fixup_f32 v112, v113, v112, 1.0
	v_pk_fma_f32 v[112:113], v[112:113], v[190:191], v[104:105] op_sel_hi:[0,1,1] neg_lo:[0,0,1] neg_hi:[0,0,1]
	v_bfe_u32 v116, v112, 16, 1
	v_add3_u32 v112, v112, v116, s57
	v_bfe_u32 v116, v113, 16, 1
	v_lshrrev_b32_e32 v112, 16, v112
	v_add3_u32 v113, v113, v116, s57
	v_and_or_b32 v182, v113, s53, v112
	v_lshlrev_b32_e32 v112, 16, v175
	v_and_b32_e32 v113, 0xffff0000, v175
	v_pk_add_f32 v[108:109], v[112:113], v[108:109] neg_lo:[0,1] neg_hi:[0,1]
	v_add_u32_e32 v116, v176, v145
	v_pk_add_f32 v[190:191], v[190:191], v[108:109]
	v_cvt_f32_i32_e32 v108, s58
	s_min_u32 s58, s76, s17
	s_sub_i32 s58, s58, s78
	s_add_i32 s58, s58, 2
	v_div_scale_f32 v109, s[80:81], v108, v108, 1.0
	v_rcp_f32_e32 v175, v109
	s_nop 0
	v_fma_f32 v192, -v109, v175, 1.0
	v_fmac_f32_e32 v175, v192, v175
	v_div_scale_f32 v192, vcc, 1.0, v108, 1.0
	v_mul_f32_e32 v193, v192, v175
	v_fma_f32 v194, -v109, v193, v192
	v_fmac_f32_e32 v193, v194, v175
	v_fma_f32 v109, -v109, v193, v192
	v_div_fmas_f32 v109, v109, v175, v193
	v_div_fixup_f32 v108, v109, v108, 1.0
	v_pk_fma_f32 v[108:109], v[108:109], v[190:191], v[100:101] op_sel_hi:[0,1,1] neg_lo:[0,0,1] neg_hi:[0,0,1]
	v_bfe_u32 v175, v108, 16, 1
	v_add3_u32 v108, v108, v175, s57
	v_bfe_u32 v175, v109, 16, 1
	v_lshrrev_b32_e32 v108, 16, v108
	v_add3_u32 v109, v109, v175, s57
	v_and_or_b32 v108, v109, s53, v108
	ds_write2st64_b32 v135, v184, v108 offset1:8
	v_lshlrev_b32_e32 v108, 16, v174
	v_and_b32_e32 v109, 0xffff0000, v174
	v_pk_add_f32 v[106:107], v[108:109], v[106:107] neg_lo:[0,1] neg_hi:[0,1]
	s_nop 0
	v_pk_add_f32 v[174:175], v[190:191], v[106:107]
	v_cvt_f32_i32_e32 v106, s58
	s_min_u32 s58, s75, s17
	s_sub_i32 s58, s58, s77
	s_add_i32 s58, s58, 2
	v_div_scale_f32 v107, s[78:79], v106, v106, 1.0
	v_rcp_f32_e32 v184, v107
	s_nop 0
	v_fma_f32 v190, -v107, v184, 1.0
	v_fmac_f32_e32 v184, v190, v184
	v_div_scale_f32 v190, vcc, 1.0, v106, 1.0
	v_mul_f32_e32 v191, v190, v184
	v_fma_f32 v192, -v107, v191, v190
	v_fmac_f32_e32 v191, v192, v184
	v_fma_f32 v107, -v107, v191, v190
	v_div_fmas_f32 v107, v107, v184, v191
	v_div_fixup_f32 v106, v107, v106, 1.0
	v_pk_fma_f32 v[106:107], v[106:107], v[174:175], v[112:113] op_sel_hi:[0,1,1] neg_lo:[0,0,1] neg_hi:[0,0,1]
	v_bfe_u32 v184, v106, 16, 1
	v_add3_u32 v106, v106, v184, s57
	v_bfe_u32 v184, v107, 16, 1
	v_lshrrev_b32_e32 v106, 16, v106
	v_add3_u32 v107, v107, v184, s57
	v_and_or_b32 v106, v107, s53, v106
	ds_write2st64_b32 v136, v185, v106 offset0:1 offset1:9
	v_lshlrev_b32_e32 v106, 16, v173
	v_and_b32_e32 v107, 0xffff0000, v173
	v_pk_add_f32 v[104:105], v[106:107], v[104:105] neg_lo:[0,1] neg_hi:[0,1]
	s_nop 0
	v_pk_add_f32 v[174:175], v[174:175], v[104:105]
	v_cvt_f32_i32_e32 v104, s58
	s_min_u32 s58, s74, s17
	s_sub_i32 s58, s58, s76
	s_add_i32 s58, s58, 2
	v_div_scale_f32 v105, s[78:79], v104, v104, 1.0
	v_rcp_f32_e32 v173, v105
	s_nop 0
	v_fma_f32 v184, -v105, v173, 1.0
	v_fmac_f32_e32 v173, v184, v173
	v_div_scale_f32 v184, vcc, 1.0, v104, 1.0
	v_mul_f32_e32 v185, v184, v173
	v_fma_f32 v190, -v105, v185, v184
	v_fmac_f32_e32 v185, v190, v173
	v_fma_f32 v105, -v105, v185, v184
	v_div_fmas_f32 v105, v105, v173, v185
	v_div_fixup_f32 v104, v105, v104, 1.0
	v_pk_fma_f32 v[104:105], v[104:105], v[174:175], v[108:109] op_sel_hi:[0,1,1] neg_lo:[0,0,1] neg_hi:[0,0,1]
	v_bfe_u32 v173, v104, 16, 1
	v_add3_u32 v104, v104, v173, s57
	v_bfe_u32 v173, v105, 16, 1
	v_lshrrev_b32_e32 v104, 16, v104
	v_add3_u32 v105, v105, v173, s57
	v_and_or_b32 v104, v105, s53, v104
	ds_write2st64_b32 v137, v186, v104 offset0:2 offset1:10
	v_lshlrev_b32_e32 v104, 16, v172
	v_and_b32_e32 v105, 0xffff0000, v172
	v_pk_add_f32 v[100:101], v[104:105], v[100:101] neg_lo:[0,1] neg_hi:[0,1]
	s_nop 0
	v_pk_add_f32 v[172:173], v[174:175], v[100:101]
	v_cvt_f32_i32_e32 v100, s58
	s_min_u32 s58, s73, s17
	s_sub_i32 s58, s58, s75
	s_add_i32 s58, s58, 2
	v_div_scale_f32 v101, s[76:77], v100, v100, 1.0
	v_rcp_f32_e32 v174, v101
	s_nop 0
	v_fma_f32 v175, -v101, v174, 1.0
	v_fmac_f32_e32 v174, v175, v174
	v_div_scale_f32 v175, vcc, 1.0, v100, 1.0
	v_mul_f32_e32 v184, v175, v174
	v_fma_f32 v185, -v101, v184, v175
	v_fmac_f32_e32 v184, v185, v174
	v_fma_f32 v101, -v101, v184, v175
	v_div_fmas_f32 v101, v101, v174, v184
	v_div_fixup_f32 v100, v101, v100, 1.0
	v_pk_fma_f32 v[100:101], v[100:101], v[172:173], v[106:107] op_sel_hi:[0,1,1] neg_lo:[0,0,1] neg_hi:[0,0,1]
	v_bfe_u32 v174, v100, 16, 1
	v_add3_u32 v100, v100, v174, s57
	v_bfe_u32 v174, v101, 16, 1
	v_lshrrev_b32_e32 v100, 16, v100
	v_add3_u32 v101, v101, v174, s57
	v_and_or_b32 v100, v101, s53, v100
	ds_write2st64_b32 v138, v187, v100 offset0:3 offset1:11
	v_lshlrev_b32_e32 v100, 16, v171
	v_and_b32_e32 v101, 0xffff0000, v171
	v_pk_add_f32 v[112:113], v[100:101], v[112:113] neg_lo:[0,1] neg_hi:[0,1]
	s_nop 0
	v_pk_add_f32 v[172:173], v[172:173], v[112:113]
	v_cvt_f32_i32_e32 v112, s58
	s_min_u32 s58, s72, s17
	s_sub_i32 s58, s58, s74
	s_add_i32 s58, s58, 2
	v_div_scale_f32 v113, s[76:77], v112, v112, 1.0
	v_rcp_f32_e32 v171, v113
	s_nop 0
	v_fma_f32 v174, -v113, v171, 1.0
	v_fmac_f32_e32 v171, v174, v171
	v_div_scale_f32 v174, vcc, 1.0, v112, 1.0
	v_mul_f32_e32 v175, v174, v171
	v_fma_f32 v184, -v113, v175, v174
	v_fmac_f32_e32 v175, v184, v171
	v_fma_f32 v113, -v113, v175, v174
	v_div_fmas_f32 v113, v113, v171, v175
	v_div_fixup_f32 v112, v113, v112, 1.0
	v_pk_fma_f32 v[112:113], v[112:113], v[172:173], v[104:105] op_sel_hi:[0,1,1] neg_lo:[0,0,1] neg_hi:[0,0,1]
	v_bfe_u32 v171, v112, 16, 1
	v_add3_u32 v112, v112, v171, s57
	v_bfe_u32 v171, v113, 16, 1
	v_lshrrev_b32_e32 v112, 16, v112
	v_add3_u32 v113, v113, v171, s57
	v_and_or_b32 v112, v113, s53, v112
	ds_write2st64_b32 v139, v188, v112 offset0:4 offset1:12
	v_lshlrev_b32_e32 v112, 16, v170
	v_and_b32_e32 v113, 0xffff0000, v170
	v_pk_add_f32 v[108:109], v[112:113], v[108:109] neg_lo:[0,1] neg_hi:[0,1]
	s_nop 0
	v_pk_add_f32 v[170:171], v[172:173], v[108:109]
	v_cvt_f32_i32_e32 v108, s58
	s_min_u32 s58, s69, s17
	s_sub_i32 s58, s58, s73
	s_add_i32 s58, s58, 2
	v_div_scale_f32 v109, s[74:75], v108, v108, 1.0
	v_rcp_f32_e32 v172, v109
	s_nop 0
	v_fma_f32 v173, -v109, v172, 1.0
	v_fmac_f32_e32 v172, v173, v172
	v_div_scale_f32 v173, vcc, 1.0, v108, 1.0
	v_mul_f32_e32 v174, v173, v172
	v_fma_f32 v175, -v109, v174, v173
	v_fmac_f32_e32 v174, v175, v172
	v_fma_f32 v109, -v109, v174, v173
	v_div_fmas_f32 v109, v109, v172, v174
	v_div_fixup_f32 v108, v109, v108, 1.0
	v_pk_fma_f32 v[108:109], v[108:109], v[170:171], v[100:101] op_sel_hi:[0,1,1] neg_lo:[0,0,1] neg_hi:[0,0,1]
	v_bfe_u32 v172, v108, 16, 1
	v_add3_u32 v108, v108, v172, s57
	v_bfe_u32 v172, v109, 16, 1
	v_lshrrev_b32_e32 v108, 16, v108
	v_add3_u32 v109, v109, v172, s57
	v_and_or_b32 v108, v109, s53, v108
	ds_write2st64_b32 v140, v189, v108 offset0:5 offset1:13
	v_lshlrev_b32_e32 v108, 16, v169
	v_and_b32_e32 v109, 0xffff0000, v169
	v_pk_add_f32 v[106:107], v[108:109], v[106:107] neg_lo:[0,1] neg_hi:[0,1]
	s_nop 0
	v_pk_add_f32 v[170:171], v[170:171], v[106:107]
	v_cvt_f32_i32_e32 v106, s58
	s_min_u32 s58, s68, s17
	s_sub_i32 s58, s58, s72
	s_add_i32 s58, s58, 2
	v_div_scale_f32 v107, s[74:75], v106, v106, 1.0
	v_rcp_f32_e32 v169, v107
	s_nop 0
	v_fma_f32 v172, -v107, v169, 1.0
	v_fmac_f32_e32 v169, v172, v169
	v_div_scale_f32 v172, vcc, 1.0, v106, 1.0
	v_mul_f32_e32 v173, v172, v169
	v_fma_f32 v174, -v107, v173, v172
	v_fmac_f32_e32 v173, v174, v169
	v_fma_f32 v107, -v107, v173, v172
	v_div_fmas_f32 v107, v107, v169, v173
	v_div_fixup_f32 v106, v107, v106, 1.0
	v_pk_fma_f32 v[106:107], v[106:107], v[170:171], v[112:113] op_sel_hi:[0,1,1] neg_lo:[0,0,1] neg_hi:[0,0,1]
	v_bfe_u32 v169, v106, 16, 1
	v_add3_u32 v106, v106, v169, s57
	v_bfe_u32 v169, v107, 16, 1
	v_lshrrev_b32_e32 v106, 16, v106
	v_add3_u32 v107, v107, v169, s57
	v_and_or_b32 v106, v107, s53, v106
	ds_write2st64_b32 v117, v183, v106 offset0:6 offset1:14
	v_lshlrev_b32_e32 v106, 16, v168
	v_and_b32_e32 v107, 0xffff0000, v168
	v_pk_add_f32 v[104:105], v[106:107], v[104:105] neg_lo:[0,1] neg_hi:[0,1]
	s_nop 0
	v_pk_add_f32 v[168:169], v[170:171], v[104:105]
	v_cvt_f32_i32_e32 v104, s58
	s_min_u32 s58, s63, s17
	s_sub_i32 s58, s58, s69
	s_add_i32 s58, s58, 2
	v_div_scale_f32 v105, s[72:73], v104, v104, 1.0
	v_rcp_f32_e32 v170, v105
	s_nop 0
	v_fma_f32 v171, -v105, v170, 1.0
	v_fmac_f32_e32 v170, v171, v170
	v_div_scale_f32 v171, vcc, 1.0, v104, 1.0
	v_mul_f32_e32 v172, v171, v170
	v_fma_f32 v173, -v105, v172, v171
	v_fmac_f32_e32 v172, v173, v170
	v_fma_f32 v105, -v105, v172, v171
	v_div_fmas_f32 v105, v105, v170, v172
	v_div_fixup_f32 v104, v105, v104, 1.0
	v_pk_fma_f32 v[104:105], v[104:105], v[168:169], v[108:109] op_sel_hi:[0,1,1] neg_lo:[0,0,1] neg_hi:[0,0,1]
	v_bfe_u32 v170, v104, 16, 1
	v_add3_u32 v104, v104, v170, s57
	v_bfe_u32 v170, v105, 16, 1
	v_lshrrev_b32_e32 v104, 16, v104
	v_add3_u32 v105, v105, v170, s57
	v_and_or_b32 v104, v105, s53, v104
	ds_write2st64_b32 v116, v182, v104 offset0:7 offset1:15
	v_lshlrev_b32_e32 v104, 16, v167
	v_and_b32_e32 v105, 0xffff0000, v167
	v_pk_add_f32 v[100:101], v[104:105], v[100:101] neg_lo:[0,1] neg_hi:[0,1]
	s_nop 0
	v_pk_add_f32 v[168:169], v[168:169], v[100:101]
	v_cvt_f32_i32_e32 v100, s58
	s_min_u32 s58, s62, s17
	s_sub_i32 s58, s58, s68
	s_add_i32 s58, s58, 2
	v_div_scale_f32 v101, s[72:73], v100, v100, 1.0
	v_rcp_f32_e32 v167, v101
	s_nop 0
	v_fma_f32 v170, -v101, v167, 1.0
	v_fmac_f32_e32 v167, v170, v167
	v_div_scale_f32 v170, vcc, 1.0, v100, 1.0
	v_mul_f32_e32 v171, v170, v167
	v_fma_f32 v172, -v101, v171, v170
	v_fmac_f32_e32 v171, v172, v167
	v_fma_f32 v101, -v101, v171, v170
	v_div_fmas_f32 v101, v101, v167, v171
	v_div_fixup_f32 v100, v101, v100, 1.0
	v_pk_fma_f32 v[100:101], v[100:101], v[168:169], v[106:107] op_sel_hi:[0,1,1] neg_lo:[0,0,1] neg_hi:[0,0,1]
	v_bfe_u32 v167, v100, 16, 1
	v_add3_u32 v100, v100, v167, s57
	v_bfe_u32 v167, v101, 16, 1
	v_lshrrev_b32_e32 v100, 16, v100
	v_add3_u32 v101, v101, v167, s57
	v_and_or_b32 v167, v101, s53, v100
	v_lshlrev_b32_e32 v100, 16, v166
	v_and_b32_e32 v101, 0xffff0000, v166
	v_pk_add_f32 v[112:113], v[100:101], v[112:113] neg_lo:[0,1] neg_hi:[0,1]
	s_nop 0
	v_pk_add_f32 v[168:169], v[168:169], v[112:113]
	v_cvt_f32_i32_e32 v112, s58
	s_min_u32 s58, s56, s17
	s_sub_i32 s58, s58, s63
	s_add_i32 s58, s58, 2
	v_div_scale_f32 v113, s[68:69], v112, v112, 1.0
	v_rcp_f32_e32 v166, v113
	s_nop 0
	v_fma_f32 v170, -v113, v166, 1.0
	v_fmac_f32_e32 v166, v170, v166
	v_div_scale_f32 v170, vcc, 1.0, v112, 1.0
	v_mul_f32_e32 v171, v170, v166
	v_fma_f32 v172, -v113, v171, v170
	v_fmac_f32_e32 v171, v172, v166
	v_fma_f32 v113, -v113, v171, v170
	v_div_fmas_f32 v113, v113, v166, v171
	v_div_fixup_f32 v112, v113, v112, 1.0
	v_pk_fma_f32 v[112:113], v[112:113], v[168:169], v[104:105] op_sel_hi:[0,1,1] neg_lo:[0,0,1] neg_hi:[0,0,1]
	v_bfe_u32 v166, v112, 16, 1
	v_add3_u32 v112, v112, v166, s57
	v_bfe_u32 v166, v113, 16, 1
	v_lshrrev_b32_e32 v112, 16, v112
	v_add3_u32 v113, v113, v166, s57
	v_and_or_b32 v166, v113, s53, v112
	v_lshlrev_b32_e32 v112, 16, v165
	v_and_b32_e32 v113, 0xffff0000, v165
	v_pk_add_f32 v[108:109], v[112:113], v[108:109] neg_lo:[0,1] neg_hi:[0,1]
	s_nop 0
	v_pk_add_f32 v[168:169], v[168:169], v[108:109]
	v_cvt_f32_i32_e32 v108, s58
	s_min_u32 s58, s54, s17
	s_sub_i32 s58, s58, s62
	s_add_i32 s58, s58, 2
	v_div_scale_f32 v109, s[68:69], v108, v108, 1.0
	v_rcp_f32_e32 v165, v109
	s_nop 0
	v_fma_f32 v170, -v109, v165, 1.0
	v_fmac_f32_e32 v165, v170, v165
	v_div_scale_f32 v170, vcc, 1.0, v108, 1.0
	v_mul_f32_e32 v171, v170, v165
	v_fma_f32 v172, -v109, v171, v170
	v_fmac_f32_e32 v171, v172, v165
	v_fma_f32 v109, -v109, v171, v170
	v_div_fmas_f32 v109, v109, v165, v171
	v_div_fixup_f32 v108, v109, v108, 1.0
	v_pk_fma_f32 v[108:109], v[108:109], v[168:169], v[100:101] op_sel_hi:[0,1,1] neg_lo:[0,0,1] neg_hi:[0,0,1]
	v_bfe_u32 v165, v108, 16, 1
	v_add3_u32 v108, v108, v165, s57
	v_bfe_u32 v165, v109, 16, 1
	v_lshrrev_b32_e32 v108, 16, v108
	v_add3_u32 v109, v109, v165, s57
	v_and_or_b32 v165, v109, s53, v108
	v_lshlrev_b32_e32 v108, 16, v164
	v_and_b32_e32 v109, 0xffff0000, v164
	v_pk_add_f32 v[106:107], v[108:109], v[106:107] neg_lo:[0,1] neg_hi:[0,1]
	s_nop 0
	v_pk_add_f32 v[168:169], v[168:169], v[106:107]
	v_cvt_f32_i32_e32 v106, s58
	s_min_u32 s58, s52, s17
	s_sub_i32 s56, s58, s56
	s_add_i32 s56, s56, 2
	v_div_scale_f32 v107, s[62:63], v106, v106, 1.0
	v_rcp_f32_e32 v164, v107
	s_nop 0
	v_fma_f32 v170, -v107, v164, 1.0
	v_fmac_f32_e32 v164, v170, v164
	v_div_scale_f32 v170, vcc, 1.0, v106, 1.0
	v_mul_f32_e32 v171, v170, v164
	v_fma_f32 v172, -v107, v171, v170
	v_fmac_f32_e32 v171, v172, v164
	v_fma_f32 v107, -v107, v171, v170
	v_div_fmas_f32 v107, v107, v164, v171
	v_div_fixup_f32 v106, v107, v106, 1.0
	v_pk_fma_f32 v[106:107], v[106:107], v[168:169], v[112:113] op_sel_hi:[0,1,1] neg_lo:[0,0,1] neg_hi:[0,0,1]
	v_bfe_u32 v164, v106, 16, 1
	v_add3_u32 v106, v106, v164, s57
	v_bfe_u32 v164, v107, 16, 1
	v_lshrrev_b32_e32 v106, 16, v106
	v_add3_u32 v107, v107, v164, s57
	v_and_or_b32 v164, v107, s53, v106
	v_lshlrev_b32_e32 v106, 16, v141
	v_and_b32_e32 v107, 0xffff0000, v141
	v_pk_add_f32 v[104:105], v[106:107], v[104:105] neg_lo:[0,1] neg_hi:[0,1]
	s_nop 0
	v_pk_add_f32 v[168:169], v[168:169], v[104:105]
	v_cvt_f32_i32_e32 v104, s56
	s_min_u32 s56, s51, s17
	s_sub_i32 s54, s56, s54
	s_add_i32 s54, s54, 2
	v_div_scale_f32 v105, s[62:63], v104, v104, 1.0
	v_rcp_f32_e32 v141, v105
	s_nop 0
	v_fma_f32 v170, -v105, v141, 1.0
	v_fmac_f32_e32 v141, v170, v141
	v_div_scale_f32 v170, vcc, 1.0, v104, 1.0
	v_mul_f32_e32 v171, v170, v141
	v_fma_f32 v172, -v105, v171, v170
	v_fmac_f32_e32 v171, v172, v141
	v_fma_f32 v105, -v105, v171, v170
	v_div_fmas_f32 v105, v105, v141, v171
	v_div_fixup_f32 v104, v105, v104, 1.0
	v_pk_fma_f32 v[104:105], v[104:105], v[168:169], v[108:109] op_sel_hi:[0,1,1] neg_lo:[0,0,1] neg_hi:[0,0,1]
	v_bfe_u32 v141, v104, 16, 1
	v_add3_u32 v104, v104, v141, s57
	v_bfe_u32 v141, v105, 16, 1
	v_lshrrev_b32_e32 v104, 16, v104
	v_add3_u32 v105, v105, v141, s57
	v_and_or_b32 v141, v105, s53, v104
	v_lshlrev_b32_e32 v104, 16, v134
	v_and_b32_e32 v105, 0xffff0000, v134
	v_pk_add_f32 v[100:101], v[104:105], v[100:101] neg_lo:[0,1] neg_hi:[0,1]
	s_nop 0
	v_pk_add_f32 v[168:169], v[168:169], v[100:101]
	v_cvt_f32_i32_e32 v100, s54
	s_min_u32 s54, s48, s17
	s_sub_i32 s52, s54, s52
	s_add_i32 s52, s52, 2
	v_div_scale_f32 v101, s[62:63], v100, v100, 1.0
	v_rcp_f32_e32 v134, v101
	s_nop 0
	v_fma_f32 v170, -v101, v134, 1.0
	v_fmac_f32_e32 v134, v170, v134
	v_div_scale_f32 v170, vcc, 1.0, v100, 1.0
	v_mul_f32_e32 v171, v170, v134
	v_fma_f32 v172, -v101, v171, v170
	v_fmac_f32_e32 v171, v172, v134
	v_fma_f32 v101, -v101, v171, v170
	v_div_fmas_f32 v101, v101, v134, v171
	v_div_fixup_f32 v100, v101, v100, 1.0
	v_pk_fma_f32 v[100:101], v[100:101], v[168:169], v[106:107] op_sel_hi:[0,1,1] neg_lo:[0,0,1] neg_hi:[0,0,1]
	v_bfe_u32 v134, v100, 16, 1
	v_add3_u32 v100, v100, v134, s57
	v_bfe_u32 v134, v101, 16, 1
	v_lshrrev_b32_e32 v100, 16, v100
	v_add3_u32 v101, v101, v134, s57
	v_and_or_b32 v134, v101, s53, v100
	v_lshlrev_b32_e32 v100, 16, v133
	v_and_b32_e32 v101, 0xffff0000, v133
	v_pk_add_f32 v[112:113], v[100:101], v[112:113] neg_lo:[0,1] neg_hi:[0,1]
	s_nop 0
	v_pk_add_f32 v[168:169], v[168:169], v[112:113]
	v_cvt_f32_i32_e32 v112, s52
	s_min_u32 s52, s46, s17
	s_sub_i32 s51, s52, s51
	s_add_i32 s51, s51, 2
	v_div_scale_f32 v113, s[62:63], v112, v112, 1.0
	v_rcp_f32_e32 v133, v113
	s_nop 0
	v_fma_f32 v170, -v113, v133, 1.0
	v_fmac_f32_e32 v133, v170, v133
	v_div_scale_f32 v170, vcc, 1.0, v112, 1.0
	v_mul_f32_e32 v171, v170, v133
	v_fma_f32 v172, -v113, v171, v170
	v_fmac_f32_e32 v171, v172, v133
	v_fma_f32 v113, -v113, v171, v170
	v_div_fmas_f32 v113, v113, v133, v171
	v_div_fixup_f32 v112, v113, v112, 1.0
	v_pk_fma_f32 v[112:113], v[112:113], v[168:169], v[104:105] op_sel_hi:[0,1,1] neg_lo:[0,0,1] neg_hi:[0,0,1]
	v_bfe_u32 v133, v112, 16, 1
	v_add3_u32 v112, v112, v133, s57
	v_bfe_u32 v133, v113, 16, 1
	v_lshrrev_b32_e32 v112, 16, v112
	v_add3_u32 v113, v113, v133, s57
	v_and_or_b32 v133, v113, s53, v112
	v_lshlrev_b32_e32 v112, 16, v132
	v_and_b32_e32 v113, 0xffff0000, v132
	v_pk_add_f32 v[108:109], v[112:113], v[108:109] neg_lo:[0,1] neg_hi:[0,1]
	s_nop 0
	v_pk_add_f32 v[168:169], v[168:169], v[108:109]
	v_cvt_f32_i32_e32 v108, s51
	s_min_u32 s51, s45, s17
	s_sub_i32 s48, s51, s48
	s_add_i32 s48, s48, 2
	v_div_scale_f32 v109, s[62:63], v108, v108, 1.0
	v_rcp_f32_e32 v132, v109
	s_nop 0
	v_fma_f32 v170, -v109, v132, 1.0
	v_fmac_f32_e32 v132, v170, v132
	v_div_scale_f32 v170, vcc, 1.0, v108, 1.0
	v_mul_f32_e32 v171, v170, v132
	v_fma_f32 v172, -v109, v171, v170
	v_fmac_f32_e32 v171, v172, v132
	v_fma_f32 v109, -v109, v171, v170
	v_div_fmas_f32 v109, v109, v132, v171
	v_div_fixup_f32 v108, v109, v108, 1.0
	v_pk_fma_f32 v[108:109], v[108:109], v[168:169], v[100:101] op_sel_hi:[0,1,1] neg_lo:[0,0,1] neg_hi:[0,0,1]
	v_bfe_u32 v132, v108, 16, 1
	v_add3_u32 v108, v108, v132, s57
	v_bfe_u32 v132, v109, 16, 1
	v_lshrrev_b32_e32 v108, 16, v108
	v_add3_u32 v109, v109, v132, s57
	v_and_or_b32 v132, v109, s53, v108
	v_lshlrev_b32_e32 v108, 16, v131
	v_and_b32_e32 v109, 0xffff0000, v131
	v_pk_add_f32 v[106:107], v[108:109], v[106:107] neg_lo:[0,1] neg_hi:[0,1]
	s_nop 0
	v_pk_add_f32 v[168:169], v[168:169], v[106:107]
	v_cvt_f32_i32_e32 v106, s48
	s_min_u32 s48, s15, s17
	s_sub_i32 s46, s48, s46
	s_add_i32 s46, s46, 2
	v_div_scale_f32 v107, s[62:63], v106, v106, 1.0
	v_rcp_f32_e32 v131, v107
	s_nop 0
	v_fma_f32 v170, -v107, v131, 1.0
	v_fmac_f32_e32 v131, v170, v131
	v_div_scale_f32 v170, vcc, 1.0, v106, 1.0
	v_mul_f32_e32 v171, v170, v131
	v_fma_f32 v172, -v107, v171, v170
	v_fmac_f32_e32 v171, v172, v131
	v_fma_f32 v107, -v107, v171, v170
	v_div_fmas_f32 v107, v107, v131, v171
	v_div_fixup_f32 v106, v107, v106, 1.0
	v_pk_fma_f32 v[106:107], v[106:107], v[168:169], v[112:113] op_sel_hi:[0,1,1] neg_lo:[0,0,1] neg_hi:[0,0,1]
	v_bfe_u32 v131, v106, 16, 1
	v_add3_u32 v106, v106, v131, s57
	v_bfe_u32 v131, v107, 16, 1
	v_lshrrev_b32_e32 v106, 16, v106
	v_add3_u32 v107, v107, v131, s57
	v_and_or_b32 v106, v107, s53, v106
	ds_write2st64_b32 v135, v167, v106 offset0:16 offset1:24
	v_lshlrev_b32_e32 v106, 16, v130
	v_and_b32_e32 v107, 0xffff0000, v130
	v_pk_add_f32 v[104:105], v[106:107], v[104:105] neg_lo:[0,1] neg_hi:[0,1]
	s_nop 0
	v_pk_add_f32 v[130:131], v[168:169], v[104:105]
	v_cvt_f32_i32_e32 v104, s46
	s_min_u32 s46, s14, s17
	s_sub_i32 s45, s46, s45
	s_add_i32 s45, s45, 2
	v_div_scale_f32 v105, s[62:63], v104, v104, 1.0
	v_rcp_f32_e32 v135, v105
	s_nop 0
	v_fma_f32 v167, -v105, v135, 1.0
	v_fmac_f32_e32 v135, v167, v135
	v_div_scale_f32 v167, vcc, 1.0, v104, 1.0
	v_mul_f32_e32 v168, v167, v135
	v_fma_f32 v169, -v105, v168, v167
	v_fmac_f32_e32 v168, v169, v135
	v_fma_f32 v105, -v105, v168, v167
	v_div_fmas_f32 v105, v105, v135, v168
	v_div_fixup_f32 v104, v105, v104, 1.0
	v_pk_fma_f32 v[104:105], v[104:105], v[130:131], v[108:109] op_sel_hi:[0,1,1] neg_lo:[0,0,1] neg_hi:[0,0,1]
	v_bfe_u32 v135, v104, 16, 1
	v_add3_u32 v104, v104, v135, s57
	v_bfe_u32 v135, v105, 16, 1
	v_lshrrev_b32_e32 v104, 16, v104
	v_add3_u32 v105, v105, v135, s57
	v_and_or_b32 v104, v105, s53, v104
	ds_write2st64_b32 v136, v166, v104 offset0:17 offset1:25
	v_lshlrev_b32_e32 v104, 16, v129
	v_and_b32_e32 v105, 0xffff0000, v129
	v_pk_add_f32 v[100:101], v[104:105], v[100:101] neg_lo:[0,1] neg_hi:[0,1]
	s_nop 0
	v_pk_add_f32 v[130:131], v[130:131], v[100:101]
	v_cvt_f32_i32_e32 v100, s45
	s_min_u32 s45, s3, s17
	s_sub_i32 s15, s45, s15
	s_add_i32 s15, s15, 2
	v_div_scale_f32 v101, s[62:63], v100, v100, 1.0
	v_rcp_f32_e32 v129, v101
	s_nop 0
	v_fma_f32 v135, -v101, v129, 1.0
	v_fmac_f32_e32 v129, v135, v129
	v_div_scale_f32 v135, vcc, 1.0, v100, 1.0
	v_mul_f32_e32 v136, v135, v129
	v_fma_f32 v166, -v101, v136, v135
	v_fmac_f32_e32 v136, v166, v129
	v_fma_f32 v101, -v101, v136, v135
	v_div_fmas_f32 v101, v101, v129, v136
	v_div_fixup_f32 v100, v101, v100, 1.0
	v_pk_fma_f32 v[100:101], v[100:101], v[130:131], v[106:107] op_sel_hi:[0,1,1] neg_lo:[0,0,1] neg_hi:[0,0,1]
	v_bfe_u32 v129, v100, 16, 1
	v_add3_u32 v100, v100, v129, s57
	v_bfe_u32 v129, v101, 16, 1
	v_lshrrev_b32_e32 v100, 16, v100
	v_add3_u32 v101, v101, v129, s57
	v_and_or_b32 v100, v101, s53, v100
	ds_write2st64_b32 v137, v165, v100 offset0:18 offset1:26
	v_lshlrev_b32_e32 v100, 16, v128
	v_and_b32_e32 v101, 0xffff0000, v128
	v_cvt_f32_i32_e32 v128, s15
	v_pk_add_f32 v[112:113], v[100:101], v[112:113] neg_lo:[0,1] neg_hi:[0,1]
	s_min_u32 s15, s1, s17
	v_pk_add_f32 v[112:113], v[130:131], v[112:113]
	v_div_scale_f32 v129, s[62:63], v128, v128, 1.0
	v_rcp_f32_e32 v130, v129
	s_sub_i32 s14, s15, s14
	s_add_i32 s14, s14, 2
	s_sub_i32 s1, s2, s1
	v_fma_f32 v131, -v129, v130, 1.0
	v_fmac_f32_e32 v130, v131, v130
	v_div_scale_f32 v131, vcc, 1.0, v128, 1.0
	v_mul_f32_e32 v135, v131, v130
	v_fma_f32 v136, -v129, v135, v131
	v_fmac_f32_e32 v135, v136, v130
	v_fma_f32 v129, -v129, v135, v131
	v_div_fmas_f32 v129, v129, v130, v135
	v_div_fixup_f32 v128, v129, v128, 1.0
	v_pk_fma_f32 v[128:129], v[128:129], v[112:113], v[104:105] op_sel_hi:[0,1,1] neg_lo:[0,0,1] neg_hi:[0,0,1]
	v_bfe_u32 v130, v128, 16, 1
	v_add3_u32 v128, v128, v130, s57
	v_bfe_u32 v130, v129, 16, 1
	v_lshrrev_b32_e32 v128, 16, v128
	v_add3_u32 v129, v129, v130, s57
	v_and_or_b32 v128, v129, s53, v128
	ds_write2st64_b32 v138, v164, v128 offset0:19 offset1:27
	v_lshlrev_b32_e32 v128, 16, v125
	v_and_b32_e32 v129, 0xffff0000, v125
	v_pk_add_f32 v[108:109], v[128:129], v[108:109] neg_lo:[0,1] neg_hi:[0,1]
	s_add_i32 s1, s1, 2
	v_pk_add_f32 v[108:109], v[112:113], v[108:109]
	v_cvt_f32_i32_e32 v112, s14
	v_div_scale_f32 v113, s[14:15], v112, v112, 1.0
	v_rcp_f32_e32 v125, v113
	s_min_u32 s14, s0, s17
	s_sub_i32 s3, s14, s3
	s_add_i32 s3, s3, 2
	v_fma_f32 v130, -v113, v125, 1.0
	v_fmac_f32_e32 v125, v130, v125
	v_div_scale_f32 v130, vcc, 1.0, v112, 1.0
	v_mul_f32_e32 v131, v130, v125
	v_fma_f32 v135, -v113, v131, v130
	v_fmac_f32_e32 v131, v135, v125
	v_fma_f32 v113, -v113, v131, v130
	v_div_fmas_f32 v113, v113, v125, v131
	v_div_fixup_f32 v112, v113, v112, 1.0
	v_pk_fma_f32 v[112:113], v[112:113], v[108:109], v[100:101] op_sel_hi:[0,1,1] neg_lo:[0,0,1] neg_hi:[0,0,1]
	v_bfe_u32 v125, v112, 16, 1
	v_add3_u32 v112, v112, v125, s57
	v_bfe_u32 v125, v113, 16, 1
	v_lshrrev_b32_e32 v112, 16, v112
	v_add3_u32 v113, v113, v125, s57
	v_and_or_b32 v112, v113, s53, v112
	ds_write2st64_b32 v139, v141, v112 offset0:20 offset1:28
	v_lshlrev_b32_e32 v112, 16, v124
	v_and_b32_e32 v113, 0xffff0000, v124
	v_pk_add_f32 v[106:107], v[112:113], v[106:107] neg_lo:[0,1] neg_hi:[0,1]
	s_nop 0
	v_pk_add_f32 v[106:107], v[108:109], v[106:107]
	v_cvt_f32_i32_e32 v108, s3
	v_div_scale_f32 v109, s[14:15], v108, v108, 1.0
	v_rcp_f32_e32 v124, v109
	s_nop 0
	v_fma_f32 v125, -v109, v124, 1.0
	v_fmac_f32_e32 v124, v125, v124
	v_div_scale_f32 v125, vcc, 1.0, v108, 1.0
	v_mul_f32_e32 v130, v125, v124
	v_fma_f32 v131, -v109, v130, v125
	v_fmac_f32_e32 v130, v131, v124
	v_fma_f32 v109, -v109, v130, v125
	v_div_fmas_f32 v109, v109, v124, v130
	v_div_fixup_f32 v108, v109, v108, 1.0
	v_pk_fma_f32 v[108:109], v[108:109], v[106:107], v[128:129] op_sel_hi:[0,1,1] neg_lo:[0,0,1] neg_hi:[0,0,1]
	v_bfe_u32 v124, v108, 16, 1
	v_add3_u32 v108, v108, v124, s57
	v_bfe_u32 v124, v109, 16, 1
	v_lshrrev_b32_e32 v108, 16, v108
	v_add3_u32 v109, v109, v124, s57
	v_and_or_b32 v108, v109, s53, v108
	ds_write2st64_b32 v140, v134, v108 offset0:21 offset1:29
	v_lshlrev_b32_e32 v108, 16, v121
	v_and_b32_e32 v109, 0xffff0000, v121
	v_pk_add_f32 v[104:105], v[108:109], v[104:105] neg_lo:[0,1] neg_hi:[0,1]
	s_nop 0
	v_pk_add_f32 v[104:105], v[106:107], v[104:105]
	v_cvt_f32_i32_e32 v106, s1
	s_add_i32 s1, s38, 33
	s_min_u32 s1, s1, s17
	s_sub_i32 s0, s1, s0
	v_div_scale_f32 v107, s[2:3], v106, v106, 1.0
	v_rcp_f32_e32 v121, v107
	s_add_i32 s0, s0, 2
	v_fma_f32 v124, -v107, v121, 1.0
	v_fmac_f32_e32 v121, v124, v121
	v_div_scale_f32 v124, vcc, 1.0, v106, 1.0
	v_mul_f32_e32 v125, v124, v121
	v_fma_f32 v128, -v107, v125, v124
	v_fmac_f32_e32 v125, v128, v121
	v_fma_f32 v107, -v107, v125, v124
	v_div_fmas_f32 v107, v107, v121, v125
	v_div_fixup_f32 v106, v107, v106, 1.0
	v_pk_fma_f32 v[106:107], v[106:107], v[104:105], v[112:113] op_sel_hi:[0,1,1] neg_lo:[0,0,1] neg_hi:[0,0,1]
	v_bfe_u32 v112, v106, 16, 1
	v_add3_u32 v106, v106, v112, s57
	v_bfe_u32 v112, v107, 16, 1
	v_lshrrev_b32_e32 v106, 16, v106
	v_add3_u32 v107, v107, v112, s57
	v_and_or_b32 v106, v107, s53, v106
	ds_write2st64_b32 v117, v133, v106 offset0:22 offset1:30
	v_lshlrev_b32_e32 v106, 16, v120
	v_and_b32_e32 v107, 0xffff0000, v120
	v_pk_add_f32 v[100:101], v[106:107], v[100:101] neg_lo:[0,1] neg_hi:[0,1]
	s_nop 0
	v_pk_add_f32 v[100:101], v[104:105], v[100:101]
	v_cvt_f32_i32_e32 v104, s0
	v_div_scale_f32 v105, s[0:1], v104, v104, 1.0
	v_rcp_f32_e32 v106, v105
	s_mov_b64 s[0:1], 0xc0
	v_lshl_add_u64 v[128:129], v[98:99], 0, s[0:1]
	v_fma_f32 v107, -v105, v106, 1.0
	v_fmac_f32_e32 v106, v107, v106
	v_div_scale_f32 v107, vcc, 1.0, v104, 1.0
	v_mul_f32_e32 v112, v107, v106
	v_fma_f32 v113, -v105, v112, v107
	v_fmac_f32_e32 v112, v113, v106
	v_fma_f32 v105, -v105, v112, v107
	v_div_fmas_f32 v105, v105, v106, v112
	v_div_fixup_f32 v104, v105, v104, 1.0
	v_pk_fma_f32 v[100:101], v[104:105], v[100:101], v[108:109] op_sel_hi:[0,1,1] neg_lo:[0,0,1] neg_hi:[0,0,1]
	v_bfe_u32 v104, v100, 16, 1
	v_add3_u32 v100, v100, v104, s57
	v_bfe_u32 v104, v101, 16, 1
	v_lshrrev_b32_e32 v100, 16, v100
	v_add3_u32 v101, v101, v104, s57
	v_and_or_b32 v100, v101, s53, v100
	ds_write2st64_b32 v116, v132, v100 offset0:23 offset1:31
	v_lshl_add_u64 v[100:101], v[98:99], 0, s[42:43]
	v_lshl_add_u64 v[104:105], v[100:101], 0, v[202:203]
	s_waitcnt lgkmcnt(0)
	global_load_dwordx4 v[130:133], v[102:103], off offset:128
	global_load_dwordx4 v[134:137], v[102:103], off offset:1152
	global_load_dwordx4 v[138:141], v[104:105], off
	v_lshl_add_u64 v[104:105], v[100:101], 0, v[110:111]
	global_load_dwordx4 v[164:167], v[104:105], off
	v_lshl_add_u64 v[104:105], v[100:101], 0, v[114:115]
	global_load_dwordx4 v[168:171], v[104:105], off
	v_lshl_add_u64 v[104:105], v[100:101], 0, v[118:119]
	global_load_dwordx4 v[172:175], v[104:105], off
	v_lshl_add_u64 v[104:105], v[100:101], 0, v[122:123]
	v_lshl_add_u64 v[100:101], v[100:101], 0, v[126:127]
	global_load_dwordx4 v[182:185], v[104:105], off
	global_load_dwordx4 v[186:189], v[100:101], off
	s_nop 0
	global_load_dwordx4 v[98:101], v[102:103], off offset:192
	s_nop 0
	global_load_dwordx4 v[102:105], v[102:103], off offset:1216
	v_lshl_add_u64 v[106:107], v[128:129], 0, v[202:203]
	v_lshl_add_u64 v[110:111], v[128:129], 0, v[110:111]
	v_lshl_add_u64 v[114:115], v[128:129], 0, v[114:115]
	v_lshl_add_u64 v[118:119], v[128:129], 0, v[118:119]
	v_lshl_add_u64 v[122:123], v[128:129], 0, v[122:123]
	v_lshl_add_u64 v[126:127], v[128:129], 0, v[126:127]
	global_load_dwordx4 v[106:109], v[106:107], off
	s_nop 0
	global_load_dwordx4 v[110:113], v[110:111], off
	s_nop 0
	global_load_dwordx4 v[114:117], v[114:115], off
	s_nop 0
	global_load_dwordx4 v[118:121], v[118:119], off
	s_nop 0
	global_load_dwordx4 v[122:125], v[122:123], off
	s_nop 0
	global_load_dwordx4 v[126:129], v[126:127], off
	v_add_u32_e32 v194, v177, v178
	ds_read_b128 v[190:193], v194
	ds_read_b128 v[194:197], v194 offset:4096
	v_add_u32_e32 v202, v177, v179
	s_add_i32 s0, s31, s35
	s_waitcnt vmcnt(25) lgkmcnt(1)
	v_mfma_f32_16x16x32_bf16 v[198:201], v[90:93], v[190:193], 0
	s_waitcnt vmcnt(23)
	v_mfma_f32_16x16x32_bf16 v[226:229], v[94:97], v[190:193], 0
	v_mfma_f32_16x16x32_bf16 v[230:233], v[66:69], v[190:193], 0
	v_mfma_f32_16x16x32_bf16 v[234:237], v[70:73], v[190:193], 0
	v_mfma_f32_16x16x32_bf16 v[238:241], v[74:77], v[190:193], 0
	v_mfma_f32_16x16x32_bf16 v[242:245], v[78:81], v[190:193], 0
	v_mfma_f32_16x16x32_bf16 v[246:249], v[82:85], v[190:193], 0
	v_mfma_f32_16x16x32_bf16 v[190:193], v[86:89], v[190:193], 0
	s_waitcnt lgkmcnt(0)
	v_mfma_f32_16x16x32_bf16 v[90:93], v[90:93], v[194:197], 0
	v_mfma_f32_16x16x32_bf16 v[94:97], v[94:97], v[194:197], 0
	v_mfma_f32_16x16x32_bf16 v[66:69], v[66:69], v[194:197], 0
	v_mfma_f32_16x16x32_bf16 v[70:73], v[70:73], v[194:197], 0
	v_mfma_f32_16x16x32_bf16 v[74:77], v[74:77], v[194:197], 0
	v_mfma_f32_16x16x32_bf16 v[78:81], v[78:81], v[194:197], 0
	v_mfma_f32_16x16x32_bf16 v[82:85], v[82:85], v[194:197], 0
	v_mfma_f32_16x16x32_bf16 v[86:89], v[86:89], v[194:197], 0
	ds_read_b128 v[194:197], v202
	ds_read_b128 v[250:253], v202 offset:4096
	s_waitcnt vmcnt(20) lgkmcnt(1)
	v_mfma_f32_16x16x32_bf16 v[234:237], v[46:49], v[194:197], v[234:237]
	s_waitcnt lgkmcnt(0)
	v_mfma_f32_16x16x32_bf16 v[46:49], v[46:49], v[250:253], v[70:73]
	s_nop 2
	v_add_u32_e32 v70, v177, v180
	v_mfma_f32_16x16x32_bf16 v[230:233], v[42:45], v[194:197], v[230:233]
	v_mfma_f32_16x16x32_bf16 v[42:45], v[42:45], v[250:253], v[66:69]
	s_nop 2
	ds_read_b128 v[66:69], v70
	ds_read_b128 v[70:73], v70 offset:4096
	v_mfma_f32_16x16x32_bf16 v[226:229], v[38:41], v[194:197], v[226:229]
	v_mfma_f32_16x16x32_bf16 v[38:41], v[38:41], v[250:253], v[94:97]
	v_mfma_f32_16x16x32_bf16 v[198:201], v[34:37], v[194:197], v[198:201]
	s_waitcnt vmcnt(18)
	v_mfma_f32_16x16x32_bf16 v[242:245], v[54:57], v[194:197], v[242:245]
	v_mfma_f32_16x16x32_bf16 v[34:37], v[34:37], v[250:253], v[90:93]
	v_mfma_f32_16x16x32_bf16 v[54:57], v[54:57], v[250:253], v[78:81]
	v_mfma_f32_16x16x32_bf16 v[238:241], v[50:53], v[194:197], v[238:241]
	s_waitcnt vmcnt(14) lgkmcnt(1)
	v_mfma_f32_16x16x32_bf16 v[78:81], v[134:137], v[66:69], v[226:229]
	s_waitcnt lgkmcnt(0)
	v_mfma_f32_16x16x32_bf16 v[38:41], v[134:137], v[70:73], v[38:41]
	s_waitcnt vmcnt(12)
	v_mfma_f32_16x16x32_bf16 v[134:137], v[164:167], v[70:73], v[46:49]
	s_nop 2
	v_add_u32_e32 v46, v177, v181
	v_mfma_f32_16x16x32_bf16 v[246:249], v[58:61], v[194:197], v[246:249]
	v_mfma_f32_16x16x32_bf16 v[50:53], v[50:53], v[250:253], v[74:77]
	v_mfma_f32_16x16x32_bf16 v[58:61], v[58:61], v[250:253], v[82:85]
	v_mfma_f32_16x16x32_bf16 v[74:77], v[130:133], v[66:69], v[198:201]
	v_mfma_f32_16x16x32_bf16 v[82:85], v[138:141], v[66:69], v[230:233]
	s_waitcnt vmcnt(10)
	v_mfma_f32_16x16x32_bf16 v[94:97], v[172:175], v[66:69], v[242:245]
	v_mfma_f32_16x16x32_bf16 v[34:37], v[130:133], v[70:73], v[34:37]
	v_mfma_f32_16x16x32_bf16 v[130:133], v[138:141], v[70:73], v[42:45]
	v_mfma_f32_16x16x32_bf16 v[138:141], v[172:175], v[70:73], v[54:57]
	s_nop 1
	ds_read_b128 v[42:45], v46
	ds_read_b128 v[172:175], v46 offset:4096
	v_mfma_f32_16x16x32_bf16 v[190:193], v[62:65], v[194:197], v[190:193]
	v_mfma_f32_16x16x32_bf16 v[62:65], v[62:65], v[250:253], v[86:89]
	v_mfma_f32_16x16x32_bf16 v[86:89], v[164:167], v[66:69], v[234:237]
	v_mfma_f32_16x16x32_bf16 v[90:93], v[168:171], v[66:69], v[238:241]
	s_waitcnt vmcnt(9)
	v_mfma_f32_16x16x32_bf16 v[194:197], v[182:185], v[66:69], v[246:249]
	s_waitcnt vmcnt(8)
	v_mfma_f32_16x16x32_bf16 v[66:69], v[186:189], v[66:69], v[190:193]
	v_mfma_f32_16x16x32_bf16 v[50:53], v[168:171], v[70:73], v[50:53]
	v_mfma_f32_16x16x32_bf16 v[164:167], v[182:185], v[70:73], v[58:61]
	v_mfma_f32_16x16x32_bf16 v[168:171], v[186:189], v[70:73], v[62:65]
	s_waitcnt vmcnt(7) lgkmcnt(1)
	v_mfma_f32_16x16x32_bf16 v[182:185], v[98:101], v[42:45], v[74:77]
	s_waitcnt vmcnt(6)
	v_mfma_f32_16x16x32_bf16 v[186:189], v[102:105], v[42:45], v[78:81]
	s_waitcnt vmcnt(5)
	v_mfma_f32_16x16x32_bf16 v[78:81], v[106:109], v[42:45], v[82:85]
	s_waitcnt vmcnt(4)
	v_mfma_f32_16x16x32_bf16 v[74:77], v[110:113], v[42:45], v[86:89]
	s_waitcnt lgkmcnt(0)
	v_mfma_f32_16x16x32_bf16 v[84:87], v[98:101], v[172:175], v[34:37]
	s_nop 1
	v_mul_f32_e64 v98, v26, v186
	v_mul_f32_e64 v99, v27, v187
	v_add_u32_e32 v100, s0, v143
	s_nop 0
	v_pk_mul_f32 v[74:75], v[18:19], v[74:75]
	s_waitcnt vmcnt(3)
	v_mfma_f32_16x16x32_bf16 v[62:65], v[114:117], v[42:45], v[90:93]
	v_add_u32_e32 v82, 8, v100
	v_mfma_f32_16x16x32_bf16 v[88:91], v[102:105], v[172:175], v[38:41]
	s_nop 0
	v_mul_f32_e64 v92, v30, v182
	v_mul_f32_e64 v93, v31, v183
	v_pk_mul_f32 v[30:31], v[30:31], v[84:85]
	v_bfe_u32 v83, v92, 16, 1
	s_waitcnt vmcnt(2)
	v_mfma_f32_16x16x32_bf16 v[58:61], v[118:121], v[42:45], v[94:97]
	v_add3_u32 v83, v92, v83, s57
	v_pk_mul_f32 v[84:85], v[28:29], v[90:91]
	v_pk_mul_f32 v[26:27], v[26:27], v[88:89]
	v_pk_mul_f32 v[96:97], v[28:29], v[188:189]
	v_bfe_u32 v28, v30, 16, 1
	v_add3_u32 v28, v30, v28, s57
	v_bfe_u32 v29, v31, 16, 1
	v_pk_mul_f32 v[94:95], v[32:33], v[184:185]
	v_pk_mul_f32 v[32:33], v[32:33], v[86:87]
	v_lshrrev_b32_e32 v28, 16, v28
	v_add3_u32 v29, v31, v29, s57
	v_and_or_b32 v28, v29, s53, v28
	v_bfe_u32 v29, v32, 16, 1
	v_add3_u32 v29, v32, v29, s57
	v_bfe_u32 v30, v33, 16, 1
	v_lshrrev_b32_e32 v29, 16, v29
	v_add3_u32 v30, v33, v30, s57
	v_and_or_b32 v29, v30, s53, v29
	v_bfe_u32 v30, v26, 16, 1
	v_add3_u32 v26, v26, v30, s57
	v_bfe_u32 v30, v27, 16, 1
	v_lshrrev_b32_e32 v26, 16, v26
	v_add3_u32 v27, v27, v30, s57
	v_and_or_b32 v30, v27, s53, v26
	v_bfe_u32 v26, v84, 16, 1
	v_add3_u32 v26, v84, v26, s57
	v_bfe_u32 v27, v85, 16, 1
	v_lshrrev_b32_e32 v26, 16, v26
	v_add3_u32 v27, v85, v27, s57
	v_and_or_b32 v31, v27, s53, v26
	v_add_u32_e32 v26, 24, v100
	v_ashrrev_i32_e32 v27, 31, v26
	v_lshlrev_b64 v[26:27], 12, v[26:27]
	v_lshl_add_u64 v[26:27], v[162:163], 0, v[26:27]
	v_bfe_u32 v92, v93, 16, 1
	global_store_dwordx4 v[26:27], v[28:31], off offset:2304 sc1
	v_lshrrev_b32_e32 v83, 16, v83
	v_add3_u32 v92, v93, v92, s57
	v_pk_mul_f32 v[28:29], v[22:23], v[78:79]
	v_pk_mul_f32 v[32:33], v[20:21], v[76:77]
	v_bfe_u32 v76, v28, 16, 1
	v_and_or_b32 v92, v92, s53, v83
	v_bfe_u32 v83, v94, 16, 1
	v_add3_u32 v28, v28, v76, s57
	v_bfe_u32 v76, v29, 16, 1
	v_add3_u32 v83, v94, v83, s57
	v_bfe_u32 v93, v95, 16, 1
	v_pk_mul_f32 v[30:31], v[24:25], v[80:81]
	v_lshrrev_b32_e32 v28, 16, v28
	v_add3_u32 v29, v29, v76, s57
	v_lshrrev_b32_e32 v83, 16, v83
	v_add3_u32 v93, v95, v93, s57
	v_and_or_b32 v28, v29, s53, v28
	v_bfe_u32 v29, v30, 16, 1
	v_and_or_b32 v93, v93, s53, v83
	v_bfe_u32 v83, v98, 16, 1
	v_add3_u32 v29, v30, v29, s57
	v_bfe_u32 v30, v31, 16, 1
	v_add3_u32 v83, v98, v83, s57
	v_bfe_u32 v94, v99, 16, 1
	v_lshrrev_b32_e32 v29, 16, v29
	v_add3_u32 v30, v31, v30, s57
	v_lshrrev_b32_e32 v83, 16, v83
	v_add3_u32 v94, v99, v94, s57
	v_and_or_b32 v29, v30, s53, v29
	v_bfe_u32 v30, v74, 16, 1
	v_and_or_b32 v94, v94, s53, v83
	v_bfe_u32 v83, v96, 16, 1
	v_add3_u32 v30, v74, v30, s57
	v_bfe_u32 v31, v75, 16, 1
	v_mfma_f32_16x16x32_bf16 v[70:73], v[106:109], v[172:175], v[130:133]
	v_add3_u32 v83, v96, v83, s57
	v_bfe_u32 v95, v97, 16, 1
	v_lshrrev_b32_e32 v30, 16, v30
	v_add3_u32 v31, v75, v31, s57
	s_waitcnt vmcnt(2)
	v_mfma_f32_16x16x32_bf16 v[46:49], v[122:125], v[42:45], v[194:197]
	v_lshrrev_b32_e32 v83, 16, v83
	v_add3_u32 v95, v97, v95, s57
	v_and_or_b32 v30, v31, s53, v30
	s_waitcnt vmcnt(1)
	v_mfma_f32_16x16x32_bf16 v[42:45], v[126:129], v[42:45], v[66:69]
	v_bfe_u32 v31, v32, 16, 1
	v_and_or_b32 v95, v95, s53, v83
	v_ashrrev_i32_e32 v83, 31, v82
	v_mfma_f32_16x16x32_bf16 v[66:69], v[110:113], v[172:175], v[134:137]
	v_add3_u32 v31, v32, v31, s57
	v_bfe_u32 v32, v33, 16, 1
	v_lshlrev_b64 v[82:83], 12, v[82:83]
	v_lshrrev_b32_e32 v31, 16, v31
	v_add3_u32 v32, v33, v32, s57
	v_lshl_add_u64 v[82:83], v[162:163], 0, v[82:83]
	v_and_or_b32 v31, v32, s53, v31
	v_pk_mul_f32 v[22:23], v[22:23], v[70:71]
	global_store_dwordx4 v[82:83], v[28:31], off offset:2368 sc1
	v_pk_mul_f32 v[24:25], v[24:25], v[72:73]
	v_mfma_f32_16x16x32_bf16 v[54:57], v[114:117], v[172:175], v[50:53]
	v_mul_f32_e64 v28, v20, v68
	v_mul_f32_e64 v29, v21, v69
	v_pk_mul_f32 v[20:21], v[18:19], v[66:67]
	v_bfe_u32 v18, v22, 16, 1
	v_add3_u32 v18, v22, v18, s57
	v_bfe_u32 v19, v23, 16, 1
	v_lshrrev_b32_e32 v18, 16, v18
	v_add3_u32 v19, v23, v19, s57
	v_and_or_b32 v18, v19, s53, v18
	v_bfe_u32 v19, v24, 16, 1
	v_add3_u32 v19, v24, v19, s57
	v_bfe_u32 v22, v25, 16, 1
	v_lshrrev_b32_e32 v19, 16, v19
	v_add3_u32 v22, v25, v22, s57
	v_and_or_b32 v19, v22, s53, v19
	v_bfe_u32 v22, v20, 16, 1
	v_add3_u32 v20, v20, v22, s57
	v_bfe_u32 v22, v21, 16, 1
	v_lshrrev_b32_e32 v20, 16, v20
	v_add3_u32 v21, v21, v22, s57
	v_and_or_b32 v20, v21, s53, v20
	v_bfe_u32 v21, v28, 16, 1
	v_add3_u32 v21, v28, v21, s57
	v_bfe_u32 v22, v29, 16, 1
	v_lshrrev_b32_e32 v21, 16, v21
	v_add3_u32 v22, v29, v22, s57
	v_and_or_b32 v21, v22, s53, v21
	global_store_dwordx4 v[26:27], v[18:21], off offset:2368 sc1
	v_pk_mul_f32 v[24:25], v[10:11], v[58:59]
	v_pk_mul_f32 v[22:23], v[12:13], v[60:61]
	v_pk_mul_f32 v[18:19], v[14:15], v[62:63]
	v_pk_mul_f32 v[20:21], v[16:17], v[64:65]
	v_bfe_u32 v28, v18, 16, 1
	v_add3_u32 v18, v18, v28, s57
	v_bfe_u32 v28, v19, 16, 1
	v_lshrrev_b32_e32 v18, 16, v18
	v_add3_u32 v19, v19, v28, s57
	v_and_or_b32 v18, v19, s53, v18
	v_bfe_u32 v19, v20, 16, 1
	v_add3_u32 v19, v20, v19, s57
	v_bfe_u32 v20, v21, 16, 1
	v_lshrrev_b32_e32 v19, 16, v19
	v_add3_u32 v20, v21, v20, s57
	v_and_or_b32 v19, v20, s53, v19
	v_bfe_u32 v20, v24, 16, 1
	v_add3_u32 v20, v24, v20, s57
	v_bfe_u32 v21, v25, 16, 1
	v_lshrrev_b32_e32 v20, 16, v20
	v_add3_u32 v21, v25, v21, s57
	v_mfma_f32_16x16x32_bf16 v[50:53], v[118:121], v[172:175], v[138:141]
	v_and_or_b32 v20, v21, s53, v20
	v_bfe_u32 v21, v22, 16, 1
	v_add3_u32 v21, v22, v21, s57
	v_bfe_u32 v22, v23, 16, 1
	v_lshrrev_b32_e32 v21, 16, v21
	v_add3_u32 v22, v23, v22, s57
	v_and_or_b32 v21, v22, s53, v21
	v_pk_mul_f32 v[14:15], v[14:15], v[54:55]
	global_store_dwordx4 v[82:83], v[18:21], off offset:2432 sc1
	v_pk_mul_f32 v[16:17], v[16:17], v[56:57]
	v_mfma_f32_16x16x32_bf16 v[38:41], v[122:125], v[172:175], v[164:167]
	v_mul_f32_e64 v18, v12, v52
	v_mul_f32_e64 v19, v13, v53
	v_pk_mul_f32 v[12:13], v[10:11], v[50:51]
	v_bfe_u32 v10, v14, 16, 1
	v_add3_u32 v10, v14, v10, s57
	v_bfe_u32 v11, v15, 16, 1
	v_lshrrev_b32_e32 v10, 16, v10
	v_add3_u32 v11, v15, v11, s57
	v_and_or_b32 v10, v11, s53, v10
	v_bfe_u32 v11, v16, 16, 1
	v_add3_u32 v11, v16, v11, s57
	v_bfe_u32 v14, v17, 16, 1
	v_lshrrev_b32_e32 v11, 16, v11
	v_add3_u32 v14, v17, v14, s57
	v_and_or_b32 v11, v14, s53, v11
	v_bfe_u32 v14, v12, 16, 1
	v_add3_u32 v12, v12, v14, s57
	v_bfe_u32 v14, v13, 16, 1
	v_lshrrev_b32_e32 v12, 16, v12
	v_add3_u32 v13, v13, v14, s57
	v_and_or_b32 v12, v13, s53, v12
	v_bfe_u32 v13, v18, 16, 1
	v_add3_u32 v13, v18, v13, s57
	v_bfe_u32 v14, v19, 16, 1
	v_lshrrev_b32_e32 v13, 16, v13
	v_add3_u32 v14, v19, v14, s57
	v_and_or_b32 v13, v14, s53, v13
	global_store_dwordx4 v[26:27], v[10:13], off offset:2432 sc1
	v_pk_mul_f32 v[16:17], v[2:3], v[42:43]
	v_pk_mul_f32 v[14:15], v[4:5], v[44:45]
	v_pk_mul_f32 v[10:11], v[6:7], v[46:47]
	v_pk_mul_f32 v[12:13], v[8:9], v[48:49]
	v_bfe_u32 v18, v10, 16, 1
	v_add3_u32 v10, v10, v18, s57
	v_bfe_u32 v18, v11, 16, 1
	v_lshrrev_b32_e32 v10, 16, v10
	v_add3_u32 v11, v11, v18, s57
	v_and_or_b32 v10, v11, s53, v10
	v_bfe_u32 v11, v12, 16, 1
	v_add3_u32 v11, v12, v11, s57
	v_bfe_u32 v12, v13, 16, 1
	v_lshrrev_b32_e32 v11, 16, v11
	v_add3_u32 v12, v13, v12, s57
	v_and_or_b32 v11, v12, s53, v11
	v_bfe_u32 v12, v16, 16, 1
	v_add3_u32 v12, v16, v12, s57
	v_bfe_u32 v13, v17, 16, 1
	v_lshrrev_b32_e32 v12, 16, v12
	v_add3_u32 v13, v17, v13, s57
	v_mfma_f32_16x16x32_bf16 v[34:37], v[126:129], v[172:175], v[168:171]
	v_and_or_b32 v12, v13, s53, v12
	v_bfe_u32 v13, v14, 16, 1
	v_add3_u32 v13, v14, v13, s57
	v_bfe_u32 v14, v15, 16, 1
	v_lshrrev_b32_e32 v13, 16, v13
	v_add3_u32 v14, v15, v14, s57
	v_and_or_b32 v13, v14, s53, v13
	v_pk_mul_f32 v[6:7], v[6:7], v[38:39]
	global_store_dwordx4 v[82:83], v[10:13], off offset:2496 sc1
	v_pk_mul_f32 v[8:9], v[8:9], v[40:41]
	global_store_dwordx4 v[82:83], v[92:95], off offset:2304 sc1
	v_pk_mul_f32 v[10:11], v[4:5], v[36:37]
	v_pk_mul_f32 v[4:5], v[2:3], v[34:35]
	v_bfe_u32 v2, v6, 16, 1
	v_add3_u32 v2, v6, v2, s57
	v_bfe_u32 v3, v7, 16, 1
	v_lshrrev_b32_e32 v2, 16, v2
	v_add3_u32 v3, v7, v3, s57
	v_and_or_b32 v2, v3, s53, v2
	v_bfe_u32 v3, v8, 16, 1
	v_add3_u32 v3, v8, v3, s57
	v_bfe_u32 v6, v9, 16, 1
	v_lshrrev_b32_e32 v3, 16, v3
	v_add3_u32 v6, v9, v6, s57
	v_and_or_b32 v3, v6, s53, v3
	v_bfe_u32 v6, v4, 16, 1
	v_add3_u32 v4, v4, v6, s57
	v_bfe_u32 v6, v5, 16, 1
	v_lshrrev_b32_e32 v4, 16, v4
	v_add3_u32 v5, v5, v6, s57
	v_and_or_b32 v4, v5, s53, v4
	v_bfe_u32 v5, v10, 16, 1
	v_add3_u32 v5, v10, v5, s57
	v_bfe_u32 v6, v11, 16, 1
	v_lshrrev_b32_e32 v5, 16, v5
	v_add3_u32 v6, v11, v6, s57
	v_and_or_b32 v5, v6, s53, v5
	global_store_dwordx4 v[26:27], v[2:5], off offset:2496 sc1
	s_waitcnt lgkmcnt(0)

.LBB0_767:
	v_lshlrev_b32_e32 v202, 1, v144
	v_lshlrev_b32_e32 v6, 2, v142
	v_lshl_add_u64 v[98:99], s[10:11], 0, v[202:203]
	v_lshlrev_b32_e32 v202, 1, v146
	global_load_dwordx4 v[26:29], v6, s[12:13] offset:16
	global_load_dwordx4 v[30:33], v6, s[12:13]
	global_load_dwordx4 v[18:21], v6, s[12:13] offset:144
	global_load_dwordx4 v[22:25], v6, s[12:13] offset:128
	global_load_dwordx4 v[10:13], v6, s[12:13] offset:272
	global_load_dwordx4 v[14:17], v6, s[12:13] offset:256
	global_load_dwordx4 v[2:5], v6, s[12:13] offset:400
	s_nop 0
	global_load_dwordx4 v[6:9], v6, s[12:13] offset:384
	v_lshl_add_u64 v[102:103], v[98:99], 0, v[202:203]
	v_lshlrev_b32_e32 v202, 1, v148
	v_lshlrev_b32_e32 v110, 1, v150
	v_mov_b32_e32 v111, v203
	v_lshl_add_u64 v[34:35], v[98:99], 0, v[202:203]
	v_lshl_add_u64 v[36:37], v[98:99], 0, v[110:111]
	v_lshlrev_b32_e32 v114, 1, v152
	v_mov_b32_e32 v115, v203
	v_lshlrev_b32_e32 v118, 1, v154
	v_mov_b32_e32 v119, v203
	global_load_dwordx4 v[66:69], v[34:35], off
	global_load_dwordx4 v[70:73], v[36:37], off
	v_lshl_add_u64 v[34:35], v[98:99], 0, v[114:115]
	v_lshl_add_u64 v[36:37], v[98:99], 0, v[118:119]
	v_lshlrev_b32_e32 v122, 1, v156
	v_mov_b32_e32 v123, v203
	v_lshlrev_b32_e32 v126, 1, v158
	v_mov_b32_e32 v127, v203
	global_load_dwordx4 v[74:77], v[34:35], off
	global_load_dwordx4 v[78:81], v[36:37], off
	v_lshl_add_u64 v[34:35], v[98:99], 0, v[122:123]
	v_lshl_add_u64 v[36:37], v[98:99], 0, v[126:127]
	global_load_dwordx4 v[82:85], v[34:35], off
	global_load_dwordx4 v[86:89], v[36:37], off
	v_lshl_add_u64 v[58:59], v[98:99], 0, 64
	global_load_dwordx4 v[90:93], v[102:103], off
	global_load_dwordx4 v[34:37], v[102:103], off offset:64
	global_load_dwordx4 v[94:97], v[102:103], off offset:1024
	global_load_dwordx4 v[38:41], v[102:103], off offset:1088
	v_lshl_add_u64 v[42:43], v[58:59], 0, v[202:203]
	v_lshl_add_u64 v[46:47], v[58:59], 0, v[110:111]
	v_lshl_add_u64 v[50:51], v[58:59], 0, v[114:115]
	v_lshl_add_u64 v[54:55], v[58:59], 0, v[118:119]
	v_lshl_add_u64 v[60:61], v[58:59], 0, v[122:123]
	v_lshl_add_u64 v[62:63], v[58:59], 0, v[126:127]
	global_load_dwordx4 v[42:45], v[42:43], off
	s_nop 0
	global_load_dwordx4 v[46:49], v[46:47], off
	s_nop 0
	global_load_dwordx4 v[50:53], v[50:51], off
	s_nop 0
	global_load_dwordx4 v[54:57], v[54:55], off
	s_nop 0
	global_load_dwordx4 v[58:61], v[60:61], off
	s_nop 0
	global_load_dwordx4 v[62:65], v[62:63], off
	s_waitcnt vmcnt(24)
	v_lshlrev_b32_e32 v230, 16, v101
	v_and_b32_e32 v231, 0xffff0000, v101
	v_pk_add_f32 v[112:113], v[230:231], 0 op_sel_hi:[1,0]
	v_lshlrev_b32_e32 v232, 16, v100
	v_and_b32_e32 v233, 0xffff0000, v100
	v_pk_add_f32 v[100:101], v[112:113], v[232:233]
	v_lshlrev_b32_e32 v112, 16, v105
	v_and_b32_e32 v113, 0xffff0000, v105
	v_pk_add_f32 v[100:101], v[100:101], v[112:113]
	v_lshlrev_b32_e32 v116, 16, v104
	v_and_b32_e32 v117, 0xffff0000, v104
	v_pk_add_f32 v[100:101], v[100:101], v[116:117]
	v_lshlrev_b32_e32 v120, 16, v108
	v_and_b32_e32 v121, 0xffff0000, v108
	v_pk_add_f32 v[100:101], v[100:101], v[120:121]
	v_lshlrev_b32_e32 v124, 16, v106
	v_and_b32_e32 v125, 0xffff0000, v106
	v_pk_add_f32 v[100:101], v[100:101], v[124:125]
	v_lshlrev_b32_e32 v164, 16, v129
	v_and_b32_e32 v165, 0xffff0000, v129
	v_pk_add_f32 v[100:101], v[100:101], v[164:165]
	v_lshlrev_b32_e32 v140, 16, v128
	v_and_b32_e32 v141, 0xffff0000, v128
	v_pk_add_f32 v[100:101], v[100:101], v[140:141]
	v_lshlrev_b32_e32 v138, 16, v131
	v_and_b32_e32 v139, 0xffff0000, v131
	v_pk_add_f32 v[100:101], v[100:101], v[138:139]
	v_lshlrev_b32_e32 v136, 16, v130
	v_and_b32_e32 v137, 0xffff0000, v130
	v_pk_add_f32 v[100:101], v[100:101], v[136:137]
	v_lshlrev_b32_e32 v134, 16, v132
	v_and_b32_e32 v135, 0xffff0000, v132
	v_pk_add_f32 v[100:101], v[100:101], v[134:135]
	v_lshlrev_b32_e32 v132, 16, v133
	v_and_b32_e32 v133, 0xffff0000, v133
	v_pk_add_f32 v[100:101], v[100:101], v[132:133]
	v_lshlrev_b32_e32 v130, 16, v167
	v_and_b32_e32 v131, 0xffff0000, v167
	v_pk_add_f32 v[100:101], v[100:101], v[130:131]
	v_lshlrev_b32_e32 v128, 16, v166
	v_and_b32_e32 v129, 0xffff0000, v166
	v_pk_add_f32 v[100:101], v[100:101], v[128:129]
	v_lshlrev_b32_e32 v166, 16, v197
	v_and_b32_e32 v167, 0xffff0000, v197
	v_pk_add_f32 v[104:105], v[100:101], v[166:167]
	v_lshlrev_b32_e32 v100, 16, v195
	v_and_b32_e32 v101, 0xffff0000, v195
	v_pk_add_f32 v[234:235], v[104:105], v[100:101]
	s_min_u32 s89, s80, s17
	v_sub_u32_e64 v104, s38, 8 clamp
	v_sub_u32_e32 v104, s89, v104
	v_cvt_f32_i32_e32 v104, v104
	s_min_u32 s89, s79, s17
	v_div_scale_f32 v105, s[92:93], v104, v104, 1.0
	v_rcp_f32_e32 v106, v105
	s_nop 0
	v_fma_f32 v108, -v105, v106, 1.0
	v_fmac_f32_e32 v106, v108, v106
	v_div_scale_f32 v108, vcc, 1.0, v104, 1.0
	v_mul_f32_e32 v195, v108, v106
	v_fma_f32 v197, -v105, v195, v108
	v_fmac_f32_e32 v195, v197, v106
	v_fma_f32 v105, -v105, v195, v108
	v_div_fmas_f32 v105, v105, v106, v195
	v_div_fixup_f32 v104, v105, v104, 1.0
	v_pk_fma_f32 v[104:105], v[104:105], v[234:235], v[138:139] op_sel_hi:[0,1,1] neg_lo:[0,0,1] neg_hi:[0,0,1]
	v_bfe_u32 v106, v104, 16, 1
	v_add3_u32 v104, v104, v106, s57
	v_bfe_u32 v106, v105, 16, 1
	v_add3_u32 v105, v105, v106, s57
	v_sub_u32_e64 v106, s88, 8 clamp
	v_sub_u32_e32 v106, s89, v106
	v_cvt_f32_i32_e32 v106, v106
	v_lshrrev_b32_e32 v104, 16, v104
	v_and_or_b32 v228, v105, s53, v104
	v_lshlrev_b32_e32 v104, 16, v196
	v_and_b32_e32 v105, 0xffff0000, v196
	v_pk_add_f32 v[196:197], v[104:105], v[230:231] neg_lo:[0,1] neg_hi:[0,1]
	v_div_scale_f32 v108, s[88:89], v106, v106, 1.0
	v_pk_add_f32 v[230:231], v[234:235], v[196:197]
	v_rcp_f32_e32 v196, v108
	s_min_u32 s88, s78, s17
	v_add_u32_e32 v195, v147, v145
	v_fma_f32 v197, -v108, v196, 1.0
	v_fmac_f32_e32 v196, v197, v196
	v_div_scale_f32 v197, vcc, 1.0, v106, 1.0
	v_mul_f32_e32 v198, v197, v196
	v_fma_f32 v229, -v108, v198, v197
	v_fmac_f32_e32 v198, v229, v196
	v_fma_f32 v108, -v108, v198, v197
	v_div_fmas_f32 v108, v108, v196, v198
	v_div_fixup_f32 v106, v108, v106, 1.0
	v_pk_fma_f32 v[196:197], v[106:107], v[230:231], v[136:137] op_sel_hi:[0,1,1] neg_lo:[0,0,1] neg_hi:[0,0,1]
	v_bfe_u32 v106, v196, 16, 1
	v_add3_u32 v106, v196, v106, s57
	v_bfe_u32 v108, v197, 16, 1
	v_lshrrev_b32_e32 v106, 16, v106
	v_add3_u32 v108, v197, v108, s57
	v_and_or_b32 v229, v108, s53, v106
	v_sub_u32_e64 v108, s87, 8 clamp
	v_sub_u32_e32 v108, s88, v108
	v_cvt_f32_i32_e32 v108, v108
	v_lshlrev_b32_e32 v106, 16, v107
	v_and_b32_e32 v107, 0xffff0000, v107
	v_pk_add_f32 v[232:233], v[106:107], v[232:233] neg_lo:[0,1] neg_hi:[0,1]
	v_div_scale_f32 v197, s[88:89], v108, v108, 1.0
	v_rcp_f32_e32 v198, v197
	v_pk_add_f32 v[232:233], v[230:231], v[232:233]
	s_min_u32 s87, s77, s17
	v_add_u32_e32 v196, v149, v145
	v_fma_f32 v230, -v197, v198, 1.0
	v_fmac_f32_e32 v198, v230, v198
	v_div_scale_f32 v230, vcc, 1.0, v108, 1.0
	v_mul_f32_e32 v231, v230, v198
	v_fma_f32 v234, -v197, v231, v230
	v_fmac_f32_e32 v231, v234, v198
	v_fma_f32 v197, -v197, v231, v230
	v_div_fmas_f32 v197, v197, v198, v231
	v_div_fixup_f32 v108, v197, v108, 1.0
	v_pk_fma_f32 v[230:231], v[108:109], v[232:233], v[134:135] op_sel_hi:[0,1,1] neg_lo:[0,0,1] neg_hi:[0,0,1]
	v_bfe_u32 v108, v230, 16, 1
	v_add3_u32 v108, v230, v108, s57
	v_bfe_u32 v197, v231, 16, 1
	v_lshrrev_b32_e32 v108, 16, v108
	v_add3_u32 v197, v231, v197, s57
	v_and_or_b32 v230, v197, s53, v108
	v_lshlrev_b32_e32 v108, 16, v109
	v_and_b32_e32 v109, 0xffff0000, v109
	v_pk_add_f32 v[112:113], v[108:109], v[112:113] neg_lo:[0,1] neg_hi:[0,1]
	v_add_u32_e32 v197, v151, v145
	v_pk_add_f32 v[232:233], v[232:233], v[112:113]
	v_sub_u32_e64 v112, s86, 8 clamp
	v_sub_u32_e32 v112, s87, v112
	v_cvt_f32_i32_e32 v112, v112
	v_div_scale_f32 v113, s[86:87], v112, v112, 1.0
	v_rcp_f32_e32 v198, v113
	s_min_u32 s86, s76, s17
	v_fma_f32 v231, -v113, v198, 1.0
	v_fmac_f32_e32 v198, v231, v198
	v_div_scale_f32 v231, vcc, 1.0, v112, 1.0
	v_mul_f32_e32 v234, v231, v198
	v_fma_f32 v235, -v113, v234, v231
	v_fmac_f32_e32 v234, v235, v198
	v_fma_f32 v113, -v113, v234, v231
	v_div_fmas_f32 v113, v113, v198, v234
	v_div_fixup_f32 v112, v113, v112, 1.0
	v_pk_fma_f32 v[112:113], v[112:113], v[232:233], v[132:133] op_sel_hi:[0,1,1] neg_lo:[0,0,1] neg_hi:[0,0,1]
	v_bfe_u32 v198, v112, 16, 1
	v_add3_u32 v112, v112, v198, s57
	v_bfe_u32 v198, v113, 16, 1
	v_lshrrev_b32_e32 v112, 16, v112
	v_add3_u32 v113, v113, v198, s57
	v_and_or_b32 v231, v113, s53, v112
	v_lshlrev_b32_e32 v112, 16, v199
	v_and_b32_e32 v113, 0xffff0000, v199
	v_pk_add_f32 v[116:117], v[112:113], v[116:117] neg_lo:[0,1] neg_hi:[0,1]
	v_add_u32_e32 v198, v153, v145
	v_pk_add_f32 v[234:235], v[232:233], v[116:117]
	v_sub_u32_e64 v116, s83, 8 clamp
	v_sub_u32_e32 v116, s86, v116
	v_cvt_f32_i32_e32 v116, v116
	s_min_u32 s83, s75, s17
	v_div_scale_f32 v117, s[86:87], v116, v116, 1.0
	v_rcp_f32_e32 v199, v117
	s_nop 0
	v_fma_f32 v232, -v117, v199, 1.0
	v_fmac_f32_e32 v199, v232, v199
	v_div_scale_f32 v232, vcc, 1.0, v116, 1.0
	v_mul_f32_e32 v233, v232, v199
	v_fma_f32 v236, -v117, v233, v232
	v_fmac_f32_e32 v233, v236, v199
	v_fma_f32 v117, -v117, v233, v232
	v_div_fmas_f32 v117, v117, v199, v233
	v_div_fixup_f32 v116, v117, v116, 1.0
	v_pk_fma_f32 v[116:117], v[116:117], v[234:235], v[130:131] op_sel_hi:[0,1,1] neg_lo:[0,0,1] neg_hi:[0,0,1]
	v_bfe_u32 v199, v116, 16, 1
	v_add3_u32 v116, v116, v199, s57
	v_bfe_u32 v199, v117, 16, 1
	v_lshrrev_b32_e32 v116, 16, v116
	v_add3_u32 v117, v117, v199, s57
	v_and_or_b32 v232, v117, s53, v116
	v_lshlrev_b32_e32 v116, 16, v200
	v_and_b32_e32 v117, 0xffff0000, v200
	v_pk_add_f32 v[120:121], v[116:117], v[120:121] neg_lo:[0,1] neg_hi:[0,1]
	v_add_u32_e32 v199, v155, v145
	v_pk_add_f32 v[234:235], v[234:235], v[120:121]
	v_sub_u32_e64 v120, s82, 8 clamp
	v_sub_u32_e32 v120, s83, v120
	v_cvt_f32_i32_e32 v120, v120
	v_div_scale_f32 v121, s[82:83], v120, v120, 1.0
	v_rcp_f32_e32 v200, v121
	s_min_u32 s82, s74, s17
	v_fma_f32 v233, -v121, v200, 1.0
	v_fmac_f32_e32 v200, v233, v200
	v_div_scale_f32 v233, vcc, 1.0, v120, 1.0
	v_mul_f32_e32 v236, v233, v200
	v_fma_f32 v237, -v121, v236, v233
	v_fmac_f32_e32 v236, v237, v200
	v_fma_f32 v121, -v121, v236, v233
	v_div_fmas_f32 v121, v121, v200, v236
	v_div_fixup_f32 v120, v121, v120, 1.0
	v_pk_fma_f32 v[120:121], v[120:121], v[234:235], v[128:129] op_sel_hi:[0,1,1] neg_lo:[0,0,1] neg_hi:[0,0,1]
	v_bfe_u32 v200, v120, 16, 1
	v_add3_u32 v120, v120, v200, s57
	v_bfe_u32 v200, v121, 16, 1
	v_lshrrev_b32_e32 v120, 16, v120
	v_add3_u32 v121, v121, v200, s57
	v_and_or_b32 v233, v121, s53, v120
	v_lshlrev_b32_e32 v120, 16, v201
	v_and_b32_e32 v121, 0xffff0000, v201
	v_pk_add_f32 v[124:125], v[120:121], v[124:125] neg_lo:[0,1] neg_hi:[0,1]
	v_add_u32_e32 v200, v157, v145
	v_pk_add_f32 v[236:237], v[234:235], v[124:125]
	v_sub_u32_e64 v124, s58, 8 clamp
	v_sub_u32_e32 v124, s82, v124
	v_cvt_f32_i32_e32 v124, v124
	s_min_u32 s58, s73, s17
	v_div_scale_f32 v125, s[82:83], v124, v124, 1.0
	v_rcp_f32_e32 v201, v125
	s_nop 0
	v_fma_f32 v234, -v125, v201, 1.0
	v_fmac_f32_e32 v201, v234, v201
	v_div_scale_f32 v234, vcc, 1.0, v124, 1.0
	v_mul_f32_e32 v235, v234, v201
	v_fma_f32 v238, -v125, v235, v234
	v_fmac_f32_e32 v235, v238, v201
	v_fma_f32 v125, -v125, v235, v234
	v_div_fmas_f32 v125, v125, v201, v235
	v_div_fixup_f32 v124, v125, v124, 1.0
	v_pk_fma_f32 v[124:125], v[124:125], v[236:237], v[166:167] op_sel_hi:[0,1,1] neg_lo:[0,0,1] neg_hi:[0,0,1]
	v_bfe_u32 v201, v124, 16, 1
	v_add3_u32 v124, v124, v201, s57
	v_bfe_u32 v201, v125, 16, 1
	v_lshrrev_b32_e32 v124, 16, v124
	v_add3_u32 v125, v125, v201, s57
	v_and_or_b32 v234, v125, s53, v124
	v_lshlrev_b32_e32 v124, 16, v194
	v_and_b32_e32 v125, 0xffff0000, v194
	v_pk_add_f32 v[164:165], v[124:125], v[164:165] neg_lo:[0,1] neg_hi:[0,1]
	v_add_u32_e32 v201, v159, v145
	v_pk_add_f32 v[236:237], v[236:237], v[164:165]
	v_sub_u32_e64 v164, s81, 8 clamp
	v_sub_u32_e32 v164, s58, v164
	v_cvt_f32_i32_e32 v164, v164
	s_min_u32 s58, s72, s17
	s_sub_i32 s58, s58, s80
	s_add_i32 s58, s58, 8
	v_div_scale_f32 v165, s[82:83], v164, v164, 1.0
	v_rcp_f32_e32 v194, v165
	s_nop 0
	v_fma_f32 v235, -v165, v194, 1.0
	v_fmac_f32_e32 v194, v235, v194
	v_div_scale_f32 v235, vcc, 1.0, v164, 1.0
	v_mul_f32_e32 v238, v235, v194
	v_fma_f32 v239, -v165, v238, v235
	v_fmac_f32_e32 v238, v239, v194
	v_fma_f32 v165, -v165, v238, v235
	v_div_fmas_f32 v165, v165, v194, v238
	v_div_fixup_f32 v164, v165, v164, 1.0
	v_pk_fma_f32 v[164:165], v[164:165], v[236:237], v[100:101] op_sel_hi:[0,1,1] neg_lo:[0,0,1] neg_hi:[0,0,1]
	v_bfe_u32 v194, v164, 16, 1
	v_add3_u32 v164, v164, v194, s57
	v_bfe_u32 v194, v165, 16, 1
	v_lshrrev_b32_e32 v164, 16, v164
	v_add3_u32 v165, v165, v194, s57
	v_and_or_b32 v235, v165, s53, v164
	v_lshlrev_b32_e32 v164, 16, v227
	v_and_b32_e32 v165, 0xffff0000, v227
	v_pk_add_f32 v[140:141], v[164:165], v[140:141] neg_lo:[0,1] neg_hi:[0,1]
	v_add_u32_e32 v194, v176, v145
	v_pk_add_f32 v[236:237], v[236:237], v[140:141]
	v_cvt_f32_i32_e32 v140, s58
	s_min_u32 s58, s69, s17
	s_sub_i32 s58, s58, s79
	s_add_i32 s58, s58, 8
	v_div_scale_f32 v141, s[80:81], v140, v140, 1.0
	v_rcp_f32_e32 v227, v141
	s_nop 0
	v_fma_f32 v238, -v141, v227, 1.0
	v_fmac_f32_e32 v227, v238, v227
	v_div_scale_f32 v238, vcc, 1.0, v140, 1.0
	v_mul_f32_e32 v239, v238, v227
	v_fma_f32 v240, -v141, v239, v238
	v_fmac_f32_e32 v239, v240, v227
	v_fma_f32 v141, -v141, v239, v238
	v_div_fmas_f32 v141, v141, v227, v239
	v_div_fixup_f32 v140, v141, v140, 1.0
	v_pk_fma_f32 v[140:141], v[140:141], v[236:237], v[104:105] op_sel_hi:[0,1,1] neg_lo:[0,0,1] neg_hi:[0,0,1]
	v_bfe_u32 v227, v140, 16, 1
	v_add3_u32 v140, v140, v227, s57
	v_bfe_u32 v227, v141, 16, 1
	v_lshrrev_b32_e32 v140, 16, v140
	v_add3_u32 v141, v141, v227, s57
	v_and_or_b32 v140, v141, s53, v140
	ds_write2st64_b32 v195, v228, v140 offset1:8
	v_lshlrev_b32_e32 v140, 16, v226
	v_and_b32_e32 v141, 0xffff0000, v226
	v_pk_add_f32 v[138:139], v[140:141], v[138:139] neg_lo:[0,1] neg_hi:[0,1]
	s_nop 0
	v_pk_add_f32 v[226:227], v[236:237], v[138:139]
	v_cvt_f32_i32_e32 v138, s58
	s_min_u32 s58, s68, s17
	s_sub_i32 s58, s58, s78
	s_add_i32 s58, s58, 8
	v_div_scale_f32 v139, s[80:81], v138, v138, 1.0
	v_rcp_f32_e32 v228, v139
	s_nop 0
	v_fma_f32 v236, -v139, v228, 1.0
	v_fmac_f32_e32 v228, v236, v228
	v_div_scale_f32 v236, vcc, 1.0, v138, 1.0
	v_mul_f32_e32 v237, v236, v228
	v_fma_f32 v238, -v139, v237, v236
	v_fmac_f32_e32 v237, v238, v228
	v_fma_f32 v139, -v139, v237, v236
	v_div_fmas_f32 v139, v139, v228, v237
	v_div_fixup_f32 v138, v139, v138, 1.0
	v_pk_fma_f32 v[138:139], v[138:139], v[226:227], v[106:107] op_sel_hi:[0,1,1] neg_lo:[0,0,1] neg_hi:[0,0,1]
	v_bfe_u32 v228, v138, 16, 1
	v_add3_u32 v138, v138, v228, s57
	v_bfe_u32 v228, v139, 16, 1
	v_lshrrev_b32_e32 v138, 16, v138
	v_add3_u32 v139, v139, v228, s57
	v_and_or_b32 v138, v139, s53, v138
	ds_write2st64_b32 v196, v229, v138 offset0:1 offset1:9
	v_lshlrev_b32_e32 v138, 16, v207
	v_and_b32_e32 v139, 0xffff0000, v207
	v_pk_add_f32 v[136:137], v[138:139], v[136:137] neg_lo:[0,1] neg_hi:[0,1]
	s_nop 0
	v_pk_add_f32 v[226:227], v[226:227], v[136:137]
	v_cvt_f32_i32_e32 v136, s58
	s_min_u32 s58, s63, s17
	s_sub_i32 s58, s58, s77
	s_add_i32 s58, s58, 8
	v_div_scale_f32 v137, s[78:79], v136, v136, 1.0
	v_rcp_f32_e32 v207, v137
	s_nop 0
	v_fma_f32 v228, -v137, v207, 1.0
	v_fmac_f32_e32 v207, v228, v207
	v_div_scale_f32 v228, vcc, 1.0, v136, 1.0
	v_mul_f32_e32 v229, v228, v207
	v_fma_f32 v236, -v137, v229, v228
	v_fmac_f32_e32 v229, v236, v207
	v_fma_f32 v137, -v137, v229, v228
	v_div_fmas_f32 v137, v137, v207, v229
	v_div_fixup_f32 v136, v137, v136, 1.0
	v_pk_fma_f32 v[136:137], v[136:137], v[226:227], v[108:109] op_sel_hi:[0,1,1] neg_lo:[0,0,1] neg_hi:[0,0,1]
	v_bfe_u32 v207, v136, 16, 1
	v_add3_u32 v136, v136, v207, s57
	v_bfe_u32 v207, v137, 16, 1
	v_lshrrev_b32_e32 v136, 16, v136
	v_add3_u32 v137, v137, v207, s57
	v_and_or_b32 v136, v137, s53, v136
	ds_write2st64_b32 v197, v230, v136 offset0:2 offset1:10
	v_lshlrev_b32_e32 v136, 16, v206
	v_and_b32_e32 v137, 0xffff0000, v206
	v_pk_add_f32 v[134:135], v[136:137], v[134:135] neg_lo:[0,1] neg_hi:[0,1]
	s_nop 0
	v_pk_add_f32 v[206:207], v[226:227], v[134:135]
	v_cvt_f32_i32_e32 v134, s58
	s_min_u32 s58, s62, s17
	s_sub_i32 s58, s58, s76
	s_add_i32 s58, s58, 8
	v_div_scale_f32 v135, s[78:79], v134, v134, 1.0
	v_rcp_f32_e32 v226, v135
	s_nop 0
	v_fma_f32 v227, -v135, v226, 1.0
	v_fmac_f32_e32 v226, v227, v226
	v_div_scale_f32 v227, vcc, 1.0, v134, 1.0
	v_mul_f32_e32 v228, v227, v226
	v_fma_f32 v229, -v135, v228, v227
	v_fmac_f32_e32 v228, v229, v226
	v_fma_f32 v135, -v135, v228, v227
	v_div_fmas_f32 v135, v135, v226, v228
	v_div_fixup_f32 v134, v135, v134, 1.0
	v_pk_fma_f32 v[134:135], v[134:135], v[206:207], v[112:113] op_sel_hi:[0,1,1] neg_lo:[0,0,1] neg_hi:[0,0,1]
	v_bfe_u32 v226, v134, 16, 1
	v_add3_u32 v134, v134, v226, s57
	v_bfe_u32 v226, v135, 16, 1
	v_lshrrev_b32_e32 v134, 16, v134
	v_add3_u32 v135, v135, v226, s57
	v_and_or_b32 v134, v135, s53, v134
	ds_write2st64_b32 v198, v231, v134 offset0:3 offset1:11
	v_lshlrev_b32_e32 v134, 16, v175
	v_and_b32_e32 v135, 0xffff0000, v175
	v_pk_add_f32 v[132:133], v[134:135], v[132:133] neg_lo:[0,1] neg_hi:[0,1]
	s_nop 0
	v_pk_add_f32 v[206:207], v[206:207], v[132:133]
	v_cvt_f32_i32_e32 v132, s58
	s_min_u32 s58, s56, s17
	s_sub_i32 s58, s58, s75
	s_add_i32 s58, s58, 8
	v_div_scale_f32 v133, s[76:77], v132, v132, 1.0
	v_rcp_f32_e32 v175, v133
	s_nop 0
	v_fma_f32 v226, -v133, v175, 1.0
	v_fmac_f32_e32 v175, v226, v175
	v_div_scale_f32 v226, vcc, 1.0, v132, 1.0
	v_mul_f32_e32 v227, v226, v175
	v_fma_f32 v228, -v133, v227, v226
	v_fmac_f32_e32 v227, v228, v175
	v_fma_f32 v133, -v133, v227, v226
	v_div_fmas_f32 v133, v133, v175, v227
	v_div_fixup_f32 v132, v133, v132, 1.0
	v_pk_fma_f32 v[132:133], v[132:133], v[206:207], v[116:117] op_sel_hi:[0,1,1] neg_lo:[0,0,1] neg_hi:[0,0,1]
	v_bfe_u32 v175, v132, 16, 1
	v_add3_u32 v132, v132, v175, s57
	v_bfe_u32 v175, v133, 16, 1
	v_lshrrev_b32_e32 v132, 16, v132
	v_add3_u32 v133, v133, v175, s57
	v_and_or_b32 v132, v133, s53, v132
	ds_write2st64_b32 v199, v232, v132 offset0:4 offset1:12
	v_lshlrev_b32_e32 v132, 16, v174
	v_and_b32_e32 v133, 0xffff0000, v174
	v_pk_add_f32 v[130:131], v[132:133], v[130:131] neg_lo:[0,1] neg_hi:[0,1]
	s_nop 0
	v_pk_add_f32 v[174:175], v[206:207], v[130:131]
	v_cvt_f32_i32_e32 v130, s58
	s_min_u32 s58, s54, s17
	s_sub_i32 s58, s58, s74
	s_add_i32 s58, s58, 8
	v_div_scale_f32 v131, s[76:77], v130, v130, 1.0
	v_rcp_f32_e32 v206, v131
	s_nop 0
	v_fma_f32 v207, -v131, v206, 1.0
	v_fmac_f32_e32 v206, v207, v206
	v_div_scale_f32 v207, vcc, 1.0, v130, 1.0
	v_mul_f32_e32 v226, v207, v206
	v_fma_f32 v227, -v131, v226, v207
	v_fmac_f32_e32 v226, v227, v206
	v_fma_f32 v131, -v131, v226, v207
	v_div_fmas_f32 v131, v131, v206, v226
	v_div_fixup_f32 v130, v131, v130, 1.0
	v_pk_fma_f32 v[130:131], v[130:131], v[174:175], v[120:121] op_sel_hi:[0,1,1] neg_lo:[0,0,1] neg_hi:[0,0,1]
	v_bfe_u32 v206, v130, 16, 1
	v_add3_u32 v130, v130, v206, s57
	v_bfe_u32 v206, v131, 16, 1
	v_lshrrev_b32_e32 v130, 16, v130
	v_add3_u32 v131, v131, v206, s57
	v_and_or_b32 v130, v131, s53, v130
	ds_write2st64_b32 v200, v233, v130 offset0:5 offset1:13
	v_lshlrev_b32_e32 v130, 16, v173
	v_and_b32_e32 v131, 0xffff0000, v173
	v_pk_add_f32 v[128:129], v[130:131], v[128:129] neg_lo:[0,1] neg_hi:[0,1]
	s_nop 0
	v_pk_add_f32 v[174:175], v[174:175], v[128:129]
	v_cvt_f32_i32_e32 v128, s58
	s_min_u32 s58, s51, s17
	s_sub_i32 s58, s58, s73
	s_add_i32 s58, s58, 8
	v_div_scale_f32 v129, s[74:75], v128, v128, 1.0
	v_rcp_f32_e32 v173, v129
	s_nop 0
	v_fma_f32 v206, -v129, v173, 1.0
	v_fmac_f32_e32 v173, v206, v173
	v_div_scale_f32 v206, vcc, 1.0, v128, 1.0
	v_mul_f32_e32 v207, v206, v173
	v_fma_f32 v226, -v129, v207, v206
	v_fmac_f32_e32 v207, v226, v173
	v_fma_f32 v129, -v129, v207, v206
	v_div_fmas_f32 v129, v129, v173, v207
	v_div_fixup_f32 v128, v129, v128, 1.0
	v_pk_fma_f32 v[128:129], v[128:129], v[174:175], v[124:125] op_sel_hi:[0,1,1] neg_lo:[0,0,1] neg_hi:[0,0,1]
	v_bfe_u32 v173, v128, 16, 1
	v_add3_u32 v128, v128, v173, s57
	v_bfe_u32 v173, v129, 16, 1
	v_lshrrev_b32_e32 v128, 16, v128
	v_add3_u32 v129, v129, v173, s57
	v_and_or_b32 v128, v129, s53, v128
	ds_write2st64_b32 v201, v234, v128 offset0:6 offset1:14
	v_lshlrev_b32_e32 v128, 16, v172
	v_and_b32_e32 v129, 0xffff0000, v172
	v_cvt_f32_i32_e32 v172, s58
	v_pk_add_f32 v[166:167], v[128:129], v[166:167] neg_lo:[0,1] neg_hi:[0,1]
	s_min_u32 s58, s46, s17
	v_pk_add_f32 v[166:167], v[174:175], v[166:167]
	v_div_scale_f32 v173, s[74:75], v172, v172, 1.0
	v_rcp_f32_e32 v174, v173
	s_sub_i32 s58, s58, s72
	s_add_i32 s58, s58, 8
	v_fma_f32 v175, -v173, v174, 1.0
	v_fmac_f32_e32 v174, v175, v174
	v_div_scale_f32 v175, vcc, 1.0, v172, 1.0
	v_mul_f32_e32 v206, v175, v174
	v_fma_f32 v207, -v173, v206, v175
	v_fmac_f32_e32 v206, v207, v174
	v_fma_f32 v173, -v173, v206, v175
	v_div_fmas_f32 v173, v173, v174, v206
	v_div_fixup_f32 v172, v173, v172, 1.0
	v_pk_fma_f32 v[172:173], v[172:173], v[166:167], v[164:165] op_sel_hi:[0,1,1] neg_lo:[0,0,1] neg_hi:[0,0,1]
	v_bfe_u32 v174, v172, 16, 1
	v_add3_u32 v172, v172, v174, s57
	v_bfe_u32 v174, v173, 16, 1
	v_add3_u32 v173, v173, v174, s57
	v_lshlrev_b32_e32 v174, 16, v171
	v_and_b32_e32 v175, 0xffff0000, v171
	v_pk_add_f32 v[100:101], v[174:175], v[100:101] neg_lo:[0,1] neg_hi:[0,1]
	v_lshrrev_b32_e32 v172, 16, v172
	v_pk_add_f32 v[100:101], v[166:167], v[100:101]
	v_cvt_f32_i32_e32 v166, s58
	v_and_or_b32 v172, v173, s53, v172
	ds_write2st64_b32 v194, v235, v172 offset0:7 offset1:15
	s_min_u32 s58, s27, s17
	v_div_scale_f32 v167, s[72:73], v166, v166, 1.0
	v_rcp_f32_e32 v171, v167
	s_sub_i32 s58, s58, s69
	s_add_i32 s58, s58, 8
	v_fma_f32 v172, -v167, v171, 1.0
	v_fmac_f32_e32 v171, v172, v171
	v_div_scale_f32 v172, vcc, 1.0, v166, 1.0
	v_mul_f32_e32 v173, v172, v171
	v_fma_f32 v206, -v167, v173, v172
	v_fmac_f32_e32 v173, v206, v171
	v_fma_f32 v167, -v167, v173, v172
	v_div_fmas_f32 v167, v167, v171, v173
	v_lshlrev_b32_e32 v172, 16, v170
	v_and_b32_e32 v173, 0xffff0000, v170
	v_div_fixup_f32 v166, v167, v166, 1.0
	v_pk_add_f32 v[104:105], v[172:173], v[104:105] neg_lo:[0,1] neg_hi:[0,1]
	v_pk_fma_f32 v[166:167], v[166:167], v[100:101], v[140:141] op_sel_hi:[0,1,1] neg_lo:[0,0,1] neg_hi:[0,0,1]
	v_pk_add_f32 v[100:101], v[100:101], v[104:105]
	v_cvt_f32_i32_e32 v104, s58
	v_bfe_u32 v171, v166, 16, 1
	v_add3_u32 v166, v166, v171, s57
	v_bfe_u32 v171, v167, 16, 1
	v_lshrrev_b32_e32 v166, 16, v166
	v_add3_u32 v167, v167, v171, s57
	v_div_scale_f32 v105, s[72:73], v104, v104, 1.0
	v_and_or_b32 v227, v167, s53, v166
	v_rcp_f32_e32 v166, v105
	s_min_u32 s58, s19, s17
	s_sub_i32 s58, s58, s68
	s_add_i32 s58, s58, 8
	v_fma_f32 v167, -v105, v166, 1.0
	v_fmac_f32_e32 v166, v167, v166
	v_div_scale_f32 v167, vcc, 1.0, v104, 1.0
	v_mul_f32_e32 v170, v167, v166
	v_fma_f32 v171, -v105, v170, v167
	v_fmac_f32_e32 v170, v171, v166
	v_fma_f32 v105, -v105, v170, v167
	v_div_fmas_f32 v105, v105, v166, v170
	v_div_fixup_f32 v104, v105, v104, 1.0
	v_pk_fma_f32 v[104:105], v[104:105], v[100:101], v[138:139] op_sel_hi:[0,1,1] neg_lo:[0,0,1] neg_hi:[0,0,1]
	v_bfe_u32 v166, v104, 16, 1
	v_add3_u32 v104, v104, v166, s57
	v_bfe_u32 v166, v105, 16, 1
	v_lshrrev_b32_e32 v104, 16, v104
	v_add3_u32 v105, v105, v166, s57
	v_lshlrev_b32_e32 v170, 16, v168
	v_and_b32_e32 v171, 0xffff0000, v168
	v_and_or_b32 v226, v105, s53, v104
	v_pk_add_f32 v[104:105], v[170:171], v[106:107] neg_lo:[0,1] neg_hi:[0,1]
	v_lshlrev_b32_e32 v168, 16, v169
	v_pk_add_f32 v[100:101], v[100:101], v[104:105]
	v_cvt_f32_i32_e32 v104, s58
	s_min_u32 s58, s16, s17
	v_and_b32_e32 v169, 0xffff0000, v169
	s_sub_i32 s58, s58, s63
	v_div_scale_f32 v105, s[68:69], v104, v104, 1.0
	v_rcp_f32_e32 v106, v105
	s_add_i32 s58, s58, 8
	v_fma_f32 v107, -v105, v106, 1.0
	v_fmac_f32_e32 v106, v107, v106
	v_div_scale_f32 v107, vcc, 1.0, v104, 1.0
	v_mul_f32_e32 v166, v107, v106
	v_fma_f32 v167, -v105, v166, v107
	v_fmac_f32_e32 v166, v167, v106
	v_fma_f32 v105, -v105, v166, v107
	v_div_fmas_f32 v105, v105, v106, v166
	v_div_fixup_f32 v104, v105, v104, 1.0
	v_pk_fma_f32 v[104:105], v[104:105], v[100:101], v[136:137] op_sel_hi:[0,1,1] neg_lo:[0,0,1] neg_hi:[0,0,1]
	v_bfe_u32 v106, v104, 16, 1
	v_add3_u32 v104, v104, v106, s57
	v_bfe_u32 v106, v105, 16, 1
	v_lshrrev_b32_e32 v104, 16, v104
	v_add3_u32 v105, v105, v106, s57
	v_and_or_b32 v207, v105, s53, v104
	v_pk_add_f32 v[104:105], v[168:169], v[108:109] neg_lo:[0,1] neg_hi:[0,1]
	v_lshlrev_b32_e32 v166, 16, v193
	v_pk_add_f32 v[100:101], v[100:101], v[104:105]
	v_cvt_f32_i32_e32 v104, s58
	s_min_u32 s58, s14, s17
	v_and_b32_e32 v167, 0xffff0000, v193
	s_sub_i32 s58, s58, s62
	v_div_scale_f32 v105, s[68:69], v104, v104, 1.0
	v_rcp_f32_e32 v106, v105
	s_add_i32 s58, s58, 8
	v_fma_f32 v107, -v105, v106, 1.0
	v_fmac_f32_e32 v106, v107, v106
	v_div_scale_f32 v107, vcc, 1.0, v104, 1.0
	v_mul_f32_e32 v108, v107, v106
	v_fma_f32 v109, -v105, v108, v107
	v_fmac_f32_e32 v108, v109, v106
	v_fma_f32 v105, -v105, v108, v107
	v_div_fmas_f32 v105, v105, v106, v108
	v_div_fixup_f32 v104, v105, v104, 1.0
	v_pk_fma_f32 v[104:105], v[104:105], v[100:101], v[134:135] op_sel_hi:[0,1,1] neg_lo:[0,0,1] neg_hi:[0,0,1]
	v_bfe_u32 v106, v104, 16, 1
	v_add3_u32 v104, v104, v106, s57
	v_bfe_u32 v106, v105, 16, 1
	v_lshrrev_b32_e32 v104, 16, v104
	v_add3_u32 v105, v105, v106, s57
	v_and_or_b32 v206, v105, s53, v104
	v_pk_add_f32 v[104:105], v[166:167], v[112:113] neg_lo:[0,1] neg_hi:[0,1]
	s_nop 0
	v_pk_add_f32 v[100:101], v[100:101], v[104:105]
	v_cvt_f32_i32_e32 v104, s58
	s_min_u32 s58, s2, s17
	s_sub_i32 s56, s58, s56
	s_add_i32 s56, s56, 8
	v_div_scale_f32 v105, s[62:63], v104, v104, 1.0
	v_rcp_f32_e32 v106, v105
	s_nop 0
	v_fma_f32 v107, -v105, v106, 1.0
	v_fmac_f32_e32 v106, v107, v106
	v_div_scale_f32 v107, vcc, 1.0, v104, 1.0
	v_mul_f32_e32 v108, v107, v106
	v_fma_f32 v109, -v105, v108, v107
	v_fmac_f32_e32 v108, v109, v106
	v_fma_f32 v105, -v105, v108, v107
	v_div_fmas_f32 v105, v105, v106, v108
	v_div_fixup_f32 v104, v105, v104, 1.0
	v_pk_fma_f32 v[104:105], v[104:105], v[100:101], v[132:133] op_sel_hi:[0,1,1] neg_lo:[0,0,1] neg_hi:[0,0,1]
	v_bfe_u32 v106, v104, 16, 1
	v_add3_u32 v104, v104, v106, s57
	v_bfe_u32 v106, v105, 16, 1
	v_lshrrev_b32_e32 v104, 16, v104
	v_add3_u32 v105, v105, v106, s57
	v_lshlrev_b32_e32 v108, 16, v192
	v_and_b32_e32 v109, 0xffff0000, v192
	v_and_or_b32 v193, v105, s53, v104
	v_pk_add_f32 v[104:105], v[108:109], v[116:117] neg_lo:[0,1] neg_hi:[0,1]
	s_nop 0
	v_pk_add_f32 v[100:101], v[100:101], v[104:105]
	v_cvt_f32_i32_e32 v104, s56
	s_min_u32 s56, s1, s17
	s_sub_i32 s54, s56, s54
	s_add_i32 s54, s54, 8
	v_div_scale_f32 v105, s[62:63], v104, v104, 1.0
	v_rcp_f32_e32 v106, v105
	s_nop 0
	v_fma_f32 v107, -v105, v106, 1.0
	v_fmac_f32_e32 v106, v107, v106
	v_div_scale_f32 v107, vcc, 1.0, v104, 1.0
	v_mul_f32_e32 v112, v107, v106
	v_fma_f32 v113, -v105, v112, v107
	v_fmac_f32_e32 v112, v113, v106
	v_fma_f32 v105, -v105, v112, v107
	v_div_fmas_f32 v105, v105, v106, v112
	v_div_fixup_f32 v104, v105, v104, 1.0
	v_pk_fma_f32 v[104:105], v[104:105], v[100:101], v[130:131] op_sel_hi:[0,1,1] neg_lo:[0,0,1] neg_hi:[0,0,1]
	v_bfe_u32 v106, v104, 16, 1
	v_add3_u32 v104, v104, v106, s57
	v_bfe_u32 v106, v105, 16, 1
	v_lshrrev_b32_e32 v104, 16, v104
	v_add3_u32 v105, v105, v106, s57
	v_lshlrev_b32_e32 v106, 16, v191
	v_and_b32_e32 v107, 0xffff0000, v191
	v_and_or_b32 v116, v105, s53, v104
	v_pk_add_f32 v[104:105], v[106:107], v[120:121] neg_lo:[0,1] neg_hi:[0,1]
	s_nop 0
	v_pk_add_f32 v[100:101], v[100:101], v[104:105]
	v_cvt_f32_i32_e32 v104, s54
	s_min_u32 s54, s0, s17
	s_sub_i32 s51, s54, s51
	s_add_i32 s51, s51, 8
	v_div_scale_f32 v105, s[62:63], v104, v104, 1.0
	v_rcp_f32_e32 v112, v105
	s_nop 0
	v_fma_f32 v113, -v105, v112, 1.0
	v_fmac_f32_e32 v112, v113, v112
	v_div_scale_f32 v113, vcc, 1.0, v104, 1.0
	v_mul_f32_e32 v117, v113, v112
	v_fma_f32 v120, -v105, v117, v113
	v_fmac_f32_e32 v117, v120, v112
	v_fma_f32 v105, -v105, v117, v113
	v_div_fmas_f32 v105, v105, v112, v117
	v_div_fixup_f32 v104, v105, v104, 1.0
	v_pk_fma_f32 v[104:105], v[104:105], v[100:101], v[128:129] op_sel_hi:[0,1,1] neg_lo:[0,0,1] neg_hi:[0,0,1]
	v_bfe_u32 v112, v104, 16, 1
	v_add3_u32 v104, v104, v112, s57
	v_bfe_u32 v112, v105, 16, 1
	v_lshrrev_b32_e32 v104, 16, v104
	v_add3_u32 v105, v105, v112, s57
	v_and_or_b32 v113, v105, s53, v104
	v_lshlrev_b32_e32 v104, 16, v190
	v_and_b32_e32 v105, 0xffff0000, v190
	v_pk_add_f32 v[120:121], v[104:105], v[124:125] neg_lo:[0,1] neg_hi:[0,1]
	s_nop 0
	v_pk_add_f32 v[120:121], v[100:101], v[120:121]
	v_cvt_f32_i32_e32 v100, s51
	s_min_u32 s51, s52, s17
	s_sub_i32 s46, s51, s46
	s_add_i32 s46, s46, 8
	v_div_scale_f32 v101, s[62:63], v100, v100, 1.0
	v_rcp_f32_e32 v112, v101
	s_nop 0
	v_fma_f32 v117, -v101, v112, 1.0
	v_fmac_f32_e32 v112, v117, v112
	v_div_scale_f32 v117, vcc, 1.0, v100, 1.0
	v_mul_f32_e32 v124, v117, v112
	v_fma_f32 v125, -v101, v124, v117
	v_fmac_f32_e32 v124, v125, v112
	v_fma_f32 v101, -v101, v124, v117
	v_div_fmas_f32 v101, v101, v112, v124
	v_div_fixup_f32 v100, v101, v100, 1.0
	v_pk_fma_f32 v[100:101], v[100:101], v[120:121], v[174:175] op_sel_hi:[0,1,1] neg_lo:[0,0,1] neg_hi:[0,0,1]
	v_bfe_u32 v112, v100, 16, 1
	v_add3_u32 v100, v100, v112, s57
	v_bfe_u32 v112, v101, 16, 1
	v_cvt_f32_i32_e32 v117, s46
	v_lshrrev_b32_e32 v100, 16, v100
	v_add3_u32 v101, v101, v112, s57
	v_and_or_b32 v112, v101, s53, v100
	v_lshlrev_b32_e32 v100, 16, v189
	v_and_b32_e32 v101, 0xffff0000, v189
	v_pk_add_f32 v[124:125], v[100:101], v[164:165] neg_lo:[0,1] neg_hi:[0,1]
	s_min_u32 s46, s48, s17
	v_pk_add_f32 v[120:121], v[120:121], v[124:125]
	v_div_scale_f32 v124, s[62:63], v117, v117, 1.0
	v_rcp_f32_e32 v125, v124
	s_sub_i32 s27, s46, s27
	s_add_i32 s27, s27, 8
	v_fma_f32 v164, -v124, v125, 1.0
	v_fmac_f32_e32 v125, v164, v125
	v_div_scale_f32 v164, vcc, 1.0, v117, 1.0
	v_mul_f32_e32 v165, v164, v125
	v_fma_f32 v174, -v124, v165, v164
	v_fmac_f32_e32 v165, v174, v125
	v_fma_f32 v124, -v124, v165, v164
	v_div_fmas_f32 v124, v124, v125, v165
	v_div_fixup_f32 v124, v124, v117, 1.0
	v_pk_fma_f32 v[124:125], v[124:125], v[120:121], v[172:173] op_sel_hi:[0,1,1] neg_lo:[0,0,1] neg_hi:[0,0,1]
	v_bfe_u32 v117, v124, 16, 1
	v_add3_u32 v117, v124, v117, s57
	v_bfe_u32 v124, v125, 16, 1
	v_lshrrev_b32_e32 v117, 16, v117
	v_add3_u32 v124, v125, v124, s57
	v_and_or_b32 v117, v124, s53, v117
	ds_write2st64_b32 v195, v227, v117 offset0:16 offset1:24
	v_cvt_f32_i32_e32 v117, s27
	v_lshlrev_b32_e32 v124, 16, v188
	v_and_b32_e32 v125, 0xffff0000, v188
	v_pk_add_f32 v[124:125], v[124:125], v[140:141] neg_lo:[0,1] neg_hi:[0,1]
	s_min_u32 s27, s45, s17
	v_pk_add_f32 v[120:121], v[120:121], v[124:125]
	v_div_scale_f32 v124, s[62:63], v117, v117, 1.0
	v_rcp_f32_e32 v125, v124
	s_sub_i32 s19, s27, s19
	s_add_i32 s19, s19, 8
	v_fma_f32 v140, -v124, v125, 1.0
	v_fmac_f32_e32 v125, v140, v125
	v_div_scale_f32 v140, vcc, 1.0, v117, 1.0
	v_mul_f32_e32 v141, v140, v125
	v_fma_f32 v164, -v124, v141, v140
	v_fmac_f32_e32 v141, v164, v125
	v_fma_f32 v124, -v124, v141, v140
	v_div_fmas_f32 v124, v124, v125, v141
	v_div_fixup_f32 v124, v124, v117, 1.0
	v_pk_fma_f32 v[124:125], v[124:125], v[120:121], v[170:171] op_sel_hi:[0,1,1] neg_lo:[0,0,1] neg_hi:[0,0,1]
	v_bfe_u32 v117, v124, 16, 1
	v_add3_u32 v117, v124, v117, s57
	v_bfe_u32 v124, v125, 16, 1
	v_lshrrev_b32_e32 v117, 16, v117
	v_add3_u32 v124, v125, v124, s57
	v_and_or_b32 v117, v124, s53, v117
	ds_write2st64_b32 v196, v226, v117 offset0:17 offset1:25
	v_cvt_f32_i32_e32 v117, s19
	v_lshlrev_b32_e32 v124, 16, v187
	v_and_b32_e32 v125, 0xffff0000, v187
	v_pk_add_f32 v[124:125], v[124:125], v[138:139] neg_lo:[0,1] neg_hi:[0,1]
	s_min_u32 s19, s26, s17
	v_pk_add_f32 v[120:121], v[120:121], v[124:125]
	v_div_scale_f32 v124, s[62:63], v117, v117, 1.0
	v_rcp_f32_e32 v125, v124
	s_sub_i32 s16, s19, s16
	s_add_i32 s16, s16, 8
	v_fma_f32 v138, -v124, v125, 1.0
	v_fmac_f32_e32 v125, v138, v125
	v_div_scale_f32 v138, vcc, 1.0, v117, 1.0
	v_mul_f32_e32 v139, v138, v125
	v_fma_f32 v140, -v124, v139, v138
	v_fmac_f32_e32 v139, v140, v125
	v_fma_f32 v124, -v124, v139, v138
	v_div_fmas_f32 v124, v124, v125, v139
	v_div_fixup_f32 v124, v124, v117, 1.0
	v_pk_fma_f32 v[124:125], v[124:125], v[120:121], v[168:169] op_sel_hi:[0,1,1] neg_lo:[0,0,1] neg_hi:[0,0,1]
	v_bfe_u32 v117, v124, 16, 1
	v_add3_u32 v117, v124, v117, s57
	v_bfe_u32 v124, v125, 16, 1
	v_lshrrev_b32_e32 v117, 16, v117
	v_add3_u32 v124, v125, v124, s57
	v_and_or_b32 v117, v124, s53, v117
	ds_write2st64_b32 v197, v207, v117 offset0:18 offset1:26
	v_cvt_f32_i32_e32 v117, s16
	v_lshlrev_b32_e32 v124, 16, v186
	v_and_b32_e32 v125, 0xffff0000, v186
	v_pk_add_f32 v[124:125], v[124:125], v[136:137] neg_lo:[0,1] neg_hi:[0,1]
	s_min_u32 s16, s18, s17
	v_pk_add_f32 v[120:121], v[120:121], v[124:125]
	v_div_scale_f32 v124, s[26:27], v117, v117, 1.0
	v_rcp_f32_e32 v125, v124
	s_sub_i32 s14, s16, s14
	s_add_i32 s14, s14, 8
	v_fma_f32 v136, -v124, v125, 1.0
	v_fmac_f32_e32 v125, v136, v125
	v_div_scale_f32 v136, vcc, 1.0, v117, 1.0
	v_mul_f32_e32 v137, v136, v125
	v_fma_f32 v138, -v124, v137, v136
	v_fmac_f32_e32 v137, v138, v125
	v_fma_f32 v124, -v124, v137, v136
	v_div_fmas_f32 v124, v124, v125, v137
	v_div_fixup_f32 v124, v124, v117, 1.0
	v_pk_fma_f32 v[124:125], v[124:125], v[120:121], v[166:167] op_sel_hi:[0,1,1] neg_lo:[0,0,1] neg_hi:[0,0,1]
	v_bfe_u32 v117, v124, 16, 1
	v_add3_u32 v117, v124, v117, s57
	v_bfe_u32 v124, v125, 16, 1
	v_lshrrev_b32_e32 v117, 16, v117
	v_add3_u32 v124, v125, v124, s57
	v_and_or_b32 v117, v124, s53, v117
	ds_write2st64_b32 v198, v206, v117 offset0:19 offset1:27
	v_cvt_f32_i32_e32 v117, s14
	v_lshlrev_b32_e32 v124, 16, v185
	v_and_b32_e32 v125, 0xffff0000, v185
	v_pk_add_f32 v[124:125], v[124:125], v[134:135] neg_lo:[0,1] neg_hi:[0,1]
	s_min_u32 s14, s15, s17
	v_pk_add_f32 v[120:121], v[120:121], v[124:125]
	v_div_scale_f32 v124, s[18:19], v117, v117, 1.0
	v_rcp_f32_e32 v125, v124
	s_sub_i32 s2, s14, s2
	s_add_i32 s2, s2, 8
	v_fma_f32 v134, -v124, v125, 1.0
	v_fmac_f32_e32 v125, v134, v125
	v_div_scale_f32 v134, vcc, 1.0, v117, 1.0
	v_mul_f32_e32 v135, v134, v125
	v_fma_f32 v136, -v124, v135, v134
	v_fmac_f32_e32 v135, v136, v125
	v_fma_f32 v124, -v124, v135, v134
	v_div_fmas_f32 v124, v124, v125, v135
	v_div_fixup_f32 v124, v124, v117, 1.0
	v_pk_fma_f32 v[108:109], v[124:125], v[120:121], v[108:109] op_sel_hi:[0,1,1] neg_lo:[0,0,1] neg_hi:[0,0,1]
	v_bfe_u32 v117, v108, 16, 1
	v_add3_u32 v108, v108, v117, s57
	v_bfe_u32 v117, v109, 16, 1
	v_lshrrev_b32_e32 v108, 16, v108
	v_add3_u32 v109, v109, v117, s57
	v_cvt_f32_i32_e32 v117, s2
	v_and_or_b32 v108, v109, s53, v108
	ds_write2st64_b32 v199, v193, v108 offset0:20 offset1:28
	v_lshlrev_b32_e32 v108, 16, v184
	v_and_b32_e32 v109, 0xffff0000, v184
	v_pk_add_f32 v[108:109], v[108:109], v[132:133] neg_lo:[0,1] neg_hi:[0,1]
	s_min_u32 s2, s3, s17
	v_pk_add_f32 v[108:109], v[120:121], v[108:109]
	v_div_scale_f32 v120, s[14:15], v117, v117, 1.0
	v_rcp_f32_e32 v121, v120
	s_sub_i32 s1, s2, s1
	s_add_i32 s1, s1, 8
	v_fma_f32 v124, -v120, v121, 1.0
	v_fmac_f32_e32 v121, v124, v121
	v_div_scale_f32 v124, vcc, 1.0, v117, 1.0
	v_mul_f32_e32 v125, v124, v121
	v_fma_f32 v132, -v120, v125, v124
	v_fmac_f32_e32 v125, v132, v121
	v_fma_f32 v120, -v120, v125, v124
	v_div_fmas_f32 v120, v120, v121, v125
	v_div_fixup_f32 v120, v120, v117, 1.0
	v_pk_fma_f32 v[106:107], v[120:121], v[108:109], v[106:107] op_sel_hi:[0,1,1] neg_lo:[0,0,1] neg_hi:[0,0,1]
	v_bfe_u32 v117, v106, 16, 1
	v_add3_u32 v106, v106, v117, s57
	v_bfe_u32 v117, v107, 16, 1
	v_lshrrev_b32_e32 v106, 16, v106
	v_add3_u32 v107, v107, v117, s57
	v_and_or_b32 v106, v107, s53, v106
	ds_write2st64_b32 v200, v116, v106 offset0:21 offset1:29
	v_lshlrev_b32_e32 v106, 16, v183
	v_and_b32_e32 v107, 0xffff0000, v183
	v_pk_add_f32 v[106:107], v[106:107], v[130:131] neg_lo:[0,1] neg_hi:[0,1]
	s_nop 0
	v_pk_add_f32 v[106:107], v[108:109], v[106:107]
	v_cvt_f32_i32_e32 v108, s1
	s_add_i32 s1, s38, 39
	s_min_u32 s1, s1, s17
	s_sub_i32 s0, s1, s0
	v_div_scale_f32 v109, s[2:3], v108, v108, 1.0
	v_rcp_f32_e32 v116, v109
	s_add_i32 s0, s0, 8
	v_fma_f32 v117, -v109, v116, 1.0
	v_fmac_f32_e32 v116, v117, v116
	v_div_scale_f32 v117, vcc, 1.0, v108, 1.0
	v_mul_f32_e32 v120, v117, v116
	v_fma_f32 v121, -v109, v120, v117
	v_fmac_f32_e32 v120, v121, v116
	v_fma_f32 v109, -v109, v120, v117
	v_div_fmas_f32 v109, v109, v116, v120
	v_div_fixup_f32 v108, v109, v108, 1.0
	v_pk_fma_f32 v[104:105], v[108:109], v[106:107], v[104:105] op_sel_hi:[0,1,1] neg_lo:[0,0,1] neg_hi:[0,0,1]
	v_bfe_u32 v108, v104, 16, 1
	v_add3_u32 v104, v104, v108, s57
	v_bfe_u32 v108, v105, 16, 1
	v_lshrrev_b32_e32 v104, 16, v104
	v_add3_u32 v105, v105, v108, s57
	v_and_or_b32 v104, v105, s53, v104
	ds_write2st64_b32 v201, v113, v104 offset0:22 offset1:30
	v_lshlrev_b32_e32 v104, 16, v182
	v_and_b32_e32 v105, 0xffff0000, v182
	v_pk_add_f32 v[104:105], v[104:105], v[128:129] neg_lo:[0,1] neg_hi:[0,1]
	s_nop 0
	v_pk_add_f32 v[104:105], v[106:107], v[104:105]
	v_cvt_f32_i32_e32 v106, s0
	v_div_scale_f32 v107, s[0:1], v106, v106, 1.0
	v_rcp_f32_e32 v108, v107
	s_mov_b64 s[0:1], 0xc0
	v_lshl_add_u64 v[128:129], v[98:99], 0, s[0:1]
	v_fma_f32 v109, -v107, v108, 1.0
	v_fmac_f32_e32 v108, v109, v108
	v_div_scale_f32 v109, vcc, 1.0, v106, 1.0
	v_mul_f32_e32 v113, v109, v108
	v_fma_f32 v116, -v107, v113, v109
	v_fmac_f32_e32 v113, v116, v108
	v_fma_f32 v107, -v107, v113, v109
	v_div_fmas_f32 v107, v107, v108, v113
	v_div_fixup_f32 v106, v107, v106, 1.0
	v_pk_fma_f32 v[100:101], v[106:107], v[104:105], v[100:101] op_sel_hi:[0,1,1] neg_lo:[0,0,1] neg_hi:[0,0,1]
	v_bfe_u32 v104, v100, 16, 1
	v_add3_u32 v100, v100, v104, s57
	v_bfe_u32 v104, v101, 16, 1
	v_lshrrev_b32_e32 v100, 16, v100
	v_add3_u32 v101, v101, v104, s57
	v_and_or_b32 v100, v101, s53, v100
	ds_write2st64_b32 v194, v112, v100 offset0:23 offset1:31
	v_lshl_add_u64 v[100:101], v[98:99], 0, s[42:43]
	v_lshl_add_u64 v[104:105], v[100:101], 0, v[202:203]
	s_waitcnt lgkmcnt(0)
	global_load_dwordx4 v[130:133], v[102:103], off offset:128
	global_load_dwordx4 v[134:137], v[102:103], off offset:1152
	global_load_dwordx4 v[138:141], v[104:105], off
	v_lshl_add_u64 v[104:105], v[100:101], 0, v[110:111]
	global_load_dwordx4 v[164:167], v[104:105], off
	v_lshl_add_u64 v[104:105], v[100:101], 0, v[114:115]
	global_load_dwordx4 v[168:171], v[104:105], off
	v_lshl_add_u64 v[104:105], v[100:101], 0, v[118:119]
	global_load_dwordx4 v[172:175], v[104:105], off
	v_lshl_add_u64 v[104:105], v[100:101], 0, v[122:123]
	v_lshl_add_u64 v[100:101], v[100:101], 0, v[126:127]
	global_load_dwordx4 v[182:185], v[104:105], off
	global_load_dwordx4 v[186:189], v[100:101], off
	s_nop 0
	global_load_dwordx4 v[98:101], v[102:103], off offset:192
	s_nop 0
	global_load_dwordx4 v[102:105], v[102:103], off offset:1216
	v_lshl_add_u64 v[106:107], v[128:129], 0, v[202:203]
	v_lshl_add_u64 v[110:111], v[128:129], 0, v[110:111]
	v_lshl_add_u64 v[114:115], v[128:129], 0, v[114:115]
	v_lshl_add_u64 v[118:119], v[128:129], 0, v[118:119]
	v_lshl_add_u64 v[122:123], v[128:129], 0, v[122:123]
	v_lshl_add_u64 v[126:127], v[128:129], 0, v[126:127]
	global_load_dwordx4 v[106:109], v[106:107], off
	s_nop 0
	global_load_dwordx4 v[110:113], v[110:111], off
	s_nop 0
	global_load_dwordx4 v[114:117], v[114:115], off
	s_nop 0
	global_load_dwordx4 v[118:121], v[118:119], off
	s_nop 0
	global_load_dwordx4 v[122:125], v[122:123], off
	s_nop 0
	global_load_dwordx4 v[126:129], v[126:127], off
	v_add_u32_e32 v194, v177, v178
	ds_read_b128 v[190:193], v194
	ds_read_b128 v[194:197], v194 offset:4096
	v_add_u32_e32 v202, v177, v179
	s_mov_b32 s92, 0x30000
	s_waitcnt vmcnt(25) lgkmcnt(1)
	v_mfma_f32_16x16x32_bf16 v[198:201], v[90:93], v[190:193], 0
	s_waitcnt vmcnt(23)
	v_mfma_f32_16x16x32_bf16 v[226:229], v[94:97], v[190:193], 0
	v_mfma_f32_16x16x32_bf16 v[230:233], v[66:69], v[190:193], 0
	v_mfma_f32_16x16x32_bf16 v[234:237], v[70:73], v[190:193], 0
	v_mfma_f32_16x16x32_bf16 v[238:241], v[74:77], v[190:193], 0
	v_mfma_f32_16x16x32_bf16 v[242:245], v[78:81], v[190:193], 0
	v_mfma_f32_16x16x32_bf16 v[246:249], v[82:85], v[190:193], 0
	v_mfma_f32_16x16x32_bf16 v[190:193], v[86:89], v[190:193], 0
	s_waitcnt lgkmcnt(0)
	v_mfma_f32_16x16x32_bf16 v[90:93], v[90:93], v[194:197], 0
	v_mfma_f32_16x16x32_bf16 v[94:97], v[94:97], v[194:197], 0
	v_mfma_f32_16x16x32_bf16 v[66:69], v[66:69], v[194:197], 0
	v_mfma_f32_16x16x32_bf16 v[70:73], v[70:73], v[194:197], 0
	v_mfma_f32_16x16x32_bf16 v[74:77], v[74:77], v[194:197], 0
	v_mfma_f32_16x16x32_bf16 v[78:81], v[78:81], v[194:197], 0
	v_mfma_f32_16x16x32_bf16 v[82:85], v[82:85], v[194:197], 0
	v_mfma_f32_16x16x32_bf16 v[86:89], v[86:89], v[194:197], 0
	ds_read_b128 v[194:197], v202
	ds_read_b128 v[250:253], v202 offset:4096
	s_waitcnt vmcnt(20) lgkmcnt(1)
	v_mfma_f32_16x16x32_bf16 v[234:237], v[46:49], v[194:197], v[234:237]
	s_waitcnt lgkmcnt(0)
	v_mfma_f32_16x16x32_bf16 v[46:49], v[46:49], v[250:253], v[70:73]
	s_nop 2
	v_add_u32_e32 v70, v177, v180
	v_mfma_f32_16x16x32_bf16 v[230:233], v[42:45], v[194:197], v[230:233]
	v_mfma_f32_16x16x32_bf16 v[42:45], v[42:45], v[250:253], v[66:69]
	s_nop 2
	ds_read_b128 v[66:69], v70
	ds_read_b128 v[70:73], v70 offset:4096
	v_mfma_f32_16x16x32_bf16 v[226:229], v[38:41], v[194:197], v[226:229]
	v_mfma_f32_16x16x32_bf16 v[38:41], v[38:41], v[250:253], v[94:97]
	v_mfma_f32_16x16x32_bf16 v[198:201], v[34:37], v[194:197], v[198:201]
	s_waitcnt vmcnt(18)
	v_mfma_f32_16x16x32_bf16 v[242:245], v[54:57], v[194:197], v[242:245]
	v_mfma_f32_16x16x32_bf16 v[34:37], v[34:37], v[250:253], v[90:93]
	v_mfma_f32_16x16x32_bf16 v[54:57], v[54:57], v[250:253], v[78:81]
	v_mfma_f32_16x16x32_bf16 v[238:241], v[50:53], v[194:197], v[238:241]
	s_waitcnt vmcnt(14) lgkmcnt(1)
	v_mfma_f32_16x16x32_bf16 v[78:81], v[134:137], v[66:69], v[226:229]
	s_waitcnt lgkmcnt(0)
	v_mfma_f32_16x16x32_bf16 v[38:41], v[134:137], v[70:73], v[38:41]
	s_waitcnt vmcnt(12)
	v_mfma_f32_16x16x32_bf16 v[134:137], v[164:167], v[70:73], v[46:49]
	s_nop 2
	v_add_u32_e32 v46, v177, v181
	v_mfma_f32_16x16x32_bf16 v[246:249], v[58:61], v[194:197], v[246:249]
	v_mfma_f32_16x16x32_bf16 v[50:53], v[50:53], v[250:253], v[74:77]
	v_mfma_f32_16x16x32_bf16 v[58:61], v[58:61], v[250:253], v[82:85]
	v_mfma_f32_16x16x32_bf16 v[74:77], v[130:133], v[66:69], v[198:201]
	v_mfma_f32_16x16x32_bf16 v[82:85], v[138:141], v[66:69], v[230:233]
	s_waitcnt vmcnt(10)
	v_mfma_f32_16x16x32_bf16 v[94:97], v[172:175], v[66:69], v[242:245]
	v_mfma_f32_16x16x32_bf16 v[34:37], v[130:133], v[70:73], v[34:37]
	v_mfma_f32_16x16x32_bf16 v[130:133], v[138:141], v[70:73], v[42:45]
	v_mfma_f32_16x16x32_bf16 v[138:141], v[172:175], v[70:73], v[54:57]
	s_nop 1
	ds_read_b128 v[42:45], v46
	ds_read_b128 v[172:175], v46 offset:4096
	v_mfma_f32_16x16x32_bf16 v[190:193], v[62:65], v[194:197], v[190:193]
	v_mfma_f32_16x16x32_bf16 v[62:65], v[62:65], v[250:253], v[86:89]
	v_mfma_f32_16x16x32_bf16 v[86:89], v[164:167], v[66:69], v[234:237]
	v_mfma_f32_16x16x32_bf16 v[90:93], v[168:171], v[66:69], v[238:241]
	s_waitcnt vmcnt(9)
	v_mfma_f32_16x16x32_bf16 v[194:197], v[182:185], v[66:69], v[246:249]
	s_waitcnt vmcnt(8)
	v_mfma_f32_16x16x32_bf16 v[66:69], v[186:189], v[66:69], v[190:193]
	v_mfma_f32_16x16x32_bf16 v[50:53], v[168:171], v[70:73], v[50:53]
	v_mfma_f32_16x16x32_bf16 v[164:167], v[182:185], v[70:73], v[58:61]
	v_mfma_f32_16x16x32_bf16 v[168:171], v[186:189], v[70:73], v[62:65]
	s_waitcnt vmcnt(7) lgkmcnt(1)
	v_mfma_f32_16x16x32_bf16 v[182:185], v[98:101], v[42:45], v[74:77]
	s_waitcnt vmcnt(6)
	v_mfma_f32_16x16x32_bf16 v[186:189], v[102:105], v[42:45], v[78:81]
	s_waitcnt vmcnt(5)
	v_mfma_f32_16x16x32_bf16 v[78:81], v[106:109], v[42:45], v[82:85]
	s_waitcnt vmcnt(4)
	v_mfma_f32_16x16x32_bf16 v[74:77], v[110:113], v[42:45], v[86:89]
	s_waitcnt lgkmcnt(0)
	v_mfma_f32_16x16x32_bf16 v[84:87], v[98:101], v[172:175], v[34:37]
	s_nop 1
	v_mul_f32_e64 v98, v26, v186
	v_mul_f32_e64 v99, v27, v187
	v_add_u32_e32 v100, s44, v143
	s_nop 0
	v_pk_mul_f32 v[74:75], v[18:19], v[74:75]
	s_waitcnt vmcnt(3)
	v_mfma_f32_16x16x32_bf16 v[62:65], v[114:117], v[42:45], v[90:93]
	v_add_u32_e32 v82, 8, v100
	v_mfma_f32_16x16x32_bf16 v[88:91], v[102:105], v[172:175], v[38:41]
	s_nop 0
	v_mul_f32_e64 v92, v30, v182
	v_mul_f32_e64 v93, v31, v183
	v_pk_mul_f32 v[30:31], v[30:31], v[84:85]
	v_bfe_u32 v83, v92, 16, 1
	s_waitcnt vmcnt(2)
	v_mfma_f32_16x16x32_bf16 v[58:61], v[118:121], v[42:45], v[94:97]
	v_add3_u32 v83, v92, v83, s57
	v_pk_mul_f32 v[84:85], v[28:29], v[90:91]
	v_pk_mul_f32 v[26:27], v[26:27], v[88:89]
	v_pk_mul_f32 v[96:97], v[28:29], v[188:189]
	v_bfe_u32 v28, v30, 16, 1
	v_add3_u32 v28, v30, v28, s57
	v_bfe_u32 v29, v31, 16, 1
	v_pk_mul_f32 v[94:95], v[32:33], v[184:185]
	v_pk_mul_f32 v[32:33], v[32:33], v[86:87]
	v_lshrrev_b32_e32 v28, 16, v28
	v_add3_u32 v29, v31, v29, s57
	v_and_or_b32 v28, v29, s53, v28
	v_bfe_u32 v29, v32, 16, 1
	v_add3_u32 v29, v32, v29, s57
	v_bfe_u32 v30, v33, 16, 1
	v_lshrrev_b32_e32 v29, 16, v29
	v_add3_u32 v30, v33, v30, s57
	v_and_or_b32 v29, v30, s53, v29
	v_bfe_u32 v30, v26, 16, 1
	v_add3_u32 v26, v26, v30, s57
	v_bfe_u32 v30, v27, 16, 1
	v_lshrrev_b32_e32 v26, 16, v26
	v_add3_u32 v27, v27, v30, s57
	v_and_or_b32 v30, v27, s53, v26
	v_bfe_u32 v26, v84, 16, 1
	v_add3_u32 v26, v84, v26, s57
	v_bfe_u32 v27, v85, 16, 1
	v_lshrrev_b32_e32 v26, 16, v26
	v_add3_u32 v27, v85, v27, s57
	v_and_or_b32 v31, v27, s53, v26
	v_add_u32_e32 v26, 24, v100
	v_ashrrev_i32_e32 v27, 31, v26
	v_lshlrev_b64 v[26:27], 12, v[26:27]
	v_lshl_add_u64 v[26:27], v[162:163], 0, v[26:27]
	v_bfe_u32 v92, v93, 16, 1
	global_store_dwordx4 v[26:27], v[28:31], off offset:2816 sc1
	v_lshrrev_b32_e32 v83, 16, v83
	v_add3_u32 v92, v93, v92, s57
	v_pk_mul_f32 v[28:29], v[22:23], v[78:79]
	v_pk_mul_f32 v[32:33], v[20:21], v[76:77]
	v_bfe_u32 v76, v28, 16, 1
	v_and_or_b32 v92, v92, s53, v83
	v_bfe_u32 v83, v94, 16, 1
	v_add3_u32 v28, v28, v76, s57
	v_bfe_u32 v76, v29, 16, 1
	v_add3_u32 v83, v94, v83, s57
	v_bfe_u32 v93, v95, 16, 1
	v_pk_mul_f32 v[30:31], v[24:25], v[80:81]
	v_lshrrev_b32_e32 v28, 16, v28
	v_add3_u32 v29, v29, v76, s57
	v_lshrrev_b32_e32 v83, 16, v83
	v_add3_u32 v93, v95, v93, s57
	v_and_or_b32 v28, v29, s53, v28
	v_bfe_u32 v29, v30, 16, 1
	v_and_or_b32 v93, v93, s53, v83
	v_bfe_u32 v83, v98, 16, 1
	v_add3_u32 v29, v30, v29, s57
	v_bfe_u32 v30, v31, 16, 1
	v_add3_u32 v83, v98, v83, s57
	v_bfe_u32 v94, v99, 16, 1
	v_lshrrev_b32_e32 v29, 16, v29
	v_add3_u32 v30, v31, v30, s57
	v_lshrrev_b32_e32 v83, 16, v83
	v_add3_u32 v94, v99, v94, s57
	v_and_or_b32 v29, v30, s53, v29
	v_bfe_u32 v30, v74, 16, 1
	v_and_or_b32 v94, v94, s53, v83
	v_bfe_u32 v83, v96, 16, 1
	v_add3_u32 v30, v74, v30, s57
	v_bfe_u32 v31, v75, 16, 1
	v_mfma_f32_16x16x32_bf16 v[70:73], v[106:109], v[172:175], v[130:133]
	v_add3_u32 v83, v96, v83, s57
	v_bfe_u32 v95, v97, 16, 1
	v_lshrrev_b32_e32 v30, 16, v30
	v_add3_u32 v31, v75, v31, s57
	s_waitcnt vmcnt(2)
	v_mfma_f32_16x16x32_bf16 v[46:49], v[122:125], v[42:45], v[194:197]
	v_lshrrev_b32_e32 v83, 16, v83
	v_add3_u32 v95, v97, v95, s57
	v_and_or_b32 v30, v31, s53, v30
	s_waitcnt vmcnt(1)
	v_mfma_f32_16x16x32_bf16 v[42:45], v[126:129], v[42:45], v[66:69]
	v_bfe_u32 v31, v32, 16, 1
	v_and_or_b32 v95, v95, s53, v83
	v_ashrrev_i32_e32 v83, 31, v82
	v_mfma_f32_16x16x32_bf16 v[66:69], v[110:113], v[172:175], v[134:137]
	v_add3_u32 v31, v32, v31, s57
	v_bfe_u32 v32, v33, 16, 1
	v_lshlrev_b64 v[82:83], 12, v[82:83]
	v_lshrrev_b32_e32 v31, 16, v31
	v_add3_u32 v32, v33, v32, s57
	v_lshl_add_u64 v[82:83], v[162:163], 0, v[82:83]
	v_and_or_b32 v31, v32, s53, v31
	v_pk_mul_f32 v[22:23], v[22:23], v[70:71]
	global_store_dwordx4 v[82:83], v[28:31], off offset:2880 sc1
	v_pk_mul_f32 v[24:25], v[24:25], v[72:73]
	v_mfma_f32_16x16x32_bf16 v[54:57], v[114:117], v[172:175], v[50:53]
	v_mul_f32_e64 v28, v20, v68
	v_mul_f32_e64 v29, v21, v69
	v_pk_mul_f32 v[20:21], v[18:19], v[66:67]
	v_bfe_u32 v18, v22, 16, 1
	v_add3_u32 v18, v22, v18, s57
	v_bfe_u32 v19, v23, 16, 1
	v_lshrrev_b32_e32 v18, 16, v18
	v_add3_u32 v19, v23, v19, s57
	v_and_or_b32 v18, v19, s53, v18
	v_bfe_u32 v19, v24, 16, 1
	v_add3_u32 v19, v24, v19, s57
	v_bfe_u32 v22, v25, 16, 1
	v_lshrrev_b32_e32 v19, 16, v19
	v_add3_u32 v22, v25, v22, s57
	v_and_or_b32 v19, v22, s53, v19
	v_bfe_u32 v22, v20, 16, 1
	v_add3_u32 v20, v20, v22, s57
	v_bfe_u32 v22, v21, 16, 1
	v_lshrrev_b32_e32 v20, 16, v20
	v_add3_u32 v21, v21, v22, s57
	v_and_or_b32 v20, v21, s53, v20
	v_bfe_u32 v21, v28, 16, 1
	v_add3_u32 v21, v28, v21, s57
	v_bfe_u32 v22, v29, 16, 1
	v_lshrrev_b32_e32 v21, 16, v21
	v_add3_u32 v22, v29, v22, s57
	v_and_or_b32 v21, v22, s53, v21
	global_store_dwordx4 v[26:27], v[18:21], off offset:2880 sc1
	v_pk_mul_f32 v[24:25], v[10:11], v[58:59]
	v_pk_mul_f32 v[22:23], v[12:13], v[60:61]
	v_pk_mul_f32 v[18:19], v[14:15], v[62:63]
	v_pk_mul_f32 v[20:21], v[16:17], v[64:65]
	v_bfe_u32 v28, v18, 16, 1
	v_add3_u32 v18, v18, v28, s57
	v_bfe_u32 v28, v19, 16, 1
	v_lshrrev_b32_e32 v18, 16, v18
	v_add3_u32 v19, v19, v28, s57
	v_and_or_b32 v18, v19, s53, v18
	v_bfe_u32 v19, v20, 16, 1
	v_add3_u32 v19, v20, v19, s57
	v_bfe_u32 v20, v21, 16, 1
	v_lshrrev_b32_e32 v19, 16, v19
	v_add3_u32 v20, v21, v20, s57
	v_and_or_b32 v19, v20, s53, v19
	v_bfe_u32 v20, v24, 16, 1
	v_add3_u32 v20, v24, v20, s57
	v_bfe_u32 v21, v25, 16, 1
	v_lshrrev_b32_e32 v20, 16, v20
	v_add3_u32 v21, v25, v21, s57
	v_mfma_f32_16x16x32_bf16 v[50:53], v[118:121], v[172:175], v[138:141]
	v_and_or_b32 v20, v21, s53, v20
	v_bfe_u32 v21, v22, 16, 1
	v_add3_u32 v21, v22, v21, s57
	v_bfe_u32 v22, v23, 16, 1
	v_lshrrev_b32_e32 v21, 16, v21
	v_add3_u32 v22, v23, v22, s57
	v_and_or_b32 v21, v22, s53, v21
	v_pk_mul_f32 v[14:15], v[14:15], v[54:55]
	global_store_dwordx4 v[82:83], v[18:21], off offset:2944 sc1
	v_pk_mul_f32 v[16:17], v[16:17], v[56:57]
	v_mfma_f32_16x16x32_bf16 v[38:41], v[122:125], v[172:175], v[164:167]
	v_mul_f32_e64 v18, v12, v52
	v_mul_f32_e64 v19, v13, v53
	v_pk_mul_f32 v[12:13], v[10:11], v[50:51]
	v_bfe_u32 v10, v14, 16, 1
	v_add3_u32 v10, v14, v10, s57
	v_bfe_u32 v11, v15, 16, 1
	v_lshrrev_b32_e32 v10, 16, v10
	v_add3_u32 v11, v15, v11, s57
	v_and_or_b32 v10, v11, s53, v10
	v_bfe_u32 v11, v16, 16, 1
	v_add3_u32 v11, v16, v11, s57
	v_bfe_u32 v14, v17, 16, 1
	v_lshrrev_b32_e32 v11, 16, v11
	v_add3_u32 v14, v17, v14, s57
	v_and_or_b32 v11, v14, s53, v11
	v_bfe_u32 v14, v12, 16, 1
	v_add3_u32 v12, v12, v14, s57
	v_bfe_u32 v14, v13, 16, 1
	v_lshrrev_b32_e32 v12, 16, v12
	v_add3_u32 v13, v13, v14, s57
	v_and_or_b32 v12, v13, s53, v12
	v_bfe_u32 v13, v18, 16, 1
	v_add3_u32 v13, v18, v13, s57
	v_bfe_u32 v14, v19, 16, 1
	v_lshrrev_b32_e32 v13, 16, v13
	v_add3_u32 v14, v19, v14, s57
	v_and_or_b32 v13, v14, s53, v13
	global_store_dwordx4 v[26:27], v[10:13], off offset:2944 sc1
	v_pk_mul_f32 v[16:17], v[2:3], v[42:43]
	v_pk_mul_f32 v[14:15], v[4:5], v[44:45]
	v_pk_mul_f32 v[10:11], v[6:7], v[46:47]
	v_pk_mul_f32 v[12:13], v[8:9], v[48:49]
	v_bfe_u32 v18, v10, 16, 1
	v_add3_u32 v10, v10, v18, s57
	v_bfe_u32 v18, v11, 16, 1
	v_lshrrev_b32_e32 v10, 16, v10
	v_add3_u32 v11, v11, v18, s57
	v_and_or_b32 v10, v11, s53, v10
	v_bfe_u32 v11, v12, 16, 1
	v_add3_u32 v11, v12, v11, s57
	v_bfe_u32 v12, v13, 16, 1
	v_lshrrev_b32_e32 v11, 16, v11
	v_add3_u32 v12, v13, v12, s57
	v_and_or_b32 v11, v12, s53, v11
	v_bfe_u32 v12, v16, 16, 1
	v_add3_u32 v12, v16, v12, s57
	v_bfe_u32 v13, v17, 16, 1
	v_lshrrev_b32_e32 v12, 16, v12
	v_add3_u32 v13, v17, v13, s57
	v_mfma_f32_16x16x32_bf16 v[34:37], v[126:129], v[172:175], v[168:171]
	v_and_or_b32 v12, v13, s53, v12
	v_bfe_u32 v13, v14, 16, 1
	v_add3_u32 v13, v14, v13, s57
	v_bfe_u32 v14, v15, 16, 1
	v_lshrrev_b32_e32 v13, 16, v13
	v_add3_u32 v14, v15, v14, s57
	v_and_or_b32 v13, v14, s53, v13
	v_pk_mul_f32 v[6:7], v[6:7], v[38:39]
	global_store_dwordx4 v[82:83], v[10:13], off offset:3008 sc1
	v_pk_mul_f32 v[8:9], v[8:9], v[40:41]
	global_store_dwordx4 v[82:83], v[92:95], off offset:2816 sc1
	v_pk_mul_f32 v[10:11], v[4:5], v[36:37]
	v_pk_mul_f32 v[4:5], v[2:3], v[34:35]
	v_bfe_u32 v2, v6, 16, 1
	v_add3_u32 v2, v6, v2, s57
	v_bfe_u32 v3, v7, 16, 1
	v_lshrrev_b32_e32 v2, 16, v2
	v_add3_u32 v3, v7, v3, s57
	v_and_or_b32 v2, v3, s53, v2
	v_bfe_u32 v3, v8, 16, 1
	v_add3_u32 v3, v8, v3, s57
	v_bfe_u32 v6, v9, 16, 1
	v_lshrrev_b32_e32 v3, 16, v3
	v_add3_u32 v6, v9, v6, s57
	v_and_or_b32 v3, v6, s53, v3
	v_bfe_u32 v6, v4, 16, 1
	v_add3_u32 v4, v4, v6, s57
	v_bfe_u32 v6, v5, 16, 1
	v_lshrrev_b32_e32 v4, 16, v4
	v_add3_u32 v5, v5, v6, s57
	v_and_or_b32 v4, v5, s53, v4
	v_bfe_u32 v5, v10, 16, 1
	v_add3_u32 v5, v10, v5, s57
	v_bfe_u32 v6, v11, 16, 1
	v_lshrrev_b32_e32 v5, 16, v5
	v_add3_u32 v6, v11, v6, s57
	v_and_or_b32 v5, v6, s53, v5
	global_store_dwordx4 v[26:27], v[2:5], off offset:3008 sc1
	s_waitcnt lgkmcnt(0)
	s_branch .LBB0_514

.LBB0_920:
	s_andn2_b64 vcc, exec, s[38:39]
	v_readlane_b32 s97, v254, 19
	s_cbranch_vccnz .LBB0_904
	s_ashr_i32 s9, s8, 31
	v_lshl_add_u32 v142, s6, 8, v147
	s_lshl_b64 s[2:3], s[8:9], 22
	v_ashrrev_i32_e32 v143, 31, v142
	s_add_u32 s2, s80, s2
	v_lshl_or_b32 v140, s76, 8, v148
	s_addc_u32 s3, s81, s3
	v_lshlrev_b64 v[142:143], 12, v[142:143]
	v_lshl_add_u64 v[142:143], s[2:3], 0, v[142:143]
	v_ashrrev_i32_e32 v141, 31, v140
	v_lshl_add_u64 v[140:141], v[140:141], 1, v[142:143]
	s_mov_b32 s2, 0x10000
	v_cvt_pk_bf16_f32 v126, v126, v127
	v_cvt_pk_bf16_f32 v127, v128, v129
	v_cvt_pk_bf16_f32 v128, v122, v123
	v_cvt_pk_bf16_f32 v129, v124, v125
	global_store_dwordx4 v[140:141], v[126:129], off sc1
	v_cvt_pk_bf16_f32 v118, v118, v119
	v_cvt_pk_bf16_f32 v119, v120, v121
	v_cvt_pk_bf16_f32 v120, v114, v115
	v_cvt_pk_bf16_f32 v121, v116, v117
	global_store_dwordx4 v[140:141], v[118:121], off offset:256 sc1
	v_cvt_pk_bf16_f32 v110, v110, v111
	v_cvt_pk_bf16_f32 v111, v112, v113
	v_cvt_pk_bf16_f32 v112, v106, v107
	v_add_co_u32_e32 v106, vcc, s2, v140
	s_mov_b32 s2, 0x20000
	s_nop 0
	v_addc_co_u32_e32 v107, vcc, 0, v141, vcc
	v_cvt_pk_bf16_f32 v113, v108, v109
	global_store_dwordx4 v[106:107], v[110:113], off sc1
	v_cvt_pk_bf16_f32 v102, v102, v103
	v_cvt_pk_bf16_f32 v103, v104, v105
	v_cvt_pk_bf16_f32 v104, v98, v99
	v_cvt_pk_bf16_f32 v105, v100, v101
	global_store_dwordx4 v[106:107], v[102:105], off offset:256 sc1
	v_cvt_pk_bf16_f32 v94, v94, v95
	v_cvt_pk_bf16_f32 v95, v96, v97
	v_cvt_pk_bf16_f32 v96, v90, v91
	v_add_co_u32_e32 v90, vcc, s2, v140
	v_cvt_pk_bf16_f32 v97, v92, v93
	s_mov_b32 s2, 0x80000
	s_nop 0
	v_addc_co_u32_e32 v91, vcc, 0, v141, vcc
	global_store_dwordx4 v[90:91], v[94:97], off sc1
	v_cvt_pk_bf16_f32 v86, v86, v87
	v_cvt_pk_bf16_f32 v87, v88, v89
	v_cvt_pk_bf16_f32 v88, v82, v83
	v_cvt_pk_bf16_f32 v89, v84, v85
	global_store_dwordx4 v[90:91], v[86:89], off offset:256 sc1
	v_cvt_pk_bf16_f32 v78, v78, v79
	v_cvt_pk_bf16_f32 v79, v80, v81
	v_cvt_pk_bf16_f32 v80, v74, v75
	v_add_co_u32_e32 v74, vcc, s90, v140
	v_cvt_pk_bf16_f32 v81, v76, v77
	s_nop 1
	v_addc_co_u32_e32 v75, vcc, 0, v141, vcc
	global_store_dwordx4 v[74:75], v[78:81], off sc1
	v_cvt_pk_bf16_f32 v70, v70, v71
	v_cvt_pk_bf16_f32 v71, v72, v73
	v_cvt_pk_bf16_f32 v72, v66, v67
	v_cvt_pk_bf16_f32 v73, v68, v69
	global_store_dwordx4 v[74:75], v[70:73], off offset:256 sc1
	v_cvt_pk_bf16_f32 v62, v62, v63
	v_cvt_pk_bf16_f32 v63, v64, v65
	v_cvt_pk_bf16_f32 v64, v58, v59
	v_add_co_u32_e32 v58, vcc, s2, v140
	s_mov_b32 s2, 0x90000
	s_nop 0
	v_addc_co_u32_e32 v59, vcc, 0, v141, vcc
	v_cvt_pk_bf16_f32 v65, v60, v61
	global_store_dwordx4 v[58:59], v[62:65], off sc1
	v_cvt_pk_bf16_f32 v54, v54, v55
	v_cvt_pk_bf16_f32 v55, v56, v57
	v_cvt_pk_bf16_f32 v56, v50, v51
	v_cvt_pk_bf16_f32 v57, v52, v53
	global_store_dwordx4 v[58:59], v[54:57], off offset:256 sc1
	v_cvt_pk_bf16_f32 v46, v46, v47
	v_cvt_pk_bf16_f32 v47, v48, v49
	v_cvt_pk_bf16_f32 v48, v42, v43
	v_add_co_u32_e32 v42, vcc, s2, v140
	s_mov_b32 s2, 0xa0000
	s_nop 0
	v_addc_co_u32_e32 v43, vcc, 0, v141, vcc
	v_cvt_pk_bf16_f32 v49, v44, v45
	global_store_dwordx4 v[42:43], v[46:49], off sc1
	v_cvt_pk_bf16_f32 v38, v38, v39
	v_cvt_pk_bf16_f32 v39, v40, v41
	v_cvt_pk_bf16_f32 v40, v34, v35
	v_cvt_pk_bf16_f32 v41, v36, v37
	global_store_dwordx4 v[42:43], v[38:41], off offset:256 sc1
	v_cvt_pk_bf16_f32 v30, v30, v31
	v_cvt_pk_bf16_f32 v31, v32, v33
	v_cvt_pk_bf16_f32 v32, v26, v27
	v_add_co_u32_e32 v26, vcc, s2, v140
	s_mov_b32 s2, 0xb0000
	s_nop 0
	v_addc_co_u32_e32 v27, vcc, 0, v141, vcc
	v_cvt_pk_bf16_f32 v33, v28, v29
	global_store_dwordx4 v[26:27], v[30:33], off sc1
	v_cvt_pk_bf16_f32 v22, v22, v23
	v_cvt_pk_bf16_f32 v23, v24, v25
	v_cvt_pk_bf16_f32 v24, v18, v19
	v_cvt_pk_bf16_f32 v25, v20, v21
	global_store_dwordx4 v[26:27], v[22:25], off offset:256 sc1
	v_cvt_pk_bf16_f32 v14, v14, v15
	v_cvt_pk_bf16_f32 v15, v16, v17
	v_cvt_pk_bf16_f32 v16, v10, v11
	v_add_co_u32_e32 v10, vcc, s2, v140
	v_cvt_pk_bf16_f32 v17, v12, v13
	s_nop 1
	v_addc_co_u32_e32 v11, vcc, 0, v141, vcc
	s_andn2_b64 vcc, exec, s[26:27]
	global_store_dwordx4 v[10:11], v[14:17], off sc1
	v_cvt_pk_bf16_f32 v6, v6, v7
	v_cvt_pk_bf16_f32 v7, v8, v9
	v_cvt_pk_bf16_f32 v8, v2, v3
	v_cvt_pk_bf16_f32 v9, v4, v5
	global_store_dwordx4 v[10:11], v[6:9], off offset:256 sc1
	s_cbranch_vccnz .LBB0_923
	s_barrier

.LBB0_942:
	s_or_b64 exec, exec, s[2:3]
	v_or_b32_e32 v136, s26, v226
	v_ashrrev_i32_e32 v137, 31, v136
	v_lshlrev_b64 v[148:149], 12, v[136:137]
	s_lshl_b64 s[2:3], s[16:17], 2
	s_waitcnt lgkmcnt(0)
	v_lshl_add_u64 v[2:3], s[8:9], 0, v[148:149]
	s_add_u32 s20, s10, s2
	v_lshl_add_u64 v[6:7], v[206:207], 1, v[2:3]
	v_cvt_pk_f16_f32 v5, v124, v125
	v_cvt_pk_f16_f32 v4, v122, v123
	v_cvt_pk_f16_f32 v3, v128, v129
	v_cvt_pk_f16_f32 v2, v126, v127
	s_mov_b32 s1, 0x10000
	s_addc_u32 s21, s11, s3
	global_store_dwordx4 v[6:7], v[2:5], off sc1
	v_add_co_u32_e64 v8, s[10:11], s1, v6
	s_nop 0
	v_cvt_pk_f16_f32 v5, v116, v117
	v_cvt_pk_f16_f32 v4, v114, v115
	v_cvt_pk_f16_f32 v3, v120, v121
	v_cvt_pk_f16_f32 v2, v118, v119
	global_store_dwordx4 v[6:7], v[2:5], off offset:256 sc1
	v_addc_co_u32_e64 v9, s[10:11], 0, v7, s[10:11]
	s_nop 0
	v_cvt_pk_f16_f32 v5, v108, v109
	v_cvt_pk_f16_f32 v4, v106, v107
	v_cvt_pk_f16_f32 v3, v112, v113
	v_cvt_pk_f16_f32 v2, v110, v111
	global_store_dwordx4 v[8:9], v[2:5], off sc1
	s_mov_b32 s1, 0x20000
	s_add_u32 s2, s6, 0x8000
	v_cvt_pk_f16_f32 v5, v100, v101
	v_cvt_pk_f16_f32 v4, v98, v99
	v_cvt_pk_f16_f32 v3, v104, v105
	v_cvt_pk_f16_f32 v2, v102, v103
	global_store_dwordx4 v[8:9], v[2:5], off offset:256 sc1
	v_add_co_u32_e64 v8, s[10:11], s1, v6
	s_nop 0
	v_cvt_pk_f16_f32 v5, v92, v93
	v_cvt_pk_f16_f32 v4, v90, v91
	v_cvt_pk_f16_f32 v3, v96, v97
	v_cvt_pk_f16_f32 v2, v94, v95
	v_addc_co_u32_e64 v9, s[10:11], 0, v7, s[10:11]
	global_store_dwordx4 v[8:9], v[2:5], off sc1
	s_mov_b32 s1, 0x80000
	s_addc_u32 s3, s7, 0
	v_cvt_pk_f16_f32 v5, v84, v85
	v_cvt_pk_f16_f32 v4, v82, v83
	v_cvt_pk_f16_f32 v3, v88, v89
	v_cvt_pk_f16_f32 v2, v86, v87
	global_store_dwordx4 v[8:9], v[2:5], off offset:256 sc1
	v_add_co_u32_e64 v8, s[10:11], s92, v6
	s_nop 0
	v_cvt_pk_f16_f32 v5, v184, v185
	v_cvt_pk_f16_f32 v4, v188, v189
	v_cvt_pk_f16_f32 v3, v182, v183
	v_cvt_pk_f16_f32 v2, v186, v187
	v_addc_co_u32_e64 v9, s[10:11], 0, v7, s[10:11]
	global_store_dwordx4 v[8:9], v[2:5], off sc1
	s_add_u32 s6, s6, 0x6000
	s_addc_u32 s7, s7, 0
	v_cvt_pk_f16_f32 v5, v68, v69
	v_cvt_pk_f16_f32 v4, v66, v67
	v_cvt_pk_f16_f32 v3, v72, v73
	v_cvt_pk_f16_f32 v2, v70, v71
	global_store_dwordx4 v[8:9], v[2:5], off offset:256 sc1
	v_add_co_u32_e64 v8, s[10:11], s1, v6
	s_nop 0
	v_cvt_pk_f16_f32 v5, v178, v179
	v_cvt_pk_f16_f32 v4, v180, v181
	v_cvt_pk_f16_f32 v3, v174, v175
	v_cvt_pk_f16_f32 v2, v176, v177
	v_addc_co_u32_e64 v9, s[10:11], 0, v7, s[10:11]
	global_store_dwordx4 v[8:9], v[2:5], off sc1
	s_mov_b32 s1, 0x90000
	v_or_b32_e32 v40, 0x84, v206
	v_cvt_pk_f16_f32 v5, v52, v53
	v_cvt_pk_f16_f32 v4, v50, v51
	v_cvt_pk_f16_f32 v3, v56, v57
	v_cvt_pk_f16_f32 v2, v54, v55
	global_store_dwordx4 v[8:9], v[2:5], off offset:256 sc1
	v_add_co_u32_e64 v8, s[10:11], s1, v6
	s_nop 0
	v_cvt_pk_f16_f32 v5, v168, v169
	v_cvt_pk_f16_f32 v4, v172, v173
	v_cvt_pk_f16_f32 v3, v166, v167
	v_cvt_pk_f16_f32 v2, v170, v171
	v_addc_co_u32_e64 v9, s[10:11], 0, v7, s[10:11]
	global_store_dwordx4 v[8:9], v[2:5], off sc1
	s_mov_b32 s1, 0xa0000
	v_ashrrev_i32_e32 v41, 31, v40
	v_cvt_pk_f16_f32 v5, v60, v61
	v_cvt_pk_f16_f32 v4, v64, v65
	v_cvt_pk_f16_f32 v3, v58, v59
	v_cvt_pk_f16_f32 v2, v62, v63
	global_store_dwordx4 v[8:9], v[2:5], off offset:256 sc1
	v_add_co_u32_e64 v8, s[10:11], s1, v6
	s_nop 0
	v_cvt_pk_f16_f32 v5, v162, v163
	v_cvt_pk_f16_f32 v4, v164, v165
	v_cvt_pk_f16_f32 v3, v158, v159
	v_cvt_pk_f16_f32 v2, v160, v161
	v_addc_co_u32_e64 v9, s[10:11], 0, v7, s[10:11]
	s_mov_b32 s1, 0xb0000
	global_store_dwordx4 v[8:9], v[2:5], off sc1
	v_add_co_u32_e64 v6, s[10:11], s1, v6
	s_nop 0
	v_cvt_pk_f16_f32 v5, v78, v79
	v_cvt_pk_f16_f32 v4, v80, v81
	v_cvt_pk_f16_f32 v3, v74, v75
	v_cvt_pk_f16_f32 v2, v76, v77
	global_store_dwordx4 v[8:9], v[2:5], off offset:256 sc1
	v_addc_co_u32_e64 v7, s[10:11], 0, v7, s[10:11]
	s_nop 0
	v_cvt_pk_f16_f32 v5, v144, v145
	v_cvt_pk_f16_f32 v4, v146, v147
	v_cvt_pk_f16_f32 v3, v142, v143
	v_cvt_pk_f16_f32 v2, v150, v151
	global_store_dwordx4 v[6:7], v[2:5], off sc1
	v_lshl_add_u64 v[40:41], v[40:41], 2, s[2:3]
	s_nop 0
	v_cvt_pk_f16_f32 v5, v132, v133
	v_cvt_pk_f16_f32 v4, v134, v135
	v_cvt_pk_f16_f32 v3, v130, v131
	v_cvt_pk_f16_f32 v2, v138, v139
	global_store_dwordx4 v[6:7], v[2:5], off offset:256 sc1
	s_nop 1
	v_lshlrev_b64 v[2:3], 2, v[206:207]
	v_lshl_add_u64 v[4:5], s[20:21], 0, v[2:3]
	v_lshl_add_u64 v[6:7], s[6:7], 0, v[2:3]
	v_lshl_add_u64 v[2:3], s[2:3], 0, v[2:3]
	global_load_dwordx4 v[22:25], v[4:5], off offset:16
	global_load_dwordx4 v[34:37], v[4:5], off
	global_load_dwordx4 v[30:33], v[2:3], off offset:16
	global_load_dwordx4 v[46:49], v[2:3], off
	global_load_dwordx4 v[10:13], v[6:7], off offset:16
	global_load_dwordx4 v[14:17], v[6:7], off
	v_or_b32_e32 v2, 0x80, v206
	v_ashrrev_i32_e32 v3, 31, v2
	v_lshlrev_b64 v[2:3], 2, v[2:3]
	v_lshl_add_u64 v[6:7], s[6:7], 0, v[2:3]
	v_lshl_add_u64 v[38:39], s[2:3], 0, v[2:3]
	global_load_dwordx4 v[18:21], v[4:5], off offset:528
	global_load_dwordx4 v[26:29], v[4:5], off offset:512
	s_nop 0
	global_load_dwordx4 v[2:5], v[6:7], off offset:16
	s_nop 0
	global_load_dwordx4 v[6:9], v[6:7], off
	s_nop 0
	global_load_dwordx4 v[42:45], v[38:39], off
	s_nop 0
	global_load_dwordx4 v[38:41], v[40:41], off
	s_and_saveexec_b64 s[6:7], vcc
	s_cbranch_execz .LBB0_958
	s_ashr_i32 s13, s12, 31
	s_memrealtime s[2:3]
	s_lshl_b64 s[8:9], s[12:13], 13
	s_add_u32 s8, s15, s8
	s_addc_u32 s9, s14, s9
	v_lshlrev_b64 v[152:153], 5, v[140:141]
	v_lshl_add_u64 v[192:193], s[8:9], 0, v[152:153]
	s_mov_b64 s[8:9], 0
	s_branch .LBB0_946

.LBB0_958:
	s_or_b64 exec, exec, s[6:7]
	s_add_u32 s6, s18, 0x1a400000
	s_waitcnt vmcnt(8)
	v_pk_add_f32 v[48:49], v[48:49], 1.0 op_sel_hi:[1,0]
	v_pk_add_f32 v[32:33], v[32:33], 1.0 op_sel_hi:[1,0]
	s_addc_u32 s7, s19, 0
	v_pk_mul_f32 v[36:37], v[36:37], v[48:49]
	v_pk_mul_f32 v[48:49], v[24:25], v[32:33]
	s_waitcnt vmcnt(1)
	v_pk_add_f32 v[24:25], v[42:43], 1.0 op_sel_hi:[1,0]
	s_lshl_b32 s0, s0, 2
	v_pk_mul_f32 v[24:25], v[26:27], v[24:25]
	s_waitcnt vmcnt(0)
	v_pk_add_f32 v[26:27], v[40:41], 1.0 op_sel_hi:[1,0]
	s_add_i32 s0, s0, 0
	v_pk_mul_f32 v[20:21], v[20:21], v[26:27]
	v_lshl_add_u32 v26, v226, 2, s0
	s_waitcnt lgkmcnt(0)
	s_barrier
	v_add_u32_e32 v26, 0x1000, v26
	ds_read2_b32 v[32:33], v26 offset1:16
	v_pk_add_f32 v[46:47], v[46:47], 1.0 op_sel_hi:[1,0]
	v_pk_add_f32 v[30:31], v[30:31], 1.0 op_sel_hi:[1,0]
	v_pk_mul_f32 v[34:35], v[34:35], v[46:47]
	v_pk_mul_f32 v[46:47], v[22:23], v[30:31]
	v_pk_add_f32 v[22:23], v[44:45], 1.0 op_sel_hi:[1,0]
	s_waitcnt lgkmcnt(0)
	v_pk_mul_f32 v[42:43], v[124:125], v[32:33] op_sel_hi:[1,0]
	v_pk_mul_f32 v[22:23], v[28:29], v[22:23]
	v_pk_add_f32 v[28:29], v[38:39], 1.0 op_sel_hi:[1,0]
	v_pk_mul_f32 v[38:39], v[128:129], v[32:33] op_sel_hi:[1,0]
	v_pk_mul_f32 v[44:45], v[122:123], v[32:33] op_sel_hi:[1,0]
	v_pk_mul_f32 v[40:41], v[126:127], v[32:33] op_sel_hi:[1,0]
	v_pk_fma_f32 v[38:39], v[36:37], v[38:39], v[16:17]
	v_pk_fma_f32 v[122:123], v[48:49], v[42:43], v[12:13]
	v_pk_fma_f32 v[44:45], v[46:47], v[44:45], v[10:11]
	v_pk_mul_f32 v[18:19], v[18:19], v[28:29]
	ds_read2_b32 v[30:31], v26 offset0:32 offset1:48
	ds_read2_b32 v[28:29], v26 offset0:128 offset1:144
	ds_read2_b32 v[26:27], v26 offset0:160 offset1:176
	v_pk_fma_f32 v[40:41], v[34:35], v[40:41], v[14:15]
	s_mov_b64 s[0:1], 0x80000
	v_cvt_pk_bf16_f32 v42, v40, v41
	v_cvt_pk_bf16_f32 v43, v38, v39
	v_cvt_pk_bf16_f32 v44, v44, v45
	v_cvt_pk_bf16_f32 v45, v122, v123
	v_lshl_add_u64 v[38:39], s[6:7], 0, v[148:149]
	v_lshlrev_b64 v[122:123], 1, v[206:207]
	v_lshl_add_u64 v[40:41], v[38:39], 0, v[122:123]
	v_mov_b32_e32 v38, v33
	global_store_dwordx4 v[40:41], v[42:45], off sc1
	v_pk_mul_f32 v[108:109], v[108:109], v[38:39] op_sel_hi:[1,0]
	v_pk_mul_f32 v[106:107], v[106:107], v[38:39] op_sel_hi:[1,0]
	v_pk_mul_f32 v[42:43], v[112:113], v[38:39] op_sel_hi:[1,0]
	v_pk_mul_f32 v[44:45], v[110:111], v[38:39] op_sel_hi:[1,0]
	v_pk_fma_f32 v[42:43], v[36:37], v[42:43], v[16:17]
	v_pk_fma_f32 v[44:45], v[34:35], v[44:45], v[14:15]
	v_pk_fma_f32 v[110:111], v[48:49], v[108:109], v[12:13]
	v_pk_fma_f32 v[108:109], v[46:47], v[106:107], v[10:11]
	v_cvt_pk_bf16_f32 v106, v44, v45
	v_cvt_pk_bf16_f32 v107, v42, v43
	v_or_b32_e32 v42, 16, v136
	v_ashrrev_i32_e32 v43, 31, v42
	v_lshlrev_b64 v[42:43], 12, v[42:43]
	v_lshl_add_u64 v[42:43], s[6:7], 0, v[42:43]
	s_waitcnt lgkmcnt(2)
	v_pk_mul_f32 v[44:45], v[96:97], v[30:31] op_sel_hi:[1,0]
	v_lshl_add_u64 v[42:43], v[42:43], 0, v[122:123]
	v_pk_mul_f32 v[94:95], v[94:95], v[30:31] op_sel_hi:[1,0]
	v_pk_fma_f32 v[44:45], v[36:37], v[44:45], v[16:17]
	v_pk_mul_f32 v[92:93], v[92:93], v[30:31] op_sel_hi:[1,0]
	v_cvt_pk_bf16_f32 v108, v108, v109
	v_cvt_pk_bf16_f32 v109, v110, v111
	global_store_dwordx4 v[42:43], v[106:109], off sc1
	v_pk_fma_f32 v[94:95], v[34:35], v[94:95], v[14:15]
	v_pk_fma_f32 v[96:97], v[48:49], v[92:93], v[12:13]
	v_cvt_pk_bf16_f32 v92, v94, v95
	v_cvt_pk_bf16_f32 v93, v44, v45
	v_or_b32_e32 v44, 32, v136
	v_ashrrev_i32_e32 v45, 31, v44
	v_pk_mul_f32 v[90:91], v[90:91], v[30:31] op_sel_hi:[1,0]
	v_lshlrev_b64 v[44:45], 12, v[44:45]
	v_pk_fma_f32 v[90:91], v[46:47], v[90:91], v[10:11]
	v_lshl_add_u64 v[44:45], s[6:7], 0, v[44:45]
	v_cvt_pk_bf16_f32 v94, v90, v91
	v_cvt_pk_bf16_f32 v95, v96, v97
	v_lshl_add_u64 v[90:91], v[44:45], 0, v[122:123]
	v_mov_b32_e32 v44, v31
	global_store_dwordx4 v[90:91], v[92:95], off sc1
	v_pk_mul_f32 v[96:97], v[184:185], v[44:45] op_sel_hi:[1,0]
	v_pk_mul_f32 v[106:107], v[188:189], v[44:45] op_sel_hi:[1,0]
	v_pk_mul_f32 v[92:93], v[182:183], v[44:45] op_sel_hi:[1,0]
	v_pk_mul_f32 v[94:95], v[186:187], v[44:45] op_sel_hi:[1,0]
	v_pk_fma_f32 v[92:93], v[36:37], v[92:93], v[16:17]
	v_pk_fma_f32 v[94:95], v[34:35], v[94:95], v[14:15]
	v_pk_fma_f32 v[108:109], v[48:49], v[96:97], v[12:13]
	v_cvt_pk_bf16_f32 v94, v94, v95
	v_cvt_pk_bf16_f32 v95, v92, v93
	v_or_b32_e32 v92, 48, v136
	v_ashrrev_i32_e32 v93, 31, v92
	v_lshlrev_b64 v[92:93], 12, v[92:93]
	v_lshl_add_u64 v[92:93], s[6:7], 0, v[92:93]
	v_pk_fma_f32 v[96:97], v[46:47], v[106:107], v[10:11]
	v_lshl_add_u64 v[92:93], v[92:93], 0, v[122:123]
	v_cvt_pk_bf16_f32 v96, v96, v97
	v_cvt_pk_bf16_f32 v97, v108, v109
	global_store_dwordx4 v[92:93], v[94:97], off sc1
	s_waitcnt lgkmcnt(1)
	v_pk_mul_f32 v[106:107], v[178:179], v[28:29] op_sel_hi:[1,0]
	v_pk_mul_f32 v[108:109], v[180:181], v[28:29] op_sel_hi:[1,0]
	v_pk_mul_f32 v[94:95], v[174:175], v[28:29] op_sel_hi:[1,0]
	v_pk_mul_f32 v[96:97], v[176:177], v[28:29] op_sel_hi:[1,0]
	v_pk_fma_f32 v[94:95], v[36:37], v[94:95], v[16:17]
	v_pk_fma_f32 v[96:97], v[34:35], v[96:97], v[14:15]
	v_pk_fma_f32 v[110:111], v[48:49], v[106:107], v[12:13]
	v_cvt_pk_bf16_f32 v106, v96, v97
	v_cvt_pk_bf16_f32 v107, v94, v95
	v_lshlrev_b64 v[94:95], 12, v[136:137]
	v_lshl_add_u64 v[94:95], s[6:7], 0, v[94:95]
	v_lshl_add_u64 v[112:113], v[94:95], 0, v[122:123]
	v_lshl_add_u64 v[96:97], v[112:113], 0, s[0:1]
	s_mov_b32 s0, 0x80000
	v_add_co_u32_e32 v94, vcc, s0, v112
	v_pk_fma_f32 v[108:109], v[46:47], v[108:109], v[10:11]
	s_nop 0
	v_addc_co_u32_e32 v95, vcc, 0, v113, vcc
	v_cvt_pk_bf16_f32 v108, v108, v109
	v_cvt_pk_bf16_f32 v109, v110, v111
	global_store_dwordx4 v[94:95], v[106:109], off sc1
	v_mov_b32_e32 v94, v29
	s_mov_b64 s[0:1], 0x90000
	v_pk_mul_f32 v[106:107], v[166:167], v[94:95] op_sel_hi:[1,0]
	v_pk_mul_f32 v[108:109], v[170:171], v[94:95] op_sel_hi:[1,0]
	v_pk_fma_f32 v[106:107], v[36:37], v[106:107], v[16:17]
	v_pk_fma_f32 v[108:109], v[34:35], v[108:109], v[14:15]
	v_pk_mul_f32 v[110:111], v[168:169], v[94:95] op_sel_hi:[1,0]
	v_pk_mul_f32 v[122:123], v[172:173], v[94:95] op_sel_hi:[1,0]
	v_cvt_pk_bf16_f32 v108, v108, v109
	v_cvt_pk_bf16_f32 v109, v106, v107
	v_lshl_add_u64 v[106:107], v[112:113], 0, s[0:1]
	s_mov_b32 s0, 0x90000
	v_pk_fma_f32 v[124:125], v[48:49], v[110:111], v[12:13]
	v_pk_fma_f32 v[110:111], v[46:47], v[122:123], v[10:11]
	v_add_co_u32_e32 v122, vcc, s0, v112
	v_cvt_pk_bf16_f32 v110, v110, v111
	v_cvt_pk_bf16_f32 v111, v124, v125
	s_mov_b64 s[0:1], 0xa0000
	s_nop 0
	v_addc_co_u32_e32 v123, vcc, 0, v113, vcc
	global_store_dwordx4 v[122:123], v[108:111], off sc1
	s_waitcnt lgkmcnt(0)
	v_pk_mul_f32 v[124:125], v[164:165], v[26:27] op_sel_hi:[1,0]
	v_pk_mul_f32 v[108:109], v[158:159], v[26:27] op_sel_hi:[1,0]
	v_pk_mul_f32 v[110:111], v[160:161], v[26:27] op_sel_hi:[1,0]
	v_pk_fma_f32 v[122:123], v[36:37], v[108:109], v[16:17]
	v_pk_fma_f32 v[108:109], v[34:35], v[110:111], v[14:15]
	v_pk_mul_f32 v[110:111], v[162:163], v[26:27] op_sel_hi:[1,0]
	v_cvt_pk_bf16_f32 v108, v108, v109
	v_cvt_pk_bf16_f32 v109, v122, v123
	v_lshl_add_u64 v[122:123], v[112:113], 0, s[0:1]
	s_mov_b32 s0, 0xa0000
	v_pk_fma_f32 v[126:127], v[48:49], v[110:111], v[12:13]
	v_pk_fma_f32 v[110:111], v[46:47], v[124:125], v[10:11]
	v_add_co_u32_e32 v124, vcc, s0, v112
	v_cvt_pk_bf16_f32 v110, v110, v111
	v_cvt_pk_bf16_f32 v111, v126, v127
	s_mov_b64 s[0:1], 0xb0000
	s_nop 0
	v_addc_co_u32_e32 v125, vcc, 0, v113, vcc
	global_store_dwordx4 v[124:125], v[108:111], off sc1
	s_nop 1
	v_mov_b32_e32 v108, v27
	v_pk_mul_f32 v[110:111], v[142:143], v[108:109] op_sel_hi:[1,0]
	v_pk_mul_f32 v[124:125], v[150:151], v[108:109] op_sel_hi:[1,0]
	v_pk_fma_f32 v[16:17], v[36:37], v[110:111], v[16:17]
	v_pk_fma_f32 v[14:15], v[34:35], v[124:125], v[14:15]
	v_pk_mul_f32 v[34:35], v[144:145], v[108:109] op_sel_hi:[1,0]
	v_pk_mul_f32 v[36:37], v[146:147], v[108:109] op_sel_hi:[1,0]
	v_pk_fma_f32 v[34:35], v[48:49], v[34:35], v[12:13]
	v_pk_fma_f32 v[12:13], v[46:47], v[36:37], v[10:11]
	v_cvt_pk_bf16_f32 v10, v14, v15
	v_lshl_add_u64 v[14:15], v[112:113], 0, s[0:1]
	s_mov_b32 s0, 0xb0000
	v_cvt_pk_bf16_f32 v11, v16, v17
	v_add_co_u32_e32 v16, vcc, s0, v112
	v_cvt_pk_bf16_f32 v12, v12, v13
	v_cvt_pk_bf16_f32 v13, v34, v35
	s_nop 1
	v_addc_co_u32_e32 v17, vcc, 0, v113, vcc
	global_store_dwordx4 v[16:17], v[10:13], off sc1
	s_nop 1
	v_pk_mul_f32 v[10:11], v[120:121], v[32:33] op_sel_hi:[1,0]
	v_pk_mul_f32 v[12:13], v[118:119], v[32:33] op_sel_hi:[1,0]
	v_pk_fma_f32 v[16:17], v[22:23], v[10:11], v[8:9]
	v_pk_fma_f32 v[10:11], v[24:25], v[12:13], v[6:7]
	v_pk_mul_f32 v[12:13], v[116:117], v[32:33] op_sel_hi:[1,0]
	v_pk_mul_f32 v[32:33], v[114:115], v[32:33] op_sel_hi:[1,0]
	v_pk_fma_f32 v[34:35], v[20:21], v[12:13], v[4:5]
	v_pk_fma_f32 v[12:13], v[18:19], v[32:33], v[2:3]
	v_cvt_pk_bf16_f32 v10, v10, v11
	v_cvt_pk_bf16_f32 v11, v16, v17
	v_pk_mul_f32 v[32:33], v[98:99], v[38:39] op_sel_hi:[1,0]
	v_cvt_pk_bf16_f32 v12, v12, v13
	v_cvt_pk_bf16_f32 v13, v34, v35
	global_store_dwordx4 v[40:41], v[10:13], off offset:256 sc1
	s_nop 1
	v_pk_mul_f32 v[10:11], v[104:105], v[38:39] op_sel_hi:[1,0]
	v_pk_mul_f32 v[12:13], v[102:103], v[38:39] op_sel_hi:[1,0]
	v_pk_fma_f32 v[16:17], v[22:23], v[10:11], v[8:9]
	v_pk_fma_f32 v[10:11], v[24:25], v[12:13], v[6:7]
	v_pk_mul_f32 v[12:13], v[100:101], v[38:39] op_sel_hi:[1,0]
	v_cvt_pk_bf16_f32 v10, v10, v11
	v_cvt_pk_bf16_f32 v11, v16, v17
	s_nop 0
	v_pk_fma_f32 v[34:35], v[20:21], v[12:13], v[4:5]
	v_pk_fma_f32 v[12:13], v[18:19], v[32:33], v[2:3]
	s_nop 0
	v_cvt_pk_bf16_f32 v12, v12, v13
	v_cvt_pk_bf16_f32 v13, v34, v35
	global_store_dwordx4 v[42:43], v[10:13], off offset:256 sc1
	s_nop 1
	v_pk_mul_f32 v[10:11], v[88:89], v[30:31] op_sel_hi:[1,0]
	v_pk_mul_f32 v[12:13], v[86:87], v[30:31] op_sel_hi:[1,0]
	v_pk_fma_f32 v[16:17], v[22:23], v[10:11], v[8:9]
	v_pk_fma_f32 v[10:11], v[24:25], v[12:13], v[6:7]
	v_pk_mul_f32 v[12:13], v[84:85], v[30:31] op_sel_hi:[1,0]
	v_pk_mul_f32 v[30:31], v[82:83], v[30:31] op_sel_hi:[1,0]
	v_pk_fma_f32 v[32:33], v[20:21], v[12:13], v[4:5]
	v_pk_fma_f32 v[12:13], v[18:19], v[30:31], v[2:3]
	v_cvt_pk_bf16_f32 v10, v10, v11
	v_cvt_pk_bf16_f32 v11, v16, v17
	v_pk_mul_f32 v[30:31], v[66:67], v[44:45] op_sel_hi:[1,0]
	v_cvt_pk_bf16_f32 v12, v12, v13
	v_cvt_pk_bf16_f32 v13, v32, v33
	global_store_dwordx4 v[90:91], v[10:13], off offset:256 sc1
	s_nop 1
	v_pk_mul_f32 v[10:11], v[72:73], v[44:45] op_sel_hi:[1,0]
	v_pk_mul_f32 v[12:13], v[70:71], v[44:45] op_sel_hi:[1,0]
	v_pk_fma_f32 v[16:17], v[22:23], v[10:11], v[8:9]
	v_pk_fma_f32 v[10:11], v[24:25], v[12:13], v[6:7]
	v_pk_mul_f32 v[12:13], v[68:69], v[44:45] op_sel_hi:[1,0]
	v_cvt_pk_bf16_f32 v10, v10, v11
	v_cvt_pk_bf16_f32 v11, v16, v17
	s_nop 0
	v_pk_fma_f32 v[32:33], v[20:21], v[12:13], v[4:5]
	v_pk_fma_f32 v[12:13], v[18:19], v[30:31], v[2:3]
	s_nop 0
	v_cvt_pk_bf16_f32 v12, v12, v13
	v_cvt_pk_bf16_f32 v13, v32, v33
	global_store_dwordx4 v[92:93], v[10:13], off offset:256 sc1
	s_nop 1
	v_pk_mul_f32 v[10:11], v[56:57], v[28:29] op_sel_hi:[1,0]
	v_pk_mul_f32 v[12:13], v[54:55], v[28:29] op_sel_hi:[1,0]
	v_pk_fma_f32 v[16:17], v[22:23], v[10:11], v[8:9]
	v_pk_fma_f32 v[10:11], v[24:25], v[12:13], v[6:7]
	v_pk_mul_f32 v[12:13], v[52:53], v[28:29] op_sel_hi:[1,0]
	v_pk_mul_f32 v[28:29], v[50:51], v[28:29] op_sel_hi:[1,0]
	v_pk_fma_f32 v[30:31], v[20:21], v[12:13], v[4:5]
	v_pk_fma_f32 v[12:13], v[18:19], v[28:29], v[2:3]
	v_cvt_pk_bf16_f32 v10, v10, v11
	v_cvt_pk_bf16_f32 v11, v16, v17
	v_pk_mul_f32 v[28:29], v[64:65], v[94:95] op_sel_hi:[1,0]
	v_cvt_pk_bf16_f32 v12, v12, v13
	v_cvt_pk_bf16_f32 v13, v30, v31
	global_store_dwordx4 v[96:97], v[10:13], off offset:256 sc1
	s_nop 1
	v_pk_mul_f32 v[10:11], v[58:59], v[94:95] op_sel_hi:[1,0]
	v_pk_mul_f32 v[12:13], v[62:63], v[94:95] op_sel_hi:[1,0]
	v_pk_fma_f32 v[16:17], v[22:23], v[10:11], v[8:9]
	v_pk_fma_f32 v[10:11], v[24:25], v[12:13], v[6:7]
	v_pk_mul_f32 v[12:13], v[60:61], v[94:95] op_sel_hi:[1,0]
	v_cvt_pk_bf16_f32 v10, v10, v11
	v_cvt_pk_bf16_f32 v11, v16, v17
	s_nop 0
	v_pk_fma_f32 v[30:31], v[20:21], v[12:13], v[4:5]
	v_pk_fma_f32 v[12:13], v[18:19], v[28:29], v[2:3]
	s_nop 0
	v_cvt_pk_bf16_f32 v12, v12, v13
	v_cvt_pk_bf16_f32 v13, v30, v31
	global_store_dwordx4 v[106:107], v[10:13], off offset:256 sc1
	s_nop 1
	v_pk_mul_f32 v[10:11], v[74:75], v[26:27] op_sel_hi:[1,0]
	v_pk_mul_f32 v[12:13], v[76:77], v[26:27] op_sel_hi:[1,0]
	v_pk_fma_f32 v[16:17], v[22:23], v[10:11], v[8:9]
	v_pk_fma_f32 v[10:11], v[24:25], v[12:13], v[6:7]
	v_pk_mul_f32 v[12:13], v[78:79], v[26:27] op_sel_hi:[1,0]
	v_pk_mul_f32 v[26:27], v[80:81], v[26:27] op_sel_hi:[1,0]
	v_pk_fma_f32 v[28:29], v[20:21], v[12:13], v[4:5]
	v_pk_fma_f32 v[12:13], v[18:19], v[26:27], v[2:3]
	v_cvt_pk_bf16_f32 v10, v10, v11
	v_cvt_pk_bf16_f32 v11, v16, v17
	s_nop 0
	v_cvt_pk_bf16_f32 v12, v12, v13
	v_cvt_pk_bf16_f32 v13, v28, v29
	global_store_dwordx4 v[122:123], v[10:13], off offset:256 sc1
	s_nop 1
	v_pk_mul_f32 v[10:11], v[130:131], v[108:109] op_sel_hi:[1,0]
	v_pk_mul_f32 v[12:13], v[138:139], v[108:109] op_sel_hi:[1,0]
	v_pk_fma_f32 v[8:9], v[22:23], v[10:11], v[8:9]
	v_pk_fma_f32 v[6:7], v[24:25], v[12:13], v[6:7]
	v_pk_mul_f32 v[10:11], v[132:133], v[108:109] op_sel_hi:[1,0]
	v_pk_mul_f32 v[12:13], v[134:135], v[108:109] op_sel_hi:[1,0]
	v_pk_fma_f32 v[10:11], v[20:21], v[10:11], v[4:5]
	v_pk_fma_f32 v[4:5], v[18:19], v[12:13], v[2:3]
	v_cvt_pk_bf16_f32 v2, v6, v7
	v_cvt_pk_bf16_f32 v3, v8, v9
	s_nop 0
	v_cvt_pk_bf16_f32 v4, v4, v5
	v_cvt_pk_bf16_f32 v5, v10, v11
	global_store_dwordx4 v[14:15], v[2:5], off offset:256 sc1

.LBB0_1063:
	v_pk_mul_f32 v[148:149], v[126:127], s[60:61] op_sel_hi:[1,0]
	v_pk_mul_f32 v[122:123], v[126:127], v[122:123]
	v_pk_mul_f32 v[126:127], v[128:129], s[60:61] op_sel_hi:[1,0]
	v_exp_f32_e32 v148, v148
	v_exp_f32_e32 v149, v149
	v_exp_f32_e32 v126, v126
	v_exp_f32_e32 v127, v127
	v_pk_mul_f32 v[124:125], v[128:129], v[124:125]
	v_pk_add_f32 v[148:149], v[148:149], 1.0 op_sel_hi:[1,0]
	v_pk_mul_f32 v[120:121], v[116:117], v[120:121]
	v_pk_add_f32 v[126:127], v[126:127], 1.0 op_sel_hi:[1,0]
	v_rcp_f32_e32 v148, v148
	v_rcp_f32_e32 v149, v149
	v_rcp_f32_e32 v126, v126
	v_rcp_f32_e32 v127, v127
	v_pk_mul_f32 v[106:107], v[110:111], v[106:107]
	v_pk_mul_f32 v[122:123], v[148:149], v[122:123]
	v_lshl_or_b32 v138, s74, 7, v143
	v_pk_mul_f32 v[124:125], v[126:127], v[124:125]
	v_cvt_pk_bf16_f32 v122, v122, v123
	v_lshl_add_u32 v145, s96, 8, v141
	v_cvt_pk_bf16_f32 v123, v124, v125
	v_pk_mul_f32 v[124:125], v[114:115], s[60:61] op_sel_hi:[1,0]
	v_pk_mul_f32 v[114:115], v[114:115], v[118:119]
	v_exp_f32_e32 v124, v124
	v_exp_f32_e32 v125, v125
	v_ashrrev_i32_e32 v139, 31, v138
	v_mov_b64_e32 v[136:137], s[18:19]
	s_movk_i32 s2, 0x2c00
	v_pk_add_f32 v[124:125], v[124:125], 1.0 op_sel_hi:[1,0]
	v_mad_i64_i32 v[146:147], s[0:1], v145, s2, v[136:137]
	v_rcp_f32_e32 v124, v124
	v_rcp_f32_e32 v125, v125
	v_lshlrev_b64 v[138:139], 1, v[138:139]
	v_pk_mul_f32 v[108:109], v[112:113], v[108:109]
	v_lshl_add_u64 v[146:147], v[146:147], 0, v[138:139]
	v_pk_mul_f32 v[114:115], v[124:125], v[114:115]
	v_pk_mul_f32 v[104:105], v[100:101], v[104:105]
	v_cvt_pk_bf16_f32 v124, v114, v115
	v_pk_mul_f32 v[114:115], v[116:117], s[60:61] op_sel_hi:[1,0]
	v_pk_mul_f32 v[116:117], v[110:111], s[60:61] op_sel_hi:[1,0]
	v_pk_mul_f32 v[110:111], v[112:113], s[60:61] op_sel_hi:[1,0]
	v_exp_f32_e32 v116, v116
	v_exp_f32_e32 v117, v117
	v_exp_f32_e32 v110, v110
	v_exp_f32_e32 v111, v111
	v_exp_f32_e32 v114, v114
	v_exp_f32_e32 v115, v115
	v_pk_add_f32 v[116:117], v[116:117], 1.0 op_sel_hi:[1,0]
	v_pk_add_f32 v[110:111], v[110:111], 1.0 op_sel_hi:[1,0]
	v_rcp_f32_e32 v116, v116
	v_pk_add_f32 v[114:115], v[114:115], 1.0 op_sel_hi:[1,0]
	v_rcp_f32_e32 v117, v117
	v_rcp_f32_e32 v110, v110
	v_rcp_f32_e32 v111, v111
	v_rcp_f32_e32 v114, v114
	v_rcp_f32_e32 v115, v115
	v_pk_mul_f32 v[106:107], v[116:117], v[106:107]
	v_pk_mul_f32 v[108:109], v[110:111], v[108:109]
	v_pk_mul_f32 v[90:91], v[94:95], v[90:91]
	v_pk_mul_f32 v[114:115], v[114:115], v[120:121]
	v_pk_mul_f32 v[92:93], v[96:97], v[92:93]
	v_cvt_pk_bf16_f32 v125, v114, v115
	global_store_dwordx4 v[146:147], v[122:125], off sc1
	v_cvt_pk_bf16_f32 v106, v106, v107
	v_cvt_pk_bf16_f32 v107, v108, v109
	v_pk_mul_f32 v[108:109], v[98:99], s[60:61] op_sel_hi:[1,0]
	v_pk_mul_f32 v[98:99], v[98:99], v[102:103]
	v_exp_f32_e32 v108, v108
	v_exp_f32_e32 v109, v109
	v_or_b32_e32 v114, 16, v145
	v_mad_i64_i32 v[114:115], s[0:1], v114, s2, v[136:137]
	v_pk_add_f32 v[108:109], v[108:109], 1.0 op_sel_hi:[1,0]
	v_lshl_add_u64 v[114:115], v[114:115], 0, v[138:139]
	v_rcp_f32_e32 v108, v108
	v_rcp_f32_e32 v109, v109
	v_pk_mul_f32 v[88:89], v[84:85], v[88:89]
	v_pk_mul_f32 v[74:75], v[78:79], v[74:75]
	v_pk_mul_f32 v[76:77], v[80:81], v[76:77]
	v_pk_mul_f32 v[98:99], v[108:109], v[98:99]
	v_pk_mul_f32 v[72:73], v[68:69], v[72:73]
	v_cvt_pk_bf16_f32 v108, v98, v99
	v_pk_mul_f32 v[98:99], v[100:101], s[60:61] op_sel_hi:[1,0]
	v_pk_mul_f32 v[100:101], v[94:95], s[60:61] op_sel_hi:[1,0]
	v_pk_mul_f32 v[94:95], v[96:97], s[60:61] op_sel_hi:[1,0]
	v_exp_f32_e32 v100, v100
	v_exp_f32_e32 v101, v101
	v_exp_f32_e32 v94, v94
	v_exp_f32_e32 v95, v95
	v_exp_f32_e32 v98, v98
	v_exp_f32_e32 v99, v99
	v_pk_add_f32 v[100:101], v[100:101], 1.0 op_sel_hi:[1,0]
	v_pk_add_f32 v[94:95], v[94:95], 1.0 op_sel_hi:[1,0]
	v_rcp_f32_e32 v100, v100
	v_pk_add_f32 v[98:99], v[98:99], 1.0 op_sel_hi:[1,0]
	v_rcp_f32_e32 v101, v101
	v_rcp_f32_e32 v94, v94
	v_rcp_f32_e32 v95, v95
	v_rcp_f32_e32 v98, v98
	v_rcp_f32_e32 v99, v99
	v_pk_mul_f32 v[90:91], v[100:101], v[90:91]
	v_pk_mul_f32 v[92:93], v[94:95], v[92:93]
	v_pk_mul_f32 v[58:59], v[62:63], v[58:59]
	v_pk_mul_f32 v[98:99], v[98:99], v[104:105]
	v_pk_mul_f32 v[60:61], v[64:65], v[60:61]
	v_cvt_pk_bf16_f32 v109, v98, v99
	global_store_dwordx4 v[114:115], v[106:109], off sc1
	v_cvt_pk_bf16_f32 v90, v90, v91
	v_cvt_pk_bf16_f32 v91, v92, v93
	v_pk_mul_f32 v[92:93], v[82:83], s[60:61] op_sel_hi:[1,0]
	v_pk_mul_f32 v[82:83], v[82:83], v[86:87]
	v_exp_f32_e32 v92, v92
	v_exp_f32_e32 v93, v93
	v_or_b32_e32 v98, 32, v145
	v_mad_i64_i32 v[98:99], s[0:1], v98, s2, v[136:137]
	v_pk_add_f32 v[92:93], v[92:93], 1.0 op_sel_hi:[1,0]
	v_lshl_add_u64 v[98:99], v[98:99], 0, v[138:139]
	v_rcp_f32_e32 v92, v92
	v_rcp_f32_e32 v93, v93
	v_pk_mul_f32 v[56:57], v[52:53], v[56:57]
	v_pk_mul_f32 v[42:43], v[46:47], v[42:43]
	v_pk_mul_f32 v[44:45], v[48:49], v[44:45]
	v_pk_mul_f32 v[82:83], v[92:93], v[82:83]
	v_pk_mul_f32 v[40:41], v[36:37], v[40:41]
	v_cvt_pk_bf16_f32 v92, v82, v83
	v_pk_mul_f32 v[82:83], v[84:85], s[60:61] op_sel_hi:[1,0]
	v_pk_mul_f32 v[84:85], v[78:79], s[60:61] op_sel_hi:[1,0]
	v_pk_mul_f32 v[78:79], v[80:81], s[60:61] op_sel_hi:[1,0]
	v_exp_f32_e32 v84, v84
	v_exp_f32_e32 v85, v85
	v_exp_f32_e32 v78, v78
	v_exp_f32_e32 v79, v79
	v_exp_f32_e32 v82, v82
	v_exp_f32_e32 v83, v83
	v_pk_add_f32 v[84:85], v[84:85], 1.0 op_sel_hi:[1,0]
	v_pk_add_f32 v[78:79], v[78:79], 1.0 op_sel_hi:[1,0]
	v_rcp_f32_e32 v84, v84
	v_pk_add_f32 v[82:83], v[82:83], 1.0 op_sel_hi:[1,0]
	v_rcp_f32_e32 v85, v85
	v_rcp_f32_e32 v78, v78
	v_rcp_f32_e32 v79, v79
	v_rcp_f32_e32 v82, v82
	v_rcp_f32_e32 v83, v83
	v_pk_mul_f32 v[74:75], v[84:85], v[74:75]
	v_pk_mul_f32 v[76:77], v[78:79], v[76:77]
	v_pk_mul_f32 v[26:27], v[30:31], v[26:27]
	v_pk_mul_f32 v[82:83], v[82:83], v[88:89]
	v_pk_mul_f32 v[28:29], v[32:33], v[28:29]
	v_cvt_pk_bf16_f32 v93, v82, v83
	global_store_dwordx4 v[98:99], v[90:93], off sc1
	v_cvt_pk_bf16_f32 v74, v74, v75
	v_cvt_pk_bf16_f32 v75, v76, v77
	v_pk_mul_f32 v[76:77], v[66:67], s[60:61] op_sel_hi:[1,0]
	v_pk_mul_f32 v[66:67], v[66:67], v[70:71]
	v_exp_f32_e32 v76, v76
	v_exp_f32_e32 v77, v77
	v_or_b32_e32 v82, 48, v145
	v_mad_i64_i32 v[82:83], s[0:1], v82, s2, v[136:137]
	v_pk_add_f32 v[76:77], v[76:77], 1.0 op_sel_hi:[1,0]
	v_lshl_add_u64 v[82:83], v[82:83], 0, v[138:139]
	v_rcp_f32_e32 v76, v76
	v_rcp_f32_e32 v77, v77
	v_pk_mul_f32 v[24:25], v[20:21], v[24:25]
	v_pk_mul_f32 v[10:11], v[14:15], v[10:11]
	v_pk_mul_f32 v[12:13], v[16:17], v[12:13]
	v_pk_mul_f32 v[66:67], v[76:77], v[66:67]
	v_pk_mul_f32 v[2:3], v[6:7], v[2:3]
	v_cvt_pk_bf16_f32 v76, v66, v67
	v_pk_mul_f32 v[66:67], v[68:69], s[60:61] op_sel_hi:[1,0]
	v_pk_mul_f32 v[68:69], v[62:63], s[60:61] op_sel_hi:[1,0]
	v_pk_mul_f32 v[62:63], v[64:65], s[60:61] op_sel_hi:[1,0]
	v_exp_f32_e32 v68, v68
	v_exp_f32_e32 v69, v69
	v_exp_f32_e32 v62, v62
	v_exp_f32_e32 v63, v63
	v_exp_f32_e32 v66, v66
	v_exp_f32_e32 v67, v67
	v_pk_add_f32 v[68:69], v[68:69], 1.0 op_sel_hi:[1,0]
	v_pk_add_f32 v[62:63], v[62:63], 1.0 op_sel_hi:[1,0]
	v_rcp_f32_e32 v68, v68
	v_pk_add_f32 v[66:67], v[66:67], 1.0 op_sel_hi:[1,0]
	v_rcp_f32_e32 v69, v69
	v_rcp_f32_e32 v62, v62
	v_rcp_f32_e32 v63, v63
	v_rcp_f32_e32 v66, v66
	v_rcp_f32_e32 v67, v67
	v_pk_mul_f32 v[58:59], v[68:69], v[58:59]
	v_pk_mul_f32 v[60:61], v[62:63], v[60:61]
	v_pk_mul_f32 v[4:5], v[8:9], v[4:5]
	v_pk_mul_f32 v[66:67], v[66:67], v[72:73]
	s_andn2_b64 vcc, exec, s[44:45]
	v_cvt_pk_bf16_f32 v77, v66, v67
	global_store_dwordx4 v[82:83], v[74:77], off sc1
	v_cvt_pk_bf16_f32 v58, v58, v59
	v_cvt_pk_bf16_f32 v59, v60, v61
	v_pk_mul_f32 v[60:61], v[50:51], s[60:61] op_sel_hi:[1,0]
	v_pk_mul_f32 v[50:51], v[50:51], v[54:55]
	v_exp_f32_e32 v60, v60
	v_exp_f32_e32 v61, v61
	v_add_u32_e32 v66, 0x80, v145
	v_mad_i64_i32 v[66:67], s[0:1], v66, s2, v[136:137]
	v_pk_add_f32 v[60:61], v[60:61], 1.0 op_sel_hi:[1,0]
	v_lshl_add_u64 v[66:67], v[66:67], 0, v[138:139]
	v_rcp_f32_e32 v60, v60
	v_rcp_f32_e32 v61, v61
	s_nop 0
	v_pk_mul_f32 v[50:51], v[60:61], v[50:51]
	s_nop 0
	v_cvt_pk_bf16_f32 v60, v50, v51
	v_pk_mul_f32 v[50:51], v[52:53], s[60:61] op_sel_hi:[1,0]
	v_pk_mul_f32 v[52:53], v[46:47], s[60:61] op_sel_hi:[1,0]
	v_pk_mul_f32 v[46:47], v[48:49], s[60:61] op_sel_hi:[1,0]
	v_exp_f32_e32 v52, v52
	v_exp_f32_e32 v53, v53
	v_exp_f32_e32 v46, v46
	v_exp_f32_e32 v47, v47
	v_exp_f32_e32 v50, v50
	v_exp_f32_e32 v51, v51
	v_pk_add_f32 v[52:53], v[52:53], 1.0 op_sel_hi:[1,0]
	v_pk_add_f32 v[46:47], v[46:47], 1.0 op_sel_hi:[1,0]
	v_rcp_f32_e32 v52, v52
	v_pk_add_f32 v[50:51], v[50:51], 1.0 op_sel_hi:[1,0]
	v_rcp_f32_e32 v53, v53
	v_rcp_f32_e32 v46, v46
	v_rcp_f32_e32 v47, v47
	v_rcp_f32_e32 v50, v50
	v_rcp_f32_e32 v51, v51
	v_pk_mul_f32 v[42:43], v[52:53], v[42:43]
	v_pk_mul_f32 v[44:45], v[46:47], v[44:45]
	v_pk_mul_f32 v[50:51], v[50:51], v[56:57]
	s_nop 0
	v_cvt_pk_bf16_f32 v61, v50, v51
	global_store_dwordx4 v[66:67], v[58:61], off sc1
	v_cvt_pk_bf16_f32 v42, v42, v43
	v_cvt_pk_bf16_f32 v43, v44, v45
	v_pk_mul_f32 v[44:45], v[34:35], s[60:61] op_sel_hi:[1,0]
	v_pk_mul_f32 v[34:35], v[34:35], v[38:39]
	v_exp_f32_e32 v44, v44
	v_exp_f32_e32 v45, v45
	v_add_u32_e32 v50, 0x90, v145
	v_mad_i64_i32 v[50:51], s[0:1], v50, s2, v[136:137]
	v_pk_add_f32 v[44:45], v[44:45], 1.0 op_sel_hi:[1,0]
	v_lshl_add_u64 v[50:51], v[50:51], 0, v[138:139]
	v_rcp_f32_e32 v44, v44
	v_rcp_f32_e32 v45, v45
	s_nop 0
	v_pk_mul_f32 v[34:35], v[44:45], v[34:35]
	s_nop 0
	v_cvt_pk_bf16_f32 v44, v34, v35
	v_pk_mul_f32 v[34:35], v[36:37], s[60:61] op_sel_hi:[1,0]
	v_pk_mul_f32 v[36:37], v[30:31], s[60:61] op_sel_hi:[1,0]
	v_pk_mul_f32 v[30:31], v[32:33], s[60:61] op_sel_hi:[1,0]
	v_exp_f32_e32 v36, v36
	v_exp_f32_e32 v37, v37
	v_exp_f32_e32 v30, v30
	v_exp_f32_e32 v31, v31
	v_exp_f32_e32 v34, v34
	v_exp_f32_e32 v35, v35
	v_pk_add_f32 v[36:37], v[36:37], 1.0 op_sel_hi:[1,0]
	v_pk_add_f32 v[30:31], v[30:31], 1.0 op_sel_hi:[1,0]
	v_rcp_f32_e32 v36, v36
	v_pk_add_f32 v[34:35], v[34:35], 1.0 op_sel_hi:[1,0]
	v_rcp_f32_e32 v37, v37
	v_rcp_f32_e32 v30, v30
	v_rcp_f32_e32 v31, v31
	v_rcp_f32_e32 v34, v34
	v_rcp_f32_e32 v35, v35
	v_pk_mul_f32 v[26:27], v[36:37], v[26:27]
	v_pk_mul_f32 v[28:29], v[30:31], v[28:29]
	v_pk_mul_f32 v[34:35], v[34:35], v[40:41]
	s_nop 0
	v_cvt_pk_bf16_f32 v45, v34, v35
	global_store_dwordx4 v[50:51], v[42:45], off sc1
	v_cvt_pk_bf16_f32 v26, v26, v27
	v_cvt_pk_bf16_f32 v27, v28, v29
	v_pk_mul_f32 v[28:29], v[18:19], s[60:61] op_sel_hi:[1,0]
	v_pk_mul_f32 v[18:19], v[18:19], v[22:23]
	v_exp_f32_e32 v28, v28
	v_exp_f32_e32 v29, v29
	v_add_u32_e32 v34, 0xa0, v145
	v_mad_i64_i32 v[34:35], s[0:1], v34, s2, v[136:137]
	v_pk_add_f32 v[28:29], v[28:29], 1.0 op_sel_hi:[1,0]
	v_lshl_add_u64 v[34:35], v[34:35], 0, v[138:139]
	v_rcp_f32_e32 v28, v28
	v_rcp_f32_e32 v29, v29
	s_nop 0
	v_pk_mul_f32 v[18:19], v[28:29], v[18:19]
	s_nop 0
	v_cvt_pk_bf16_f32 v28, v18, v19
	v_pk_mul_f32 v[18:19], v[20:21], s[60:61] op_sel_hi:[1,0]
	v_pk_mul_f32 v[20:21], v[14:15], s[60:61] op_sel_hi:[1,0]
	v_pk_mul_f32 v[14:15], v[16:17], s[60:61] op_sel_hi:[1,0]
	v_exp_f32_e32 v20, v20
	v_exp_f32_e32 v21, v21
	v_exp_f32_e32 v14, v14
	v_exp_f32_e32 v15, v15
	v_exp_f32_e32 v18, v18
	v_exp_f32_e32 v19, v19
	v_pk_add_f32 v[20:21], v[20:21], 1.0 op_sel_hi:[1,0]
	v_pk_add_f32 v[14:15], v[14:15], 1.0 op_sel_hi:[1,0]
	v_rcp_f32_e32 v20, v20
	v_pk_add_f32 v[18:19], v[18:19], 1.0 op_sel_hi:[1,0]
	v_rcp_f32_e32 v21, v21
	v_rcp_f32_e32 v14, v14
	v_rcp_f32_e32 v15, v15
	v_rcp_f32_e32 v18, v18
	v_rcp_f32_e32 v19, v19
	v_pk_mul_f32 v[10:11], v[20:21], v[10:11]
	v_pk_mul_f32 v[12:13], v[14:15], v[12:13]
	v_pk_mul_f32 v[18:19], v[18:19], v[24:25]
	s_nop 0
	v_cvt_pk_bf16_f32 v29, v18, v19
	global_store_dwordx4 v[34:35], v[26:29], off sc1
	v_cvt_pk_bf16_f32 v10, v10, v11
	v_cvt_pk_bf16_f32 v11, v12, v13
	v_pk_mul_f32 v[12:13], v[6:7], s[60:61] op_sel_hi:[1,0]
	v_add_u32_e32 v18, 0xb0, v145
	v_exp_f32_e32 v12, v12
	v_exp_f32_e32 v13, v13
	v_mad_i64_i32 v[18:19], s[0:1], v18, s2, v[136:137]
	v_lshl_add_u64 v[18:19], v[18:19], 0, v[138:139]
	v_pk_add_f32 v[12:13], v[12:13], 1.0 op_sel_hi:[1,0]
	s_mov_b64 s[0:1], -1
	v_rcp_f32_e32 v12, v12
	v_rcp_f32_e32 v13, v13
	s_nop 0
	v_pk_mul_f32 v[2:3], v[12:13], v[2:3]
	s_nop 0
	v_cvt_pk_bf16_f32 v12, v2, v3
	v_pk_mul_f32 v[2:3], v[8:9], s[60:61] op_sel_hi:[1,0]
	s_nop 0
	v_exp_f32_e32 v2, v2
	v_exp_f32_e32 v3, v3
	s_nop 0
	v_pk_add_f32 v[2:3], v[2:3], 1.0 op_sel_hi:[1,0]
	s_nop 0
	v_rcp_f32_e32 v2, v2
	v_rcp_f32_e32 v3, v3
	s_nop 0
	v_pk_mul_f32 v[2:3], v[2:3], v[4:5]
	s_nop 0
	v_cvt_pk_bf16_f32 v13, v2, v3
	global_store_dwordx4 v[18:19], v[10:13], off sc1
	s_cbranch_vccnz .LBB0_1042
	s_andn2_b64 vcc, exec, s[16:17]
	s_cbranch_vccnz .LBB0_1041
	s_barrier
	s_branch .LBB0_1041

.LBB0_1137:
	s_ashr_i32 s69, s68, 31
	v_add_u32_e32 v126, s28, v139
	s_lshl_b64 s[0:1], s[68:69], 2
	s_add_u32 s0, s2, s0
	v_add_u32_e32 v106, 16, v126
	v_add_u32_e32 v114, 32, v126
	s_addc_u32 s1, s3, s1
	v_ashrrev_i32_e32 v98, 31, v126
	v_ashrrev_i32_e32 v107, 31, v106
	v_ashrrev_i32_e32 v115, 31, v114
	v_add_u32_e32 v124, 48, v126
	v_lshl_add_u64 v[122:123], s[0:1], 0, v[202:203]
	v_mul_lo_u32 v100, s62, v98
	v_mul_lo_u32 v101, s63, v126
	v_mad_u64_u32 v[98:99], s[0:1], s62, v126, 0
	v_mul_lo_u32 v108, s62, v107
	v_mul_lo_u32 v109, s63, v106
	v_mad_u64_u32 v[106:107], s[0:1], s62, v106, 0
	v_mul_lo_u32 v116, s62, v115
	v_mul_lo_u32 v117, s63, v114
	v_mad_u64_u32 v[114:115], s[0:1], s62, v114, 0
	v_ashrrev_i32_e32 v125, 31, v124
	v_add3_u32 v99, v99, v100, v101
	v_add_u32_e32 v100, 8, v126
	v_add3_u32 v107, v107, v108, v109
	v_add_u32_e32 v108, 24, v126
	v_add3_u32 v115, v115, v116, v117
	v_add_u32_e32 v116, 40, v126
	v_mul_lo_u32 v127, s62, v125
	v_mul_lo_u32 v128, s63, v124
	v_mad_u64_u32 v[124:125], s[0:1], s62, v124, 0
	v_add_u32_e32 v126, 56, v126
	v_ashrrev_i32_e32 v101, 31, v100
	v_ashrrev_i32_e32 v109, 31, v108
	v_ashrrev_i32_e32 v117, 31, v116
	v_add3_u32 v125, v125, v127, v128
	v_ashrrev_i32_e32 v127, 31, v126
	v_mul_lo_u32 v102, s62, v101
	v_mul_lo_u32 v103, s63, v100
	v_mad_u64_u32 v[100:101], s[0:1], s62, v100, 0
	v_mul_lo_u32 v110, s62, v109
	v_mul_lo_u32 v111, s63, v108
	v_mad_u64_u32 v[108:109], s[0:1], s62, v108, 0
	v_mul_lo_u32 v118, s62, v117
	v_mul_lo_u32 v119, s63, v116
	v_mad_u64_u32 v[116:117], s[0:1], s62, v116, 0
	v_mul_lo_u32 v128, s62, v127
	v_mul_lo_u32 v129, s63, v126
	v_mad_u64_u32 v[126:127], s[0:1], s62, v126, 0
	v_add3_u32 v101, v101, v102, v103
	v_add3_u32 v109, v109, v110, v111
	v_add3_u32 v117, v117, v118, v119
	v_add3_u32 v127, v127, v128, v129
	v_lshl_add_u64 v[98:99], v[98:99], 2, v[122:123]
	v_lshl_add_u64 v[100:101], v[100:101], 2, v[122:123]
	v_lshl_add_u64 v[106:107], v[106:107], 2, v[122:123]
	v_lshl_add_u64 v[108:109], v[108:109], 2, v[122:123]
	v_lshl_add_u64 v[114:115], v[114:115], 2, v[122:123]
	v_lshl_add_u64 v[116:117], v[116:117], 2, v[122:123]
	v_lshl_add_u64 v[124:125], v[124:125], 2, v[122:123]
	v_lshl_add_u64 v[122:123], v[126:127], 2, v[122:123]
	global_load_dwordx4 v[102:105], v[98:99], off nt
	s_nop 0
	global_load_dwordx4 v[98:101], v[100:101], off nt
	s_nop 0
	global_load_dwordx4 v[110:113], v[106:107], off nt
	s_nop 0
	global_load_dwordx4 v[106:109], v[108:109], off nt
	s_nop 0
	global_load_dwordx4 v[118:121], v[114:115], off nt
	s_nop 0
	global_load_dwordx4 v[114:117], v[116:117], off nt
	s_nop 0
	global_load_dwordx4 v[126:129], v[124:125], off nt
	s_nop 0
	global_load_dwordx4 v[122:125], v[122:123], off nt
	s_waitcnt vmcnt(31)
	ds_write2_b32 v145, v6, v7 offset1:1
	ds_write2_b32 v145, v8, v9 offset0:2 offset1:3
	v_add_u32_e32 v6, 0x420, v145
	s_waitcnt vmcnt(30)
	ds_write2_b32 v6, v2, v3 offset1:1
	v_add_u32_e32 v2, 0x428, v145
	ds_write2_b32 v2, v4, v5 offset1:1
	v_add_u32_e32 v3, 0x840, v145
	v_add_u32_e32 v5, 0xc60, v145
	v_add_u32_e32 v7, 0xc68, v145
	s_waitcnt vmcnt(29)
	ds_write2_b32 v3, v14, v15 offset1:1
	v_add_u32_e32 v4, 0x848, v145
	s_waitcnt vmcnt(28)
	ds_write2_b32 v5, v10, v11 offset1:1
	ds_write2_b32 v7, v12, v13 offset1:1
	v_add_u32_e32 v8, 0x1080, v145
	v_add_u32_e32 v9, 0x1088, v145
	v_add_u32_e32 v10, 0x14a0, v145
	v_add_u32_e32 v11, 0x14a8, v145
	v_add_u32_e32 v12, 0x18c0, v145
	v_add_u32_e32 v13, 0x18c8, v145
	v_add_u32_e32 v14, 0x1ce0, v145
	v_add_u32_e32 v15, 0x1ce8, v145
	ds_write2_b32 v4, v16, v17 offset1:1
	s_waitcnt vmcnt(27)
	ds_write2_b32 v8, v22, v23 offset1:1
	ds_write2_b32 v9, v24, v25 offset1:1
	s_waitcnt vmcnt(26)
	ds_write2_b32 v10, v18, v19 offset1:1
	ds_write2_b32 v11, v20, v21 offset1:1
	s_waitcnt vmcnt(25)
	ds_write2_b32 v12, v30, v31 offset1:1
	ds_write2_b32 v13, v32, v33 offset1:1
	s_waitcnt vmcnt(24)
	ds_write2_b32 v14, v26, v27 offset1:1
	ds_write2_b32 v15, v28, v29 offset1:1
	s_waitcnt lgkmcnt(0)
	ds_read2_b32 v[20:21], v144 offset1:8
	ds_read2_b32 v[24:25], v144 offset0:33 offset1:41
	ds_read2_b32 v[26:27], v144 offset0:66 offset1:74
	ds_read2_b32 v[28:29], v144 offset0:99 offset1:107
	ds_read2_b32 v[30:31], v144 offset0:132 offset1:140
	s_waitcnt lgkmcnt(4)
	v_bfe_u32 v16, v20, 16, 1
	v_add3_u32 v16, v20, v16, s57
	s_waitcnt lgkmcnt(3)
	v_bfe_u32 v17, v24, 16, 1
	v_lshrrev_b32_e32 v16, 16, v16
	v_add3_u32 v17, v24, v17, s57
	ds_read2_b32 v[32:33], v144 offset0:165 offset1:173
	v_and_or_b32 v16, v17, s53, v16
	s_waitcnt lgkmcnt(3)
	v_bfe_u32 v17, v26, 16, 1
	v_add3_u32 v17, v26, v17, s57
	s_waitcnt lgkmcnt(2)
	v_bfe_u32 v18, v28, 16, 1
	ds_read2_b32 v[146:147], v144 offset0:198 offset1:206
	v_lshrrev_b32_e32 v17, 16, v17
	v_add3_u32 v18, v28, v18, s57
	ds_read2_b32 v[148:149], v144 offset0:231 offset1:239
	v_and_or_b32 v17, v18, s53, v17
	s_waitcnt lgkmcnt(3)
	v_bfe_u32 v18, v30, 16, 1
	v_add3_u32 v18, v30, v18, s57
	s_waitcnt lgkmcnt(2)
	v_bfe_u32 v19, v32, 16, 1
	v_lshrrev_b32_e32 v18, 16, v18
	v_add3_u32 v19, v32, v19, s57
	v_and_or_b32 v18, v19, s53, v18
	s_waitcnt lgkmcnt(1)
	v_bfe_u32 v19, v146, 16, 1
	s_ashr_i32 s7, s6, 31
	v_add3_u32 v19, v146, v19, s57
	s_waitcnt lgkmcnt(0)
	v_bfe_u32 v20, v148, 16, 1
	s_lshl_b64 s[0:1], s[6:7], 1
	v_lshrrev_b32_e32 v19, 16, v19
	v_add3_u32 v20, v148, v20, s57
	s_add_u32 s0, s20, s0
	v_and_or_b32 v19, v20, s53, v19
	v_add_u32_e32 v20, s48, v139
	s_addc_u32 s1, s21, s1
	v_mov_b32_e32 v135, v203
	v_ashrrev_i32_e32 v24, 31, v20
	v_lshl_add_u64 v[22:23], s[0:1], 0, v[134:135]
	v_mul_lo_u32 v24, s16, v24
	v_mul_lo_u32 v26, s17, v20
	v_mad_u64_u32 v[150:151], s[0:1], s16, v20, 0
	v_add3_u32 v151, v151, v24, v26
	v_lshl_add_u64 v[150:151], v[150:151], 1, v[22:23]
	global_store_dwordx4 v[150:151], v[16:19], off sc1
	v_bfe_u32 v20, v149, 16, 1
	v_add3_u32 v20, v149, v20, s57
	v_bfe_u32 v16, v21, 16, 1
	v_add3_u32 v16, v21, v16, s57
	v_bfe_u32 v17, v25, 16, 1
	v_lshrrev_b32_e32 v16, 16, v16
	v_add3_u32 v17, v25, v17, s57
	v_and_or_b32 v16, v17, s53, v16
	v_bfe_u32 v17, v27, 16, 1
	v_add3_u32 v17, v27, v17, s57
	v_bfe_u32 v18, v29, 16, 1
	v_lshrrev_b32_e32 v17, 16, v17
	v_add3_u32 v18, v29, v18, s57
	v_and_or_b32 v17, v18, s53, v17
	v_bfe_u32 v18, v31, 16, 1
	v_add3_u32 v18, v31, v18, s57
	v_bfe_u32 v19, v33, 16, 1
	v_lshrrev_b32_e32 v18, 16, v18
	v_add3_u32 v19, v33, v19, s57
	v_and_or_b32 v18, v19, s53, v18
	v_bfe_u32 v19, v147, 16, 1
	v_add3_u32 v19, v147, v19, s57
	v_lshrrev_b32_e32 v19, 16, v19
	v_and_or_b32 v19, v20, s53, v19
	v_add_u32_e32 v20, s48, v141
	v_ashrrev_i32_e32 v21, 31, v20
	v_mul_lo_u32 v26, s16, v21
	v_mul_lo_u32 v27, s17, v20
	v_mad_u64_u32 v[20:21], s[0:1], s16, v20, 0
	v_add3_u32 v21, v21, v26, v27
	ds_read2_b32 v[24:25], v144 offset0:16 offset1:24
	v_lshl_add_u64 v[20:21], v[20:21], 1, v[22:23]
	global_store_dwordx4 v[20:21], v[16:19], off sc1
	ds_read2_b32 v[20:21], v144 offset0:49 offset1:57
	ds_read2_b32 v[26:27], v144 offset0:82 offset1:90
	ds_read2_b32 v[28:29], v144 offset0:115 offset1:123
	s_waitcnt lgkmcnt(3)
	v_bfe_u32 v16, v24, 16, 1
	v_add3_u32 v16, v24, v16, s57
	s_waitcnt lgkmcnt(2)
	v_bfe_u32 v17, v20, 16, 1
	ds_read2_b32 v[30:31], v144 offset0:148 offset1:156
	v_lshrrev_b32_e32 v16, 16, v16
	v_add3_u32 v17, v20, v17, s57
	ds_read2_b32 v[32:33], v144 offset0:181 offset1:189
	v_and_or_b32 v16, v17, s53, v16
	s_waitcnt lgkmcnt(3)
	v_bfe_u32 v17, v26, 16, 1
	v_add3_u32 v17, v26, v17, s57
	s_waitcnt lgkmcnt(2)
	v_bfe_u32 v18, v28, 16, 1
	ds_read2_b32 v[146:147], v144 offset0:214 offset1:222
	v_lshrrev_b32_e32 v17, 16, v17
	v_add3_u32 v18, v28, v18, s57
	ds_read2_b32 v[148:149], v144 offset0:247 offset1:255
	v_and_or_b32 v17, v18, s53, v17
	s_waitcnt lgkmcnt(3)
	v_bfe_u32 v18, v30, 16, 1
	v_add3_u32 v18, v30, v18, s57
	s_waitcnt lgkmcnt(2)
	v_bfe_u32 v19, v32, 16, 1
	v_lshrrev_b32_e32 v18, 16, v18
	v_add3_u32 v19, v32, v19, s57
	v_and_or_b32 v18, v19, s53, v18
	s_waitcnt lgkmcnt(1)
	v_bfe_u32 v19, v146, 16, 1
	v_add3_u32 v19, v146, v19, s57
	s_waitcnt lgkmcnt(0)
	v_bfe_u32 v20, v148, 16, 1
	v_lshrrev_b32_e32 v19, 16, v19
	v_add3_u32 v20, v148, v20, s57
	v_and_or_b32 v19, v20, s53, v19
	v_add_u32_e32 v20, s48, v142
	v_ashrrev_i32_e32 v24, 31, v20
	v_mul_lo_u32 v24, s16, v24
	v_mul_lo_u32 v26, s17, v20
	v_mad_u64_u32 v[150:151], s[0:1], s16, v20, 0
	v_add3_u32 v151, v151, v24, v26
	v_lshl_add_u64 v[150:151], v[150:151], 1, v[22:23]
	global_store_dwordx4 v[150:151], v[16:19], off sc1
	v_bfe_u32 v20, v149, 16, 1
	v_add3_u32 v20, v149, v20, s57
	v_bfe_u32 v16, v25, 16, 1
	v_add3_u32 v16, v25, v16, s57
	v_bfe_u32 v17, v21, 16, 1
	v_lshrrev_b32_e32 v16, 16, v16
	v_add3_u32 v17, v21, v17, s57
	v_and_or_b32 v16, v17, s53, v16
	v_bfe_u32 v17, v27, 16, 1
	v_add3_u32 v17, v27, v17, s57
	v_bfe_u32 v18, v29, 16, 1
	v_lshrrev_b32_e32 v17, 16, v17
	v_add3_u32 v18, v29, v18, s57
	v_and_or_b32 v17, v18, s53, v17
	v_bfe_u32 v18, v31, 16, 1
	v_add3_u32 v18, v31, v18, s57
	v_bfe_u32 v19, v33, 16, 1
	v_lshrrev_b32_e32 v18, 16, v18
	v_add3_u32 v19, v33, v19, s57
	v_and_or_b32 v18, v19, s53, v18
	v_bfe_u32 v19, v147, 16, 1
	v_add3_u32 v19, v147, v19, s57
	v_lshrrev_b32_e32 v19, 16, v19
	v_and_or_b32 v19, v20, s53, v19
	v_add_u32_e32 v20, s48, v143
	v_ashrrev_i32_e32 v21, 31, v20
	v_mul_lo_u32 v24, s16, v21
	v_mul_lo_u32 v25, s17, v20
	v_mad_u64_u32 v[20:21], s[0:1], s16, v20, 0
	v_add3_u32 v21, v21, v24, v25
	v_lshl_add_u64 v[20:21], v[20:21], 1, v[22:23]
	global_store_dwordx4 v[20:21], v[16:19], off sc1
	s_waitcnt lgkmcnt(0)
	s_waitcnt vmcnt(27)
	ds_write2_b32 v145, v38, v39 offset1:1
	ds_write2_b32 v145, v40, v41 offset0:2 offset1:3
	s_waitcnt vmcnt(26)
	ds_write2_b32 v6, v34, v35 offset1:1
	ds_write2_b32 v2, v36, v37 offset1:1
	s_waitcnt vmcnt(25)
	ds_write2_b32 v3, v46, v47 offset1:1
	ds_write2_b32 v4, v48, v49 offset1:1
	s_waitcnt vmcnt(24)
	ds_write2_b32 v5, v42, v43 offset1:1
	ds_write2_b32 v7, v44, v45 offset1:1
	s_waitcnt vmcnt(23)
	ds_write2_b32 v8, v54, v55 offset1:1
	ds_write2_b32 v9, v56, v57 offset1:1
	s_waitcnt vmcnt(22)
	ds_write2_b32 v10, v50, v51 offset1:1
	ds_write2_b32 v11, v52, v53 offset1:1
	s_waitcnt vmcnt(21)
	ds_write2_b32 v12, v62, v63 offset1:1
	ds_write2_b32 v13, v64, v65 offset1:1
	s_waitcnt vmcnt(20)
	ds_write2_b32 v14, v58, v59 offset1:1
	ds_write2_b32 v15, v60, v61 offset1:1
	s_waitcnt lgkmcnt(0)
	ds_read2_b32 v[20:21], v144 offset1:8
	ds_read2_b32 v[24:25], v144 offset0:33 offset1:41
	ds_read2_b32 v[26:27], v144 offset0:66 offset1:74
	ds_read2_b32 v[28:29], v144 offset0:99 offset1:107
	ds_read2_b32 v[30:31], v144 offset0:132 offset1:140
	s_waitcnt lgkmcnt(4)
	v_bfe_u32 v16, v20, 16, 1
	v_add3_u32 v16, v20, v16, s57
	s_waitcnt lgkmcnt(3)
	v_bfe_u32 v17, v24, 16, 1
	v_lshrrev_b32_e32 v16, 16, v16
	v_add3_u32 v17, v24, v17, s57
	ds_read2_b32 v[32:33], v144 offset0:165 offset1:173
	v_and_or_b32 v16, v17, s53, v16
	s_waitcnt lgkmcnt(3)
	v_bfe_u32 v17, v26, 16, 1
	v_add3_u32 v17, v26, v17, s57
	s_waitcnt lgkmcnt(2)
	v_bfe_u32 v18, v28, 16, 1
	ds_read2_b32 v[34:35], v144 offset0:198 offset1:206
	v_lshrrev_b32_e32 v17, 16, v17
	v_add3_u32 v18, v28, v18, s57
	ds_read2_b32 v[36:37], v144 offset0:231 offset1:239
	v_and_or_b32 v17, v18, s53, v17
	s_waitcnt lgkmcnt(3)
	v_bfe_u32 v18, v30, 16, 1
	v_add3_u32 v18, v30, v18, s57
	s_waitcnt lgkmcnt(2)
	v_bfe_u32 v19, v32, 16, 1
	v_lshrrev_b32_e32 v18, 16, v18
	v_add3_u32 v19, v32, v19, s57
	v_and_or_b32 v18, v19, s53, v18
	s_waitcnt lgkmcnt(1)
	v_bfe_u32 v19, v34, 16, 1
	s_ashr_i32 s81, s80, 31
	v_add3_u32 v19, v34, v19, s57
	s_waitcnt lgkmcnt(0)
	v_bfe_u32 v20, v36, 16, 1
	s_lshl_b64 s[0:1], s[80:81], 1
	v_lshrrev_b32_e32 v19, 16, v19
	v_add3_u32 v20, v36, v20, s57
	s_add_u32 s0, s8, s0
	v_and_or_b32 v19, v20, s53, v19
	v_add_u32_e32 v20, s54, v139
	s_addc_u32 s1, s9, s1
	v_ashrrev_i32_e32 v24, 31, v20
	v_lshl_add_u64 v[22:23], s[0:1], 0, v[134:135]
	v_mul_lo_u32 v24, s18, v24
	v_mul_lo_u32 v26, s19, v20
	v_mad_u64_u32 v[38:39], s[0:1], s18, v20, 0
	v_add3_u32 v39, v39, v24, v26
	v_lshl_add_u64 v[38:39], v[38:39], 1, v[22:23]
	global_store_dwordx4 v[38:39], v[16:19], off sc1
	v_bfe_u32 v20, v37, 16, 1
	v_add3_u32 v20, v37, v20, s57
	v_bfe_u32 v16, v21, 16, 1
	v_add3_u32 v16, v21, v16, s57
	v_bfe_u32 v17, v25, 16, 1
	v_lshrrev_b32_e32 v16, 16, v16
	v_add3_u32 v17, v25, v17, s57
	v_and_or_b32 v16, v17, s53, v16
	v_bfe_u32 v17, v27, 16, 1
	v_add3_u32 v17, v27, v17, s57
	v_bfe_u32 v18, v29, 16, 1
	v_lshrrev_b32_e32 v17, 16, v17
	v_add3_u32 v18, v29, v18, s57
	v_and_or_b32 v17, v18, s53, v17
	v_bfe_u32 v18, v31, 16, 1
	v_add3_u32 v18, v31, v18, s57
	v_bfe_u32 v19, v33, 16, 1
	v_lshrrev_b32_e32 v18, 16, v18
	v_add3_u32 v19, v33, v19, s57
	v_and_or_b32 v18, v19, s53, v18
	v_bfe_u32 v19, v35, 16, 1
	v_add3_u32 v19, v35, v19, s57
	v_lshrrev_b32_e32 v19, 16, v19
	v_and_or_b32 v19, v20, s53, v19
	v_add_u32_e32 v20, s54, v141
	v_ashrrev_i32_e32 v21, 31, v20
	v_mul_lo_u32 v26, s18, v21
	v_mul_lo_u32 v27, s19, v20
	v_mad_u64_u32 v[20:21], s[0:1], s18, v20, 0
	v_add3_u32 v21, v21, v26, v27
	ds_read2_b32 v[24:25], v144 offset0:16 offset1:24
	v_lshl_add_u64 v[20:21], v[20:21], 1, v[22:23]
	global_store_dwordx4 v[20:21], v[16:19], off sc1
	ds_read2_b32 v[20:21], v144 offset0:49 offset1:57
	ds_read2_b32 v[26:27], v144 offset0:82 offset1:90
	ds_read2_b32 v[28:29], v144 offset0:115 offset1:123
	s_waitcnt lgkmcnt(3)
	v_bfe_u32 v16, v24, 16, 1
	v_add3_u32 v16, v24, v16, s57
	s_waitcnt lgkmcnt(2)
	v_bfe_u32 v17, v20, 16, 1
	ds_read2_b32 v[30:31], v144 offset0:148 offset1:156
	v_lshrrev_b32_e32 v16, 16, v16
	v_add3_u32 v17, v20, v17, s57
	ds_read2_b32 v[32:33], v144 offset0:181 offset1:189
	v_and_or_b32 v16, v17, s53, v16
	s_waitcnt lgkmcnt(3)
	v_bfe_u32 v17, v26, 16, 1
	v_add3_u32 v17, v26, v17, s57
	s_waitcnt lgkmcnt(2)
	v_bfe_u32 v18, v28, 16, 1
	ds_read2_b32 v[34:35], v144 offset0:214 offset1:222
	v_lshrrev_b32_e32 v17, 16, v17
	v_add3_u32 v18, v28, v18, s57
	ds_read2_b32 v[36:37], v144 offset0:247 offset1:255
	v_and_or_b32 v17, v18, s53, v17
	s_waitcnt lgkmcnt(3)
	v_bfe_u32 v18, v30, 16, 1
	v_add3_u32 v18, v30, v18, s57
	s_waitcnt lgkmcnt(2)
	v_bfe_u32 v19, v32, 16, 1
	v_lshrrev_b32_e32 v18, 16, v18
	v_add3_u32 v19, v32, v19, s57
	v_and_or_b32 v18, v19, s53, v18
	s_waitcnt lgkmcnt(1)
	v_bfe_u32 v19, v34, 16, 1
	v_add3_u32 v19, v34, v19, s57
	s_waitcnt lgkmcnt(0)
	v_bfe_u32 v20, v36, 16, 1
	v_lshrrev_b32_e32 v19, 16, v19
	v_add3_u32 v20, v36, v20, s57
	v_and_or_b32 v19, v20, s53, v19
	v_add_u32_e32 v20, s54, v142
	v_ashrrev_i32_e32 v24, 31, v20
	v_mul_lo_u32 v24, s18, v24
	v_mul_lo_u32 v26, s19, v20
	v_mad_u64_u32 v[38:39], s[0:1], s18, v20, 0
	v_add3_u32 v39, v39, v24, v26
	v_lshl_add_u64 v[38:39], v[38:39], 1, v[22:23]
	global_store_dwordx4 v[38:39], v[16:19], off sc1
	v_bfe_u32 v20, v37, 16, 1
	v_add3_u32 v20, v37, v20, s57
	v_bfe_u32 v16, v25, 16, 1
	v_add3_u32 v16, v25, v16, s57
	v_bfe_u32 v17, v21, 16, 1
	v_lshrrev_b32_e32 v16, 16, v16
	v_add3_u32 v17, v21, v17, s57
	v_and_or_b32 v16, v17, s53, v16
	v_bfe_u32 v17, v27, 16, 1
	v_add3_u32 v17, v27, v17, s57
	v_bfe_u32 v18, v29, 16, 1
	v_lshrrev_b32_e32 v17, 16, v17
	v_add3_u32 v18, v29, v18, s57
	v_and_or_b32 v17, v18, s53, v17
	v_bfe_u32 v18, v31, 16, 1
	v_add3_u32 v18, v31, v18, s57
	v_bfe_u32 v19, v33, 16, 1
	v_lshrrev_b32_e32 v18, 16, v18
	v_add3_u32 v19, v33, v19, s57
	v_and_or_b32 v18, v19, s53, v18
	v_bfe_u32 v19, v35, 16, 1
	v_add3_u32 v19, v35, v19, s57
	v_lshrrev_b32_e32 v19, 16, v19
	v_and_or_b32 v19, v20, s53, v19
	v_add_u32_e32 v20, s54, v143
	v_ashrrev_i32_e32 v21, 31, v20
	v_mul_lo_u32 v24, s18, v21
	v_mul_lo_u32 v25, s19, v20
	v_mad_u64_u32 v[20:21], s[0:1], s18, v20, 0
	v_add3_u32 v21, v21, v24, v25
	v_lshl_add_u64 v[20:21], v[20:21], 1, v[22:23]
	global_store_dwordx4 v[20:21], v[16:19], off sc1
	s_waitcnt lgkmcnt(0)
	s_waitcnt vmcnt(23)
	ds_write2_b32 v145, v70, v71 offset1:1
	ds_write2_b32 v145, v72, v73 offset0:2 offset1:3
	s_waitcnt vmcnt(22)
	ds_write2_b32 v6, v66, v67 offset1:1
	ds_write2_b32 v2, v68, v69 offset1:1
	s_waitcnt vmcnt(21)
	ds_write2_b32 v3, v78, v79 offset1:1
	ds_write2_b32 v4, v80, v81 offset1:1
	s_waitcnt vmcnt(20)
	ds_write2_b32 v5, v74, v75 offset1:1
	ds_write2_b32 v7, v76, v77 offset1:1
	s_waitcnt vmcnt(19)
	ds_write2_b32 v8, v86, v87 offset1:1
	ds_write2_b32 v9, v88, v89 offset1:1
	s_waitcnt vmcnt(18)
	ds_write2_b32 v10, v82, v83 offset1:1
	ds_write2_b32 v11, v84, v85 offset1:1
	s_waitcnt vmcnt(17)
	ds_write2_b32 v12, v94, v95 offset1:1
	ds_write2_b32 v13, v96, v97 offset1:1
	s_waitcnt vmcnt(16)
	ds_write2_b32 v14, v90, v91 offset1:1
	ds_write2_b32 v15, v92, v93 offset1:1
	s_waitcnt lgkmcnt(0)
	ds_read2_b32 v[20:21], v144 offset1:8
	ds_read2_b32 v[24:25], v144 offset0:33 offset1:41
	ds_read2_b32 v[26:27], v144 offset0:66 offset1:74
	ds_read2_b32 v[28:29], v144 offset0:99 offset1:107
	ds_read2_b32 v[30:31], v144 offset0:132 offset1:140
	s_waitcnt lgkmcnt(4)
	v_bfe_u32 v16, v20, 16, 1
	v_add3_u32 v16, v20, v16, s57
	s_waitcnt lgkmcnt(3)
	v_bfe_u32 v17, v24, 16, 1
	v_lshrrev_b32_e32 v16, 16, v16
	v_add3_u32 v17, v24, v17, s57
	ds_read2_b32 v[32:33], v144 offset0:165 offset1:173
	v_and_or_b32 v16, v17, s53, v16
	s_waitcnt lgkmcnt(3)
	v_bfe_u32 v17, v26, 16, 1
	v_add3_u32 v17, v26, v17, s57
	s_waitcnt lgkmcnt(2)
	v_bfe_u32 v18, v28, 16, 1
	ds_read2_b32 v[34:35], v144 offset0:198 offset1:206
	v_lshrrev_b32_e32 v17, 16, v17
	v_add3_u32 v18, v28, v18, s57
	ds_read2_b32 v[36:37], v144 offset0:231 offset1:239
	v_and_or_b32 v17, v18, s53, v17
	s_waitcnt lgkmcnt(3)
	v_bfe_u32 v18, v30, 16, 1
	v_add3_u32 v18, v30, v18, s57
	s_waitcnt lgkmcnt(2)
	v_bfe_u32 v19, v32, 16, 1
	v_lshrrev_b32_e32 v18, 16, v18
	v_add3_u32 v19, v32, v19, s57
	v_and_or_b32 v18, v19, s53, v18
	s_waitcnt lgkmcnt(1)
	v_bfe_u32 v19, v34, 16, 1
	s_ashr_i32 s83, s82, 31
	v_add3_u32 v19, v34, v19, s57
	s_waitcnt lgkmcnt(0)
	v_bfe_u32 v20, v36, 16, 1
	s_lshl_b64 s[0:1], s[82:83], 1
	v_lshrrev_b32_e32 v19, 16, v19
	v_add3_u32 v20, v36, v20, s57
	s_add_u32 s0, s90, s0
	v_and_or_b32 v19, v20, s53, v19
	v_add_u32_e32 v20, s56, v139
	s_addc_u32 s1, s91, s1
	v_ashrrev_i32_e32 v24, 31, v20
	v_lshl_add_u64 v[22:23], s[0:1], 0, v[134:135]
	v_mul_lo_u32 v24, s86, v24
	v_mul_lo_u32 v26, s87, v20
	v_mad_u64_u32 v[38:39], s[0:1], s86, v20, 0
	v_add3_u32 v39, v39, v24, v26
	v_lshl_add_u64 v[38:39], v[38:39], 1, v[22:23]
	global_store_dwordx4 v[38:39], v[16:19], off sc1
	v_bfe_u32 v20, v37, 16, 1
	v_add3_u32 v20, v37, v20, s57
	v_bfe_u32 v16, v21, 16, 1
	v_add3_u32 v16, v21, v16, s57
	v_bfe_u32 v17, v25, 16, 1
	v_lshrrev_b32_e32 v16, 16, v16
	v_add3_u32 v17, v25, v17, s57
	v_and_or_b32 v16, v17, s53, v16
	v_bfe_u32 v17, v27, 16, 1
	v_add3_u32 v17, v27, v17, s57
	v_bfe_u32 v18, v29, 16, 1
	v_lshrrev_b32_e32 v17, 16, v17
	v_add3_u32 v18, v29, v18, s57
	v_and_or_b32 v17, v18, s53, v17
	v_bfe_u32 v18, v31, 16, 1
	v_add3_u32 v18, v31, v18, s57
	v_bfe_u32 v19, v33, 16, 1
	v_lshrrev_b32_e32 v18, 16, v18
	v_add3_u32 v19, v33, v19, s57
	v_and_or_b32 v18, v19, s53, v18
	v_bfe_u32 v19, v35, 16, 1
	v_add3_u32 v19, v35, v19, s57
	v_lshrrev_b32_e32 v19, 16, v19
	v_and_or_b32 v19, v20, s53, v19
	v_add_u32_e32 v20, s56, v141
	v_ashrrev_i32_e32 v21, 31, v20
	v_mul_lo_u32 v26, s86, v21
	v_mul_lo_u32 v27, s87, v20
	v_mad_u64_u32 v[20:21], s[0:1], s86, v20, 0
	v_add3_u32 v21, v21, v26, v27
	ds_read2_b32 v[24:25], v144 offset0:16 offset1:24
	v_lshl_add_u64 v[20:21], v[20:21], 1, v[22:23]
	global_store_dwordx4 v[20:21], v[16:19], off sc1
	ds_read2_b32 v[20:21], v144 offset0:49 offset1:57
	ds_read2_b32 v[26:27], v144 offset0:82 offset1:90
	ds_read2_b32 v[28:29], v144 offset0:115 offset1:123
	s_waitcnt lgkmcnt(3)
	v_bfe_u32 v16, v24, 16, 1
	v_add3_u32 v16, v24, v16, s57
	s_waitcnt lgkmcnt(2)
	v_bfe_u32 v17, v20, 16, 1
	ds_read2_b32 v[30:31], v144 offset0:148 offset1:156
	v_lshrrev_b32_e32 v16, 16, v16
	v_add3_u32 v17, v20, v17, s57
	ds_read2_b32 v[32:33], v144 offset0:181 offset1:189
	v_and_or_b32 v16, v17, s53, v16
	s_waitcnt lgkmcnt(3)
	v_bfe_u32 v17, v26, 16, 1
	v_add3_u32 v17, v26, v17, s57
	s_waitcnt lgkmcnt(2)
	v_bfe_u32 v18, v28, 16, 1
	ds_read2_b32 v[34:35], v144 offset0:214 offset1:222
	v_lshrrev_b32_e32 v17, 16, v17
	v_add3_u32 v18, v28, v18, s57
	ds_read2_b32 v[36:37], v144 offset0:247 offset1:255
	v_and_or_b32 v17, v18, s53, v17
	s_waitcnt lgkmcnt(3)
	v_bfe_u32 v18, v30, 16, 1
	v_add3_u32 v18, v30, v18, s57
	s_waitcnt lgkmcnt(2)
	v_bfe_u32 v19, v32, 16, 1
	v_lshrrev_b32_e32 v18, 16, v18
	v_add3_u32 v19, v32, v19, s57
	v_and_or_b32 v18, v19, s53, v18
	s_waitcnt lgkmcnt(1)
	v_bfe_u32 v19, v34, 16, 1
	v_add3_u32 v19, v34, v19, s57
	s_waitcnt lgkmcnt(0)
	v_bfe_u32 v20, v36, 16, 1
	v_lshrrev_b32_e32 v19, 16, v19
	v_add3_u32 v20, v36, v20, s57
	v_and_or_b32 v19, v20, s53, v19
	v_add_u32_e32 v20, s56, v142
	v_ashrrev_i32_e32 v24, 31, v20
	v_mul_lo_u32 v24, s86, v24
	v_mul_lo_u32 v26, s87, v20
	v_mad_u64_u32 v[38:39], s[0:1], s86, v20, 0
	v_add3_u32 v39, v39, v24, v26
	v_lshl_add_u64 v[38:39], v[38:39], 1, v[22:23]
	global_store_dwordx4 v[38:39], v[16:19], off sc1
	v_bfe_u32 v20, v37, 16, 1
	v_add3_u32 v20, v37, v20, s57
	v_bfe_u32 v16, v25, 16, 1
	v_add3_u32 v16, v25, v16, s57
	v_bfe_u32 v17, v21, 16, 1
	v_lshrrev_b32_e32 v16, 16, v16
	v_add3_u32 v17, v21, v17, s57
	v_and_or_b32 v16, v17, s53, v16
	v_bfe_u32 v17, v27, 16, 1
	v_add3_u32 v17, v27, v17, s57
	v_bfe_u32 v18, v29, 16, 1
	v_lshrrev_b32_e32 v17, 16, v17
	v_add3_u32 v18, v29, v18, s57
	v_and_or_b32 v17, v18, s53, v17
	v_bfe_u32 v18, v31, 16, 1
	v_add3_u32 v18, v31, v18, s57
	v_bfe_u32 v19, v33, 16, 1
	v_lshrrev_b32_e32 v18, 16, v18
	v_add3_u32 v19, v33, v19, s57
	v_and_or_b32 v18, v19, s53, v18
	v_bfe_u32 v19, v35, 16, 1
	v_add3_u32 v19, v35, v19, s57
	v_lshrrev_b32_e32 v19, 16, v19
	v_and_or_b32 v19, v20, s53, v19
	v_add_u32_e32 v20, s56, v143
	v_ashrrev_i32_e32 v21, 31, v20
	v_mul_lo_u32 v24, s86, v21
	v_mul_lo_u32 v25, s87, v20
	v_mad_u64_u32 v[20:21], s[0:1], s86, v20, 0
	v_add3_u32 v21, v21, v24, v25
	v_lshl_add_u64 v[20:21], v[20:21], 1, v[22:23]
	global_store_dwordx4 v[20:21], v[16:19], off sc1
	s_waitcnt lgkmcnt(0)
	s_waitcnt vmcnt(19)
	ds_write2_b32 v145, v102, v103 offset1:1
	ds_write2_b32 v145, v104, v105 offset0:2 offset1:3
	s_waitcnt vmcnt(18)
	ds_write2_b32 v6, v98, v99 offset1:1
	ds_write2_b32 v2, v100, v101 offset1:1
	s_waitcnt vmcnt(17)
	ds_write2_b32 v3, v110, v111 offset1:1
	ds_write2_b32 v4, v112, v113 offset1:1
	s_waitcnt vmcnt(16)
	ds_write2_b32 v5, v106, v107 offset1:1
	ds_write2_b32 v7, v108, v109 offset1:1
	s_waitcnt vmcnt(15)
	ds_write2_b32 v8, v118, v119 offset1:1
	ds_write2_b32 v9, v120, v121 offset1:1
	s_waitcnt vmcnt(14)
	ds_write2_b32 v10, v114, v115 offset1:1
	ds_write2_b32 v11, v116, v117 offset1:1
	s_waitcnt vmcnt(13)
	ds_write2_b32 v12, v126, v127 offset1:1
	ds_write2_b32 v13, v128, v129 offset1:1
	s_waitcnt vmcnt(12)
	ds_write2_b32 v14, v122, v123 offset1:1
	ds_write2_b32 v15, v124, v125 offset1:1
	s_waitcnt lgkmcnt(0)
	ds_read2_b32 v[6:7], v144 offset1:8
	ds_read2_b32 v[10:11], v144 offset0:33 offset1:41
	ds_read2_b32 v[12:13], v144 offset0:66 offset1:74
	ds_read2_b32 v[14:15], v144 offset0:99 offset1:107
	ds_read2_b32 v[16:17], v144 offset0:132 offset1:140
	s_waitcnt lgkmcnt(4)
	v_bfe_u32 v2, v6, 16, 1
	v_add3_u32 v2, v6, v2, s57
	s_waitcnt lgkmcnt(3)
	v_bfe_u32 v3, v10, 16, 1
	v_lshrrev_b32_e32 v2, 16, v2
	v_add3_u32 v3, v10, v3, s57
	ds_read2_b32 v[18:19], v144 offset0:165 offset1:173
	v_and_or_b32 v2, v3, s53, v2
	s_waitcnt lgkmcnt(3)
	v_bfe_u32 v3, v12, 16, 1
	v_add3_u32 v3, v12, v3, s57
	s_waitcnt lgkmcnt(2)
	v_bfe_u32 v4, v14, 16, 1
	ds_read2_b32 v[20:21], v144 offset0:198 offset1:206
	v_lshrrev_b32_e32 v3, 16, v3
	v_add3_u32 v4, v14, v4, s57
	ds_read2_b32 v[22:23], v144 offset0:231 offset1:239
	v_and_or_b32 v3, v4, s53, v3
	s_waitcnt lgkmcnt(3)
	v_bfe_u32 v4, v16, 16, 1
	v_add3_u32 v4, v16, v4, s57
	s_waitcnt lgkmcnt(2)
	v_bfe_u32 v5, v18, 16, 1
	v_lshrrev_b32_e32 v4, 16, v4
	v_add3_u32 v5, v18, v5, s57
	v_and_or_b32 v4, v5, s53, v4
	s_waitcnt lgkmcnt(1)
	v_bfe_u32 v5, v20, 16, 1
	s_ashr_i32 s29, s28, 31
	v_add3_u32 v5, v20, v5, s57
	s_waitcnt lgkmcnt(0)
	v_bfe_u32 v6, v22, 16, 1
	s_lshl_b64 s[0:1], s[28:29], 1
	v_lshrrev_b32_e32 v5, 16, v5
	v_add3_u32 v6, v22, v6, s57
	s_add_u32 s0, s38, s0
	v_and_or_b32 v5, v6, s53, v5
	v_add_u32_e32 v6, s97, v139
	s_addc_u32 s1, s39, s1
	v_ashrrev_i32_e32 v10, 31, v6
	v_lshl_add_u64 v[8:9], s[0:1], 0, v[134:135]
	v_mul_lo_u32 v10, s72, v10
	v_mul_lo_u32 v12, s73, v6
	v_mad_u64_u32 v[24:25], s[0:1], s72, v6, 0
	v_add3_u32 v25, v25, v10, v12
	v_lshl_add_u64 v[24:25], v[24:25], 1, v[8:9]
	global_store_dwordx4 v[24:25], v[2:5], off sc1
	v_bfe_u32 v6, v23, 16, 1
	v_add3_u32 v6, v23, v6, s57
	v_bfe_u32 v2, v7, 16, 1
	v_add3_u32 v2, v7, v2, s57
	v_bfe_u32 v3, v11, 16, 1
	v_lshrrev_b32_e32 v2, 16, v2
	v_add3_u32 v3, v11, v3, s57
	v_and_or_b32 v2, v3, s53, v2
	v_bfe_u32 v3, v13, 16, 1
	v_add3_u32 v3, v13, v3, s57
	v_bfe_u32 v4, v15, 16, 1
	v_lshrrev_b32_e32 v3, 16, v3
	v_add3_u32 v4, v15, v4, s57
	v_and_or_b32 v3, v4, s53, v3
	v_bfe_u32 v4, v17, 16, 1
	v_add3_u32 v4, v17, v4, s57
	v_bfe_u32 v5, v19, 16, 1
	v_lshrrev_b32_e32 v4, 16, v4
	v_add3_u32 v5, v19, v5, s57
	v_and_or_b32 v4, v5, s53, v4
	v_bfe_u32 v5, v21, 16, 1
	v_add3_u32 v5, v21, v5, s57
	v_lshrrev_b32_e32 v5, 16, v5
	v_and_or_b32 v5, v6, s53, v5
	v_add_u32_e32 v6, s97, v141
	v_ashrrev_i32_e32 v7, 31, v6
	v_mul_lo_u32 v12, s72, v7
	v_mul_lo_u32 v13, s73, v6
	v_mad_u64_u32 v[6:7], s[0:1], s72, v6, 0
	v_add3_u32 v7, v7, v12, v13
	ds_read2_b32 v[10:11], v144 offset0:16 offset1:24
	v_lshl_add_u64 v[6:7], v[6:7], 1, v[8:9]
	global_store_dwordx4 v[6:7], v[2:5], off sc1
	ds_read2_b32 v[6:7], v144 offset0:49 offset1:57
	ds_read2_b32 v[12:13], v144 offset0:82 offset1:90
	ds_read2_b32 v[14:15], v144 offset0:115 offset1:123
	s_waitcnt lgkmcnt(3)
	v_bfe_u32 v2, v10, 16, 1
	v_add3_u32 v2, v10, v2, s57
	s_waitcnt lgkmcnt(2)
	v_bfe_u32 v3, v6, 16, 1
	ds_read2_b32 v[16:17], v144 offset0:148 offset1:156
	v_lshrrev_b32_e32 v2, 16, v2
	v_add3_u32 v3, v6, v3, s57
	ds_read2_b32 v[18:19], v144 offset0:181 offset1:189
	v_and_or_b32 v2, v3, s53, v2
	s_waitcnt lgkmcnt(3)
	v_bfe_u32 v3, v12, 16, 1
	v_add3_u32 v3, v12, v3, s57
	s_waitcnt lgkmcnt(2)
	v_bfe_u32 v4, v14, 16, 1
	ds_read2_b32 v[20:21], v144 offset0:214 offset1:222
	v_lshrrev_b32_e32 v3, 16, v3
	v_add3_u32 v4, v14, v4, s57
	ds_read2_b32 v[22:23], v144 offset0:247 offset1:255
	v_and_or_b32 v3, v4, s53, v3
	s_waitcnt lgkmcnt(3)
	v_bfe_u32 v4, v16, 16, 1
	v_add3_u32 v4, v16, v4, s57
	s_waitcnt lgkmcnt(2)
	v_bfe_u32 v5, v18, 16, 1
	v_lshrrev_b32_e32 v4, 16, v4
	v_add3_u32 v5, v18, v5, s57
	v_and_or_b32 v4, v5, s53, v4
	s_waitcnt lgkmcnt(1)
	v_bfe_u32 v5, v20, 16, 1
	v_add3_u32 v5, v20, v5, s57
	s_waitcnt lgkmcnt(0)
	v_bfe_u32 v6, v22, 16, 1
	v_lshrrev_b32_e32 v5, 16, v5
	v_add3_u32 v6, v22, v6, s57
	v_and_or_b32 v5, v6, s53, v5
	v_add_u32_e32 v6, s97, v142
	v_ashrrev_i32_e32 v10, 31, v6
	v_mul_lo_u32 v10, s72, v10
	v_mul_lo_u32 v12, s73, v6
	v_mad_u64_u32 v[24:25], s[0:1], s72, v6, 0
	v_add3_u32 v25, v25, v10, v12
	v_lshl_add_u64 v[24:25], v[24:25], 1, v[8:9]
	global_store_dwordx4 v[24:25], v[2:5], off sc1
	v_bfe_u32 v6, v23, 16, 1
	v_add3_u32 v6, v23, v6, s57
	v_bfe_u32 v2, v11, 16, 1
	v_add3_u32 v2, v11, v2, s57
	v_bfe_u32 v3, v7, 16, 1
	v_lshrrev_b32_e32 v2, 16, v2
	v_add3_u32 v3, v7, v3, s57
	v_and_or_b32 v2, v3, s53, v2
	v_bfe_u32 v3, v13, 16, 1
	v_add3_u32 v3, v13, v3, s57
	v_bfe_u32 v4, v15, 16, 1
	v_lshrrev_b32_e32 v3, 16, v3
	v_add3_u32 v4, v15, v4, s57
	v_and_or_b32 v3, v4, s53, v3
	v_bfe_u32 v4, v17, 16, 1
	v_add3_u32 v4, v17, v4, s57
	v_bfe_u32 v5, v19, 16, 1
	v_lshrrev_b32_e32 v4, 16, v4
	v_add3_u32 v5, v19, v5, s57
	v_and_or_b32 v4, v5, s53, v4
	v_bfe_u32 v5, v21, 16, 1
	v_add3_u32 v5, v21, v5, s57
	v_lshrrev_b32_e32 v5, 16, v5
	v_and_or_b32 v5, v6, s53, v5
	v_add_u32_e32 v6, s97, v143
	v_ashrrev_i32_e32 v7, 31, v6
	v_mul_lo_u32 v10, s72, v7
	v_mul_lo_u32 v11, s73, v6
	v_mad_u64_u32 v[6:7], s[0:1], s72, v6, 0
	v_add3_u32 v7, v7, v10, v11
	v_lshl_add_u64 v[6:7], v[6:7], 1, v[8:9]
	global_store_dwordx4 v[6:7], v[2:5], off sc1
	s_waitcnt lgkmcnt(0)
	s_mov_b64 s[0:1], 0
	v_readlane_b32 s97, v254, 19
	s_movk_i32 s38, 0x2ff

.LBB0_1250:
	s_and_b64 vcc, exec, s[10:11]
	s_cbranch_vccnz .LBB0_1226
	v_lshl_or_b32 v140, s7, 8, v148
	s_ashr_i32 s7, s6, 31
	v_lshl_add_u32 v142, s90, 8, v147
	s_lshl_b64 s[0:1], s[6:7], 22
	v_ashrrev_i32_e32 v143, 31, v142
	s_add_u32 s0, s79, s0
	s_addc_u32 s1, s80, s1
	v_lshlrev_b64 v[142:143], 12, v[142:143]
	v_lshl_add_u64 v[142:143], s[0:1], 0, v[142:143]
	v_ashrrev_i32_e32 v141, 31, v140
	v_lshl_add_u64 v[140:141], v[140:141], 1, v[142:143]
	s_mov_b32 s0, 0x10000
	v_cvt_pk_bf16_f32 v126, v126, v127
	v_cvt_pk_bf16_f32 v127, v128, v129
	v_cvt_pk_bf16_f32 v128, v122, v123
	v_cvt_pk_bf16_f32 v129, v124, v125
	global_store_dwordx4 v[140:141], v[126:129], off sc1
	v_cvt_pk_bf16_f32 v118, v118, v119
	v_cvt_pk_bf16_f32 v119, v120, v121
	v_cvt_pk_bf16_f32 v120, v114, v115
	v_cvt_pk_bf16_f32 v121, v116, v117
	global_store_dwordx4 v[140:141], v[118:121], off offset:256 sc1
	v_cvt_pk_bf16_f32 v110, v110, v111
	v_cvt_pk_bf16_f32 v111, v112, v113
	v_cvt_pk_bf16_f32 v112, v106, v107
	v_add_co_u32_e32 v106, vcc, s0, v140
	s_mov_b32 s0, 0x20000
	s_nop 0
	v_addc_co_u32_e32 v107, vcc, 0, v141, vcc
	v_cvt_pk_bf16_f32 v113, v108, v109
	global_store_dwordx4 v[106:107], v[110:113], off sc1
	v_cvt_pk_bf16_f32 v102, v102, v103
	v_cvt_pk_bf16_f32 v103, v104, v105
	v_cvt_pk_bf16_f32 v104, v98, v99
	v_cvt_pk_bf16_f32 v105, v100, v101
	global_store_dwordx4 v[106:107], v[102:105], off offset:256 sc1
	v_cvt_pk_bf16_f32 v94, v94, v95
	v_cvt_pk_bf16_f32 v95, v96, v97
	v_cvt_pk_bf16_f32 v96, v90, v91
	v_add_co_u32_e32 v90, vcc, s0, v140
	v_cvt_pk_bf16_f32 v97, v92, v93
	s_mov_b32 s0, 0x80000
	s_nop 0
	v_addc_co_u32_e32 v91, vcc, 0, v141, vcc
	global_store_dwordx4 v[90:91], v[94:97], off sc1
	v_cvt_pk_bf16_f32 v86, v86, v87
	v_cvt_pk_bf16_f32 v87, v88, v89
	v_cvt_pk_bf16_f32 v88, v82, v83
	v_cvt_pk_bf16_f32 v89, v84, v85
	global_store_dwordx4 v[90:91], v[86:89], off offset:256 sc1
	v_cvt_pk_bf16_f32 v78, v78, v79
	v_cvt_pk_bf16_f32 v79, v80, v81
	v_cvt_pk_bf16_f32 v80, v74, v75
	v_add_co_u32_e32 v74, vcc, s92, v140
	v_cvt_pk_bf16_f32 v81, v76, v77
	s_nop 1
	v_addc_co_u32_e32 v75, vcc, 0, v141, vcc
	global_store_dwordx4 v[74:75], v[78:81], off sc1
	v_cvt_pk_bf16_f32 v70, v70, v71
	v_cvt_pk_bf16_f32 v71, v72, v73
	v_cvt_pk_bf16_f32 v72, v66, v67
	v_cvt_pk_bf16_f32 v73, v68, v69
	global_store_dwordx4 v[74:75], v[70:73], off offset:256 sc1
	v_cvt_pk_bf16_f32 v62, v62, v63
	v_cvt_pk_bf16_f32 v63, v64, v65
	v_cvt_pk_bf16_f32 v64, v58, v59
	v_add_co_u32_e32 v58, vcc, s0, v140
	s_mov_b32 s0, 0x90000
	s_nop 0
	v_addc_co_u32_e32 v59, vcc, 0, v141, vcc
	v_cvt_pk_bf16_f32 v65, v60, v61
	global_store_dwordx4 v[58:59], v[62:65], off sc1
	v_cvt_pk_bf16_f32 v54, v54, v55
	v_cvt_pk_bf16_f32 v55, v56, v57
	v_cvt_pk_bf16_f32 v56, v50, v51
	v_cvt_pk_bf16_f32 v57, v52, v53
	global_store_dwordx4 v[58:59], v[54:57], off offset:256 sc1
	v_cvt_pk_bf16_f32 v46, v46, v47
	v_cvt_pk_bf16_f32 v47, v48, v49
	v_cvt_pk_bf16_f32 v48, v42, v43
	v_add_co_u32_e32 v42, vcc, s0, v140
	s_mov_b32 s0, 0xa0000
	s_nop 0
	v_addc_co_u32_e32 v43, vcc, 0, v141, vcc
	v_cvt_pk_bf16_f32 v49, v44, v45
	global_store_dwordx4 v[42:43], v[46:49], off sc1
	v_cvt_pk_bf16_f32 v38, v38, v39
	v_cvt_pk_bf16_f32 v39, v40, v41
	v_cvt_pk_bf16_f32 v40, v34, v35
	v_cvt_pk_bf16_f32 v41, v36, v37
	global_store_dwordx4 v[42:43], v[38:41], off offset:256 sc1
	v_cvt_pk_bf16_f32 v30, v30, v31
	v_cvt_pk_bf16_f32 v31, v32, v33
	v_cvt_pk_bf16_f32 v32, v26, v27
	v_add_co_u32_e32 v26, vcc, s0, v140
	s_mov_b32 s0, 0xb0000
	s_nop 0
	v_addc_co_u32_e32 v27, vcc, 0, v141, vcc
	v_cvt_pk_bf16_f32 v33, v28, v29
	global_store_dwordx4 v[26:27], v[30:33], off sc1
	v_cvt_pk_bf16_f32 v22, v22, v23
	v_cvt_pk_bf16_f32 v23, v24, v25
	v_cvt_pk_bf16_f32 v24, v18, v19
	v_cvt_pk_bf16_f32 v25, v20, v21
	global_store_dwordx4 v[26:27], v[22:25], off offset:256 sc1
	v_cvt_pk_bf16_f32 v14, v14, v15
	v_cvt_pk_bf16_f32 v15, v16, v17
	v_cvt_pk_bf16_f32 v16, v10, v11
	v_add_co_u32_e32 v10, vcc, s0, v140
	v_cvt_pk_bf16_f32 v17, v12, v13
	s_nop 1
	v_addc_co_u32_e32 v11, vcc, 0, v141, vcc
	s_andn2_b64 vcc, exec, s[30:31]
	global_store_dwordx4 v[10:11], v[14:17], off sc1
	v_cvt_pk_bf16_f32 v6, v6, v7
	v_cvt_pk_bf16_f32 v7, v8, v9
	v_cvt_pk_bf16_f32 v8, v2, v3
	v_cvt_pk_bf16_f32 v9, v4, v5
	global_store_dwordx4 v[10:11], v[6:9], off offset:256 sc1
	s_cbranch_vccnz .LBB0_1253
	s_barrier

.LBB0_1272:
	s_or_b64 exec, exec, s[0:1]
	s_cmp_eq_u64 s[16:17], 0
	s_cselect_b64 s[28:29], -1, 0
	s_cmp_lg_u64 s[16:17], 0
	v_or_b32_e32 v130, s30, v226
	s_cselect_b64 s[26:27], -1, 0
	s_and_b64 vcc, exec, s[26:27]
	v_ashrrev_i32_e32 v131, 31, v130
	s_cbranch_vccnz .LBB0_1274
	s_waitcnt lgkmcnt(0)
	v_lshlrev_b64 v[2:3], 12, v[130:131]
	v_lshl_add_u64 v[2:3], s[8:9], 0, v[2:3]
	v_lshl_add_u64 v[6:7], v[206:207], 1, v[2:3]
	v_cvt_pk_f16_f32 v5, v124, v125
	v_cvt_pk_f16_f32 v4, v122, v123
	v_cvt_pk_f16_f32 v3, v128, v129
	v_cvt_pk_f16_f32 v2, v126, v127
	s_mov_b32 s0, 0x10000
	global_store_dwordx4 v[6:7], v[2:5], off sc1
	v_add_co_u32_e32 v8, vcc, s0, v6
	s_nop 0
	v_cvt_pk_f16_f32 v5, v116, v117
	v_cvt_pk_f16_f32 v4, v114, v115
	v_cvt_pk_f16_f32 v3, v120, v121
	v_cvt_pk_f16_f32 v2, v118, v119
	global_store_dwordx4 v[6:7], v[2:5], off offset:256 sc1
	v_addc_co_u32_e32 v9, vcc, 0, v7, vcc
	s_nop 0
	v_cvt_pk_f16_f32 v5, v108, v109
	v_cvt_pk_f16_f32 v4, v106, v107
	v_cvt_pk_f16_f32 v3, v112, v113
	v_cvt_pk_f16_f32 v2, v110, v111
	global_store_dwordx4 v[8:9], v[2:5], off sc1
	s_mov_b32 s0, 0x20000
	s_nop 0
	v_cvt_pk_f16_f32 v5, v100, v101
	v_cvt_pk_f16_f32 v4, v98, v99
	v_cvt_pk_f16_f32 v3, v104, v105
	v_cvt_pk_f16_f32 v2, v102, v103
	global_store_dwordx4 v[8:9], v[2:5], off offset:256 sc1
	v_add_co_u32_e32 v8, vcc, s0, v6
	s_nop 0
	v_cvt_pk_f16_f32 v5, v92, v93
	v_cvt_pk_f16_f32 v4, v90, v91
	v_cvt_pk_f16_f32 v3, v96, v97
	v_cvt_pk_f16_f32 v2, v94, v95
	v_addc_co_u32_e32 v9, vcc, 0, v7, vcc
	global_store_dwordx4 v[8:9], v[2:5], off sc1
	s_mov_b32 s0, 0x80000
	s_nop 0
	v_cvt_pk_f16_f32 v5, v84, v85
	v_cvt_pk_f16_f32 v4, v82, v83
	v_cvt_pk_f16_f32 v3, v88, v89
	v_cvt_pk_f16_f32 v2, v86, v87
	global_store_dwordx4 v[8:9], v[2:5], off offset:256 sc1
	v_add_co_u32_e32 v8, vcc, s92, v6
	s_nop 0
	v_cvt_pk_f16_f32 v5, v76, v77
	v_cvt_pk_f16_f32 v4, v74, v75
	v_cvt_pk_f16_f32 v3, v80, v81
	v_cvt_pk_f16_f32 v2, v78, v79
	v_addc_co_u32_e32 v9, vcc, 0, v7, vcc
	global_store_dwordx4 v[8:9], v[2:5], off sc1
	s_nop 1
	v_cvt_pk_f16_f32 v5, v68, v69
	v_cvt_pk_f16_f32 v4, v66, v67
	v_cvt_pk_f16_f32 v3, v72, v73
	v_cvt_pk_f16_f32 v2, v70, v71
	global_store_dwordx4 v[8:9], v[2:5], off offset:256 sc1
	v_add_co_u32_e32 v8, vcc, s0, v6
	s_nop 0
	v_cvt_pk_f16_f32 v5, v178, v179
	v_cvt_pk_f16_f32 v4, v180, v181
	v_cvt_pk_f16_f32 v3, v174, v175
	v_cvt_pk_f16_f32 v2, v176, v177
	v_addc_co_u32_e32 v9, vcc, 0, v7, vcc
	global_store_dwordx4 v[8:9], v[2:5], off sc1
	s_mov_b32 s0, 0x90000
	s_nop 0
	v_cvt_pk_f16_f32 v5, v52, v53
	v_cvt_pk_f16_f32 v4, v50, v51
	v_cvt_pk_f16_f32 v3, v56, v57
	v_cvt_pk_f16_f32 v2, v54, v55
	global_store_dwordx4 v[8:9], v[2:5], off offset:256 sc1
	v_add_co_u32_e32 v8, vcc, s0, v6
	s_nop 0
	v_cvt_pk_f16_f32 v5, v168, v169
	v_cvt_pk_f16_f32 v4, v172, v173
	v_cvt_pk_f16_f32 v3, v166, v167
	v_cvt_pk_f16_f32 v2, v170, v171
	v_addc_co_u32_e32 v9, vcc, 0, v7, vcc
	global_store_dwordx4 v[8:9], v[2:5], off sc1
	s_mov_b32 s0, 0xa0000
	s_nop 0
	v_cvt_pk_f16_f32 v5, v36, v37
	v_cvt_pk_f16_f32 v4, v34, v35
	v_cvt_pk_f16_f32 v3, v40, v41
	v_cvt_pk_f16_f32 v2, v38, v39
	global_store_dwordx4 v[8:9], v[2:5], off offset:256 sc1
	v_add_co_u32_e32 v8, vcc, s0, v6
	s_nop 0
	v_cvt_pk_f16_f32 v5, v162, v163
	v_cvt_pk_f16_f32 v4, v164, v165
	v_cvt_pk_f16_f32 v3, v158, v159
	v_cvt_pk_f16_f32 v2, v160, v161
	v_addc_co_u32_e32 v9, vcc, 0, v7, vcc
	s_mov_b32 s0, 0xb0000
	global_store_dwordx4 v[8:9], v[2:5], off sc1
	v_add_co_u32_e32 v6, vcc, s0, v6
	s_nop 0
	v_cvt_pk_f16_f32 v5, v46, v47
	v_cvt_pk_f16_f32 v4, v48, v49
	v_cvt_pk_f16_f32 v3, v42, v43
	v_cvt_pk_f16_f32 v2, v44, v45
	global_store_dwordx4 v[8:9], v[2:5], off offset:256 sc1
	v_addc_co_u32_e32 v7, vcc, 0, v7, vcc
	s_nop 0
	v_cvt_pk_f16_f32 v5, v144, v145
	v_cvt_pk_f16_f32 v4, v146, v147
	v_cvt_pk_f16_f32 v3, v142, v143
	v_cvt_pk_f16_f32 v2, v150, v151
	global_store_dwordx4 v[6:7], v[2:5], off sc1
	s_nop 1
	v_cvt_pk_f16_f32 v5, v60, v61
	v_cvt_pk_f16_f32 v4, v64, v65
	v_cvt_pk_f16_f32 v3, v58, v59
	v_cvt_pk_f16_f32 v2, v62, v63
	global_store_dwordx4 v[6:7], v[2:5], off offset:256 sc1

.LBB0_1298:
	s_or_b64 exec, exec, s[6:7]
	s_add_u32 s6, s18, 0x1a400000
	s_addc_u32 s7, s19, 0
	s_lshl_b32 s0, s14, 2
	s_add_i32 s0, s0, 0
	v_lshl_add_u32 v134, v226, 2, s0
	s_waitcnt lgkmcnt(0)
	s_barrier
	v_add_u32_e32 v134, 0x1000, v134
	ds_read2_b32 v[154:155], v134 offset1:16
	ds_read2_b32 v[140:141], v134 offset0:32 offset1:48
	ds_read2_b32 v[136:137], v134 offset0:128 offset1:144
	ds_read2_b32 v[134:135], v134 offset0:160 offset1:176
	v_cndmask_b32_e64 v138, 0, 1, s[26:27]
	v_cmp_ne_u32_e64 s[10:11], 1, v138
	v_or_b32_e32 v152, 16, v130
	v_or_b32_e32 v148, 32, v130
	v_or_b32_e32 v138, 48, v130
	s_mov_b64 s[0:1], -1
	s_andn2_b64 vcc, exec, s[26:27]
	v_ashrrev_i32_e32 v153, 31, v152
	v_ashrrev_i32_e32 v149, 31, v148
	v_ashrrev_i32_e32 v139, 31, v138
	s_cbranch_vccnz .LBB0_1302
	v_lshlrev_b64 v[156:157], 13, v[130:131]
	v_lshl_add_u64 v[156:157], s[16:17], 0, v[156:157]
	s_waitcnt lgkmcnt(3)
	v_pk_mul_f32 v[182:183], v[128:129], v[154:155] op_sel_hi:[1,0]
	v_pk_mul_f32 v[186:187], v[126:127], v[154:155] op_sel_hi:[1,0]
	v_lshl_add_u64 v[156:157], v[156:157], 0, v[132:133]
	s_waitcnt vmcnt(3)
	v_pk_mul_f32 v[184:185], v[20:21], v[182:183]
	v_pk_mul_f32 v[182:183], v[18:19], v[186:187]
	global_store_dwordx4 v[156:157], v[182:185], off sc1
	v_pk_mul_f32 v[186:187], v[122:123], v[154:155] op_sel_hi:[1,0]
	v_mov_b32_e32 v188, v155
	v_pk_mul_f32 v[182:183], v[124:125], v[154:155] op_sel_hi:[1,0]
	v_pk_mul_f32 v[190:191], v[110:111], v[188:189] op_sel_hi:[1,0]
	s_waitcnt vmcnt(3)
	v_pk_mul_f32 v[184:185], v[32:33], v[182:183]
	v_pk_mul_f32 v[182:183], v[30:31], v[186:187]
	global_store_dwordx4 v[156:157], v[182:185], off offset:16 sc1
	s_mov_b64 s[0:1], 0x100000
	s_nop 0
	v_lshlrev_b64 v[182:183], 13, v[152:153]
	v_lshl_add_u64 v[182:183], s[16:17], 0, v[182:183]
	v_lshl_add_u64 v[186:187], v[182:183], 0, v[132:133]
	v_pk_mul_f32 v[182:183], v[112:113], v[188:189] op_sel_hi:[1,0]
	s_nop 0
	v_pk_mul_f32 v[184:185], v[20:21], v[182:183]
	v_pk_mul_f32 v[182:183], v[18:19], v[190:191]
	global_store_dwordx4 v[186:187], v[182:185], off sc1
	s_nop 1
	v_pk_mul_f32 v[182:183], v[108:109], v[188:189] op_sel_hi:[1,0]
	v_pk_mul_f32 v[188:189], v[106:107], v[188:189] op_sel_hi:[1,0]
	v_pk_mul_f32 v[184:185], v[32:33], v[182:183]
	v_pk_mul_f32 v[182:183], v[30:31], v[188:189]
	global_store_dwordx4 v[186:187], v[182:185], off offset:16 sc1
	s_waitcnt lgkmcnt(2)
	v_pk_mul_f32 v[188:189], v[94:95], v[140:141] op_sel_hi:[1,0]
	v_lshlrev_b64 v[182:183], 13, v[148:149]
	v_lshl_add_u64 v[182:183], s[16:17], 0, v[182:183]
	v_lshl_add_u64 v[186:187], v[182:183], 0, v[132:133]
	v_pk_mul_f32 v[182:183], v[96:97], v[140:141] op_sel_hi:[1,0]
	s_nop 0
	v_pk_mul_f32 v[184:185], v[20:21], v[182:183]
	v_pk_mul_f32 v[182:183], v[18:19], v[188:189]
	global_store_dwordx4 v[186:187], v[182:185], off sc1
	v_pk_mul_f32 v[188:189], v[90:91], v[140:141] op_sel_hi:[1,0]
	s_nop 0
	v_pk_mul_f32 v[182:183], v[92:93], v[140:141] op_sel_hi:[1,0]
	s_nop 0
	v_pk_mul_f32 v[184:185], v[32:33], v[182:183]
	v_pk_mul_f32 v[182:183], v[30:31], v[188:189]
	global_store_dwordx4 v[186:187], v[182:185], off offset:16 sc1
	v_mov_b32_e32 v188, v141
	v_pk_mul_f32 v[190:191], v[78:79], v[188:189] op_sel_hi:[1,0]
	v_lshlrev_b64 v[182:183], 13, v[138:139]
	v_lshl_add_u64 v[182:183], s[16:17], 0, v[182:183]
	v_lshl_add_u64 v[186:187], v[182:183], 0, v[132:133]
	v_pk_mul_f32 v[182:183], v[80:81], v[188:189] op_sel_hi:[1,0]
	s_nop 0
	v_pk_mul_f32 v[184:185], v[20:21], v[182:183]
	v_pk_mul_f32 v[182:183], v[18:19], v[190:191]
	global_store_dwordx4 v[186:187], v[182:185], off sc1
	s_nop 1
	v_pk_mul_f32 v[182:183], v[76:77], v[188:189] op_sel_hi:[1,0]
	v_pk_mul_f32 v[188:189], v[74:75], v[188:189] op_sel_hi:[1,0]
	v_pk_mul_f32 v[184:185], v[32:33], v[182:183]
	v_pk_mul_f32 v[182:183], v[30:31], v[188:189]
	global_store_dwordx4 v[186:187], v[182:185], off offset:16 sc1
	v_lshl_add_u64 v[186:187], v[156:157], 0, s[0:1]
	s_waitcnt lgkmcnt(1)
	v_pk_mul_f32 v[188:189], v[176:177], v[136:137] op_sel_hi:[1,0]
	v_pk_mul_f32 v[182:183], v[174:175], v[136:137] op_sel_hi:[1,0]
	s_mov_b32 s0, 0x100000
	v_pk_mul_f32 v[184:185], v[20:21], v[182:183]
	v_pk_mul_f32 v[182:183], v[18:19], v[188:189]
	v_add_co_u32_e32 v188, vcc, s0, v156
	s_mov_b64 s[0:1], 0x120000
	s_nop 0
	v_addc_co_u32_e32 v189, vcc, 0, v157, vcc
	global_store_dwordx4 v[188:189], v[182:185], off sc1
	v_pk_mul_f32 v[188:189], v[180:181], v[136:137] op_sel_hi:[1,0]
	s_nop 0
	v_pk_mul_f32 v[182:183], v[178:179], v[136:137] op_sel_hi:[1,0]
	s_nop 0
	v_pk_mul_f32 v[184:185], v[32:33], v[182:183]
	v_pk_mul_f32 v[182:183], v[30:31], v[188:189]
	v_mov_b32_e32 v188, v137
	global_store_dwordx4 v[186:187], v[182:185], off offset:16 sc1
	v_lshl_add_u64 v[186:187], v[156:157], 0, s[0:1]
	v_pk_mul_f32 v[190:191], v[170:171], v[188:189] op_sel_hi:[1,0]
	v_pk_mul_f32 v[182:183], v[166:167], v[188:189] op_sel_hi:[1,0]
	s_mov_b32 s0, 0x120000
	v_pk_mul_f32 v[184:185], v[20:21], v[182:183]
	v_pk_mul_f32 v[182:183], v[18:19], v[190:191]
	v_add_co_u32_e32 v190, vcc, s0, v156
	s_mov_b64 s[0:1], 0x140000
	s_nop 0
	v_addc_co_u32_e32 v191, vcc, 0, v157, vcc
	global_store_dwordx4 v[190:191], v[182:185], off sc1
	s_nop 1
	v_pk_mul_f32 v[182:183], v[168:169], v[188:189] op_sel_hi:[1,0]
	v_pk_mul_f32 v[188:189], v[172:173], v[188:189] op_sel_hi:[1,0]
	v_pk_mul_f32 v[184:185], v[32:33], v[182:183]
	v_pk_mul_f32 v[182:183], v[30:31], v[188:189]
	global_store_dwordx4 v[186:187], v[182:185], off offset:16 sc1
	v_lshl_add_u64 v[186:187], v[156:157], 0, s[0:1]
	s_waitcnt lgkmcnt(0)
	v_pk_mul_f32 v[188:189], v[160:161], v[134:135] op_sel_hi:[1,0]
	v_pk_mul_f32 v[182:183], v[158:159], v[134:135] op_sel_hi:[1,0]
	s_mov_b32 s0, 0x140000
	v_pk_mul_f32 v[184:185], v[20:21], v[182:183]
	v_pk_mul_f32 v[182:183], v[18:19], v[188:189]
	v_add_co_u32_e32 v188, vcc, s0, v156
	s_mov_b64 s[0:1], 0x160000
	s_nop 0
	v_addc_co_u32_e32 v189, vcc, 0, v157, vcc
	global_store_dwordx4 v[188:189], v[182:185], off sc1
	v_pk_mul_f32 v[188:189], v[164:165], v[134:135] op_sel_hi:[1,0]
	s_nop 0
	v_pk_mul_f32 v[182:183], v[162:163], v[134:135] op_sel_hi:[1,0]
	s_nop 0
	v_pk_mul_f32 v[184:185], v[32:33], v[182:183]
	v_pk_mul_f32 v[182:183], v[30:31], v[188:189]
	v_mov_b32_e32 v188, v135
	global_store_dwordx4 v[186:187], v[182:185], off offset:16 sc1
	v_lshl_add_u64 v[186:187], v[156:157], 0, s[0:1]
	v_pk_mul_f32 v[190:191], v[150:151], v[188:189] op_sel_hi:[1,0]
	v_pk_mul_f32 v[182:183], v[142:143], v[188:189] op_sel_hi:[1,0]
	v_add_co_u32_e32 v156, vcc, 0x160000, v156
	v_pk_mul_f32 v[184:185], v[20:21], v[182:183]
	v_pk_mul_f32 v[182:183], v[18:19], v[190:191]
	v_addc_co_u32_e32 v157, vcc, 0, v157, vcc
	global_store_dwordx4 v[156:157], v[182:185], off sc1
	v_pk_mul_f32 v[156:157], v[144:145], v[188:189] op_sel_hi:[1,0]
	s_nop 0
	v_pk_mul_f32 v[182:183], v[146:147], v[188:189] op_sel_hi:[1,0]
	v_pk_mul_f32 v[184:185], v[32:33], v[156:157]
	v_pk_mul_f32 v[182:183], v[30:31], v[182:183]
	global_store_dwordx4 v[186:187], v[182:185], off offset:16 sc1
	v_lshlrev_b64 v[156:157], 1, v[206:207]
	s_cbranch_execz .LBB0_1303

.LBB0_1301:
	s_waitcnt vmcnt(3)
	v_lshlrev_b64 v[18:19], 13, v[130:131]
	v_lshl_add_u64 v[18:19], s[16:17], 0, v[18:19]
	s_waitcnt vmcnt(2)
	v_lshl_add_u64 v[22:23], v[18:19], 0, v[132:133]
	s_waitcnt lgkmcnt(3)
	v_pk_mul_f32 v[18:19], v[120:121], v[154:155] op_sel_hi:[1,0]
	v_pk_mul_f32 v[24:25], v[118:119], v[154:155] op_sel_hi:[1,0]
	s_waitcnt vmcnt(1)
	v_pk_mul_f32 v[20:21], v[4:5], v[18:19]
	v_pk_mul_f32 v[18:19], v[2:3], v[24:25]
	global_store_dwordx4 v[22:23], v[18:21], off offset:512 sc1
	v_pk_mul_f32 v[24:25], v[114:115], v[154:155] op_sel_hi:[1,0]
	v_mov_b32_e32 v26, v155
	v_pk_mul_f32 v[18:19], v[116:117], v[154:155] op_sel_hi:[1,0]
	v_pk_mul_f32 v[28:29], v[102:103], v[26:27] op_sel_hi:[1,0]
	s_waitcnt vmcnt(1)
	v_pk_mul_f32 v[20:21], v[16:17], v[18:19]
	v_pk_mul_f32 v[18:19], v[14:15], v[24:25]
	global_store_dwordx4 v[22:23], v[18:21], off offset:528 sc1
	s_mov_b64 s[0:1], 0x100000
	s_nop 0
	v_lshlrev_b64 v[18:19], 13, v[152:153]
	v_lshl_add_u64 v[18:19], s[16:17], 0, v[18:19]
	v_lshl_add_u64 v[24:25], v[18:19], 0, v[132:133]
	v_pk_mul_f32 v[18:19], v[104:105], v[26:27] op_sel_hi:[1,0]
	s_nop 0
	v_pk_mul_f32 v[20:21], v[4:5], v[18:19]
	v_pk_mul_f32 v[18:19], v[2:3], v[28:29]
	global_store_dwordx4 v[24:25], v[18:21], off offset:512 sc1
	s_nop 1
	v_pk_mul_f32 v[18:19], v[100:101], v[26:27] op_sel_hi:[1,0]
	v_pk_mul_f32 v[26:27], v[98:99], v[26:27] op_sel_hi:[1,0]
	v_pk_mul_f32 v[20:21], v[16:17], v[18:19]
	v_pk_mul_f32 v[18:19], v[14:15], v[26:27]
	global_store_dwordx4 v[24:25], v[18:21], off offset:528 sc1
	s_waitcnt lgkmcnt(2)
	v_pk_mul_f32 v[26:27], v[86:87], v[140:141] op_sel_hi:[1,0]
	v_lshlrev_b64 v[18:19], 13, v[148:149]
	v_lshl_add_u64 v[18:19], s[16:17], 0, v[18:19]
	v_lshl_add_u64 v[24:25], v[18:19], 0, v[132:133]
	v_pk_mul_f32 v[18:19], v[88:89], v[140:141] op_sel_hi:[1,0]
	s_nop 0
	v_pk_mul_f32 v[20:21], v[4:5], v[18:19]
	v_pk_mul_f32 v[18:19], v[2:3], v[26:27]
	global_store_dwordx4 v[24:25], v[18:21], off offset:512 sc1
	v_pk_mul_f32 v[26:27], v[82:83], v[140:141] op_sel_hi:[1,0]
	s_nop 0
	v_pk_mul_f32 v[18:19], v[84:85], v[140:141] op_sel_hi:[1,0]
	s_nop 0
	v_pk_mul_f32 v[20:21], v[16:17], v[18:19]
	v_pk_mul_f32 v[18:19], v[14:15], v[26:27]
	global_store_dwordx4 v[24:25], v[18:21], off offset:528 sc1
	v_mov_b32_e32 v26, v141
	v_pk_mul_f32 v[28:29], v[70:71], v[26:27] op_sel_hi:[1,0]
	v_lshlrev_b64 v[18:19], 13, v[138:139]
	v_lshl_add_u64 v[18:19], s[16:17], 0, v[18:19]
	v_lshl_add_u64 v[24:25], v[18:19], 0, v[132:133]
	v_pk_mul_f32 v[18:19], v[72:73], v[26:27] op_sel_hi:[1,0]
	s_nop 0
	v_pk_mul_f32 v[20:21], v[4:5], v[18:19]
	v_pk_mul_f32 v[18:19], v[2:3], v[28:29]
	global_store_dwordx4 v[24:25], v[18:21], off offset:512 sc1
	s_nop 1
	v_pk_mul_f32 v[18:19], v[68:69], v[26:27] op_sel_hi:[1,0]
	v_pk_mul_f32 v[26:27], v[66:67], v[26:27] op_sel_hi:[1,0]
	v_pk_mul_f32 v[20:21], v[16:17], v[18:19]
	v_pk_mul_f32 v[18:19], v[14:15], v[26:27]
	global_store_dwordx4 v[24:25], v[18:21], off offset:528 sc1
	s_waitcnt lgkmcnt(1)
	v_pk_mul_f32 v[26:27], v[54:55], v[136:137] op_sel_hi:[1,0]
	v_lshl_add_u64 v[24:25], v[22:23], 0, s[0:1]
	v_pk_mul_f32 v[18:19], v[56:57], v[136:137] op_sel_hi:[1,0]
	s_mov_b64 s[0:1], 0x120000
	v_pk_mul_f32 v[20:21], v[4:5], v[18:19]
	v_pk_mul_f32 v[18:19], v[2:3], v[26:27]
	global_store_dwordx4 v[24:25], v[18:21], off offset:512 sc1
	v_pk_mul_f32 v[26:27], v[50:51], v[136:137] op_sel_hi:[1,0]
	s_nop 0
	v_pk_mul_f32 v[18:19], v[52:53], v[136:137] op_sel_hi:[1,0]
	s_nop 0
	v_pk_mul_f32 v[20:21], v[16:17], v[18:19]
	v_pk_mul_f32 v[18:19], v[14:15], v[26:27]
	v_mov_b32_e32 v26, v137
	global_store_dwordx4 v[24:25], v[18:21], off offset:528 sc1
	v_pk_mul_f32 v[28:29], v[38:39], v[26:27] op_sel_hi:[1,0]
	v_lshl_add_u64 v[24:25], v[22:23], 0, s[0:1]
	v_pk_mul_f32 v[18:19], v[40:41], v[26:27] op_sel_hi:[1,0]
	s_mov_b64 s[0:1], 0x140000
	v_pk_mul_f32 v[20:21], v[4:5], v[18:19]
	v_pk_mul_f32 v[18:19], v[2:3], v[28:29]
	global_store_dwordx4 v[24:25], v[18:21], off offset:512 sc1
	s_nop 1
	v_pk_mul_f32 v[18:19], v[36:37], v[26:27] op_sel_hi:[1,0]
	v_pk_mul_f32 v[26:27], v[34:35], v[26:27] op_sel_hi:[1,0]
	v_pk_mul_f32 v[20:21], v[16:17], v[18:19]
	v_pk_mul_f32 v[18:19], v[14:15], v[26:27]
	global_store_dwordx4 v[24:25], v[18:21], off offset:528 sc1
	s_waitcnt lgkmcnt(0)
	v_pk_mul_f32 v[26:27], v[44:45], v[134:135] op_sel_hi:[1,0]
	v_lshl_add_u64 v[24:25], v[22:23], 0, s[0:1]
	v_pk_mul_f32 v[18:19], v[42:43], v[134:135] op_sel_hi:[1,0]
	s_mov_b64 s[0:1], 0x160000
	v_pk_mul_f32 v[20:21], v[4:5], v[18:19]
	v_pk_mul_f32 v[18:19], v[2:3], v[26:27]
	global_store_dwordx4 v[24:25], v[18:21], off offset:512 sc1
	v_pk_mul_f32 v[26:27], v[48:49], v[134:135] op_sel_hi:[1,0]
	v_lshl_add_u64 v[22:23], v[22:23], 0, s[0:1]
	v_pk_mul_f32 v[18:19], v[46:47], v[134:135] op_sel_hi:[1,0]
	s_nop 0
	v_pk_mul_f32 v[20:21], v[16:17], v[18:19]
	v_pk_mul_f32 v[18:19], v[14:15], v[26:27]
	global_store_dwordx4 v[24:25], v[18:21], off offset:528 sc1
	v_mov_b32_e32 v24, v135
	v_pk_mul_f32 v[26:27], v[62:63], v[24:25] op_sel_hi:[1,0]
	v_pk_mul_f32 v[18:19], v[58:59], v[24:25] op_sel_hi:[1,0]
	s_nop 0
	v_pk_mul_f32 v[20:21], v[4:5], v[18:19]
	v_pk_mul_f32 v[18:19], v[2:3], v[26:27]
	global_store_dwordx4 v[22:23], v[18:21], off offset:512 sc1
	s_nop 1
	v_pk_mul_f32 v[18:19], v[60:61], v[24:25] op_sel_hi:[1,0]
	v_pk_mul_f32 v[24:25], v[64:65], v[24:25] op_sel_hi:[1,0]
	v_pk_mul_f32 v[20:21], v[16:17], v[18:19]
	v_pk_mul_f32 v[18:19], v[14:15], v[24:25]
	global_store_dwordx4 v[22:23], v[18:21], off offset:528 sc1
	s_cbranch_execz .LBB0_1305
	s_branch .LBB0_1306

.LBB0_1303:
	s_waitcnt lgkmcnt(3)
	v_pk_mul_f32 v[126:127], v[126:127], v[154:155] op_sel_hi:[1,0]
	v_pk_mul_f32 v[124:125], v[124:125], v[154:155] op_sel_hi:[1,0]
	s_waitcnt vmcnt(3)
	v_pk_fma_f32 v[126:127], v[18:19], v[126:127], v[26:27]
	v_pk_mul_f32 v[122:123], v[122:123], v[154:155] op_sel_hi:[1,0]
	s_waitcnt vmcnt(2)
	v_pk_fma_f32 v[182:183], v[32:33], v[124:125], v[24:25]
	v_pk_fma_f32 v[124:125], v[30:31], v[122:123], v[22:23]
	v_cvt_pk_bf16_f32 v122, v126, v127
	v_lshlrev_b64 v[126:127], 12, v[130:131]
	v_lshl_add_u64 v[126:127], s[6:7], 0, v[126:127]
	v_pk_mul_f32 v[128:129], v[128:129], v[154:155] op_sel_hi:[1,0]
	v_lshl_add_u64 v[126:127], v[126:127], 0, v[156:157]
	v_pk_fma_f32 v[128:129], v[20:21], v[128:129], v[28:29]
	s_waitcnt lgkmcnt(2)
	v_pk_mul_f32 v[94:95], v[94:95], v[140:141] op_sel_hi:[1,0]
	v_cvt_pk_bf16_f32 v123, v128, v129
	v_cvt_pk_bf16_f32 v124, v124, v125
	v_cvt_pk_bf16_f32 v125, v182, v183
	global_store_dwordx4 v[126:127], v[122:125], off sc1
	v_pk_fma_f32 v[94:95], v[18:19], v[94:95], v[26:27]
	v_pk_mul_f32 v[92:93], v[92:93], v[140:141] op_sel_hi:[1,0]
	v_mov_b32_e32 v122, v155
	v_pk_mul_f32 v[110:111], v[110:111], v[122:123] op_sel_hi:[1,0]
	v_pk_mul_f32 v[108:109], v[108:109], v[122:123] op_sel_hi:[1,0]
	v_pk_fma_f32 v[110:111], v[18:19], v[110:111], v[26:27]
	v_pk_mul_f32 v[106:107], v[106:107], v[122:123] op_sel_hi:[1,0]
	v_pk_mul_f32 v[112:113], v[112:113], v[122:123] op_sel_hi:[1,0]
	v_pk_fma_f32 v[122:123], v[32:33], v[108:109], v[24:25]
	v_pk_fma_f32 v[108:109], v[30:31], v[106:107], v[22:23]
	v_cvt_pk_bf16_f32 v106, v110, v111
	v_lshlrev_b64 v[110:111], 12, v[152:153]
	v_lshl_add_u64 v[110:111], s[6:7], 0, v[110:111]
	v_pk_fma_f32 v[112:113], v[20:21], v[112:113], v[28:29]
	v_lshl_add_u64 v[110:111], v[110:111], 0, v[156:157]
	v_cvt_pk_bf16_f32 v107, v112, v113
	v_pk_mul_f32 v[90:91], v[90:91], v[140:141] op_sel_hi:[1,0]
	v_cvt_pk_bf16_f32 v108, v108, v109
	v_cvt_pk_bf16_f32 v109, v122, v123
	global_store_dwordx4 v[110:111], v[106:109], off sc1
	v_pk_mul_f32 v[96:97], v[96:97], v[140:141] op_sel_hi:[1,0]
	s_mov_b32 s0, 0x80000
	v_pk_fma_f32 v[106:107], v[32:33], v[92:93], v[24:25]
	v_pk_fma_f32 v[92:93], v[30:31], v[90:91], v[22:23]
	v_cvt_pk_bf16_f32 v90, v94, v95
	v_lshlrev_b64 v[94:95], 12, v[148:149]
	v_lshl_add_u64 v[94:95], s[6:7], 0, v[94:95]
	v_lshl_add_u64 v[94:95], v[94:95], 0, v[156:157]
	v_pk_fma_f32 v[96:97], v[20:21], v[96:97], v[28:29]
	s_nop 0
	v_cvt_pk_bf16_f32 v91, v96, v97
	v_cvt_pk_bf16_f32 v92, v92, v93
	v_cvt_pk_bf16_f32 v93, v106, v107
	global_store_dwordx4 v[94:95], v[90:93], off sc1
	s_nop 1
	v_mov_b32_e32 v90, v141
	v_pk_mul_f32 v[78:79], v[78:79], v[90:91] op_sel_hi:[1,0]
	v_pk_mul_f32 v[76:77], v[76:77], v[90:91] op_sel_hi:[1,0]
	v_pk_fma_f32 v[78:79], v[18:19], v[78:79], v[26:27]
	v_pk_mul_f32 v[74:75], v[74:75], v[90:91] op_sel_hi:[1,0]
	v_pk_mul_f32 v[80:81], v[80:81], v[90:91] op_sel_hi:[1,0]
	v_pk_fma_f32 v[90:91], v[32:33], v[76:77], v[24:25]
	v_pk_fma_f32 v[76:77], v[30:31], v[74:75], v[22:23]
	v_cvt_pk_bf16_f32 v74, v78, v79
	v_lshlrev_b64 v[78:79], 12, v[138:139]
	v_lshl_add_u64 v[78:79], s[6:7], 0, v[78:79]
	v_pk_fma_f32 v[80:81], v[20:21], v[80:81], v[28:29]
	v_lshl_add_u64 v[78:79], v[78:79], 0, v[156:157]
	v_cvt_pk_bf16_f32 v75, v80, v81
	v_cvt_pk_bf16_f32 v76, v76, v77
	v_cvt_pk_bf16_f32 v77, v90, v91
	global_store_dwordx4 v[78:79], v[74:77], off sc1
	s_waitcnt lgkmcnt(1)
	v_pk_mul_f32 v[80:81], v[180:181], v[136:137] op_sel_hi:[1,0]
	v_pk_mul_f32 v[74:75], v[174:175], v[136:137] op_sel_hi:[1,0]
	v_pk_mul_f32 v[76:77], v[176:177], v[136:137] op_sel_hi:[1,0]
	v_pk_fma_f32 v[78:79], v[20:21], v[74:75], v[28:29]
	v_pk_fma_f32 v[74:75], v[18:19], v[76:77], v[26:27]
	v_pk_mul_f32 v[76:77], v[178:179], v[136:137] op_sel_hi:[1,0]
	v_cvt_pk_bf16_f32 v74, v74, v75
	v_cvt_pk_bf16_f32 v75, v78, v79
	v_add_co_u32_e32 v78, vcc, s0, v126
	v_pk_fma_f32 v[90:91], v[32:33], v[76:77], v[24:25]
	v_pk_fma_f32 v[76:77], v[30:31], v[80:81], v[22:23]
	v_addc_co_u32_e32 v79, vcc, 0, v127, vcc
	v_cvt_pk_bf16_f32 v76, v76, v77
	v_cvt_pk_bf16_f32 v77, v90, v91
	global_store_dwordx4 v[78:79], v[74:77], off sc1
	s_mov_b32 s0, 0x90000
	s_nop 0
	v_mov_b32_e32 v74, v137
	v_pk_mul_f32 v[78:79], v[170:171], v[74:75] op_sel_hi:[1,0]
	v_pk_mul_f32 v[76:77], v[166:167], v[74:75] op_sel_hi:[1,0]
	v_pk_fma_f32 v[78:79], v[18:19], v[78:79], v[26:27]
	v_pk_mul_f32 v[80:81], v[168:169], v[74:75] op_sel_hi:[1,0]
	v_pk_mul_f32 v[74:75], v[172:173], v[74:75] op_sel_hi:[1,0]
	v_pk_fma_f32 v[76:77], v[20:21], v[76:77], v[28:29]
	v_pk_fma_f32 v[90:91], v[30:31], v[74:75], v[22:23]
	v_cvt_pk_bf16_f32 v74, v78, v79
	v_add_co_u32_e32 v78, vcc, s0, v126
	v_pk_fma_f32 v[80:81], v[32:33], v[80:81], v[24:25]
	v_cvt_pk_bf16_f32 v75, v76, v77
	v_cvt_pk_bf16_f32 v76, v90, v91
	s_nop 0
	v_addc_co_u32_e32 v79, vcc, 0, v127, vcc
	v_cvt_pk_bf16_f32 v77, v80, v81
	global_store_dwordx4 v[78:79], v[74:77], off sc1
	s_mov_b32 s0, 0xa0000
	s_waitcnt lgkmcnt(0)
	v_pk_mul_f32 v[80:81], v[164:165], v[134:135] op_sel_hi:[1,0]
	v_pk_mul_f32 v[74:75], v[158:159], v[134:135] op_sel_hi:[1,0]
	v_pk_mul_f32 v[76:77], v[160:161], v[134:135] op_sel_hi:[1,0]
	v_pk_fma_f32 v[78:79], v[20:21], v[74:75], v[28:29]
	v_pk_fma_f32 v[74:75], v[18:19], v[76:77], v[26:27]
	v_pk_mul_f32 v[76:77], v[162:163], v[134:135] op_sel_hi:[1,0]
	v_cvt_pk_bf16_f32 v74, v74, v75
	v_cvt_pk_bf16_f32 v75, v78, v79
	v_add_co_u32_e32 v78, vcc, s0, v126
	v_pk_fma_f32 v[90:91], v[32:33], v[76:77], v[24:25]
	v_pk_fma_f32 v[76:77], v[30:31], v[80:81], v[22:23]
	v_addc_co_u32_e32 v79, vcc, 0, v127, vcc
	v_cvt_pk_bf16_f32 v76, v76, v77
	v_cvt_pk_bf16_f32 v77, v90, v91
	global_store_dwordx4 v[78:79], v[74:77], off sc1
	s_nop 1
	v_mov_b32_e32 v74, v135
	v_pk_mul_f32 v[76:77], v[142:143], v[74:75] op_sel_hi:[1,0]
	v_pk_mul_f32 v[78:79], v[150:151], v[74:75] op_sel_hi:[1,0]
	v_pk_fma_f32 v[20:21], v[20:21], v[76:77], v[28:29]
	v_pk_mul_f32 v[28:29], v[146:147], v[74:75] op_sel_hi:[1,0]
	v_pk_fma_f32 v[18:19], v[18:19], v[78:79], v[26:27]
	v_pk_fma_f32 v[22:23], v[30:31], v[28:29], v[22:23]
	v_cvt_pk_bf16_f32 v18, v18, v19
	v_cvt_pk_bf16_f32 v19, v20, v21
	v_pk_mul_f32 v[26:27], v[144:145], v[74:75] op_sel_hi:[1,0]
	v_cvt_pk_bf16_f32 v20, v22, v23
	v_add_co_u32_e32 v22, vcc, 0xb0000, v126
	v_pk_fma_f32 v[24:25], v[32:33], v[26:27], v[24:25]
	s_nop 0
	v_addc_co_u32_e32 v23, vcc, 0, v127, vcc
	v_cvt_pk_bf16_f32 v21, v24, v25
	global_store_dwordx4 v[22:23], v[18:21], off sc1
	s_and_b64 vcc, exec, s[10:11]
	s_mov_b64 s[0:1], -1
	s_cbranch_vccz .LBB0_1301

.LBB0_1305:
	s_waitcnt vmcnt(3) lgkmcnt(3)
	v_pk_mul_f32 v[18:19], v[120:121], v[154:155] op_sel_hi:[1,0]
	v_pk_mul_f32 v[20:21], v[118:119], v[154:155] op_sel_hi:[1,0]
	s_waitcnt vmcnt(1)
	v_pk_fma_f32 v[22:23], v[4:5], v[18:19], v[12:13]
	v_pk_fma_f32 v[18:19], v[2:3], v[20:21], v[10:11]
	v_pk_mul_f32 v[20:21], v[116:117], v[154:155] op_sel_hi:[1,0]
	v_cvt_pk_bf16_f32 v18, v18, v19
	v_cvt_pk_bf16_f32 v19, v22, v23
	v_lshlrev_b64 v[22:23], 12, v[130:131]
	v_pk_mul_f32 v[24:25], v[114:115], v[154:155] op_sel_hi:[1,0]
	v_lshl_add_u64 v[22:23], s[6:7], 0, v[22:23]
	s_waitcnt vmcnt(0)
	v_pk_fma_f32 v[26:27], v[16:17], v[20:21], v[8:9]
	v_pk_fma_f32 v[20:21], v[14:15], v[24:25], v[6:7]
	v_lshl_add_u64 v[22:23], v[22:23], 0, v[156:157]
	v_cvt_pk_bf16_f32 v20, v20, v21
	v_cvt_pk_bf16_f32 v21, v26, v27
	global_store_dwordx4 v[22:23], v[18:21], off offset:256 sc1
	s_mov_b32 s0, 0x80000
	s_nop 0
	v_mov_b32_e32 v18, v155
	v_pk_mul_f32 v[24:25], v[102:103], v[18:19] op_sel_hi:[1,0]
	v_pk_mul_f32 v[20:21], v[104:105], v[18:19] op_sel_hi:[1,0]
	v_pk_fma_f32 v[24:25], v[2:3], v[24:25], v[10:11]
	v_pk_mul_f32 v[26:27], v[100:101], v[18:19] op_sel_hi:[1,0]
	v_pk_mul_f32 v[18:19], v[98:99], v[18:19] op_sel_hi:[1,0]
	v_pk_fma_f32 v[20:21], v[4:5], v[20:21], v[12:13]
	v_pk_fma_f32 v[28:29], v[14:15], v[18:19], v[6:7]
	v_cvt_pk_bf16_f32 v18, v24, v25
	v_lshlrev_b64 v[24:25], 12, v[152:153]
	v_lshl_add_u64 v[24:25], s[6:7], 0, v[24:25]
	v_pk_fma_f32 v[26:27], v[16:17], v[26:27], v[8:9]
	v_cvt_pk_bf16_f32 v19, v20, v21
	v_cvt_pk_bf16_f32 v20, v28, v29
	v_lshl_add_u64 v[24:25], v[24:25], 0, v[156:157]
	v_cvt_pk_bf16_f32 v21, v26, v27
	global_store_dwordx4 v[24:25], v[18:21], off offset:256 sc1
	s_waitcnt lgkmcnt(2)
	v_pk_mul_f32 v[26:27], v[82:83], v[140:141] op_sel_hi:[1,0]
	v_pk_mul_f32 v[18:19], v[88:89], v[140:141] op_sel_hi:[1,0]
	v_pk_mul_f32 v[20:21], v[86:87], v[140:141] op_sel_hi:[1,0]
	v_pk_fma_f32 v[24:25], v[4:5], v[18:19], v[12:13]
	v_pk_fma_f32 v[18:19], v[2:3], v[20:21], v[10:11]
	v_pk_mul_f32 v[20:21], v[84:85], v[140:141] op_sel_hi:[1,0]
	v_cvt_pk_bf16_f32 v18, v18, v19
	v_cvt_pk_bf16_f32 v19, v24, v25
	v_lshlrev_b64 v[24:25], 12, v[148:149]
	v_lshl_add_u64 v[24:25], s[6:7], 0, v[24:25]
	v_pk_fma_f32 v[28:29], v[16:17], v[20:21], v[8:9]
	v_pk_fma_f32 v[20:21], v[14:15], v[26:27], v[6:7]
	v_lshl_add_u64 v[24:25], v[24:25], 0, v[156:157]
	v_cvt_pk_bf16_f32 v20, v20, v21
	v_cvt_pk_bf16_f32 v21, v28, v29
	global_store_dwordx4 v[24:25], v[18:21], off offset:256 sc1
	s_nop 1
	v_mov_b32_e32 v18, v141
	v_pk_mul_f32 v[24:25], v[70:71], v[18:19] op_sel_hi:[1,0]
	v_pk_mul_f32 v[20:21], v[72:73], v[18:19] op_sel_hi:[1,0]
	v_pk_fma_f32 v[24:25], v[2:3], v[24:25], v[10:11]
	v_pk_mul_f32 v[26:27], v[68:69], v[18:19] op_sel_hi:[1,0]
	v_pk_mul_f32 v[18:19], v[66:67], v[18:19] op_sel_hi:[1,0]
	v_pk_fma_f32 v[20:21], v[4:5], v[20:21], v[12:13]
	v_pk_fma_f32 v[28:29], v[14:15], v[18:19], v[6:7]
	v_cvt_pk_bf16_f32 v18, v24, v25
	v_lshlrev_b64 v[24:25], 12, v[138:139]
	v_lshl_add_u64 v[24:25], s[6:7], 0, v[24:25]
	v_pk_fma_f32 v[26:27], v[16:17], v[26:27], v[8:9]
	v_cvt_pk_bf16_f32 v19, v20, v21
	v_cvt_pk_bf16_f32 v20, v28, v29
	v_lshl_add_u64 v[24:25], v[24:25], 0, v[156:157]
	v_cvt_pk_bf16_f32 v21, v26, v27
	global_store_dwordx4 v[24:25], v[18:21], off offset:256 sc1
	s_waitcnt lgkmcnt(1)
	v_pk_mul_f32 v[26:27], v[50:51], v[136:137] op_sel_hi:[1,0]
	v_pk_mul_f32 v[18:19], v[56:57], v[136:137] op_sel_hi:[1,0]
	v_pk_mul_f32 v[20:21], v[54:55], v[136:137] op_sel_hi:[1,0]
	v_pk_fma_f32 v[24:25], v[4:5], v[18:19], v[12:13]
	v_pk_fma_f32 v[18:19], v[2:3], v[20:21], v[10:11]
	v_pk_mul_f32 v[20:21], v[52:53], v[136:137] op_sel_hi:[1,0]
	v_cvt_pk_bf16_f32 v18, v18, v19
	v_cvt_pk_bf16_f32 v19, v24, v25
	v_add_co_u32_e32 v24, vcc, s0, v22
	v_pk_fma_f32 v[28:29], v[16:17], v[20:21], v[8:9]
	v_pk_fma_f32 v[20:21], v[14:15], v[26:27], v[6:7]
	v_addc_co_u32_e32 v25, vcc, 0, v23, vcc
	v_cvt_pk_bf16_f32 v20, v20, v21
	v_cvt_pk_bf16_f32 v21, v28, v29
	global_store_dwordx4 v[24:25], v[18:21], off offset:256 sc1
	s_mov_b32 s0, 0x90000
	s_nop 0
	v_mov_b32_e32 v18, v137
	v_pk_mul_f32 v[24:25], v[38:39], v[18:19] op_sel_hi:[1,0]
	v_pk_mul_f32 v[20:21], v[40:41], v[18:19] op_sel_hi:[1,0]
	v_pk_fma_f32 v[24:25], v[2:3], v[24:25], v[10:11]
	v_pk_mul_f32 v[26:27], v[36:37], v[18:19] op_sel_hi:[1,0]
	v_pk_mul_f32 v[18:19], v[34:35], v[18:19] op_sel_hi:[1,0]
	v_pk_fma_f32 v[20:21], v[4:5], v[20:21], v[12:13]
	v_pk_fma_f32 v[28:29], v[14:15], v[18:19], v[6:7]
	v_cvt_pk_bf16_f32 v18, v24, v25
	v_add_co_u32_e32 v24, vcc, s0, v22
	v_pk_fma_f32 v[26:27], v[16:17], v[26:27], v[8:9]
	v_cvt_pk_bf16_f32 v19, v20, v21
	v_cvt_pk_bf16_f32 v20, v28, v29
	s_nop 0
	v_addc_co_u32_e32 v25, vcc, 0, v23, vcc
	v_cvt_pk_bf16_f32 v21, v26, v27
	global_store_dwordx4 v[24:25], v[18:21], off offset:256 sc1
	s_mov_b32 s0, 0xa0000
	s_waitcnt lgkmcnt(0)
	v_pk_mul_f32 v[26:27], v[48:49], v[134:135] op_sel_hi:[1,0]
	v_pk_mul_f32 v[18:19], v[42:43], v[134:135] op_sel_hi:[1,0]
	v_pk_mul_f32 v[20:21], v[44:45], v[134:135] op_sel_hi:[1,0]
	v_pk_fma_f32 v[24:25], v[4:5], v[18:19], v[12:13]
	v_pk_fma_f32 v[18:19], v[2:3], v[20:21], v[10:11]
	v_pk_mul_f32 v[20:21], v[46:47], v[134:135] op_sel_hi:[1,0]
	v_cvt_pk_bf16_f32 v18, v18, v19
	v_cvt_pk_bf16_f32 v19, v24, v25
	v_add_co_u32_e32 v24, vcc, s0, v22
	v_pk_fma_f32 v[28:29], v[16:17], v[20:21], v[8:9]
	v_pk_fma_f32 v[20:21], v[14:15], v[26:27], v[6:7]
	v_addc_co_u32_e32 v25, vcc, 0, v23, vcc
	v_cvt_pk_bf16_f32 v20, v20, v21
	v_cvt_pk_bf16_f32 v21, v28, v29
	global_store_dwordx4 v[24:25], v[18:21], off offset:256 sc1
	s_nop 1
	v_mov_b32_e32 v18, v135
	v_pk_mul_f32 v[20:21], v[58:59], v[18:19] op_sel_hi:[1,0]
	v_pk_mul_f32 v[24:25], v[62:63], v[18:19] op_sel_hi:[1,0]
	v_pk_fma_f32 v[4:5], v[4:5], v[20:21], v[12:13]
	v_pk_mul_f32 v[12:13], v[64:65], v[18:19] op_sel_hi:[1,0]
	v_pk_fma_f32 v[2:3], v[2:3], v[24:25], v[10:11]
	v_pk_fma_f32 v[6:7], v[14:15], v[12:13], v[6:7]
	v_cvt_pk_bf16_f32 v2, v2, v3
	v_cvt_pk_bf16_f32 v3, v4, v5
	v_pk_mul_f32 v[10:11], v[60:61], v[18:19] op_sel_hi:[1,0]
	v_cvt_pk_bf16_f32 v4, v6, v7
	v_add_co_u32_e32 v6, vcc, 0xb0000, v22
	v_pk_fma_f32 v[8:9], v[16:17], v[10:11], v[8:9]
	s_nop 0
	v_addc_co_u32_e32 v7, vcc, 0, v23, vcc
	v_cvt_pk_bf16_f32 v5, v8, v9
	global_store_dwordx4 v[6:7], v[2:5], off offset:256 sc1
